# in-proj conv epilogue: 768 dead zero-initialisations in front of full-mask row_ror DPP moves deleted (wait states re-padded where the DPP source was just written)
# speedup vs baseline: 1.0179x; 1.0083x over previous
; __device__ __forceinline__ float dpp_ror1(float v) { return __builtin_bit_cast(float, __builtin_amdgcn_update_dpp(0, __builtin_bit_cast(int, v), 0x121, 0xf, 0xf, false)); }
; __device__ __forceinline__ float dpp_ror2(float v) { return __builtin_bit_cast(float, __builtin_amdgcn_update_dpp(0, __builtin_bit_cast(int, v), 0x122, 0xf, 0xf, false)); }
; __device__ __forceinline__ float dpp_ror3(float v) { return __builtin_bit_cast(float, __builtin_amdgcn_update_dpp(0, __builtin_bit_cast(int, v), 0x123, 0xf, 0xf, false)); }
;     __device__ __forceinline__ void operator()(f32x4 (&acc)[2][2][4][2], const pg8::Unit& u, int wr, int wc, int fr, int fq) const {
;     ...
;                 for (int n = 0; n < 2; ++n) { const int ch = ch0 + bj * 128 + 4 * n;
;                     const f32x4 w0 = *(const f32x4*)(cw + ch), w1 = *(const f32x4*)(cw + CW + ch), w2 = *(const f32x4*)(cw + 2 * CW + ch), w3 = *(const f32x4*)(cw + 3 * CW + ch), bb = *(const f32x4*)(cb + ch);
; #pragma unroll
;                     for (int m = 0; m < 4; ++m) { const int row = row0 + ai * 128 + m * 16; const f32x4 g = acc[ai][bj][m][n]; f32x4 p1, p2, p3;
;                         if (prompt) { const f32x4 gp = (m == 0) ? hal[n] : acc[ai][bj][m > 0 ? m - 1 : 0][n];
; #pragma unroll
;                             for (int j = 0; j < 4; ++j) { p1[j] = dpp_ror1(fr == 15 ? gp[j] : g[j]); p2[j] = dpp_ror2(fr >= 14 ? gp[j] : g[j]); p3[j] = dpp_ror3(fr >= 13 ? gp[j] : g[j]); } }
;                         else { const int t = fr & 3; const float* sp = stp + (size_t)((row - MP) >> 2) * 3 * CW + ch;
;                             const f32x4 b0 = *(const f32x4*)sp, b1 = *(const f32x4*)(sp + CW), b2 = *(const f32x4*)(sp + 2 * CW);
; #pragma unroll
;                             for (int j = 0; j < 4; ++j) { const float r1 = dpp_ror1(g[j]), r2 = dpp_ror2(g[j]), r3 = dpp_ror3(g[j]);
;                                 p1[j] = t >= 1 ? r1 : b2[j]; p2[j] = t >= 2 ? r2 : (t == 1 ? b2[j] : b1[j]); p3[j] = t >= 3 ? r3 : (t == 2 ? b2[j] : (t == 1 ? b1[j] : b0[j])); } }
.LBB0_287:
	s_and_b64 s[2:3], s[4:5], exec
	v_readlane_b32 s2, v255, 13
	v_readlane_b32 s3, v255, 14
	s_cselect_b32 s3, 0, s3
	s_cselect_b32 s2, 0, s2
	s_lshl_b64 s[2:3], s[2:3], 2
	s_add_u32 s2, s38, s2
	s_addc_u32 s3, s39, s3
	s_lshl_b32 s24, s47, 2
	s_add_u32 s8, s2, s24
	s_addc_u32 s9, s3, 0
	s_lshl_b32 s27, s47, 1
	s_lshl_b32 s10, s47, 3
	s_add_u32 s10, s2, s10
	s_addc_u32 s11, s3, 0
	s_mul_i32 s12, s47, 12
	s_add_u32 s12, s2, s12
	s_addc_u32 s13, s3, 0
	s_and_b64 s[14:15], s[4:5], exec
	v_readlane_b32 s14, v255, 15
	v_readlane_b32 s15, v255, 16
	s_cselect_b32 s15, 0, s15
	s_cselect_b32 s14, 0, s14
	s_lshl_b64 s[14:15], s[14:15], 2
	s_add_u32 s14, s40, s14
	v_ashrrev_i32_e32 v221, 31, v220
	s_addc_u32 s15, s41, s15
	v_lshlrev_b64 v[158:159], 2, v[220:221]
	v_lshl_add_u64 v[210:211], s[2:3], 0, v[158:159]
	v_lshl_add_u64 v[214:215], s[10:11], 0, v[158:159]
	v_lshl_add_u64 v[218:219], s[14:15], 0, v[158:159]
	v_lshl_add_u64 v[212:213], s[8:9], 0, v[158:159]
	global_load_dwordx4 v[134:137], v[210:211], off
	global_load_dwordx4 v[154:157], v[212:213], off
	v_lshl_add_u64 v[216:217], s[12:13], 0, v[158:159]
	global_load_dwordx4 v[138:141], v[214:215], off
	global_load_dwordx4 v[150:153], v[216:217], off
	global_load_dwordx4 v[142:145], v[218:219], off
	s_and_b64 s[2:3], s[4:5], exec
	v_readlane_b32 s2, v255, 17
	v_readlane_b32 s3, v255, 18
	s_cselect_b32 s3, 0, s3
	s_cselect_b32 s2, 0, s2
	v_readlane_b32 s52, v254, 2
	s_lshl_b64 s[2:3], s[2:3], 2
	v_readlane_b32 s58, v254, 8
	v_readlane_b32 s59, v254, 9
	s_add_u32 s2, s58, s2
	s_addc_u32 s3, s59, s3
	v_cmp_eq_u32_e64 s[16:17], 0, v205
	v_cmp_lt_u32_e64 s[12:13], 1, v205
	v_cmp_eq_u32_e64 s[14:15], 1, v205
	v_cmp_eq_u32_e64 s[10:11], 15, v207
	v_cmp_lt_i32_e64 s[8:9], 13, v207
	v_lshl_add_u64 v[208:209], s[2:3], 0, v[158:159]
	s_mov_b64 s[2:3], -1
	s_and_b64 vcc, exec, s[80:81]
	v_mov_b32_e32 v228, v122
	v_mov_b32_e32 v226, v123
	v_mov_b32_e32 v224, v124
	v_mov_b32_e32 v222, v125
	v_readlane_b32 s53, v254, 3
	v_readlane_b32 s54, v254, 4
	v_readlane_b32 s55, v254, 5
	v_readlane_b32 s56, v254, 6
	v_readlane_b32 s57, v254, 7
	v_readlane_b32 s60, v254, 10
	v_readlane_b32 s61, v254, 11
	v_readlane_b32 s62, v254, 12
	v_readlane_b32 s63, v254, 13
	v_readlane_b32 s64, v254, 14
	v_readlane_b32 s65, v254, 15
	v_readlane_b32 s66, v254, 16
	v_readlane_b32 s67, v254, 17
	s_cbranch_vccz .LBB0_329
	v_add_u32_e32 v159, 0xffffe000, v202
	v_ashrrev_i32_e32 v159, 2, v159
	v_lshl_add_u32 v159, v159, 1, v159
	v_mad_i64_i32 v[160:161], s[2:3], v159, s47, 0
	v_lshl_add_u64 v[160:161], v[160:161], 2, v[208:209]
	v_lshl_add_u64 v[162:163], v[160:161], 0, s[24:25]
	s_lshl_b32 s2, s27, 2
	s_mov_b32 s3, s25
	global_load_dwordx4 v[170:173], v[160:161], off
	s_nop 0
	global_load_dwordx4 v[162:165], v[162:163], off
	v_lshl_add_u64 v[160:161], v[160:161], 0, s[2:3]
	global_load_dwordx4 v[166:169], v[160:161], off
	v_mov_b32_dpp v182, v122 row_ror:1 row_mask:0xf bank_mask:0xf
	v_mov_b32_dpp v221, v122 row_ror:2 row_mask:0xf bank_mask:0xf
	v_mov_b32_dpp v158, v122 row_ror:3 row_mask:0xf bank_mask:0xf
	v_cmp_lt_i32_e32 vcc, 1, v205
	s_and_saveexec_b64 s[2:3], vcc
	s_xor_b64 s[2:3], exec, s[2:3]
	s_cbranch_execz .LBB0_292
	v_cmp_gt_i32_e32 vcc, 3, v205
	s_and_saveexec_b64 s[18:19], vcc
	s_cbranch_execz .LBB0_291
	s_waitcnt vmcnt(0)
	v_mov_b32_e32 v158, v166

; __device__ __forceinline__ float dpp_ror1(float v) { return __builtin_bit_cast(float, __builtin_amdgcn_update_dpp(0, __builtin_bit_cast(int, v), 0x121, 0xf, 0xf, false)); }
; __device__ __forceinline__ float dpp_ror2(float v) { return __builtin_bit_cast(float, __builtin_amdgcn_update_dpp(0, __builtin_bit_cast(int, v), 0x122, 0xf, 0xf, false)); }
; __device__ __forceinline__ float dpp_ror3(float v) { return __builtin_bit_cast(float, __builtin_amdgcn_update_dpp(0, __builtin_bit_cast(int, v), 0x123, 0xf, 0xf, false)); }
;     __device__ __forceinline__ void operator()(f32x4 (&acc)[2][2][4][2], const pg8::Unit& u, int wr, int wc, int fr, int fq) const {
;     ...
;                             for (int j = 0; j < 4; ++j) { const float r1 = dpp_ror1(g[j]), r2 = dpp_ror2(g[j]), r3 = dpp_ror3(g[j]);
;                                 p1[j] = t >= 1 ? r1 : b2[j]; p2[j] = t >= 2 ? r2 : (t == 1 ? b2[j] : b1[j]); p3[j] = t >= 3 ? r3 : (t == 2 ? b2[j] : (t == 1 ? b1[j] : b0[j])); } }
.LBB0_298:
	s_or_b64 exec, exec, s[2:3]
	v_mov_b32_dpp v222, v123 row_ror:1 row_mask:0xf bank_mask:0xf
	v_mov_b32_dpp v223, v123 row_ror:2 row_mask:0xf bank_mask:0xf
	v_mov_b32_dpp v159, v123 row_ror:3 row_mask:0xf bank_mask:0xf
	v_cmp_lt_i32_e32 vcc, 1, v205
	s_and_saveexec_b64 s[2:3], vcc
	s_xor_b64 s[2:3], exec, s[2:3]
	s_cbranch_execz .LBB0_302
	v_cmp_gt_i32_e32 vcc, 3, v205
	s_and_saveexec_b64 s[18:19], vcc
	s_cbranch_execz .LBB0_301
	s_waitcnt vmcnt(0)
	v_mov_b32_e32 v159, v167

; __device__ __forceinline__ float dpp_ror1(float v) { return __builtin_bit_cast(float, __builtin_amdgcn_update_dpp(0, __builtin_bit_cast(int, v), 0x121, 0xf, 0xf, false)); }
; __device__ __forceinline__ float dpp_ror2(float v) { return __builtin_bit_cast(float, __builtin_amdgcn_update_dpp(0, __builtin_bit_cast(int, v), 0x122, 0xf, 0xf, false)); }
; __device__ __forceinline__ float dpp_ror3(float v) { return __builtin_bit_cast(float, __builtin_amdgcn_update_dpp(0, __builtin_bit_cast(int, v), 0x123, 0xf, 0xf, false)); }
;     __device__ __forceinline__ void operator()(f32x4 (&acc)[2][2][4][2], const pg8::Unit& u, int wr, int wc, int fr, int fq) const {
;     ...
;                             for (int j = 0; j < 4; ++j) { const float r1 = dpp_ror1(g[j]), r2 = dpp_ror2(g[j]), r3 = dpp_ror3(g[j]);
;                                 p1[j] = t >= 1 ? r1 : b2[j]; p2[j] = t >= 2 ? r2 : (t == 1 ? b2[j] : b1[j]); p3[j] = t >= 3 ? r3 : (t == 2 ? b2[j] : (t == 1 ? b1[j] : b0[j])); } }
.LBB0_308:
	s_or_b64 exec, exec, s[2:3]
	v_mov_b32_dpp v224, v124 row_ror:1 row_mask:0xf bank_mask:0xf
	v_mov_b32_dpp v225, v124 row_ror:2 row_mask:0xf bank_mask:0xf
	v_mov_b32_dpp v160, v124 row_ror:3 row_mask:0xf bank_mask:0xf
	v_cmp_lt_i32_e32 vcc, 1, v205
	s_and_saveexec_b64 s[2:3], vcc
	s_xor_b64 s[2:3], exec, s[2:3]
	s_cbranch_execz .LBB0_312
	v_cmp_gt_i32_e32 vcc, 3, v205
	s_and_saveexec_b64 s[18:19], vcc
	s_cbranch_execz .LBB0_311
	s_waitcnt vmcnt(0)
	v_mov_b32_e32 v160, v168

; __device__ __forceinline__ float dpp_ror1(float v) { return __builtin_bit_cast(float, __builtin_amdgcn_update_dpp(0, __builtin_bit_cast(int, v), 0x121, 0xf, 0xf, false)); }
; __device__ __forceinline__ float dpp_ror2(float v) { return __builtin_bit_cast(float, __builtin_amdgcn_update_dpp(0, __builtin_bit_cast(int, v), 0x122, 0xf, 0xf, false)); }
; __device__ __forceinline__ float dpp_ror3(float v) { return __builtin_bit_cast(float, __builtin_amdgcn_update_dpp(0, __builtin_bit_cast(int, v), 0x123, 0xf, 0xf, false)); }
;     __device__ __forceinline__ void operator()(f32x4 (&acc)[2][2][4][2], const pg8::Unit& u, int wr, int wc, int fr, int fq) const {
;     ...
;                             for (int j = 0; j < 4; ++j) { const float r1 = dpp_ror1(g[j]), r2 = dpp_ror2(g[j]), r3 = dpp_ror3(g[j]);
;                                 p1[j] = t >= 1 ? r1 : b2[j]; p2[j] = t >= 2 ? r2 : (t == 1 ? b2[j] : b1[j]); p3[j] = t >= 3 ? r3 : (t == 2 ? b2[j] : (t == 1 ? b1[j] : b0[j])); } }
.LBB0_318:
	s_or_b64 exec, exec, s[2:3]
	v_mov_b32_dpp v227, v125 row_ror:1 row_mask:0xf bank_mask:0xf
	v_mov_b32_dpp v226, v125 row_ror:2 row_mask:0xf bank_mask:0xf
	v_mov_b32_dpp v161, v125 row_ror:3 row_mask:0xf bank_mask:0xf
	v_cmp_lt_i32_e32 vcc, 1, v205
	s_and_saveexec_b64 s[2:3], vcc
	s_xor_b64 s[2:3], exec, s[2:3]
	s_cbranch_execz .LBB0_322
	v_cmp_gt_i32_e32 vcc, 3, v205
	s_and_saveexec_b64 s[18:19], vcc
	s_cbranch_execz .LBB0_321
	s_waitcnt vmcnt(0)
	v_mov_b32_e32 v161, v169

; __device__ __forceinline__ unsigned cvt_pk_bf16(float lo, float hi) { unsigned r; asm("v_cvt_pk_bf16_f32 %0, %1, %2" : "=v"(r) : "v"(lo), "v"(hi)); return r; }
; __device__ __forceinline__ float siluf_(float x) { return x * sigmoidf_(x); }
; __device__ __forceinline__ float dpp_ror1(float v) { return __builtin_bit_cast(float, __builtin_amdgcn_update_dpp(0, __builtin_bit_cast(int, v), 0x121, 0xf, 0xf, false)); }
; __device__ __forceinline__ float dpp_ror2(float v) { return __builtin_bit_cast(float, __builtin_amdgcn_update_dpp(0, __builtin_bit_cast(int, v), 0x122, 0xf, 0xf, false)); }
; __device__ __forceinline__ float dpp_ror3(float v) { return __builtin_bit_cast(float, __builtin_amdgcn_update_dpp(0, __builtin_bit_cast(int, v), 0x123, 0xf, 0xf, false)); }
;     __device__ __forceinline__ void operator()(f32x4 (&acc)[2][2][4][2], const pg8::Unit& u, int wr, int wc, int fr, int fq) const {
;     ...
;                         if (prompt) { const f32x4 gp = (m == 0) ? hal[n] : acc[ai][bj][m > 0 ? m - 1 : 0][n];
; #pragma unroll
;                             for (int j = 0; j < 4; ++j) { p1[j] = dpp_ror1(fr == 15 ? gp[j] : g[j]); p2[j] = dpp_ror2(fr >= 14 ? gp[j] : g[j]); p3[j] = dpp_ror3(fr >= 13 ? gp[j] : g[j]); } }
;                         else { const int t = fr & 3; const float* sp = stp + (size_t)((row - MP) >> 2) * 3 * CW + ch;
;                             const f32x4 b0 = *(const f32x4*)sp, b1 = *(const f32x4*)(sp + CW), b2 = *(const f32x4*)(sp + 2 * CW);
; #pragma unroll
;                             for (int j = 0; j < 4; ++j) { const float r1 = dpp_ror1(g[j]), r2 = dpp_ror2(g[j]), r3 = dpp_ror3(g[j]);
;                                 p1[j] = t >= 1 ? r1 : b2[j]; p2[j] = t >= 2 ? r2 : (t == 1 ? b2[j] : b1[j]); p3[j] = t >= 3 ? r3 : (t == 2 ? b2[j] : (t == 1 ? b1[j] : b0[j])); } }
;                         float o[4];
; #pragma unroll
;                         for (int j = 0; j < 4; ++j) { const float y = bb[j] + w0[j] * p3[j] + w1[j] * p2[j] + w2[j] * p1[j] + w3[j] * g[j]; o[j] = is_rg ? y : siluf_(y); }
;                         u32x2 w; w.x = cvt_pk_bf16(o[0], o[1]); w.y = cvt_pk_bf16(o[2], o[3]);
;                         *(u32x2*)(dst + (size_t)row * ld + bj * 128 + 4 * n) = w; }
.LBB0_329:
	s_and_b64 vcc, exec, s[2:3]
	s_cbranch_vccz .LBB0_331
	s_waitcnt vmcnt(0) lgkmcnt(0)
	v_cndmask_b32_e64 v158, v122, v146, s[10:11]
	s_nop 1
	v_mov_b32_dpp v170, v158 row_ror:1 row_mask:0xf bank_mask:0xf
	v_cndmask_b32_e64 v158, v122, v146, s[8:9]
	v_cndmask_b32_e64 v146, v122, v146, s[6:7]
	s_nop 0
	v_mov_b32_dpp v162, v158 row_ror:2 row_mask:0xf bank_mask:0xf
	v_mov_b32_dpp v158, v146 row_ror:3 row_mask:0xf bank_mask:0xf
	v_cndmask_b32_e64 v146, v123, v147, s[10:11]
	s_nop 1
	v_mov_b32_dpp v171, v146 row_ror:1 row_mask:0xf bank_mask:0xf
	v_cndmask_b32_e64 v146, v123, v147, s[8:9]
	s_nop 1
	v_mov_b32_dpp v163, v146 row_ror:2 row_mask:0xf bank_mask:0xf
	v_cndmask_b32_e64 v146, v123, v147, s[6:7]
	s_nop 0
	s_nop 0
	v_mov_b32_dpp v159, v146 row_ror:3 row_mask:0xf bank_mask:0xf
	v_cndmask_b32_e64 v146, v124, v148, s[10:11]
	s_nop 1
	v_mov_b32_dpp v172, v146 row_ror:1 row_mask:0xf bank_mask:0xf
	v_cndmask_b32_e64 v146, v124, v148, s[8:9]
	s_nop 1
	v_mov_b32_dpp v164, v146 row_ror:2 row_mask:0xf bank_mask:0xf
	v_cndmask_b32_e64 v146, v124, v148, s[6:7]
	s_nop 1
	v_mov_b32_dpp v160, v146 row_ror:3 row_mask:0xf bank_mask:0xf
	v_cndmask_b32_e64 v146, v125, v149, s[10:11]
	s_nop 1
	v_mov_b32_dpp v173, v146 row_ror:1 row_mask:0xf bank_mask:0xf
	v_cndmask_b32_e64 v146, v125, v149, s[8:9]
	s_nop 1
	v_mov_b32_dpp v165, v146 row_ror:2 row_mask:0xf bank_mask:0xf
	v_cndmask_b32_e64 v146, v125, v149, s[6:7]
	s_nop 1
	v_mov_b32_dpp v161, v146 row_ror:3 row_mask:0xf bank_mask:0xf
.LBB0_331:
	s_movk_i32 s2, 0x800
	v_cmp_gt_i32_e32 vcc, s2, v220
	s_waitcnt vmcnt(0) lgkmcnt(0)
	v_add_u32_e32 v148, 0xfffff800, v220
	v_mov_b32_e32 v166, v154
	v_cndmask_b32_e32 v146, v249, v250, vcc
	v_cndmask_b32_e64 v182, v146, v251, s[4:5]
	v_lshl_add_u64 v[146:147], s[74:75], 0, v[182:183]
	v_cndmask_b32_e32 v182, v148, v220, vcc
	v_mov_b32_e32 v167, v134
	v_mov_b32_e32 v148, v162
	v_mov_b32_e32 v149, v158
	v_pk_mul_f32 v[148:149], v[166:167], v[148:149]
	v_mov_b32_e32 v168, v150
	v_add_f32_e32 v134, v142, v149
	v_mov_b32_e32 v169, v138
	v_mov_b32_e32 v229, v170
	v_add_f32_e32 v134, v148, v134
	v_pk_mul_f32 v[148:149], v[168:169], v[228:229]
	v_mov_b32_e32 v158, v163
	v_add_f32_e32 v134, v149, v134
	v_add_f32_e32 v150, v148, v134
	v_mul_f32_e32 v134, 0xbfb8aa3b, v150
	v_exp_f32_e32 v134, v134
	v_cndmask_b32_e64 v148, v182, v204, s[4:5]
	v_ashrrev_i32_e32 v149, 31, v148
	v_lshl_add_u64 v[220:221], v[148:149], 1, v[146:147]
	v_add_f32_e32 v134, 1.0, v134
	v_rcp_f32_e32 v148, v134
	v_mov_b32_e32 v134, v155
	v_pk_mul_f32 v[146:147], v[134:135], v[158:159]
	v_mov_b32_e32 v227, v171
	v_add_f32_e32 v138, v143, v147
	v_add_f32_e32 v149, v146, v138
	v_mov_b32_e32 v138, v151
	v_pk_mul_f32 v[146:147], v[138:139], v[226:227]
	v_mov_b32_e32 v162, v156
	v_add_f32_e32 v147, v147, v149
	v_add_f32_e32 v149, v146, v147
	v_mul_f32_e32 v146, 0xbfb8aa3b, v149
	v_exp_f32_e32 v146, v146
	v_mul_f32_e32 v147, v150, v148
	v_cndmask_b32_e64 v148, v147, v150, s[4:5]
	v_mov_b32_e32 v163, v136
	v_add_f32_e32 v146, 1.0, v146
	v_rcp_f32_e32 v150, v146
	v_mov_b32_e32 v146, v164
	v_mov_b32_e32 v147, v160
	v_pk_mul_f32 v[146:147], v[162:163], v[146:147]
	v_mov_b32_e32 v170, v152
	v_add_f32_e32 v136, v144, v147
	v_mov_b32_e32 v171, v140
	v_mov_b32_e32 v225, v172
	v_add_f32_e32 v136, v146, v136
	v_pk_mul_f32 v[146:147], v[170:171], v[224:225]
	v_mov_b32_e32 v160, v165
	v_add_f32_e32 v136, v147, v136
	v_add_f32_e32 v151, v146, v136
	v_mul_f32_e32 v136, 0xbfb8aa3b, v151
	v_exp_f32_e32 v152, v136
	v_mov_b32_e32 v136, v157
	v_pk_mul_f32 v[146:147], v[136:137], v[160:161]
	v_mov_b32_e32 v223, v173
	v_add_f32_e32 v140, v145, v147
	v_add_f32_e32 v154, v146, v140
	v_mov_b32_e32 v140, v153
	v_pk_mul_f32 v[146:147], v[140:141], v[222:223]
	v_add_f32_e32 v152, 1.0, v152
	v_add_f32_e32 v147, v147, v154
	v_add_f32_e32 v146, v146, v147
	v_mul_f32_e32 v147, 0xbfb8aa3b, v146
	v_exp_f32_e32 v147, v147
	v_rcp_f32_e32 v152, v152
	s_or_b64 s[2:3], s[4:5], vcc
	v_mul_f32_e32 v150, v149, v150
	v_add_f32_e32 v147, 1.0, v147
	v_rcp_f32_e32 v147, v147
	v_cndmask_b32_e64 v182, 10, 11, s[2:3]
	v_cndmask_b32_e64 v149, v150, v149, s[4:5]
	v_mul_f32_e32 v150, v151, v152
	v_mul_f32_e32 v147, v146, v147
	v_cndmask_b32_e64 v147, v147, v146, s[4:5]
	v_cvt_pk_bf16_f32 v146, v148, v149
	v_lshlrev_b64 v[148:149], v182, v[202:203]
	v_lshl_add_u64 v[222:223], v[148:149], 1, v[220:221]
	v_cndmask_b32_e64 v150, v150, v151, s[4:5]
	v_cvt_pk_bf16_f32 v147, v150, v147
	flat_store_dwordx2 v[222:223], v[146:147]
	v_cndmask_b32_e64 v146, 0, 1, s[80:81]
	s_mov_b64 s[2:3], -1
	v_cmp_ne_u32_e64 s[18:19], 1, v146
	s_andn2_b64 vcc, exec, s[80:81]
	v_mov_b32_e32 v172, v110
	v_mov_b32_e32 v164, v111
	v_mov_b32_e32 v156, v112
	v_mov_b32_e32 v154, v113
	s_cbranch_vccnz .LBB0_373
	v_add_u32_e32 v147, 0xffffe010, v202
	v_ashrrev_i32_e32 v147, 2, v147
	v_lshl_add_u32 v147, v147, 1, v147
	v_mad_i64_i32 v[148:149], s[2:3], v147, s47, 0
	v_lshl_add_u64 v[148:149], v[148:149], 2, v[208:209]
	v_lshl_add_u64 v[150:151], v[148:149], 0, s[24:25]
	s_lshl_b32 s2, s27, 2
	s_mov_b32 s3, s25
	global_load_dwordx4 v[158:161], v[148:149], off
	s_nop 0
	global_load_dwordx4 v[150:153], v[150:151], off
	v_lshl_add_u64 v[148:149], v[148:149], 0, s[2:3]
	global_load_dwordx4 v[154:157], v[148:149], off
	v_mov_b32_dpp v164, v110 row_ror:1 row_mask:0xf bank_mask:0xf
	v_mov_b32_dpp v165, v110 row_ror:2 row_mask:0xf bank_mask:0xf
	v_mov_b32_dpp v146, v110 row_ror:3 row_mask:0xf bank_mask:0xf
	v_cmp_lt_i32_e32 vcc, 1, v205
	s_and_saveexec_b64 s[2:3], vcc
	s_xor_b64 s[2:3], exec, s[2:3]
	s_cbranch_execz .LBB0_336
	v_cmp_gt_i32_e32 vcc, 3, v205
	s_and_saveexec_b64 s[80:81], vcc
	s_cbranch_execz .LBB0_335
	s_waitcnt vmcnt(0)
	v_mov_b32_e32 v146, v154

; __device__ __forceinline__ float dpp_ror1(float v) { return __builtin_bit_cast(float, __builtin_amdgcn_update_dpp(0, __builtin_bit_cast(int, v), 0x121, 0xf, 0xf, false)); }
; __device__ __forceinline__ float dpp_ror2(float v) { return __builtin_bit_cast(float, __builtin_amdgcn_update_dpp(0, __builtin_bit_cast(int, v), 0x122, 0xf, 0xf, false)); }
; __device__ __forceinline__ float dpp_ror3(float v) { return __builtin_bit_cast(float, __builtin_amdgcn_update_dpp(0, __builtin_bit_cast(int, v), 0x123, 0xf, 0xf, false)); }
;     __device__ __forceinline__ void operator()(f32x4 (&acc)[2][2][4][2], const pg8::Unit& u, int wr, int wc, int fr, int fq) const {
;     ...
;                             for (int j = 0; j < 4; ++j) { const float r1 = dpp_ror1(g[j]), r2 = dpp_ror2(g[j]), r3 = dpp_ror3(g[j]);
;                                 p1[j] = t >= 1 ? r1 : b2[j]; p2[j] = t >= 2 ? r2 : (t == 1 ? b2[j] : b1[j]); p3[j] = t >= 3 ? r3 : (t == 2 ? b2[j] : (t == 1 ? b1[j] : b0[j])); } }
.LBB0_342:
	s_or_b64 exec, exec, s[2:3]
	v_mov_b32_dpp v172, v111 row_ror:1 row_mask:0xf bank_mask:0xf
	v_mov_b32_dpp v173, v111 row_ror:2 row_mask:0xf bank_mask:0xf
	v_mov_b32_dpp v147, v111 row_ror:3 row_mask:0xf bank_mask:0xf
	v_cmp_lt_i32_e32 vcc, 1, v205
	s_and_saveexec_b64 s[2:3], vcc
	s_xor_b64 s[2:3], exec, s[2:3]
	s_cbranch_execz .LBB0_346
	v_cmp_gt_i32_e32 vcc, 3, v205
	s_and_saveexec_b64 s[80:81], vcc
	s_cbranch_execz .LBB0_345
	s_waitcnt vmcnt(0)
	v_mov_b32_e32 v147, v155

; __device__ __forceinline__ float dpp_ror1(float v) { return __builtin_bit_cast(float, __builtin_amdgcn_update_dpp(0, __builtin_bit_cast(int, v), 0x121, 0xf, 0xf, false)); }
; __device__ __forceinline__ float dpp_ror2(float v) { return __builtin_bit_cast(float, __builtin_amdgcn_update_dpp(0, __builtin_bit_cast(int, v), 0x122, 0xf, 0xf, false)); }
; __device__ __forceinline__ float dpp_ror3(float v) { return __builtin_bit_cast(float, __builtin_amdgcn_update_dpp(0, __builtin_bit_cast(int, v), 0x123, 0xf, 0xf, false)); }
;     __device__ __forceinline__ void operator()(f32x4 (&acc)[2][2][4][2], const pg8::Unit& u, int wr, int wc, int fr, int fq) const {
;     ...
;                             for (int j = 0; j < 4; ++j) { const float r1 = dpp_ror1(g[j]), r2 = dpp_ror2(g[j]), r3 = dpp_ror3(g[j]);
;                                 p1[j] = t >= 1 ? r1 : b2[j]; p2[j] = t >= 2 ? r2 : (t == 1 ? b2[j] : b1[j]); p3[j] = t >= 3 ? r3 : (t == 2 ? b2[j] : (t == 1 ? b1[j] : b0[j])); } }
.LBB0_352:
	s_or_b64 exec, exec, s[2:3]
	v_mov_b32_dpp v224, v112 row_ror:1 row_mask:0xf bank_mask:0xf
	v_mov_b32_dpp v225, v112 row_ror:2 row_mask:0xf bank_mask:0xf
	v_mov_b32_dpp v148, v112 row_ror:3 row_mask:0xf bank_mask:0xf
	v_cmp_lt_i32_e32 vcc, 1, v205
	s_and_saveexec_b64 s[2:3], vcc
	s_xor_b64 s[2:3], exec, s[2:3]
	s_cbranch_execz .LBB0_356
	v_cmp_gt_i32_e32 vcc, 3, v205
	s_and_saveexec_b64 s[80:81], vcc
	s_cbranch_execz .LBB0_355
	s_waitcnt vmcnt(0)
	v_mov_b32_e32 v148, v156

; __device__ __forceinline__ float dpp_ror1(float v) { return __builtin_bit_cast(float, __builtin_amdgcn_update_dpp(0, __builtin_bit_cast(int, v), 0x121, 0xf, 0xf, false)); }
; __device__ __forceinline__ float dpp_ror2(float v) { return __builtin_bit_cast(float, __builtin_amdgcn_update_dpp(0, __builtin_bit_cast(int, v), 0x122, 0xf, 0xf, false)); }
; __device__ __forceinline__ float dpp_ror3(float v) { return __builtin_bit_cast(float, __builtin_amdgcn_update_dpp(0, __builtin_bit_cast(int, v), 0x123, 0xf, 0xf, false)); }
;     __device__ __forceinline__ void operator()(f32x4 (&acc)[2][2][4][2], const pg8::Unit& u, int wr, int wc, int fr, int fq) const {
;     ...
;                             for (int j = 0; j < 4; ++j) { const float r1 = dpp_ror1(g[j]), r2 = dpp_ror2(g[j]), r3 = dpp_ror3(g[j]);
;                                 p1[j] = t >= 1 ? r1 : b2[j]; p2[j] = t >= 2 ? r2 : (t == 1 ? b2[j] : b1[j]); p3[j] = t >= 3 ? r3 : (t == 2 ? b2[j] : (t == 1 ? b1[j] : b0[j])); } }
.LBB0_362:
	s_or_b64 exec, exec, s[2:3]
	v_mov_b32_dpp v227, v113 row_ror:1 row_mask:0xf bank_mask:0xf
	v_mov_b32_dpp v226, v113 row_ror:2 row_mask:0xf bank_mask:0xf
	v_mov_b32_dpp v149, v113 row_ror:3 row_mask:0xf bank_mask:0xf
	v_cmp_lt_i32_e32 vcc, 1, v205
	s_and_saveexec_b64 s[2:3], vcc
	s_xor_b64 s[2:3], exec, s[2:3]
	s_cbranch_execz .LBB0_366
	v_cmp_gt_i32_e32 vcc, 3, v205
	s_and_saveexec_b64 s[80:81], vcc
	s_cbranch_execz .LBB0_365
	s_waitcnt vmcnt(0)
	v_mov_b32_e32 v149, v157

; __device__ __forceinline__ unsigned cvt_pk_bf16(float lo, float hi) { unsigned r; asm("v_cvt_pk_bf16_f32 %0, %1, %2" : "=v"(r) : "v"(lo), "v"(hi)); return r; }
; __device__ __forceinline__ float siluf_(float x) { return x * sigmoidf_(x); }
; __device__ __forceinline__ float dpp_ror1(float v) { return __builtin_bit_cast(float, __builtin_amdgcn_update_dpp(0, __builtin_bit_cast(int, v), 0x121, 0xf, 0xf, false)); }
; __device__ __forceinline__ float dpp_ror2(float v) { return __builtin_bit_cast(float, __builtin_amdgcn_update_dpp(0, __builtin_bit_cast(int, v), 0x122, 0xf, 0xf, false)); }
; __device__ __forceinline__ float dpp_ror3(float v) { return __builtin_bit_cast(float, __builtin_amdgcn_update_dpp(0, __builtin_bit_cast(int, v), 0x123, 0xf, 0xf, false)); }
;     __device__ __forceinline__ void operator()(f32x4 (&acc)[2][2][4][2], const pg8::Unit& u, int wr, int wc, int fr, int fq) const {
;     ...
;                         if (prompt) { const f32x4 gp = (m == 0) ? hal[n] : acc[ai][bj][m > 0 ? m - 1 : 0][n];
; #pragma unroll
;                             for (int j = 0; j < 4; ++j) { p1[j] = dpp_ror1(fr == 15 ? gp[j] : g[j]); p2[j] = dpp_ror2(fr >= 14 ? gp[j] : g[j]); p3[j] = dpp_ror3(fr >= 13 ? gp[j] : g[j]); } }
;                         else { const int t = fr & 3; const float* sp = stp + (size_t)((row - MP) >> 2) * 3 * CW + ch;
;                             const f32x4 b0 = *(const f32x4*)sp, b1 = *(const f32x4*)(sp + CW), b2 = *(const f32x4*)(sp + 2 * CW);
; #pragma unroll
;                             for (int j = 0; j < 4; ++j) { const float r1 = dpp_ror1(g[j]), r2 = dpp_ror2(g[j]), r3 = dpp_ror3(g[j]);
;                                 p1[j] = t >= 1 ? r1 : b2[j]; p2[j] = t >= 2 ? r2 : (t == 1 ? b2[j] : b1[j]); p3[j] = t >= 3 ? r3 : (t == 2 ? b2[j] : (t == 1 ? b1[j] : b0[j])); } }
;                         float o[4];
; #pragma unroll
;                         for (int j = 0; j < 4; ++j) { const float y = bb[j] + w0[j] * p3[j] + w1[j] * p2[j] + w2[j] * p1[j] + w3[j] * g[j]; o[j] = is_rg ? y : siluf_(y); }
;                         u32x2 w; w.x = cvt_pk_bf16(o[0], o[1]); w.y = cvt_pk_bf16(o[2], o[3]);
;                         *(u32x2*)(dst + (size_t)row * ld + bj * 128 + 4 * n) = w; }
.LBB0_373:
	s_and_b64 vcc, exec, s[2:3]
	s_cbranch_vccz .LBB0_375
	v_cndmask_b32_e64 v146, v110, v122, s[10:11]
	v_cndmask_b32_e64 v147, v110, v122, s[6:7]
	s_nop 0
	v_mov_b32_dpp v158, v146 row_ror:1 row_mask:0xf bank_mask:0xf
	v_cndmask_b32_e64 v146, v110, v122, s[8:9]
	s_nop 1
	v_mov_b32_dpp v150, v146 row_ror:2 row_mask:0xf bank_mask:0xf
	v_cndmask_b32_e64 v148, v111, v123, s[6:7]
	v_mov_b32_dpp v146, v147 row_ror:3 row_mask:0xf bank_mask:0xf
	v_cndmask_b32_e64 v147, v111, v123, s[10:11]
	v_cndmask_b32_e64 v149, v112, v124, s[6:7]
	s_nop 0
	v_mov_b32_dpp v159, v147 row_ror:1 row_mask:0xf bank_mask:0xf
	v_cndmask_b32_e64 v147, v111, v123, s[8:9]
	s_nop 1
	v_mov_b32_dpp v151, v147 row_ror:2 row_mask:0xf bank_mask:0xf
	v_cndmask_b32_e64 v155, v113, v125, s[6:7]
	s_nop 0
	v_mov_b32_dpp v147, v148 row_ror:3 row_mask:0xf bank_mask:0xf
	v_cndmask_b32_e64 v148, v112, v124, s[10:11]
	s_nop 1
	v_mov_b32_dpp v160, v148 row_ror:1 row_mask:0xf bank_mask:0xf
	v_cndmask_b32_e64 v148, v112, v124, s[8:9]
	s_nop 1
	v_mov_b32_dpp v152, v148 row_ror:2 row_mask:0xf bank_mask:0xf
	s_nop 1
	v_mov_b32_dpp v148, v149 row_ror:3 row_mask:0xf bank_mask:0xf
	v_cndmask_b32_e64 v149, v113, v125, s[10:11]
	s_nop 1
	v_mov_b32_dpp v161, v149 row_ror:1 row_mask:0xf bank_mask:0xf
	v_cndmask_b32_e64 v149, v113, v125, s[8:9]
	s_nop 1
	v_mov_b32_dpp v153, v149 row_ror:2 row_mask:0xf bank_mask:0xf
	s_nop 1
	v_mov_b32_dpp v149, v155 row_ror:3 row_mask:0xf bank_mask:0xf
.LBB0_375:
	v_mov_b32_e32 v224, v150
	v_mov_b32_e32 v225, v146
	v_pk_mul_f32 v[224:225], v[166:167], v[224:225]
	v_mov_b32_e32 v173, v158
	v_add_f32_e32 v146, v142, v225
	v_add_f32_e32 v146, v224, v146
	v_pk_mul_f32 v[172:173], v[168:169], v[172:173]
	v_mov_b32_e32 v165, v159
	v_add_f32_e32 v146, v173, v146
	v_add_f32_e32 v150, v172, v146
	v_mul_f32_e32 v146, 0xbfb8aa3b, v150
	v_exp_f32_e32 v146, v146
	v_mov_b32_e32 v157, v160
	s_mov_b64 s[2:3], -1
	s_and_b64 vcc, exec, s[18:19]
	v_add_f32_e32 v146, 1.0, v146
	v_rcp_f32_e32 v155, v146
	v_mov_b32_e32 v146, v151
	v_pk_mul_f32 v[146:147], v[134:135], v[146:147]
	v_mov_b32_e32 v172, v94
	v_add_f32_e32 v147, v143, v147
	v_add_f32_e32 v151, v146, v147
	v_pk_mul_f32 v[146:147], v[138:139], v[164:165]
	v_mov_b32_e32 v164, v95
	v_add_f32_e32 v147, v147, v151
	v_add_f32_e32 v151, v146, v147
	v_mul_f32_e32 v146, 0xbfb8aa3b, v151
	v_exp_f32_e32 v146, v146
	v_mul_f32_e32 v147, v150, v155
	v_cndmask_b32_e64 v150, v147, v150, s[4:5]
	v_mov_b32_e32 v147, v148
	v_add_f32_e32 v146, 1.0, v146
	v_rcp_f32_e32 v158, v146
	v_mov_b32_e32 v146, v152
	v_pk_mul_f32 v[146:147], v[162:163], v[146:147]
	v_mov_b32_e32 v155, v161
	v_add_f32_e32 v147, v144, v147
	v_add_f32_e32 v148, v146, v147
	v_pk_mul_f32 v[146:147], v[170:171], v[156:157]
	s_nop 0
	v_add_f32_e32 v147, v147, v148
	v_add_f32_e32 v152, v146, v147
	v_mul_f32_e32 v146, 0xbfb8aa3b, v152
	v_mov_b32_e32 v148, v153
	v_exp_f32_e32 v156, v146
	v_pk_mul_f32 v[146:147], v[136:137], v[148:149]
	v_add_f32_e32 v149, 1.0, v156
	v_add_f32_e32 v147, v145, v147
	v_add_f32_e32 v148, v146, v147
	v_pk_mul_f32 v[146:147], v[140:141], v[154:155]
	v_rcp_f32_e32 v149, v149
	v_add_f32_e32 v147, v147, v148
	v_add_f32_e32 v146, v146, v147
	v_mul_f32_e32 v147, 0xbfb8aa3b, v146
	v_exp_f32_e32 v147, v147
	v_mul_f32_e32 v148, v151, v158
	v_mul_f32_e32 v149, v152, v149
	v_cndmask_b32_e64 v148, v148, v151, s[4:5]
	v_add_f32_e32 v147, 1.0, v147
	v_rcp_f32_e32 v147, v147
	v_cndmask_b32_e64 v149, v149, v152, s[4:5]
	v_mov_b32_e32 v156, v96
	v_mov_b32_e32 v154, v97
	v_mul_f32_e32 v147, v146, v147
	v_cndmask_b32_e64 v147, v147, v146, s[4:5]
	v_cvt_pk_bf16_f32 v146, v150, v148
	v_cvt_pk_bf16_f32 v147, v149, v147
	v_lshlrev_b64 v[148:149], v182, v[200:201]
	v_lshl_add_u64 v[224:225], v[148:149], 1, v[220:221]
	v_mov_b32_e32 v122, v146
	v_mov_b32_e32 v123, v147
	s_cbranch_vccnz .LBB0_417
	v_add_u32_e32 v147, 0xffffe020, v202
	v_ashrrev_i32_e32 v147, 2, v147
	v_lshl_add_u32 v147, v147, 1, v147
	v_mad_i64_i32 v[148:149], s[2:3], v147, s47, 0
	v_lshl_add_u64 v[148:149], v[148:149], 2, v[208:209]
	v_lshl_add_u64 v[150:151], v[148:149], 0, s[24:25]
	s_lshl_b32 s2, s27, 2
	s_mov_b32 s3, s25
	global_load_dwordx4 v[158:161], v[148:149], off
	s_nop 0
	global_load_dwordx4 v[150:153], v[150:151], off
	v_lshl_add_u64 v[148:149], v[148:149], 0, s[2:3]
	global_load_dwordx4 v[154:157], v[148:149], off
	v_mov_b32_dpp v164, v94 row_ror:1 row_mask:0xf bank_mask:0xf
	v_mov_b32_dpp v165, v94 row_ror:2 row_mask:0xf bank_mask:0xf
	v_mov_b32_dpp v146, v94 row_ror:3 row_mask:0xf bank_mask:0xf
	v_cmp_lt_i32_e32 vcc, 1, v205
	s_and_saveexec_b64 s[2:3], vcc
	s_xor_b64 s[2:3], exec, s[2:3]
	s_cbranch_execz .LBB0_380
	v_cmp_gt_i32_e32 vcc, 3, v205
	s_and_saveexec_b64 s[80:81], vcc
	s_cbranch_execz .LBB0_379
	s_waitcnt vmcnt(0)
	v_mov_b32_e32 v146, v154

; __device__ __forceinline__ float dpp_ror1(float v) { return __builtin_bit_cast(float, __builtin_amdgcn_update_dpp(0, __builtin_bit_cast(int, v), 0x121, 0xf, 0xf, false)); }
; __device__ __forceinline__ float dpp_ror2(float v) { return __builtin_bit_cast(float, __builtin_amdgcn_update_dpp(0, __builtin_bit_cast(int, v), 0x122, 0xf, 0xf, false)); }
; __device__ __forceinline__ float dpp_ror3(float v) { return __builtin_bit_cast(float, __builtin_amdgcn_update_dpp(0, __builtin_bit_cast(int, v), 0x123, 0xf, 0xf, false)); }
;     __device__ __forceinline__ void operator()(f32x4 (&acc)[2][2][4][2], const pg8::Unit& u, int wr, int wc, int fr, int fq) const {
;     ...
;                             for (int j = 0; j < 4; ++j) { const float r1 = dpp_ror1(g[j]), r2 = dpp_ror2(g[j]), r3 = dpp_ror3(g[j]);
;                                 p1[j] = t >= 1 ? r1 : b2[j]; p2[j] = t >= 2 ? r2 : (t == 1 ? b2[j] : b1[j]); p3[j] = t >= 3 ? r3 : (t == 2 ? b2[j] : (t == 1 ? b1[j] : b0[j])); } }
.LBB0_386:
	s_or_b64 exec, exec, s[2:3]
	v_mov_b32_dpp v172, v95 row_ror:1 row_mask:0xf bank_mask:0xf
	v_mov_b32_dpp v173, v95 row_ror:2 row_mask:0xf bank_mask:0xf
	v_mov_b32_dpp v147, v95 row_ror:3 row_mask:0xf bank_mask:0xf
	v_cmp_lt_i32_e32 vcc, 1, v205
	s_and_saveexec_b64 s[2:3], vcc
	s_xor_b64 s[2:3], exec, s[2:3]
	s_cbranch_execz .LBB0_390
	v_cmp_gt_i32_e32 vcc, 3, v205
	s_and_saveexec_b64 s[80:81], vcc
	s_cbranch_execz .LBB0_389
	s_waitcnt vmcnt(0)
	v_mov_b32_e32 v147, v155

; __device__ __forceinline__ float dpp_ror1(float v) { return __builtin_bit_cast(float, __builtin_amdgcn_update_dpp(0, __builtin_bit_cast(int, v), 0x121, 0xf, 0xf, false)); }
; __device__ __forceinline__ float dpp_ror2(float v) { return __builtin_bit_cast(float, __builtin_amdgcn_update_dpp(0, __builtin_bit_cast(int, v), 0x122, 0xf, 0xf, false)); }
; __device__ __forceinline__ float dpp_ror3(float v) { return __builtin_bit_cast(float, __builtin_amdgcn_update_dpp(0, __builtin_bit_cast(int, v), 0x123, 0xf, 0xf, false)); }
;     __device__ __forceinline__ void operator()(f32x4 (&acc)[2][2][4][2], const pg8::Unit& u, int wr, int wc, int fr, int fq) const {
;     ...
;                             for (int j = 0; j < 4; ++j) { const float r1 = dpp_ror1(g[j]), r2 = dpp_ror2(g[j]), r3 = dpp_ror3(g[j]);
;                                 p1[j] = t >= 1 ? r1 : b2[j]; p2[j] = t >= 2 ? r2 : (t == 1 ? b2[j] : b1[j]); p3[j] = t >= 3 ? r3 : (t == 2 ? b2[j] : (t == 1 ? b1[j] : b0[j])); } }
.LBB0_396:
	s_or_b64 exec, exec, s[2:3]
	v_mov_b32_dpp v226, v96 row_ror:1 row_mask:0xf bank_mask:0xf
	v_mov_b32_dpp v227, v96 row_ror:2 row_mask:0xf bank_mask:0xf
	v_mov_b32_dpp v148, v96 row_ror:3 row_mask:0xf bank_mask:0xf
	v_cmp_lt_i32_e32 vcc, 1, v205
	s_and_saveexec_b64 s[2:3], vcc
	s_xor_b64 s[2:3], exec, s[2:3]
	s_cbranch_execz .LBB0_400
	v_cmp_gt_i32_e32 vcc, 3, v205
	s_and_saveexec_b64 s[80:81], vcc
	s_cbranch_execz .LBB0_399
	s_waitcnt vmcnt(0)
	v_mov_b32_e32 v148, v156

; __device__ __forceinline__ float dpp_ror1(float v) { return __builtin_bit_cast(float, __builtin_amdgcn_update_dpp(0, __builtin_bit_cast(int, v), 0x121, 0xf, 0xf, false)); }
; __device__ __forceinline__ float dpp_ror2(float v) { return __builtin_bit_cast(float, __builtin_amdgcn_update_dpp(0, __builtin_bit_cast(int, v), 0x122, 0xf, 0xf, false)); }
; __device__ __forceinline__ float dpp_ror3(float v) { return __builtin_bit_cast(float, __builtin_amdgcn_update_dpp(0, __builtin_bit_cast(int, v), 0x123, 0xf, 0xf, false)); }
;     __device__ __forceinline__ void operator()(f32x4 (&acc)[2][2][4][2], const pg8::Unit& u, int wr, int wc, int fr, int fq) const {
;     ...
;                             for (int j = 0; j < 4; ++j) { const float r1 = dpp_ror1(g[j]), r2 = dpp_ror2(g[j]), r3 = dpp_ror3(g[j]);
;                                 p1[j] = t >= 1 ? r1 : b2[j]; p2[j] = t >= 2 ? r2 : (t == 1 ? b2[j] : b1[j]); p3[j] = t >= 3 ? r3 : (t == 2 ? b2[j] : (t == 1 ? b1[j] : b0[j])); } }
.LBB0_406:
	s_or_b64 exec, exec, s[2:3]
	v_mov_b32_dpp v229, v97 row_ror:1 row_mask:0xf bank_mask:0xf
	v_mov_b32_dpp v228, v97 row_ror:2 row_mask:0xf bank_mask:0xf
	v_mov_b32_dpp v149, v97 row_ror:3 row_mask:0xf bank_mask:0xf
	v_cmp_lt_i32_e32 vcc, 1, v205
	s_and_saveexec_b64 s[2:3], vcc
	s_xor_b64 s[2:3], exec, s[2:3]
	s_cbranch_execz .LBB0_410
	v_cmp_gt_i32_e32 vcc, 3, v205
	s_and_saveexec_b64 s[80:81], vcc
	s_cbranch_execz .LBB0_409
	s_waitcnt vmcnt(0)
	v_mov_b32_e32 v149, v157

; __device__ __forceinline__ unsigned cvt_pk_bf16(float lo, float hi) { unsigned r; asm("v_cvt_pk_bf16_f32 %0, %1, %2" : "=v"(r) : "v"(lo), "v"(hi)); return r; }
; __device__ __forceinline__ float siluf_(float x) { return x * sigmoidf_(x); }
; __device__ __forceinline__ float dpp_ror1(float v) { return __builtin_bit_cast(float, __builtin_amdgcn_update_dpp(0, __builtin_bit_cast(int, v), 0x121, 0xf, 0xf, false)); }
; __device__ __forceinline__ float dpp_ror2(float v) { return __builtin_bit_cast(float, __builtin_amdgcn_update_dpp(0, __builtin_bit_cast(int, v), 0x122, 0xf, 0xf, false)); }
; __device__ __forceinline__ float dpp_ror3(float v) { return __builtin_bit_cast(float, __builtin_amdgcn_update_dpp(0, __builtin_bit_cast(int, v), 0x123, 0xf, 0xf, false)); }
;     __device__ __forceinline__ void operator()(f32x4 (&acc)[2][2][4][2], const pg8::Unit& u, int wr, int wc, int fr, int fq) const {
;     ...
;                         if (prompt) { const f32x4 gp = (m == 0) ? hal[n] : acc[ai][bj][m > 0 ? m - 1 : 0][n];
; #pragma unroll
;                             for (int j = 0; j < 4; ++j) { p1[j] = dpp_ror1(fr == 15 ? gp[j] : g[j]); p2[j] = dpp_ror2(fr >= 14 ? gp[j] : g[j]); p3[j] = dpp_ror3(fr >= 13 ? gp[j] : g[j]); } }
;                         else { const int t = fr & 3; const float* sp = stp + (size_t)((row - MP) >> 2) * 3 * CW + ch;
;                             const f32x4 b0 = *(const f32x4*)sp, b1 = *(const f32x4*)(sp + CW), b2 = *(const f32x4*)(sp + 2 * CW);
; #pragma unroll
;                             for (int j = 0; j < 4; ++j) { const float r1 = dpp_ror1(g[j]), r2 = dpp_ror2(g[j]), r3 = dpp_ror3(g[j]);
;                                 p1[j] = t >= 1 ? r1 : b2[j]; p2[j] = t >= 2 ? r2 : (t == 1 ? b2[j] : b1[j]); p3[j] = t >= 3 ? r3 : (t == 2 ? b2[j] : (t == 1 ? b1[j] : b0[j])); } }
;                         float o[4];
; #pragma unroll
;                         for (int j = 0; j < 4; ++j) { const float y = bb[j] + w0[j] * p3[j] + w1[j] * p2[j] + w2[j] * p1[j] + w3[j] * g[j]; o[j] = is_rg ? y : siluf_(y); }
;                         u32x2 w; w.x = cvt_pk_bf16(o[0], o[1]); w.y = cvt_pk_bf16(o[2], o[3]);
;                         *(u32x2*)(dst + (size_t)row * ld + bj * 128 + 4 * n) = w; }
.LBB0_417:
	s_and_b64 vcc, exec, s[2:3]
	s_cbranch_vccz .LBB0_419
	v_cndmask_b32_e64 v146, v94, v110, s[10:11]
	v_cndmask_b32_e64 v147, v94, v110, s[6:7]
	s_nop 0
	v_mov_b32_dpp v158, v146 row_ror:1 row_mask:0xf bank_mask:0xf
	v_cndmask_b32_e64 v146, v94, v110, s[8:9]
	s_nop 1
	v_mov_b32_dpp v150, v146 row_ror:2 row_mask:0xf bank_mask:0xf
	v_cndmask_b32_e64 v148, v95, v111, s[6:7]
	v_mov_b32_dpp v146, v147 row_ror:3 row_mask:0xf bank_mask:0xf
	v_cndmask_b32_e64 v147, v95, v111, s[10:11]
	v_cndmask_b32_e64 v149, v96, v112, s[6:7]
	s_nop 0
	v_mov_b32_dpp v159, v147 row_ror:1 row_mask:0xf bank_mask:0xf
	v_cndmask_b32_e64 v147, v95, v111, s[8:9]
	s_nop 1
	v_mov_b32_dpp v151, v147 row_ror:2 row_mask:0xf bank_mask:0xf
	v_cndmask_b32_e64 v155, v97, v113, s[6:7]
	s_nop 0
	v_mov_b32_dpp v147, v148 row_ror:3 row_mask:0xf bank_mask:0xf
	v_cndmask_b32_e64 v148, v96, v112, s[10:11]
	s_nop 1
	v_mov_b32_dpp v160, v148 row_ror:1 row_mask:0xf bank_mask:0xf
	v_cndmask_b32_e64 v148, v96, v112, s[8:9]
	s_nop 1
	v_mov_b32_dpp v152, v148 row_ror:2 row_mask:0xf bank_mask:0xf
	s_nop 1
	v_mov_b32_dpp v148, v149 row_ror:3 row_mask:0xf bank_mask:0xf
	v_cndmask_b32_e64 v149, v97, v113, s[10:11]
	s_nop 1
	v_mov_b32_dpp v161, v149 row_ror:1 row_mask:0xf bank_mask:0xf
	v_cndmask_b32_e64 v149, v97, v113, s[8:9]
	s_nop 1
	v_mov_b32_dpp v153, v149 row_ror:2 row_mask:0xf bank_mask:0xf
	s_nop 1
	v_mov_b32_dpp v149, v155 row_ror:3 row_mask:0xf bank_mask:0xf
.LBB0_419:
	v_mov_b32_e32 v226, v150
	v_mov_b32_e32 v227, v146
	v_pk_mul_f32 v[226:227], v[166:167], v[226:227]
	v_mov_b32_e32 v173, v158
	v_add_f32_e32 v146, v142, v227
	v_add_f32_e32 v146, v226, v146
	v_pk_mul_f32 v[172:173], v[168:169], v[172:173]
	v_mov_b32_e32 v165, v159
	v_add_f32_e32 v146, v173, v146
	v_add_f32_e32 v150, v172, v146
	v_mul_f32_e32 v146, 0xbfb8aa3b, v150
	v_exp_f32_e32 v146, v146
	v_mov_b32_e32 v157, v160
	s_mov_b64 s[2:3], -1
	s_and_b64 vcc, exec, s[18:19]
	v_add_f32_e32 v146, 1.0, v146
	v_rcp_f32_e32 v155, v146
	v_mov_b32_e32 v146, v151
	v_pk_mul_f32 v[146:147], v[134:135], v[146:147]
	v_mov_b32_e32 v172, v78
	v_add_f32_e32 v147, v143, v147
	v_add_f32_e32 v151, v146, v147
	v_pk_mul_f32 v[146:147], v[138:139], v[164:165]
	v_mov_b32_e32 v164, v79
	v_add_f32_e32 v147, v147, v151
	v_add_f32_e32 v151, v146, v147
	v_mul_f32_e32 v146, 0xbfb8aa3b, v151
	v_exp_f32_e32 v146, v146
	v_mul_f32_e32 v147, v150, v155
	v_cndmask_b32_e64 v150, v147, v150, s[4:5]
	v_mov_b32_e32 v147, v148
	v_add_f32_e32 v146, 1.0, v146
	v_rcp_f32_e32 v158, v146
	v_mov_b32_e32 v146, v152
	v_pk_mul_f32 v[146:147], v[162:163], v[146:147]
	v_mov_b32_e32 v155, v161
	v_add_f32_e32 v147, v144, v147
	v_add_f32_e32 v148, v146, v147
	v_pk_mul_f32 v[146:147], v[170:171], v[156:157]
	s_nop 0
	v_add_f32_e32 v147, v147, v148
	v_add_f32_e32 v152, v146, v147
	v_mul_f32_e32 v146, 0xbfb8aa3b, v152
	v_mov_b32_e32 v148, v153
	v_exp_f32_e32 v156, v146
	v_pk_mul_f32 v[146:147], v[136:137], v[148:149]
	v_add_f32_e32 v149, 1.0, v156
	v_add_f32_e32 v147, v145, v147
	v_add_f32_e32 v148, v146, v147
	v_pk_mul_f32 v[146:147], v[140:141], v[154:155]
	v_rcp_f32_e32 v149, v149
	v_add_f32_e32 v147, v147, v148
	v_add_f32_e32 v146, v146, v147
	v_mul_f32_e32 v147, 0xbfb8aa3b, v146
	v_exp_f32_e32 v147, v147
	v_mul_f32_e32 v148, v151, v158
	v_mul_f32_e32 v149, v152, v149
	v_cndmask_b32_e64 v148, v148, v151, s[4:5]
	v_add_f32_e32 v147, 1.0, v147
	v_rcp_f32_e32 v147, v147
	v_cndmask_b32_e64 v149, v149, v152, s[4:5]
	v_mov_b32_e32 v156, v80
	v_mov_b32_e32 v154, v81
	v_mul_f32_e32 v147, v146, v147
	v_cndmask_b32_e64 v147, v147, v146, s[4:5]
	v_cvt_pk_bf16_f32 v146, v150, v148
	v_cvt_pk_bf16_f32 v147, v149, v147
	v_lshlrev_b64 v[148:149], v182, v[198:199]
	v_lshl_add_u64 v[226:227], v[148:149], 1, v[220:221]
	v_mov_b32_e32 v110, v146
	v_mov_b32_e32 v111, v147
	s_cbranch_vccnz .LBB0_461
	v_add_u32_e32 v147, 0xffffe030, v202
	v_ashrrev_i32_e32 v147, 2, v147
	v_lshl_add_u32 v147, v147, 1, v147
	v_mad_i64_i32 v[148:149], s[2:3], v147, s47, 0
	v_lshl_add_u64 v[148:149], v[148:149], 2, v[208:209]
	v_lshl_add_u64 v[150:151], v[148:149], 0, s[24:25]
	s_lshl_b32 s2, s27, 2
	s_mov_b32 s3, s25
	global_load_dwordx4 v[158:161], v[148:149], off
	s_nop 0
	global_load_dwordx4 v[150:153], v[150:151], off
	v_lshl_add_u64 v[148:149], v[148:149], 0, s[2:3]
	global_load_dwordx4 v[154:157], v[148:149], off
	v_mov_b32_dpp v164, v78 row_ror:1 row_mask:0xf bank_mask:0xf
	v_mov_b32_dpp v165, v78 row_ror:2 row_mask:0xf bank_mask:0xf
	v_mov_b32_dpp v146, v78 row_ror:3 row_mask:0xf bank_mask:0xf
	v_cmp_lt_i32_e32 vcc, 1, v205
	s_and_saveexec_b64 s[2:3], vcc
	s_xor_b64 s[2:3], exec, s[2:3]
	s_cbranch_execz .LBB0_424
	v_cmp_gt_i32_e32 vcc, 3, v205
	s_and_saveexec_b64 s[80:81], vcc
	s_cbranch_execz .LBB0_423
	s_waitcnt vmcnt(0)
	v_mov_b32_e32 v146, v154

; __device__ __forceinline__ float dpp_ror1(float v) { return __builtin_bit_cast(float, __builtin_amdgcn_update_dpp(0, __builtin_bit_cast(int, v), 0x121, 0xf, 0xf, false)); }
; __device__ __forceinline__ float dpp_ror2(float v) { return __builtin_bit_cast(float, __builtin_amdgcn_update_dpp(0, __builtin_bit_cast(int, v), 0x122, 0xf, 0xf, false)); }
; __device__ __forceinline__ float dpp_ror3(float v) { return __builtin_bit_cast(float, __builtin_amdgcn_update_dpp(0, __builtin_bit_cast(int, v), 0x123, 0xf, 0xf, false)); }
;     __device__ __forceinline__ void operator()(f32x4 (&acc)[2][2][4][2], const pg8::Unit& u, int wr, int wc, int fr, int fq) const {
;     ...
;                             for (int j = 0; j < 4; ++j) { const float r1 = dpp_ror1(g[j]), r2 = dpp_ror2(g[j]), r3 = dpp_ror3(g[j]);
;                                 p1[j] = t >= 1 ? r1 : b2[j]; p2[j] = t >= 2 ? r2 : (t == 1 ? b2[j] : b1[j]); p3[j] = t >= 3 ? r3 : (t == 2 ? b2[j] : (t == 1 ? b1[j] : b0[j])); } }
.LBB0_430:
	s_or_b64 exec, exec, s[2:3]
	v_mov_b32_dpp v172, v79 row_ror:1 row_mask:0xf bank_mask:0xf
	v_mov_b32_dpp v173, v79 row_ror:2 row_mask:0xf bank_mask:0xf
	v_mov_b32_dpp v147, v79 row_ror:3 row_mask:0xf bank_mask:0xf
	v_cmp_lt_i32_e32 vcc, 1, v205
	s_and_saveexec_b64 s[2:3], vcc
	s_xor_b64 s[2:3], exec, s[2:3]
	s_cbranch_execz .LBB0_434
	v_cmp_gt_i32_e32 vcc, 3, v205
	s_and_saveexec_b64 s[80:81], vcc
	s_cbranch_execz .LBB0_433
	s_waitcnt vmcnt(0)
	v_mov_b32_e32 v147, v155

; __device__ __forceinline__ float dpp_ror1(float v) { return __builtin_bit_cast(float, __builtin_amdgcn_update_dpp(0, __builtin_bit_cast(int, v), 0x121, 0xf, 0xf, false)); }
; __device__ __forceinline__ float dpp_ror2(float v) { return __builtin_bit_cast(float, __builtin_amdgcn_update_dpp(0, __builtin_bit_cast(int, v), 0x122, 0xf, 0xf, false)); }
; __device__ __forceinline__ float dpp_ror3(float v) { return __builtin_bit_cast(float, __builtin_amdgcn_update_dpp(0, __builtin_bit_cast(int, v), 0x123, 0xf, 0xf, false)); }
;     __device__ __forceinline__ void operator()(f32x4 (&acc)[2][2][4][2], const pg8::Unit& u, int wr, int wc, int fr, int fq) const {
;     ...
;                             for (int j = 0; j < 4; ++j) { const float r1 = dpp_ror1(g[j]), r2 = dpp_ror2(g[j]), r3 = dpp_ror3(g[j]);
;                                 p1[j] = t >= 1 ? r1 : b2[j]; p2[j] = t >= 2 ? r2 : (t == 1 ? b2[j] : b1[j]); p3[j] = t >= 3 ? r3 : (t == 2 ? b2[j] : (t == 1 ? b1[j] : b0[j])); } }
.LBB0_440:
	s_or_b64 exec, exec, s[2:3]
	v_mov_b32_dpp v228, v80 row_ror:1 row_mask:0xf bank_mask:0xf
	v_mov_b32_dpp v229, v80 row_ror:2 row_mask:0xf bank_mask:0xf
	v_mov_b32_dpp v148, v80 row_ror:3 row_mask:0xf bank_mask:0xf
	v_cmp_lt_i32_e32 vcc, 1, v205
	s_and_saveexec_b64 s[2:3], vcc
	s_xor_b64 s[2:3], exec, s[2:3]
	s_cbranch_execz .LBB0_444
	v_cmp_gt_i32_e32 vcc, 3, v205
	s_and_saveexec_b64 s[80:81], vcc
	s_cbranch_execz .LBB0_443
	s_waitcnt vmcnt(0)
	v_mov_b32_e32 v148, v156

; __device__ __forceinline__ float dpp_ror1(float v) { return __builtin_bit_cast(float, __builtin_amdgcn_update_dpp(0, __builtin_bit_cast(int, v), 0x121, 0xf, 0xf, false)); }
; __device__ __forceinline__ float dpp_ror2(float v) { return __builtin_bit_cast(float, __builtin_amdgcn_update_dpp(0, __builtin_bit_cast(int, v), 0x122, 0xf, 0xf, false)); }
; __device__ __forceinline__ float dpp_ror3(float v) { return __builtin_bit_cast(float, __builtin_amdgcn_update_dpp(0, __builtin_bit_cast(int, v), 0x123, 0xf, 0xf, false)); }
;     __device__ __forceinline__ void operator()(f32x4 (&acc)[2][2][4][2], const pg8::Unit& u, int wr, int wc, int fr, int fq) const {
;     ...
;                             for (int j = 0; j < 4; ++j) { const float r1 = dpp_ror1(g[j]), r2 = dpp_ror2(g[j]), r3 = dpp_ror3(g[j]);
;                                 p1[j] = t >= 1 ? r1 : b2[j]; p2[j] = t >= 2 ? r2 : (t == 1 ? b2[j] : b1[j]); p3[j] = t >= 3 ? r3 : (t == 2 ? b2[j] : (t == 1 ? b1[j] : b0[j])); } }
.LBB0_450:
	s_or_b64 exec, exec, s[2:3]
	v_mov_b32_dpp v233, v81 row_ror:1 row_mask:0xf bank_mask:0xf
	v_mov_b32_dpp v232, v81 row_ror:2 row_mask:0xf bank_mask:0xf
	v_mov_b32_dpp v149, v81 row_ror:3 row_mask:0xf bank_mask:0xf
	v_cmp_lt_i32_e32 vcc, 1, v205
	s_and_saveexec_b64 s[2:3], vcc
	s_xor_b64 s[2:3], exec, s[2:3]
	s_cbranch_execz .LBB0_454
	v_cmp_gt_i32_e32 vcc, 3, v205
	s_and_saveexec_b64 s[80:81], vcc
	s_cbranch_execz .LBB0_453
	s_waitcnt vmcnt(0)
	v_mov_b32_e32 v149, v157

; __device__ __forceinline__ unsigned cvt_pk_bf16(float lo, float hi) { unsigned r; asm("v_cvt_pk_bf16_f32 %0, %1, %2" : "=v"(r) : "v"(lo), "v"(hi)); return r; }
; __device__ __forceinline__ float siluf_(float x) { return x * sigmoidf_(x); }
; __device__ __forceinline__ float dpp_ror1(float v) { return __builtin_bit_cast(float, __builtin_amdgcn_update_dpp(0, __builtin_bit_cast(int, v), 0x121, 0xf, 0xf, false)); }
; __device__ __forceinline__ float dpp_ror2(float v) { return __builtin_bit_cast(float, __builtin_amdgcn_update_dpp(0, __builtin_bit_cast(int, v), 0x122, 0xf, 0xf, false)); }
; __device__ __forceinline__ float dpp_ror3(float v) { return __builtin_bit_cast(float, __builtin_amdgcn_update_dpp(0, __builtin_bit_cast(int, v), 0x123, 0xf, 0xf, false)); }
;     __device__ __forceinline__ void operator()(f32x4 (&acc)[2][2][4][2], const pg8::Unit& u, int wr, int wc, int fr, int fq) const {
;     ...
;                         if (prompt) { const f32x4 gp = (m == 0) ? hal[n] : acc[ai][bj][m > 0 ? m - 1 : 0][n];
; #pragma unroll
;                             for (int j = 0; j < 4; ++j) { p1[j] = dpp_ror1(fr == 15 ? gp[j] : g[j]); p2[j] = dpp_ror2(fr >= 14 ? gp[j] : g[j]); p3[j] = dpp_ror3(fr >= 13 ? gp[j] : g[j]); } }
;                         else { const int t = fr & 3; const float* sp = stp + (size_t)((row - MP) >> 2) * 3 * CW + ch;
;                             const f32x4 b0 = *(const f32x4*)sp, b1 = *(const f32x4*)(sp + CW), b2 = *(const f32x4*)(sp + 2 * CW);
; #pragma unroll
;                             for (int j = 0; j < 4; ++j) { const float r1 = dpp_ror1(g[j]), r2 = dpp_ror2(g[j]), r3 = dpp_ror3(g[j]);
;                                 p1[j] = t >= 1 ? r1 : b2[j]; p2[j] = t >= 2 ? r2 : (t == 1 ? b2[j] : b1[j]); p3[j] = t >= 3 ? r3 : (t == 2 ? b2[j] : (t == 1 ? b1[j] : b0[j])); } }
;                         float o[4];
; #pragma unroll
;                         for (int j = 0; j < 4; ++j) { const float y = bb[j] + w0[j] * p3[j] + w1[j] * p2[j] + w2[j] * p1[j] + w3[j] * g[j]; o[j] = is_rg ? y : siluf_(y); }
;                         u32x2 w; w.x = cvt_pk_bf16(o[0], o[1]); w.y = cvt_pk_bf16(o[2], o[3]);
;                         *(u32x2*)(dst + (size_t)row * ld + bj * 128 + 4 * n) = w; }
.LBB0_461:
	s_and_b64 vcc, exec, s[2:3]
	s_cbranch_vccz .LBB0_463
	v_cndmask_b32_e64 v146, v78, v94, s[10:11]
	v_cndmask_b32_e64 v147, v78, v94, s[6:7]
	s_nop 0
	v_mov_b32_dpp v158, v146 row_ror:1 row_mask:0xf bank_mask:0xf
	v_cndmask_b32_e64 v146, v78, v94, s[8:9]
	s_nop 1
	v_mov_b32_dpp v150, v146 row_ror:2 row_mask:0xf bank_mask:0xf
	v_cndmask_b32_e64 v148, v79, v95, s[6:7]
	v_mov_b32_dpp v146, v147 row_ror:3 row_mask:0xf bank_mask:0xf
	v_cndmask_b32_e64 v147, v79, v95, s[10:11]
	v_cndmask_b32_e64 v149, v80, v96, s[6:7]
	s_nop 0
	v_mov_b32_dpp v159, v147 row_ror:1 row_mask:0xf bank_mask:0xf
	v_cndmask_b32_e64 v147, v79, v95, s[8:9]
	s_nop 1
	v_mov_b32_dpp v151, v147 row_ror:2 row_mask:0xf bank_mask:0xf
	v_cndmask_b32_e64 v155, v81, v97, s[6:7]
	s_nop 0
	v_mov_b32_dpp v147, v148 row_ror:3 row_mask:0xf bank_mask:0xf
	v_cndmask_b32_e64 v148, v80, v96, s[10:11]
	s_nop 1
	v_mov_b32_dpp v160, v148 row_ror:1 row_mask:0xf bank_mask:0xf
	v_cndmask_b32_e64 v148, v80, v96, s[8:9]
	s_nop 1
	v_mov_b32_dpp v152, v148 row_ror:2 row_mask:0xf bank_mask:0xf
	s_nop 1
	v_mov_b32_dpp v148, v149 row_ror:3 row_mask:0xf bank_mask:0xf
	v_cndmask_b32_e64 v149, v81, v97, s[10:11]
	s_nop 1
	v_mov_b32_dpp v161, v149 row_ror:1 row_mask:0xf bank_mask:0xf
	v_cndmask_b32_e64 v149, v81, v97, s[8:9]
	s_nop 1
	v_mov_b32_dpp v153, v149 row_ror:2 row_mask:0xf bank_mask:0xf
	s_nop 1
	v_mov_b32_dpp v149, v155 row_ror:3 row_mask:0xf bank_mask:0xf
.LBB0_463:
	v_mov_b32_e32 v228, v150
	v_mov_b32_e32 v229, v146
	v_pk_mul_f32 v[166:167], v[166:167], v[228:229]
	v_mov_b32_e32 v173, v158
	v_add_f32_e32 v142, v142, v167
	v_add_f32_e32 v142, v166, v142
	v_pk_mul_f32 v[166:167], v[168:169], v[172:173]
	v_mov_b32_e32 v165, v159
	v_add_f32_e32 v142, v167, v142
	v_add_f32_e32 v142, v166, v142
	v_mul_f32_e32 v146, 0xbfb8aa3b, v142
	v_exp_f32_e32 v146, v146
	v_mov_b32_e32 v157, v160
	v_mov_b32_e32 v155, v161
	s_mov_b64 s[2:3], -1
	v_add_f32_e32 v146, 1.0, v146
	v_rcp_f32_e32 v150, v146
	v_mov_b32_e32 v146, v151
	v_pk_mul_f32 v[134:135], v[134:135], v[146:147]
	s_and_b64 vcc, exec, s[18:19]
	v_add_f32_e32 v135, v143, v135
	v_add_f32_e32 v143, v134, v135
	v_pk_mul_f32 v[134:135], v[138:139], v[164:165]
	v_mov_b32_e32 v234, v126
	v_add_f32_e32 v135, v135, v143
	v_add_f32_e32 v138, v134, v135
	v_mul_f32_e32 v134, 0xbfb8aa3b, v138
	v_exp_f32_e32 v134, v134
	v_mul_f32_e32 v135, v142, v150
	v_cndmask_b32_e64 v139, v135, v142, s[4:5]
	v_mov_b32_e32 v135, v148
	v_add_f32_e32 v134, 1.0, v134
	v_rcp_f32_e32 v142, v134
	v_mov_b32_e32 v134, v152
	v_pk_mul_f32 v[134:135], v[162:163], v[134:135]
	v_mov_b32_e32 v148, v153
	v_add_f32_e32 v135, v144, v135
	v_add_f32_e32 v143, v134, v135
	v_pk_mul_f32 v[134:135], v[170:171], v[156:157]
	v_mov_b32_e32 v232, v127
	v_add_f32_e32 v135, v135, v143
	v_add_f32_e32 v143, v134, v135
	v_mul_f32_e32 v134, 0xbfb8aa3b, v143
	v_exp_f32_e32 v144, v134
	v_pk_mul_f32 v[134:135], v[136:137], v[148:149]
	v_mov_b32_e32 v172, v128
	v_add_f32_e32 v135, v145, v135
	v_add_f32_e32 v136, v134, v135
	v_pk_mul_f32 v[134:135], v[140:141], v[154:155]
	v_add_f32_e32 v137, 1.0, v144
	v_add_f32_e32 v135, v135, v136
	v_add_f32_e32 v134, v134, v135
	v_mul_f32_e32 v135, 0xbfb8aa3b, v134
	v_exp_f32_e32 v135, v135
	v_rcp_f32_e32 v137, v137
	v_mul_f32_e32 v136, v138, v142
	v_cndmask_b32_e64 v136, v136, v138, s[4:5]
	v_add_f32_e32 v135, 1.0, v135
	v_rcp_f32_e32 v135, v135
	v_mul_f32_e32 v137, v143, v137
	v_cndmask_b32_e64 v137, v137, v143, s[4:5]
	v_mov_b32_e32 v170, v129
	v_mul_f32_e32 v135, v134, v135
	v_cndmask_b32_e64 v135, v135, v134, s[4:5]
	v_cvt_pk_bf16_f32 v134, v139, v136
	v_cvt_pk_bf16_f32 v135, v137, v135
	v_lshlrev_b64 v[136:137], v182, v[196:197]
	v_lshl_add_u64 v[228:229], v[136:137], 1, v[220:221]
	v_mov_b32_e32 v94, v134
	v_mov_b32_e32 v95, v135
	global_load_dwordx4 v[138:141], v[210:211], off offset:16
	global_load_dwordx4 v[150:153], v[212:213], off offset:16
	global_load_dwordx4 v[134:137], v[214:215], off offset:16
	global_load_dwordx4 v[146:149], v[216:217], off offset:16
	global_load_dwordx4 v[142:145], v[218:219], off offset:16
	s_cbranch_vccnz .LBB0_505
	v_add_u32_e32 v155, 0xffffe000, v202
	v_ashrrev_i32_e32 v155, 2, v155
	v_lshl_add_u32 v155, v155, 1, v155
	v_mad_i64_i32 v[156:157], s[2:3], v155, s47, 0
	v_lshl_add_u64 v[156:157], v[156:157], 2, v[208:209]
	v_lshl_add_u64 v[158:159], v[156:157], 0, s[24:25]
	s_lshl_b32 s2, s27, 2
	s_mov_b32 s3, s25
	global_load_dwordx4 v[166:169], v[156:157], off offset:16
	s_nop 0
	global_load_dwordx4 v[158:161], v[158:159], off offset:16
	v_lshl_add_u64 v[156:157], v[156:157], 0, s[2:3]
	global_load_dwordx4 v[162:165], v[156:157], off offset:16
	v_mov_b32_dpp v170, v126 row_ror:1 row_mask:0xf bank_mask:0xf
	v_mov_b32_dpp v171, v126 row_ror:2 row_mask:0xf bank_mask:0xf
	v_mov_b32_dpp v154, v126 row_ror:3 row_mask:0xf bank_mask:0xf
	v_cmp_lt_i32_e32 vcc, 1, v205
	s_and_saveexec_b64 s[2:3], vcc
	s_xor_b64 s[2:3], exec, s[2:3]
	s_cbranch_execz .LBB0_468
	v_cmp_gt_i32_e32 vcc, 3, v205
	s_and_saveexec_b64 s[80:81], vcc
	s_cbranch_execz .LBB0_467
	s_waitcnt vmcnt(0)
	v_mov_b32_e32 v154, v162

; __device__ __forceinline__ float dpp_ror1(float v) { return __builtin_bit_cast(float, __builtin_amdgcn_update_dpp(0, __builtin_bit_cast(int, v), 0x121, 0xf, 0xf, false)); }
; __device__ __forceinline__ float dpp_ror2(float v) { return __builtin_bit_cast(float, __builtin_amdgcn_update_dpp(0, __builtin_bit_cast(int, v), 0x122, 0xf, 0xf, false)); }
; __device__ __forceinline__ float dpp_ror3(float v) { return __builtin_bit_cast(float, __builtin_amdgcn_update_dpp(0, __builtin_bit_cast(int, v), 0x123, 0xf, 0xf, false)); }
;     __device__ __forceinline__ void operator()(f32x4 (&acc)[2][2][4][2], const pg8::Unit& u, int wr, int wc, int fr, int fq) const {
;     ...
;                             for (int j = 0; j < 4; ++j) { const float r1 = dpp_ror1(g[j]), r2 = dpp_ror2(g[j]), r3 = dpp_ror3(g[j]);
;                                 p1[j] = t >= 1 ? r1 : b2[j]; p2[j] = t >= 2 ? r2 : (t == 1 ? b2[j] : b1[j]); p3[j] = t >= 3 ? r3 : (t == 2 ? b2[j] : (t == 1 ? b1[j] : b0[j])); } }
.LBB0_474:
	s_or_b64 exec, exec, s[2:3]
	v_mov_b32_dpp v172, v127 row_ror:1 row_mask:0xf bank_mask:0xf
	v_mov_b32_dpp v173, v127 row_ror:2 row_mask:0xf bank_mask:0xf
	v_mov_b32_dpp v155, v127 row_ror:3 row_mask:0xf bank_mask:0xf
	v_cmp_lt_i32_e32 vcc, 1, v205
	s_and_saveexec_b64 s[2:3], vcc
	s_xor_b64 s[2:3], exec, s[2:3]
	s_cbranch_execz .LBB0_478
	v_cmp_gt_i32_e32 vcc, 3, v205
	s_and_saveexec_b64 s[80:81], vcc
	s_cbranch_execz .LBB0_477
	s_waitcnt vmcnt(0)
	v_mov_b32_e32 v155, v163

; __device__ __forceinline__ float dpp_ror1(float v) { return __builtin_bit_cast(float, __builtin_amdgcn_update_dpp(0, __builtin_bit_cast(int, v), 0x121, 0xf, 0xf, false)); }
; __device__ __forceinline__ float dpp_ror2(float v) { return __builtin_bit_cast(float, __builtin_amdgcn_update_dpp(0, __builtin_bit_cast(int, v), 0x122, 0xf, 0xf, false)); }
; __device__ __forceinline__ float dpp_ror3(float v) { return __builtin_bit_cast(float, __builtin_amdgcn_update_dpp(0, __builtin_bit_cast(int, v), 0x123, 0xf, 0xf, false)); }
;     __device__ __forceinline__ void operator()(f32x4 (&acc)[2][2][4][2], const pg8::Unit& u, int wr, int wc, int fr, int fq) const {
;     ...
;                             for (int j = 0; j < 4; ++j) { const float r1 = dpp_ror1(g[j]), r2 = dpp_ror2(g[j]), r3 = dpp_ror3(g[j]);
;                                 p1[j] = t >= 1 ? r1 : b2[j]; p2[j] = t >= 2 ? r2 : (t == 1 ? b2[j] : b1[j]); p3[j] = t >= 3 ? r3 : (t == 2 ? b2[j] : (t == 1 ? b1[j] : b0[j])); } }
.LBB0_484:
	s_or_b64 exec, exec, s[2:3]
	v_mov_b32_dpp v232, v128 row_ror:1 row_mask:0xf bank_mask:0xf
	v_mov_b32_dpp v233, v128 row_ror:2 row_mask:0xf bank_mask:0xf
	v_mov_b32_dpp v156, v128 row_ror:3 row_mask:0xf bank_mask:0xf
	v_cmp_lt_i32_e32 vcc, 1, v205
	s_and_saveexec_b64 s[2:3], vcc
	s_xor_b64 s[2:3], exec, s[2:3]
	s_cbranch_execz .LBB0_488
	v_cmp_gt_i32_e32 vcc, 3, v205
	s_and_saveexec_b64 s[80:81], vcc
	s_cbranch_execz .LBB0_487
	s_waitcnt vmcnt(0)
	v_mov_b32_e32 v156, v164

; __device__ __forceinline__ float dpp_ror1(float v) { return __builtin_bit_cast(float, __builtin_amdgcn_update_dpp(0, __builtin_bit_cast(int, v), 0x121, 0xf, 0xf, false)); }
; __device__ __forceinline__ float dpp_ror2(float v) { return __builtin_bit_cast(float, __builtin_amdgcn_update_dpp(0, __builtin_bit_cast(int, v), 0x122, 0xf, 0xf, false)); }
; __device__ __forceinline__ float dpp_ror3(float v) { return __builtin_bit_cast(float, __builtin_amdgcn_update_dpp(0, __builtin_bit_cast(int, v), 0x123, 0xf, 0xf, false)); }
;     __device__ __forceinline__ void operator()(f32x4 (&acc)[2][2][4][2], const pg8::Unit& u, int wr, int wc, int fr, int fq) const {
;     ...
;                             for (int j = 0; j < 4; ++j) { const float r1 = dpp_ror1(g[j]), r2 = dpp_ror2(g[j]), r3 = dpp_ror3(g[j]);
;                                 p1[j] = t >= 1 ? r1 : b2[j]; p2[j] = t >= 2 ? r2 : (t == 1 ? b2[j] : b1[j]); p3[j] = t >= 3 ? r3 : (t == 2 ? b2[j] : (t == 1 ? b1[j] : b0[j])); } }
.LBB0_494:
	s_or_b64 exec, exec, s[2:3]
	v_mov_b32_dpp v235, v129 row_ror:1 row_mask:0xf bank_mask:0xf
	v_mov_b32_dpp v234, v129 row_ror:2 row_mask:0xf bank_mask:0xf
	v_mov_b32_dpp v157, v129 row_ror:3 row_mask:0xf bank_mask:0xf
	v_cmp_lt_i32_e32 vcc, 1, v205
	s_and_saveexec_b64 s[2:3], vcc
	s_xor_b64 s[2:3], exec, s[2:3]
	s_cbranch_execz .LBB0_498
	v_cmp_gt_i32_e32 vcc, 3, v205
	s_and_saveexec_b64 s[80:81], vcc
	s_cbranch_execz .LBB0_497
	s_waitcnt vmcnt(0)
	v_mov_b32_e32 v157, v165

; __device__ __forceinline__ unsigned cvt_pk_bf16(float lo, float hi) { unsigned r; asm("v_cvt_pk_bf16_f32 %0, %1, %2" : "=v"(r) : "v"(lo), "v"(hi)); return r; }
; __device__ __forceinline__ float siluf_(float x) { return x * sigmoidf_(x); }
; __device__ __forceinline__ float dpp_ror1(float v) { return __builtin_bit_cast(float, __builtin_amdgcn_update_dpp(0, __builtin_bit_cast(int, v), 0x121, 0xf, 0xf, false)); }
; __device__ __forceinline__ float dpp_ror2(float v) { return __builtin_bit_cast(float, __builtin_amdgcn_update_dpp(0, __builtin_bit_cast(int, v), 0x122, 0xf, 0xf, false)); }
; __device__ __forceinline__ float dpp_ror3(float v) { return __builtin_bit_cast(float, __builtin_amdgcn_update_dpp(0, __builtin_bit_cast(int, v), 0x123, 0xf, 0xf, false)); }
;     __device__ __forceinline__ void operator()(f32x4 (&acc)[2][2][4][2], const pg8::Unit& u, int wr, int wc, int fr, int fq) const {
;     ...
;                         if (prompt) { const f32x4 gp = (m == 0) ? hal[n] : acc[ai][bj][m > 0 ? m - 1 : 0][n];
; #pragma unroll
;                             for (int j = 0; j < 4; ++j) { p1[j] = dpp_ror1(fr == 15 ? gp[j] : g[j]); p2[j] = dpp_ror2(fr >= 14 ? gp[j] : g[j]); p3[j] = dpp_ror3(fr >= 13 ? gp[j] : g[j]); } }
;                         else { const int t = fr & 3; const float* sp = stp + (size_t)((row - MP) >> 2) * 3 * CW + ch;
;                             const f32x4 b0 = *(const f32x4*)sp, b1 = *(const f32x4*)(sp + CW), b2 = *(const f32x4*)(sp + 2 * CW);
; #pragma unroll
;                             for (int j = 0; j < 4; ++j) { const float r1 = dpp_ror1(g[j]), r2 = dpp_ror2(g[j]), r3 = dpp_ror3(g[j]);
;                                 p1[j] = t >= 1 ? r1 : b2[j]; p2[j] = t >= 2 ? r2 : (t == 1 ? b2[j] : b1[j]); p3[j] = t >= 3 ? r3 : (t == 2 ? b2[j] : (t == 1 ? b1[j] : b0[j])); } }
;                         float o[4];
; #pragma unroll
;                         for (int j = 0; j < 4; ++j) { const float y = bb[j] + w0[j] * p3[j] + w1[j] * p2[j] + w2[j] * p1[j] + w3[j] * g[j]; o[j] = is_rg ? y : siluf_(y); }
;                         u32x2 w; w.x = cvt_pk_bf16(o[0], o[1]); w.y = cvt_pk_bf16(o[2], o[3]);
;                         *(u32x2*)(dst + (size_t)row * ld + bj * 128 + 4 * n) = w; }
.LBB0_505:
	s_and_b64 vcc, exec, s[2:3]
	s_cbranch_vccz .LBB0_507
	v_cndmask_b32_e64 v154, v126, v130, s[10:11]
	s_nop 1
	v_mov_b32_dpp v166, v154 row_ror:1 row_mask:0xf bank_mask:0xf
	v_cndmask_b32_e64 v154, v126, v130, s[8:9]
	v_cndmask_b32_e64 v130, v126, v130, s[6:7]
	s_nop 0
	v_mov_b32_dpp v158, v154 row_ror:2 row_mask:0xf bank_mask:0xf
	v_mov_b32_dpp v154, v130 row_ror:3 row_mask:0xf bank_mask:0xf
	v_cndmask_b32_e64 v130, v127, v131, s[10:11]
	s_nop 1
	v_mov_b32_dpp v167, v130 row_ror:1 row_mask:0xf bank_mask:0xf
	v_cndmask_b32_e64 v130, v127, v131, s[8:9]
	s_nop 1
	v_mov_b32_dpp v159, v130 row_ror:2 row_mask:0xf bank_mask:0xf
	v_cndmask_b32_e64 v130, v127, v131, s[6:7]
	s_nop 0
	s_nop 0
	v_mov_b32_dpp v155, v130 row_ror:3 row_mask:0xf bank_mask:0xf
	v_cndmask_b32_e64 v130, v128, v132, s[10:11]
	s_nop 1
	v_mov_b32_dpp v168, v130 row_ror:1 row_mask:0xf bank_mask:0xf
	v_cndmask_b32_e64 v130, v128, v132, s[8:9]
	s_nop 1
	v_mov_b32_dpp v160, v130 row_ror:2 row_mask:0xf bank_mask:0xf
	v_cndmask_b32_e64 v130, v128, v132, s[6:7]
	s_nop 1
	v_mov_b32_dpp v156, v130 row_ror:3 row_mask:0xf bank_mask:0xf
	v_cndmask_b32_e64 v130, v129, v133, s[10:11]
	s_nop 1
	v_mov_b32_dpp v169, v130 row_ror:1 row_mask:0xf bank_mask:0xf
	v_cndmask_b32_e64 v130, v129, v133, s[8:9]
	s_nop 1
	v_mov_b32_dpp v161, v130 row_ror:2 row_mask:0xf bank_mask:0xf
	v_cndmask_b32_e64 v130, v129, v133, s[6:7]
	s_nop 1
	v_mov_b32_dpp v157, v130 row_ror:3 row_mask:0xf bank_mask:0xf
.LBB0_507:
	s_waitcnt vmcnt(0)
	v_mov_b32_e32 v162, v150
	v_mov_b32_e32 v163, v138
	v_mov_b32_e32 v130, v158
	v_mov_b32_e32 v131, v154
	v_pk_mul_f32 v[130:131], v[162:163], v[130:131]
	v_mov_b32_e32 v164, v146
	v_add_f32_e32 v131, v142, v131
	v_mov_b32_e32 v165, v134
	v_mov_b32_e32 v235, v166
	v_add_f32_e32 v132, v130, v131
	v_pk_mul_f32 v[130:131], v[164:165], v[234:235]
	v_mov_b32_e32 v138, v151
	v_add_f32_e32 v131, v131, v132
	v_add_f32_e32 v132, v130, v131
	v_mul_f32_e32 v130, 0xbfb8aa3b, v132
	v_exp_f32_e32 v130, v130
	v_mov_b32_e32 v154, v159
	v_mov_b32_e32 v134, v147
	v_mov_b32_e32 v233, v167
	v_add_f32_e32 v130, 1.0, v130
	v_rcp_f32_e32 v133, v130
	v_pk_mul_f32 v[130:131], v[138:139], v[154:155]
	v_mov_b32_e32 v158, v152
	v_add_f32_e32 v131, v143, v131
	v_add_f32_e32 v146, v130, v131
	v_pk_mul_f32 v[130:131], v[134:135], v[232:233]
	v_mov_b32_e32 v159, v140
	v_add_f32_e32 v131, v131, v146
	v_add_f32_e32 v146, v130, v131
	v_mul_f32_e32 v130, 0xbfb8aa3b, v146
	v_exp_f32_e32 v130, v130
	v_mul_f32_e32 v131, v132, v133
	v_cndmask_b32_e64 v132, v131, v132, s[4:5]
	v_mov_b32_e32 v131, v156
	v_add_f32_e32 v130, 1.0, v130
	v_rcp_f32_e32 v133, v130
	v_mov_b32_e32 v130, v160
	v_pk_mul_f32 v[130:131], v[158:159], v[130:131]
	v_mov_b32_e32 v166, v148
	v_add_f32_e32 v131, v144, v131
	v_mov_b32_e32 v167, v136
	v_mov_b32_e32 v173, v168
	v_add_f32_e32 v140, v130, v131
	v_pk_mul_f32 v[130:131], v[166:167], v[172:173]
	v_mov_b32_e32 v156, v161
	v_add_f32_e32 v131, v131, v140
	v_add_f32_e32 v147, v130, v131
	v_mul_f32_e32 v130, 0xbfb8aa3b, v147
	v_mov_b32_e32 v140, v153
	v_exp_f32_e32 v148, v130
	v_pk_mul_f32 v[130:131], v[140:141], v[156:157]
	v_mov_b32_e32 v136, v149
	v_add_f32_e32 v131, v145, v131
	v_mov_b32_e32 v171, v169
	v_add_f32_e32 v150, v130, v131
	v_pk_mul_f32 v[130:131], v[136:137], v[170:171]
	v_add_f32_e32 v148, 1.0, v148
	v_add_f32_e32 v131, v131, v150
	v_add_f32_e32 v130, v130, v131
	v_mul_f32_e32 v131, 0xbfb8aa3b, v130
	v_exp_f32_e32 v131, v131
	v_rcp_f32_e32 v148, v148
	v_mul_f32_e32 v133, v146, v133
	v_cndmask_b32_e64 v133, v133, v146, s[4:5]
	v_add_f32_e32 v131, 1.0, v131
	v_rcp_f32_e32 v131, v131
	v_mul_f32_e32 v146, v147, v148
	v_cndmask_b32_e64 v146, v146, v147, s[4:5]
	s_mov_b64 s[2:3], -1
	v_mul_f32_e32 v131, v130, v131
	v_cndmask_b32_e64 v131, v131, v130, s[4:5]
	v_cvt_pk_bf16_f32 v130, v132, v133
	v_cvt_pk_bf16_f32 v131, v146, v131
	s_and_b64 vcc, exec, s[18:19]
	v_mov_b32_e32 v168, v106
	v_mov_b32_e32 v160, v107
	v_mov_b32_e32 v152, v108
	v_mov_b32_e32 v150, v109
	flat_store_dwordx2 v[222:223], v[130:131] offset:8
	s_cbranch_vccnz .LBB0_549
	v_add_u32_e32 v131, 0xffffe010, v202
	v_ashrrev_i32_e32 v131, 2, v131
	v_lshl_add_u32 v131, v131, 1, v131
	v_mad_i64_i32 v[132:133], s[2:3], v131, s47, 0
	v_lshl_add_u64 v[132:133], v[132:133], 2, v[208:209]
	v_lshl_add_u64 v[146:147], v[132:133], 0, s[24:25]
	s_lshl_b32 s2, s27, 2
	s_mov_b32 s3, s25
	global_load_dwordx4 v[154:157], v[132:133], off offset:16
	s_nop 0
	global_load_dwordx4 v[146:149], v[146:147], off offset:16
	v_lshl_add_u64 v[132:133], v[132:133], 0, s[2:3]
	global_load_dwordx4 v[150:153], v[132:133], off offset:16
	v_mov_b32_dpp v160, v106 row_ror:1 row_mask:0xf bank_mask:0xf
	v_mov_b32_dpp v161, v106 row_ror:2 row_mask:0xf bank_mask:0xf
	v_mov_b32_dpp v130, v106 row_ror:3 row_mask:0xf bank_mask:0xf
	v_cmp_lt_i32_e32 vcc, 1, v205
	s_and_saveexec_b64 s[2:3], vcc
	s_xor_b64 s[2:3], exec, s[2:3]
	s_cbranch_execz .LBB0_512
	v_cmp_gt_i32_e32 vcc, 3, v205
	s_and_saveexec_b64 s[80:81], vcc
	s_cbranch_execz .LBB0_511
	s_waitcnt vmcnt(0)
	v_mov_b32_e32 v130, v150

; __device__ __forceinline__ float dpp_ror1(float v) { return __builtin_bit_cast(float, __builtin_amdgcn_update_dpp(0, __builtin_bit_cast(int, v), 0x121, 0xf, 0xf, false)); }
; __device__ __forceinline__ float dpp_ror2(float v) { return __builtin_bit_cast(float, __builtin_amdgcn_update_dpp(0, __builtin_bit_cast(int, v), 0x122, 0xf, 0xf, false)); }
; __device__ __forceinline__ float dpp_ror3(float v) { return __builtin_bit_cast(float, __builtin_amdgcn_update_dpp(0, __builtin_bit_cast(int, v), 0x123, 0xf, 0xf, false)); }
;     __device__ __forceinline__ void operator()(f32x4 (&acc)[2][2][4][2], const pg8::Unit& u, int wr, int wc, int fr, int fq) const {
;     ...
;                             for (int j = 0; j < 4; ++j) { const float r1 = dpp_ror1(g[j]), r2 = dpp_ror2(g[j]), r3 = dpp_ror3(g[j]);
;                                 p1[j] = t >= 1 ? r1 : b2[j]; p2[j] = t >= 2 ? r2 : (t == 1 ? b2[j] : b1[j]); p3[j] = t >= 3 ? r3 : (t == 2 ? b2[j] : (t == 1 ? b1[j] : b0[j])); } }
.LBB0_518:
	s_or_b64 exec, exec, s[2:3]
	v_mov_b32_dpp v168, v107 row_ror:1 row_mask:0xf bank_mask:0xf
	v_mov_b32_dpp v169, v107 row_ror:2 row_mask:0xf bank_mask:0xf
	v_mov_b32_dpp v131, v107 row_ror:3 row_mask:0xf bank_mask:0xf
	v_cmp_lt_i32_e32 vcc, 1, v205
	s_and_saveexec_b64 s[2:3], vcc
	s_xor_b64 s[2:3], exec, s[2:3]
	s_cbranch_execz .LBB0_522
	v_cmp_gt_i32_e32 vcc, 3, v205
	s_and_saveexec_b64 s[80:81], vcc
	s_cbranch_execz .LBB0_521
	s_waitcnt vmcnt(0)
	v_mov_b32_e32 v131, v151

; __device__ __forceinline__ float dpp_ror1(float v) { return __builtin_bit_cast(float, __builtin_amdgcn_update_dpp(0, __builtin_bit_cast(int, v), 0x121, 0xf, 0xf, false)); }
; __device__ __forceinline__ float dpp_ror2(float v) { return __builtin_bit_cast(float, __builtin_amdgcn_update_dpp(0, __builtin_bit_cast(int, v), 0x122, 0xf, 0xf, false)); }
; __device__ __forceinline__ float dpp_ror3(float v) { return __builtin_bit_cast(float, __builtin_amdgcn_update_dpp(0, __builtin_bit_cast(int, v), 0x123, 0xf, 0xf, false)); }
;     __device__ __forceinline__ void operator()(f32x4 (&acc)[2][2][4][2], const pg8::Unit& u, int wr, int wc, int fr, int fq) const {
;     ...
;                             for (int j = 0; j < 4; ++j) { const float r1 = dpp_ror1(g[j]), r2 = dpp_ror2(g[j]), r3 = dpp_ror3(g[j]);
;                                 p1[j] = t >= 1 ? r1 : b2[j]; p2[j] = t >= 2 ? r2 : (t == 1 ? b2[j] : b1[j]); p3[j] = t >= 3 ? r3 : (t == 2 ? b2[j] : (t == 1 ? b1[j] : b0[j])); } }
.LBB0_528:
	s_or_b64 exec, exec, s[2:3]
	v_mov_b32_dpp v170, v108 row_ror:1 row_mask:0xf bank_mask:0xf
	v_mov_b32_dpp v171, v108 row_ror:2 row_mask:0xf bank_mask:0xf
	v_mov_b32_dpp v132, v108 row_ror:3 row_mask:0xf bank_mask:0xf
	v_cmp_lt_i32_e32 vcc, 1, v205
	s_and_saveexec_b64 s[2:3], vcc
	s_xor_b64 s[2:3], exec, s[2:3]
	s_cbranch_execz .LBB0_532
	v_cmp_gt_i32_e32 vcc, 3, v205
	s_and_saveexec_b64 s[80:81], vcc
	s_cbranch_execz .LBB0_531
	s_waitcnt vmcnt(0)
	v_mov_b32_e32 v132, v152

; __device__ __forceinline__ float dpp_ror1(float v) { return __builtin_bit_cast(float, __builtin_amdgcn_update_dpp(0, __builtin_bit_cast(int, v), 0x121, 0xf, 0xf, false)); }
; __device__ __forceinline__ float dpp_ror2(float v) { return __builtin_bit_cast(float, __builtin_amdgcn_update_dpp(0, __builtin_bit_cast(int, v), 0x122, 0xf, 0xf, false)); }
; __device__ __forceinline__ float dpp_ror3(float v) { return __builtin_bit_cast(float, __builtin_amdgcn_update_dpp(0, __builtin_bit_cast(int, v), 0x123, 0xf, 0xf, false)); }
;     __device__ __forceinline__ void operator()(f32x4 (&acc)[2][2][4][2], const pg8::Unit& u, int wr, int wc, int fr, int fq) const {
;     ...
;                             for (int j = 0; j < 4; ++j) { const float r1 = dpp_ror1(g[j]), r2 = dpp_ror2(g[j]), r3 = dpp_ror3(g[j]);
;                                 p1[j] = t >= 1 ? r1 : b2[j]; p2[j] = t >= 2 ? r2 : (t == 1 ? b2[j] : b1[j]); p3[j] = t >= 3 ? r3 : (t == 2 ? b2[j] : (t == 1 ? b1[j] : b0[j])); } }
.LBB0_538:
	s_or_b64 exec, exec, s[2:3]
	v_mov_b32_dpp v173, v109 row_ror:1 row_mask:0xf bank_mask:0xf
	v_mov_b32_dpp v172, v109 row_ror:2 row_mask:0xf bank_mask:0xf
	v_mov_b32_dpp v133, v109 row_ror:3 row_mask:0xf bank_mask:0xf
	v_cmp_lt_i32_e32 vcc, 1, v205
	s_and_saveexec_b64 s[2:3], vcc
	s_xor_b64 s[2:3], exec, s[2:3]
	s_cbranch_execz .LBB0_542
	v_cmp_gt_i32_e32 vcc, 3, v205
	s_and_saveexec_b64 s[80:81], vcc
	s_cbranch_execz .LBB0_541
	s_waitcnt vmcnt(0)
	v_mov_b32_e32 v133, v153

; __device__ __forceinline__ unsigned cvt_pk_bf16(float lo, float hi) { unsigned r; asm("v_cvt_pk_bf16_f32 %0, %1, %2" : "=v"(r) : "v"(lo), "v"(hi)); return r; }
; __device__ __forceinline__ float siluf_(float x) { return x * sigmoidf_(x); }
; __device__ __forceinline__ float dpp_ror1(float v) { return __builtin_bit_cast(float, __builtin_amdgcn_update_dpp(0, __builtin_bit_cast(int, v), 0x121, 0xf, 0xf, false)); }
; __device__ __forceinline__ float dpp_ror2(float v) { return __builtin_bit_cast(float, __builtin_amdgcn_update_dpp(0, __builtin_bit_cast(int, v), 0x122, 0xf, 0xf, false)); }
; __device__ __forceinline__ float dpp_ror3(float v) { return __builtin_bit_cast(float, __builtin_amdgcn_update_dpp(0, __builtin_bit_cast(int, v), 0x123, 0xf, 0xf, false)); }
;     __device__ __forceinline__ void operator()(f32x4 (&acc)[2][2][4][2], const pg8::Unit& u, int wr, int wc, int fr, int fq) const {
;     ...
;                         if (prompt) { const f32x4 gp = (m == 0) ? hal[n] : acc[ai][bj][m > 0 ? m - 1 : 0][n];
; #pragma unroll
;                             for (int j = 0; j < 4; ++j) { p1[j] = dpp_ror1(fr == 15 ? gp[j] : g[j]); p2[j] = dpp_ror2(fr >= 14 ? gp[j] : g[j]); p3[j] = dpp_ror3(fr >= 13 ? gp[j] : g[j]); } }
;                         else { const int t = fr & 3; const float* sp = stp + (size_t)((row - MP) >> 2) * 3 * CW + ch;
;                             const f32x4 b0 = *(const f32x4*)sp, b1 = *(const f32x4*)(sp + CW), b2 = *(const f32x4*)(sp + 2 * CW);
; #pragma unroll
;                             for (int j = 0; j < 4; ++j) { const float r1 = dpp_ror1(g[j]), r2 = dpp_ror2(g[j]), r3 = dpp_ror3(g[j]);
;                                 p1[j] = t >= 1 ? r1 : b2[j]; p2[j] = t >= 2 ? r2 : (t == 1 ? b2[j] : b1[j]); p3[j] = t >= 3 ? r3 : (t == 2 ? b2[j] : (t == 1 ? b1[j] : b0[j])); } }
;                         float o[4];
; #pragma unroll
;                         for (int j = 0; j < 4; ++j) { const float y = bb[j] + w0[j] * p3[j] + w1[j] * p2[j] + w2[j] * p1[j] + w3[j] * g[j]; o[j] = is_rg ? y : siluf_(y); }
;                         u32x2 w; w.x = cvt_pk_bf16(o[0], o[1]); w.y = cvt_pk_bf16(o[2], o[3]);
;                         *(u32x2*)(dst + (size_t)row * ld + bj * 128 + 4 * n) = w; }
.LBB0_549:
	s_and_b64 vcc, exec, s[2:3]
	s_cbranch_vccz .LBB0_551
	v_cndmask_b32_e64 v130, v106, v126, s[10:11]
	v_cndmask_b32_e64 v131, v106, v126, s[6:7]
	s_nop 0
	v_mov_b32_dpp v154, v130 row_ror:1 row_mask:0xf bank_mask:0xf
	v_cndmask_b32_e64 v130, v106, v126, s[8:9]
	s_nop 1
	v_mov_b32_dpp v146, v130 row_ror:2 row_mask:0xf bank_mask:0xf
	v_cndmask_b32_e64 v132, v107, v127, s[6:7]
	v_mov_b32_dpp v130, v131 row_ror:3 row_mask:0xf bank_mask:0xf
	v_cndmask_b32_e64 v131, v107, v127, s[10:11]
	v_cndmask_b32_e64 v133, v108, v128, s[6:7]
	s_nop 0
	v_mov_b32_dpp v155, v131 row_ror:1 row_mask:0xf bank_mask:0xf
	v_cndmask_b32_e64 v131, v107, v127, s[8:9]
	s_nop 1
	v_mov_b32_dpp v147, v131 row_ror:2 row_mask:0xf bank_mask:0xf
	v_cndmask_b32_e64 v151, v109, v129, s[6:7]
	s_nop 0
	v_mov_b32_dpp v131, v132 row_ror:3 row_mask:0xf bank_mask:0xf
	v_cndmask_b32_e64 v132, v108, v128, s[10:11]
	s_nop 1
	v_mov_b32_dpp v156, v132 row_ror:1 row_mask:0xf bank_mask:0xf
	v_cndmask_b32_e64 v132, v108, v128, s[8:9]
	s_nop 1
	v_mov_b32_dpp v148, v132 row_ror:2 row_mask:0xf bank_mask:0xf
	s_nop 1
	v_mov_b32_dpp v132, v133 row_ror:3 row_mask:0xf bank_mask:0xf
	v_cndmask_b32_e64 v133, v109, v129, s[10:11]
	s_nop 1
	v_mov_b32_dpp v157, v133 row_ror:1 row_mask:0xf bank_mask:0xf
	v_cndmask_b32_e64 v133, v109, v129, s[8:9]
	s_nop 1
	v_mov_b32_dpp v149, v133 row_ror:2 row_mask:0xf bank_mask:0xf
	s_nop 1
	v_mov_b32_dpp v133, v151 row_ror:3 row_mask:0xf bank_mask:0xf
.LBB0_551:
	v_mov_b32_e32 v170, v146
	v_mov_b32_e32 v171, v130
	v_pk_mul_f32 v[170:171], v[162:163], v[170:171]
	v_mov_b32_e32 v169, v154
	v_add_f32_e32 v130, v142, v171
	v_add_f32_e32 v130, v170, v130
	v_pk_mul_f32 v[168:169], v[164:165], v[168:169]
	v_mov_b32_e32 v161, v155
	v_add_f32_e32 v130, v169, v130
	v_add_f32_e32 v146, v168, v130
	v_mul_f32_e32 v130, 0xbfb8aa3b, v146
	v_exp_f32_e32 v130, v130
	v_mov_b32_e32 v153, v156
	s_mov_b64 s[2:3], -1
	s_and_b64 vcc, exec, s[18:19]
	v_add_f32_e32 v130, 1.0, v130
	v_rcp_f32_e32 v151, v130
	v_mov_b32_e32 v130, v147
	v_pk_mul_f32 v[130:131], v[138:139], v[130:131]
	v_mov_b32_e32 v168, v90
	v_add_f32_e32 v131, v143, v131
	v_add_f32_e32 v147, v130, v131
	v_pk_mul_f32 v[130:131], v[134:135], v[160:161]
	v_mov_b32_e32 v160, v91
	v_add_f32_e32 v131, v131, v147
	v_add_f32_e32 v147, v130, v131
	v_mul_f32_e32 v130, 0xbfb8aa3b, v147
	v_exp_f32_e32 v130, v130
	v_mul_f32_e32 v131, v146, v151
	v_cndmask_b32_e64 v146, v131, v146, s[4:5]
	v_mov_b32_e32 v131, v132
	v_add_f32_e32 v130, 1.0, v130
	v_rcp_f32_e32 v154, v130
	v_mov_b32_e32 v130, v148
	v_pk_mul_f32 v[130:131], v[158:159], v[130:131]
	v_mov_b32_e32 v151, v157
	v_add_f32_e32 v131, v144, v131
	v_add_f32_e32 v132, v130, v131
	v_pk_mul_f32 v[130:131], v[166:167], v[152:153]
	s_nop 0
	v_add_f32_e32 v131, v131, v132
	v_add_f32_e32 v148, v130, v131
	v_mul_f32_e32 v130, 0xbfb8aa3b, v148
	v_mov_b32_e32 v132, v149
	v_exp_f32_e32 v152, v130
	v_pk_mul_f32 v[130:131], v[140:141], v[132:133]
	v_add_f32_e32 v133, 1.0, v152
	v_add_f32_e32 v131, v145, v131
	v_add_f32_e32 v132, v130, v131
	v_pk_mul_f32 v[130:131], v[136:137], v[150:151]
	v_rcp_f32_e32 v133, v133
	v_add_f32_e32 v131, v131, v132
	v_add_f32_e32 v130, v130, v131
	v_mul_f32_e32 v131, 0xbfb8aa3b, v130
	v_exp_f32_e32 v131, v131
	v_mul_f32_e32 v132, v147, v154
	v_mul_f32_e32 v133, v148, v133
	v_cndmask_b32_e64 v132, v132, v147, s[4:5]
	v_add_f32_e32 v131, 1.0, v131
	v_rcp_f32_e32 v131, v131
	v_cndmask_b32_e64 v133, v133, v148, s[4:5]
	v_mov_b32_e32 v152, v92
	v_mov_b32_e32 v150, v93
	v_mul_f32_e32 v131, v130, v131
	v_cndmask_b32_e64 v131, v131, v130, s[4:5]
	v_cvt_pk_bf16_f32 v130, v146, v132
	v_cvt_pk_bf16_f32 v131, v133, v131
	v_mov_b32_e32 v124, v130
	v_mov_b32_e32 v125, v131
	flat_store_dwordx4 v[224:225], v[122:125]
	s_cbranch_vccnz .LBB0_593
	v_add_u32_e32 v131, 0xffffe020, v202
	v_ashrrev_i32_e32 v131, 2, v131
	v_lshl_add_u32 v131, v131, 1, v131
	v_mad_i64_i32 v[132:133], s[2:3], v131, s47, 0
	v_lshl_add_u64 v[132:133], v[132:133], 2, v[208:209]
	v_lshl_add_u64 v[146:147], v[132:133], 0, s[24:25]
	s_lshl_b32 s2, s27, 2
	s_mov_b32 s3, s25
	global_load_dwordx4 v[154:157], v[132:133], off offset:16
	s_nop 0
	global_load_dwordx4 v[146:149], v[146:147], off offset:16
	v_lshl_add_u64 v[132:133], v[132:133], 0, s[2:3]
	global_load_dwordx4 v[150:153], v[132:133], off offset:16
	v_mov_b32_dpp v160, v90 row_ror:1 row_mask:0xf bank_mask:0xf
	v_mov_b32_dpp v161, v90 row_ror:2 row_mask:0xf bank_mask:0xf
	v_mov_b32_dpp v130, v90 row_ror:3 row_mask:0xf bank_mask:0xf
	v_cmp_lt_i32_e32 vcc, 1, v205
	s_and_saveexec_b64 s[2:3], vcc
	s_xor_b64 s[2:3], exec, s[2:3]
	s_cbranch_execz .LBB0_556
	v_cmp_gt_i32_e32 vcc, 3, v205
	s_and_saveexec_b64 s[80:81], vcc
	s_cbranch_execz .LBB0_555
	s_waitcnt vmcnt(0)
	v_mov_b32_e32 v130, v150

; __device__ __forceinline__ float dpp_ror1(float v) { return __builtin_bit_cast(float, __builtin_amdgcn_update_dpp(0, __builtin_bit_cast(int, v), 0x121, 0xf, 0xf, false)); }
; __device__ __forceinline__ float dpp_ror2(float v) { return __builtin_bit_cast(float, __builtin_amdgcn_update_dpp(0, __builtin_bit_cast(int, v), 0x122, 0xf, 0xf, false)); }
; __device__ __forceinline__ float dpp_ror3(float v) { return __builtin_bit_cast(float, __builtin_amdgcn_update_dpp(0, __builtin_bit_cast(int, v), 0x123, 0xf, 0xf, false)); }
;     __device__ __forceinline__ void operator()(f32x4 (&acc)[2][2][4][2], const pg8::Unit& u, int wr, int wc, int fr, int fq) const {
;     ...
;                             for (int j = 0; j < 4; ++j) { const float r1 = dpp_ror1(g[j]), r2 = dpp_ror2(g[j]), r3 = dpp_ror3(g[j]);
;                                 p1[j] = t >= 1 ? r1 : b2[j]; p2[j] = t >= 2 ? r2 : (t == 1 ? b2[j] : b1[j]); p3[j] = t >= 3 ? r3 : (t == 2 ? b2[j] : (t == 1 ? b1[j] : b0[j])); } }
.LBB0_562:
	s_or_b64 exec, exec, s[2:3]
	v_mov_b32_dpp v168, v91 row_ror:1 row_mask:0xf bank_mask:0xf
	v_mov_b32_dpp v169, v91 row_ror:2 row_mask:0xf bank_mask:0xf
	v_mov_b32_dpp v131, v91 row_ror:3 row_mask:0xf bank_mask:0xf
	v_cmp_lt_i32_e32 vcc, 1, v205
	s_and_saveexec_b64 s[2:3], vcc
	s_xor_b64 s[2:3], exec, s[2:3]
	s_cbranch_execz .LBB0_566
	v_cmp_gt_i32_e32 vcc, 3, v205
	s_and_saveexec_b64 s[80:81], vcc
	s_cbranch_execz .LBB0_565
	s_waitcnt vmcnt(0)
	v_mov_b32_e32 v131, v151

; __device__ __forceinline__ float dpp_ror1(float v) { return __builtin_bit_cast(float, __builtin_amdgcn_update_dpp(0, __builtin_bit_cast(int, v), 0x121, 0xf, 0xf, false)); }
; __device__ __forceinline__ float dpp_ror2(float v) { return __builtin_bit_cast(float, __builtin_amdgcn_update_dpp(0, __builtin_bit_cast(int, v), 0x122, 0xf, 0xf, false)); }
; __device__ __forceinline__ float dpp_ror3(float v) { return __builtin_bit_cast(float, __builtin_amdgcn_update_dpp(0, __builtin_bit_cast(int, v), 0x123, 0xf, 0xf, false)); }
;     __device__ __forceinline__ void operator()(f32x4 (&acc)[2][2][4][2], const pg8::Unit& u, int wr, int wc, int fr, int fq) const {
;     ...
;                             for (int j = 0; j < 4; ++j) { const float r1 = dpp_ror1(g[j]), r2 = dpp_ror2(g[j]), r3 = dpp_ror3(g[j]);
;                                 p1[j] = t >= 1 ? r1 : b2[j]; p2[j] = t >= 2 ? r2 : (t == 1 ? b2[j] : b1[j]); p3[j] = t >= 3 ? r3 : (t == 2 ? b2[j] : (t == 1 ? b1[j] : b0[j])); } }
.LBB0_572:
	s_or_b64 exec, exec, s[2:3]
	v_mov_b32_dpp v170, v92 row_ror:1 row_mask:0xf bank_mask:0xf
	v_mov_b32_dpp v171, v92 row_ror:2 row_mask:0xf bank_mask:0xf
	v_mov_b32_dpp v132, v92 row_ror:3 row_mask:0xf bank_mask:0xf
	v_cmp_lt_i32_e32 vcc, 1, v205
	s_and_saveexec_b64 s[2:3], vcc
	s_xor_b64 s[2:3], exec, s[2:3]
	s_cbranch_execz .LBB0_576
	v_cmp_gt_i32_e32 vcc, 3, v205
	s_and_saveexec_b64 s[80:81], vcc
	s_cbranch_execz .LBB0_575
	s_waitcnt vmcnt(0)
	v_mov_b32_e32 v132, v152

; __device__ __forceinline__ float dpp_ror1(float v) { return __builtin_bit_cast(float, __builtin_amdgcn_update_dpp(0, __builtin_bit_cast(int, v), 0x121, 0xf, 0xf, false)); }
; __device__ __forceinline__ float dpp_ror2(float v) { return __builtin_bit_cast(float, __builtin_amdgcn_update_dpp(0, __builtin_bit_cast(int, v), 0x122, 0xf, 0xf, false)); }
; __device__ __forceinline__ float dpp_ror3(float v) { return __builtin_bit_cast(float, __builtin_amdgcn_update_dpp(0, __builtin_bit_cast(int, v), 0x123, 0xf, 0xf, false)); }
;     __device__ __forceinline__ void operator()(f32x4 (&acc)[2][2][4][2], const pg8::Unit& u, int wr, int wc, int fr, int fq) const {
;     ...
;                             for (int j = 0; j < 4; ++j) { const float r1 = dpp_ror1(g[j]), r2 = dpp_ror2(g[j]), r3 = dpp_ror3(g[j]);
;                                 p1[j] = t >= 1 ? r1 : b2[j]; p2[j] = t >= 2 ? r2 : (t == 1 ? b2[j] : b1[j]); p3[j] = t >= 3 ? r3 : (t == 2 ? b2[j] : (t == 1 ? b1[j] : b0[j])); } }
.LBB0_582:
	s_or_b64 exec, exec, s[2:3]
	v_mov_b32_dpp v173, v93 row_ror:1 row_mask:0xf bank_mask:0xf
	v_mov_b32_dpp v172, v93 row_ror:2 row_mask:0xf bank_mask:0xf
	v_mov_b32_dpp v133, v93 row_ror:3 row_mask:0xf bank_mask:0xf
	v_cmp_lt_i32_e32 vcc, 1, v205
	s_and_saveexec_b64 s[2:3], vcc
	s_xor_b64 s[2:3], exec, s[2:3]
	s_cbranch_execz .LBB0_586
	v_cmp_gt_i32_e32 vcc, 3, v205
	s_and_saveexec_b64 s[80:81], vcc
	s_cbranch_execz .LBB0_585
	s_waitcnt vmcnt(0)
	v_mov_b32_e32 v133, v153

; __device__ __forceinline__ unsigned cvt_pk_bf16(float lo, float hi) { unsigned r; asm("v_cvt_pk_bf16_f32 %0, %1, %2" : "=v"(r) : "v"(lo), "v"(hi)); return r; }
; __device__ __forceinline__ float siluf_(float x) { return x * sigmoidf_(x); }
; __device__ __forceinline__ float dpp_ror1(float v) { return __builtin_bit_cast(float, __builtin_amdgcn_update_dpp(0, __builtin_bit_cast(int, v), 0x121, 0xf, 0xf, false)); }
; __device__ __forceinline__ float dpp_ror2(float v) { return __builtin_bit_cast(float, __builtin_amdgcn_update_dpp(0, __builtin_bit_cast(int, v), 0x122, 0xf, 0xf, false)); }
; __device__ __forceinline__ float dpp_ror3(float v) { return __builtin_bit_cast(float, __builtin_amdgcn_update_dpp(0, __builtin_bit_cast(int, v), 0x123, 0xf, 0xf, false)); }
;     __device__ __forceinline__ void operator()(f32x4 (&acc)[2][2][4][2], const pg8::Unit& u, int wr, int wc, int fr, int fq) const {
;     ...
;                         if (prompt) { const f32x4 gp = (m == 0) ? hal[n] : acc[ai][bj][m > 0 ? m - 1 : 0][n];
; #pragma unroll
;                             for (int j = 0; j < 4; ++j) { p1[j] = dpp_ror1(fr == 15 ? gp[j] : g[j]); p2[j] = dpp_ror2(fr >= 14 ? gp[j] : g[j]); p3[j] = dpp_ror3(fr >= 13 ? gp[j] : g[j]); } }
;                         else { const int t = fr & 3; const float* sp = stp + (size_t)((row - MP) >> 2) * 3 * CW + ch;
;                             const f32x4 b0 = *(const f32x4*)sp, b1 = *(const f32x4*)(sp + CW), b2 = *(const f32x4*)(sp + 2 * CW);
; #pragma unroll
;                             for (int j = 0; j < 4; ++j) { const float r1 = dpp_ror1(g[j]), r2 = dpp_ror2(g[j]), r3 = dpp_ror3(g[j]);
;                                 p1[j] = t >= 1 ? r1 : b2[j]; p2[j] = t >= 2 ? r2 : (t == 1 ? b2[j] : b1[j]); p3[j] = t >= 3 ? r3 : (t == 2 ? b2[j] : (t == 1 ? b1[j] : b0[j])); } }
;                         float o[4];
; #pragma unroll
;                         for (int j = 0; j < 4; ++j) { const float y = bb[j] + w0[j] * p3[j] + w1[j] * p2[j] + w2[j] * p1[j] + w3[j] * g[j]; o[j] = is_rg ? y : siluf_(y); }
;                         u32x2 w; w.x = cvt_pk_bf16(o[0], o[1]); w.y = cvt_pk_bf16(o[2], o[3]);
;                         *(u32x2*)(dst + (size_t)row * ld + bj * 128 + 4 * n) = w; }
.LBB0_593:
	s_and_b64 vcc, exec, s[2:3]
	s_cbranch_vccz .LBB0_595
	v_cndmask_b32_e64 v130, v90, v106, s[10:11]
	v_cndmask_b32_e64 v131, v90, v106, s[6:7]
	s_nop 0
	v_mov_b32_dpp v154, v130 row_ror:1 row_mask:0xf bank_mask:0xf
	v_cndmask_b32_e64 v130, v90, v106, s[8:9]
	s_nop 1
	v_mov_b32_dpp v146, v130 row_ror:2 row_mask:0xf bank_mask:0xf
	v_cndmask_b32_e64 v132, v91, v107, s[6:7]
	v_mov_b32_dpp v130, v131 row_ror:3 row_mask:0xf bank_mask:0xf
	v_cndmask_b32_e64 v131, v91, v107, s[10:11]
	v_cndmask_b32_e64 v133, v92, v108, s[6:7]
	s_nop 0
	v_mov_b32_dpp v155, v131 row_ror:1 row_mask:0xf bank_mask:0xf
	v_cndmask_b32_e64 v131, v91, v107, s[8:9]
	s_nop 1
	v_mov_b32_dpp v147, v131 row_ror:2 row_mask:0xf bank_mask:0xf
	v_cndmask_b32_e64 v151, v93, v109, s[6:7]
	s_nop 0
	v_mov_b32_dpp v131, v132 row_ror:3 row_mask:0xf bank_mask:0xf
	v_cndmask_b32_e64 v132, v92, v108, s[10:11]
	s_nop 1
	v_mov_b32_dpp v156, v132 row_ror:1 row_mask:0xf bank_mask:0xf
	v_cndmask_b32_e64 v132, v92, v108, s[8:9]
	s_nop 1
	v_mov_b32_dpp v148, v132 row_ror:2 row_mask:0xf bank_mask:0xf
	s_nop 1
	v_mov_b32_dpp v132, v133 row_ror:3 row_mask:0xf bank_mask:0xf
	v_cndmask_b32_e64 v133, v93, v109, s[10:11]
	s_nop 1
	v_mov_b32_dpp v157, v133 row_ror:1 row_mask:0xf bank_mask:0xf
	v_cndmask_b32_e64 v133, v93, v109, s[8:9]
	s_nop 1
	v_mov_b32_dpp v149, v133 row_ror:2 row_mask:0xf bank_mask:0xf
	s_nop 1
	v_mov_b32_dpp v133, v151 row_ror:3 row_mask:0xf bank_mask:0xf
.LBB0_595:
	v_mov_b32_e32 v170, v146
	v_mov_b32_e32 v171, v130
	v_pk_mul_f32 v[170:171], v[162:163], v[170:171]
	v_mov_b32_e32 v169, v154
	v_add_f32_e32 v130, v142, v171
	v_add_f32_e32 v130, v170, v130
	v_pk_mul_f32 v[168:169], v[164:165], v[168:169]
	v_mov_b32_e32 v161, v155
	v_add_f32_e32 v130, v169, v130
	v_add_f32_e32 v146, v168, v130
	v_mul_f32_e32 v130, 0xbfb8aa3b, v146
	v_exp_f32_e32 v130, v130
	v_mov_b32_e32 v153, v156
	s_mov_b64 s[2:3], -1
	s_and_b64 vcc, exec, s[18:19]
	v_add_f32_e32 v130, 1.0, v130
	v_rcp_f32_e32 v151, v130
	v_mov_b32_e32 v130, v147
	v_pk_mul_f32 v[130:131], v[138:139], v[130:131]
	v_mov_b32_e32 v168, v74
	v_add_f32_e32 v131, v143, v131
	v_add_f32_e32 v147, v130, v131
	v_pk_mul_f32 v[130:131], v[134:135], v[160:161]
	v_mov_b32_e32 v160, v75
	v_add_f32_e32 v131, v131, v147
	v_add_f32_e32 v147, v130, v131
	v_mul_f32_e32 v130, 0xbfb8aa3b, v147
	v_exp_f32_e32 v130, v130
	v_mul_f32_e32 v131, v146, v151
	v_cndmask_b32_e64 v146, v131, v146, s[4:5]
	v_mov_b32_e32 v131, v132
	v_add_f32_e32 v130, 1.0, v130
	v_rcp_f32_e32 v154, v130
	v_mov_b32_e32 v130, v148
	v_pk_mul_f32 v[130:131], v[158:159], v[130:131]
	v_mov_b32_e32 v151, v157
	v_add_f32_e32 v131, v144, v131
	v_add_f32_e32 v132, v130, v131
	v_pk_mul_f32 v[130:131], v[166:167], v[152:153]
	s_nop 0
	v_add_f32_e32 v131, v131, v132
	v_add_f32_e32 v148, v130, v131
	v_mul_f32_e32 v130, 0xbfb8aa3b, v148
	v_mov_b32_e32 v132, v149
	v_exp_f32_e32 v152, v130
	v_pk_mul_f32 v[130:131], v[140:141], v[132:133]
	v_add_f32_e32 v133, 1.0, v152
	v_add_f32_e32 v131, v145, v131
	v_add_f32_e32 v132, v130, v131
	v_pk_mul_f32 v[130:131], v[136:137], v[150:151]
	v_rcp_f32_e32 v133, v133
	v_add_f32_e32 v131, v131, v132
	v_add_f32_e32 v130, v130, v131
	v_mul_f32_e32 v131, 0xbfb8aa3b, v130
	v_exp_f32_e32 v131, v131
	v_mul_f32_e32 v132, v147, v154
	v_mul_f32_e32 v133, v148, v133
	v_cndmask_b32_e64 v132, v132, v147, s[4:5]
	v_add_f32_e32 v131, 1.0, v131
	v_rcp_f32_e32 v131, v131
	v_cndmask_b32_e64 v133, v133, v148, s[4:5]
	v_mov_b32_e32 v152, v76
	v_mov_b32_e32 v150, v77
	v_mul_f32_e32 v131, v130, v131
	v_cndmask_b32_e64 v131, v131, v130, s[4:5]
	v_cvt_pk_bf16_f32 v130, v146, v132
	v_cvt_pk_bf16_f32 v131, v133, v131
	v_mov_b32_e32 v112, v130
	v_mov_b32_e32 v113, v131
	flat_store_dwordx4 v[226:227], v[110:113]
	s_cbranch_vccnz .LBB0_637
	v_add_u32_e32 v131, 0xffffe030, v202
	v_ashrrev_i32_e32 v131, 2, v131
	v_lshl_add_u32 v131, v131, 1, v131
	v_mad_i64_i32 v[132:133], s[2:3], v131, s47, 0
	v_lshl_add_u64 v[132:133], v[132:133], 2, v[208:209]
	v_lshl_add_u64 v[146:147], v[132:133], 0, s[24:25]
	s_lshl_b32 s2, s27, 2
	s_mov_b32 s3, s25
	global_load_dwordx4 v[154:157], v[132:133], off offset:16
	s_nop 0
	global_load_dwordx4 v[146:149], v[146:147], off offset:16
	v_lshl_add_u64 v[132:133], v[132:133], 0, s[2:3]
	global_load_dwordx4 v[150:153], v[132:133], off offset:16
	v_mov_b32_dpp v160, v74 row_ror:1 row_mask:0xf bank_mask:0xf
	v_mov_b32_dpp v161, v74 row_ror:2 row_mask:0xf bank_mask:0xf
	v_mov_b32_dpp v130, v74 row_ror:3 row_mask:0xf bank_mask:0xf
	v_cmp_lt_i32_e32 vcc, 1, v205
	s_and_saveexec_b64 s[2:3], vcc
	s_xor_b64 s[2:3], exec, s[2:3]
	s_cbranch_execz .LBB0_600
	v_cmp_gt_i32_e32 vcc, 3, v205
	s_and_saveexec_b64 s[80:81], vcc
	s_cbranch_execz .LBB0_599
	s_waitcnt vmcnt(0)
	v_mov_b32_e32 v130, v150

; __device__ __forceinline__ float dpp_ror1(float v) { return __builtin_bit_cast(float, __builtin_amdgcn_update_dpp(0, __builtin_bit_cast(int, v), 0x121, 0xf, 0xf, false)); }
; __device__ __forceinline__ float dpp_ror2(float v) { return __builtin_bit_cast(float, __builtin_amdgcn_update_dpp(0, __builtin_bit_cast(int, v), 0x122, 0xf, 0xf, false)); }
; __device__ __forceinline__ float dpp_ror3(float v) { return __builtin_bit_cast(float, __builtin_amdgcn_update_dpp(0, __builtin_bit_cast(int, v), 0x123, 0xf, 0xf, false)); }
;     __device__ __forceinline__ void operator()(f32x4 (&acc)[2][2][4][2], const pg8::Unit& u, int wr, int wc, int fr, int fq) const {
;     ...
;                             for (int j = 0; j < 4; ++j) { const float r1 = dpp_ror1(g[j]), r2 = dpp_ror2(g[j]), r3 = dpp_ror3(g[j]);
;                                 p1[j] = t >= 1 ? r1 : b2[j]; p2[j] = t >= 2 ? r2 : (t == 1 ? b2[j] : b1[j]); p3[j] = t >= 3 ? r3 : (t == 2 ? b2[j] : (t == 1 ? b1[j] : b0[j])); } }
.LBB0_606:
	s_or_b64 exec, exec, s[2:3]
	v_mov_b32_dpp v168, v75 row_ror:1 row_mask:0xf bank_mask:0xf
	v_mov_b32_dpp v169, v75 row_ror:2 row_mask:0xf bank_mask:0xf
	v_mov_b32_dpp v131, v75 row_ror:3 row_mask:0xf bank_mask:0xf
	v_cmp_lt_i32_e32 vcc, 1, v205
	s_and_saveexec_b64 s[2:3], vcc
	s_xor_b64 s[2:3], exec, s[2:3]
	s_cbranch_execz .LBB0_610
	v_cmp_gt_i32_e32 vcc, 3, v205
	s_and_saveexec_b64 s[80:81], vcc
	s_cbranch_execz .LBB0_609
	s_waitcnt vmcnt(0)
	v_mov_b32_e32 v131, v151

; __device__ __forceinline__ float dpp_ror1(float v) { return __builtin_bit_cast(float, __builtin_amdgcn_update_dpp(0, __builtin_bit_cast(int, v), 0x121, 0xf, 0xf, false)); }
; __device__ __forceinline__ float dpp_ror2(float v) { return __builtin_bit_cast(float, __builtin_amdgcn_update_dpp(0, __builtin_bit_cast(int, v), 0x122, 0xf, 0xf, false)); }
; __device__ __forceinline__ float dpp_ror3(float v) { return __builtin_bit_cast(float, __builtin_amdgcn_update_dpp(0, __builtin_bit_cast(int, v), 0x123, 0xf, 0xf, false)); }
;     __device__ __forceinline__ void operator()(f32x4 (&acc)[2][2][4][2], const pg8::Unit& u, int wr, int wc, int fr, int fq) const {
;     ...
;                             for (int j = 0; j < 4; ++j) { const float r1 = dpp_ror1(g[j]), r2 = dpp_ror2(g[j]), r3 = dpp_ror3(g[j]);
;                                 p1[j] = t >= 1 ? r1 : b2[j]; p2[j] = t >= 2 ? r2 : (t == 1 ? b2[j] : b1[j]); p3[j] = t >= 3 ? r3 : (t == 2 ? b2[j] : (t == 1 ? b1[j] : b0[j])); } }
.LBB0_616:
	s_or_b64 exec, exec, s[2:3]
	v_mov_b32_dpp v170, v76 row_ror:1 row_mask:0xf bank_mask:0xf
	v_mov_b32_dpp v171, v76 row_ror:2 row_mask:0xf bank_mask:0xf
	v_mov_b32_dpp v132, v76 row_ror:3 row_mask:0xf bank_mask:0xf
	v_cmp_lt_i32_e32 vcc, 1, v205
	s_and_saveexec_b64 s[2:3], vcc
	s_xor_b64 s[2:3], exec, s[2:3]
	s_cbranch_execz .LBB0_620
	v_cmp_gt_i32_e32 vcc, 3, v205
	s_and_saveexec_b64 s[80:81], vcc
	s_cbranch_execz .LBB0_619
	s_waitcnt vmcnt(0)
	v_mov_b32_e32 v132, v152

; __device__ __forceinline__ float dpp_ror1(float v) { return __builtin_bit_cast(float, __builtin_amdgcn_update_dpp(0, __builtin_bit_cast(int, v), 0x121, 0xf, 0xf, false)); }
; __device__ __forceinline__ float dpp_ror2(float v) { return __builtin_bit_cast(float, __builtin_amdgcn_update_dpp(0, __builtin_bit_cast(int, v), 0x122, 0xf, 0xf, false)); }
; __device__ __forceinline__ float dpp_ror3(float v) { return __builtin_bit_cast(float, __builtin_amdgcn_update_dpp(0, __builtin_bit_cast(int, v), 0x123, 0xf, 0xf, false)); }
;     __device__ __forceinline__ void operator()(f32x4 (&acc)[2][2][4][2], const pg8::Unit& u, int wr, int wc, int fr, int fq) const {
;     ...
;                             for (int j = 0; j < 4; ++j) { const float r1 = dpp_ror1(g[j]), r2 = dpp_ror2(g[j]), r3 = dpp_ror3(g[j]);
;                                 p1[j] = t >= 1 ? r1 : b2[j]; p2[j] = t >= 2 ? r2 : (t == 1 ? b2[j] : b1[j]); p3[j] = t >= 3 ? r3 : (t == 2 ? b2[j] : (t == 1 ? b1[j] : b0[j])); } }
.LBB0_626:
	s_or_b64 exec, exec, s[2:3]
	v_mov_b32_dpp v173, v77 row_ror:1 row_mask:0xf bank_mask:0xf
	v_mov_b32_dpp v172, v77 row_ror:2 row_mask:0xf bank_mask:0xf
	v_mov_b32_dpp v133, v77 row_ror:3 row_mask:0xf bank_mask:0xf
	v_cmp_lt_i32_e32 vcc, 1, v205
	s_and_saveexec_b64 s[2:3], vcc
	s_xor_b64 s[2:3], exec, s[2:3]
	s_cbranch_execz .LBB0_630
	v_cmp_gt_i32_e32 vcc, 3, v205
	s_and_saveexec_b64 s[80:81], vcc
	s_cbranch_execz .LBB0_629
	s_waitcnt vmcnt(0)
	v_mov_b32_e32 v133, v153

; __device__ __forceinline__ float dpp_ror1(float v) { return __builtin_bit_cast(float, __builtin_amdgcn_update_dpp(0, __builtin_bit_cast(int, v), 0x121, 0xf, 0xf, false)); }
; __device__ __forceinline__ float dpp_ror2(float v) { return __builtin_bit_cast(float, __builtin_amdgcn_update_dpp(0, __builtin_bit_cast(int, v), 0x122, 0xf, 0xf, false)); }
; __device__ __forceinline__ float dpp_ror3(float v) { return __builtin_bit_cast(float, __builtin_amdgcn_update_dpp(0, __builtin_bit_cast(int, v), 0x123, 0xf, 0xf, false)); }
;     __device__ __forceinline__ void operator()(f32x4 (&acc)[2][2][4][2], const pg8::Unit& u, int wr, int wc, int fr, int fq) const {
;     ...
;                         if (prompt) { const f32x4 gp = (m == 0) ? hal[n] : acc[ai][bj][m > 0 ? m - 1 : 0][n];
; #pragma unroll
;                             for (int j = 0; j < 4; ++j) { p1[j] = dpp_ror1(fr == 15 ? gp[j] : g[j]); p2[j] = dpp_ror2(fr >= 14 ? gp[j] : g[j]); p3[j] = dpp_ror3(fr >= 13 ? gp[j] : g[j]); } }
.LBB0_637:
	s_and_b64 vcc, exec, s[2:3]
	s_cbranch_vccz .LBB0_639
	v_cndmask_b32_e64 v130, v74, v90, s[10:11]
	v_cndmask_b32_e64 v131, v74, v90, s[6:7]
	s_nop 0
	v_mov_b32_dpp v154, v130 row_ror:1 row_mask:0xf bank_mask:0xf
	v_cndmask_b32_e64 v130, v74, v90, s[8:9]
	s_nop 1
	v_mov_b32_dpp v146, v130 row_ror:2 row_mask:0xf bank_mask:0xf
	v_cndmask_b32_e64 v132, v75, v91, s[6:7]
	v_mov_b32_dpp v130, v131 row_ror:3 row_mask:0xf bank_mask:0xf
	v_cndmask_b32_e64 v131, v75, v91, s[10:11]
	v_cndmask_b32_e64 v133, v76, v92, s[6:7]
	s_nop 0
	v_mov_b32_dpp v155, v131 row_ror:1 row_mask:0xf bank_mask:0xf
	v_cndmask_b32_e64 v131, v75, v91, s[8:9]
	s_nop 1
	v_mov_b32_dpp v147, v131 row_ror:2 row_mask:0xf bank_mask:0xf
	v_cndmask_b32_e64 v151, v77, v93, s[6:7]
	s_nop 0
	v_mov_b32_dpp v131, v132 row_ror:3 row_mask:0xf bank_mask:0xf
	v_cndmask_b32_e64 v132, v76, v92, s[10:11]
	s_nop 1
	v_mov_b32_dpp v156, v132 row_ror:1 row_mask:0xf bank_mask:0xf
	v_cndmask_b32_e64 v132, v76, v92, s[8:9]
	s_nop 1
	v_mov_b32_dpp v148, v132 row_ror:2 row_mask:0xf bank_mask:0xf
	s_nop 1
	v_mov_b32_dpp v132, v133 row_ror:3 row_mask:0xf bank_mask:0xf
	v_cndmask_b32_e64 v133, v77, v93, s[10:11]
	s_nop 1
	v_mov_b32_dpp v157, v133 row_ror:1 row_mask:0xf bank_mask:0xf
	v_cndmask_b32_e64 v133, v77, v93, s[8:9]
	s_nop 1
	v_mov_b32_dpp v149, v133 row_ror:2 row_mask:0xf bank_mask:0xf
	s_nop 1
	v_mov_b32_dpp v133, v151 row_ror:3 row_mask:0xf bank_mask:0xf

; __device__ __forceinline__ float dpp_ror1(float v) { return __builtin_bit_cast(float, __builtin_amdgcn_update_dpp(0, __builtin_bit_cast(int, v), 0x121, 0xf, 0xf, false)); }
; __device__ __forceinline__ float dpp_ror2(float v) { return __builtin_bit_cast(float, __builtin_amdgcn_update_dpp(0, __builtin_bit_cast(int, v), 0x122, 0xf, 0xf, false)); }
; __device__ __forceinline__ float dpp_ror3(float v) { return __builtin_bit_cast(float, __builtin_amdgcn_update_dpp(0, __builtin_bit_cast(int, v), 0x123, 0xf, 0xf, false)); }
;     __device__ __forceinline__ void operator()(f32x4 (&acc)[2][2][4][2], const pg8::Unit& u, int wr, int wc, int fr, int fq) const {
;     ...
;                 for (int n = 0; n < 2; ++n) { const int ch = ch0 + bj * 128 + 4 * n;
;                     const f32x4 w0 = *(const f32x4*)(cw + ch), w1 = *(const f32x4*)(cw + CW + ch), w2 = *(const f32x4*)(cw + 2 * CW + ch), w3 = *(const f32x4*)(cw + 3 * CW + ch), bb = *(const f32x4*)(cb + ch);
; #pragma unroll
;                     for (int m = 0; m < 4; ++m) { const int row = row0 + ai * 128 + m * 16; const f32x4 g = acc[ai][bj][m][n]; f32x4 p1, p2, p3;
;                         if (prompt) { const f32x4 gp = (m == 0) ? hal[n] : acc[ai][bj][m > 0 ? m - 1 : 0][n];
; #pragma unroll
;                             for (int j = 0; j < 4; ++j) { p1[j] = dpp_ror1(fr == 15 ? gp[j] : g[j]); p2[j] = dpp_ror2(fr >= 14 ? gp[j] : g[j]); p3[j] = dpp_ror3(fr >= 13 ? gp[j] : g[j]); } }
;                         else { const int t = fr & 3; const float* sp = stp + (size_t)((row - MP) >> 2) * 3 * CW + ch;
;                             const f32x4 b0 = *(const f32x4*)sp, b1 = *(const f32x4*)(sp + CW), b2 = *(const f32x4*)(sp + 2 * CW);
; #pragma unroll
;                             for (int j = 0; j < 4; ++j) { const float r1 = dpp_ror1(g[j]), r2 = dpp_ror2(g[j]), r3 = dpp_ror3(g[j]);
;                                 p1[j] = t >= 1 ? r1 : b2[j]; p2[j] = t >= 2 ? r2 : (t == 1 ? b2[j] : b1[j]); p3[j] = t >= 3 ? r3 : (t == 2 ? b2[j] : (t == 1 ? b1[j] : b0[j])); } }
.LBB0_663:
	global_load_dwordx4 v[138:141], v[210:211], off offset:512
	global_load_dwordx4 v[154:157], v[212:213], off offset:512
	global_load_dwordx4 v[134:137], v[214:215], off offset:512
	global_load_dwordx4 v[150:153], v[216:217], off offset:512
	global_load_dwordx4 v[142:145], v[218:219], off offset:512
	v_readlane_b32 s84, v255, 23
	s_mov_b64 s[0:1], -1
	s_and_b64 vcc, exec, s[18:19]
	v_mov_b32_e32 v236, v118
	v_mov_b32_e32 v234, v119
	v_mov_b32_e32 v232, v120
	v_mov_b32_e32 v230, v121
	s_mov_b64 s[78:79], s[22:23]
	s_mov_b32 s23, s31
	s_mov_b32 s31, s37
	v_readlane_b32 s85, v255, 24
	s_cbranch_vccnz .LBB0_705
	v_add_u32_e32 v159, 0xffffe000, v202
	v_ashrrev_i32_e32 v159, 2, v159
	v_lshl_add_u32 v159, v159, 1, v159
	v_mad_i64_i32 v[160:161], s[0:1], v159, s47, 0
	v_lshl_add_u64 v[160:161], v[160:161], 2, v[208:209]
	v_lshl_add_u64 v[162:163], v[160:161], 0, s[24:25]
	s_lshl_b32 s0, s27, 2
	s_mov_b32 s1, s25
	global_load_dwordx4 v[170:173], v[160:161], off offset:512
	s_nop 0
	global_load_dwordx4 v[162:165], v[162:163], off offset:512
	v_lshl_add_u64 v[160:161], v[160:161], 0, s[0:1]
	global_load_dwordx4 v[166:169], v[160:161], off offset:512
	v_mov_b32_dpp v230, v118 row_ror:1 row_mask:0xf bank_mask:0xf
	v_mov_b32_dpp v231, v118 row_ror:2 row_mask:0xf bank_mask:0xf
	v_mov_b32_dpp v158, v118 row_ror:3 row_mask:0xf bank_mask:0xf
	v_cmp_lt_i32_e32 vcc, 1, v205
	s_and_saveexec_b64 s[0:1], vcc
	s_xor_b64 s[0:1], exec, s[0:1]
	s_cbranch_execz .LBB0_668
	v_cmp_gt_i32_e32 vcc, 3, v205
	s_and_saveexec_b64 s[2:3], vcc
	s_cbranch_execz .LBB0_667
	s_waitcnt vmcnt(0)
	v_mov_b32_e32 v158, v166

; __device__ __forceinline__ float dpp_ror1(float v) { return __builtin_bit_cast(float, __builtin_amdgcn_update_dpp(0, __builtin_bit_cast(int, v), 0x121, 0xf, 0xf, false)); }
; __device__ __forceinline__ float dpp_ror2(float v) { return __builtin_bit_cast(float, __builtin_amdgcn_update_dpp(0, __builtin_bit_cast(int, v), 0x122, 0xf, 0xf, false)); }
; __device__ __forceinline__ float dpp_ror3(float v) { return __builtin_bit_cast(float, __builtin_amdgcn_update_dpp(0, __builtin_bit_cast(int, v), 0x123, 0xf, 0xf, false)); }
;     __device__ __forceinline__ void operator()(f32x4 (&acc)[2][2][4][2], const pg8::Unit& u, int wr, int wc, int fr, int fq) const {
;     ...
;                         else { const int t = fr & 3; const float* sp = stp + (size_t)((row - MP) >> 2) * 3 * CW + ch;
;                             const f32x4 b0 = *(const f32x4*)sp, b1 = *(const f32x4*)(sp + CW), b2 = *(const f32x4*)(sp + 2 * CW);
; #pragma unroll
;                             for (int j = 0; j < 4; ++j) { const float r1 = dpp_ror1(g[j]), r2 = dpp_ror2(g[j]), r3 = dpp_ror3(g[j]);
;                                 p1[j] = t >= 1 ? r1 : b2[j]; p2[j] = t >= 2 ? r2 : (t == 1 ? b2[j] : b1[j]); p3[j] = t >= 3 ? r3 : (t == 2 ? b2[j] : (t == 1 ? b1[j] : b0[j])); } }
.LBB0_674:
	s_or_b64 exec, exec, s[0:1]
	v_mov_b32_dpp v232, v119 row_ror:1 row_mask:0xf bank_mask:0xf
	v_mov_b32_dpp v233, v119 row_ror:2 row_mask:0xf bank_mask:0xf
	v_mov_b32_dpp v159, v119 row_ror:3 row_mask:0xf bank_mask:0xf
	v_cmp_lt_i32_e32 vcc, 1, v205
	s_and_saveexec_b64 s[0:1], vcc
	s_xor_b64 s[0:1], exec, s[0:1]
	s_cbranch_execz .LBB0_678
	v_cmp_gt_i32_e32 vcc, 3, v205
	s_and_saveexec_b64 s[2:3], vcc
	s_cbranch_execz .LBB0_677
	s_waitcnt vmcnt(0)
	v_mov_b32_e32 v159, v167

; __device__ __forceinline__ float dpp_ror1(float v) { return __builtin_bit_cast(float, __builtin_amdgcn_update_dpp(0, __builtin_bit_cast(int, v), 0x121, 0xf, 0xf, false)); }
; __device__ __forceinline__ float dpp_ror2(float v) { return __builtin_bit_cast(float, __builtin_amdgcn_update_dpp(0, __builtin_bit_cast(int, v), 0x122, 0xf, 0xf, false)); }
; __device__ __forceinline__ float dpp_ror3(float v) { return __builtin_bit_cast(float, __builtin_amdgcn_update_dpp(0, __builtin_bit_cast(int, v), 0x123, 0xf, 0xf, false)); }
;     __device__ __forceinline__ void operator()(f32x4 (&acc)[2][2][4][2], const pg8::Unit& u, int wr, int wc, int fr, int fq) const {
;     ...
;                         else { const int t = fr & 3; const float* sp = stp + (size_t)((row - MP) >> 2) * 3 * CW + ch;
;                             const f32x4 b0 = *(const f32x4*)sp, b1 = *(const f32x4*)(sp + CW), b2 = *(const f32x4*)(sp + 2 * CW);
; #pragma unroll
;                             for (int j = 0; j < 4; ++j) { const float r1 = dpp_ror1(g[j]), r2 = dpp_ror2(g[j]), r3 = dpp_ror3(g[j]);
;                                 p1[j] = t >= 1 ? r1 : b2[j]; p2[j] = t >= 2 ? r2 : (t == 1 ? b2[j] : b1[j]); p3[j] = t >= 3 ? r3 : (t == 2 ? b2[j] : (t == 1 ? b1[j] : b0[j])); } }
.LBB0_684:
	s_or_b64 exec, exec, s[0:1]
	v_mov_b32_dpp v234, v120 row_ror:1 row_mask:0xf bank_mask:0xf
	v_mov_b32_dpp v235, v120 row_ror:2 row_mask:0xf bank_mask:0xf
	v_mov_b32_dpp v160, v120 row_ror:3 row_mask:0xf bank_mask:0xf
	v_cmp_lt_i32_e32 vcc, 1, v205
	s_and_saveexec_b64 s[0:1], vcc
	s_xor_b64 s[0:1], exec, s[0:1]
	s_cbranch_execz .LBB0_688
	v_cmp_gt_i32_e32 vcc, 3, v205
	s_and_saveexec_b64 s[2:3], vcc
	s_cbranch_execz .LBB0_687
	s_waitcnt vmcnt(0)
	v_mov_b32_e32 v160, v168

; __device__ __forceinline__ float dpp_ror1(float v) { return __builtin_bit_cast(float, __builtin_amdgcn_update_dpp(0, __builtin_bit_cast(int, v), 0x121, 0xf, 0xf, false)); }
; __device__ __forceinline__ float dpp_ror2(float v) { return __builtin_bit_cast(float, __builtin_amdgcn_update_dpp(0, __builtin_bit_cast(int, v), 0x122, 0xf, 0xf, false)); }
; __device__ __forceinline__ float dpp_ror3(float v) { return __builtin_bit_cast(float, __builtin_amdgcn_update_dpp(0, __builtin_bit_cast(int, v), 0x123, 0xf, 0xf, false)); }
;     __device__ __forceinline__ void operator()(f32x4 (&acc)[2][2][4][2], const pg8::Unit& u, int wr, int wc, int fr, int fq) const {
;     ...
;                         else { const int t = fr & 3; const float* sp = stp + (size_t)((row - MP) >> 2) * 3 * CW + ch;
;                             const f32x4 b0 = *(const f32x4*)sp, b1 = *(const f32x4*)(sp + CW), b2 = *(const f32x4*)(sp + 2 * CW);
; #pragma unroll
;                             for (int j = 0; j < 4; ++j) { const float r1 = dpp_ror1(g[j]), r2 = dpp_ror2(g[j]), r3 = dpp_ror3(g[j]);
;                                 p1[j] = t >= 1 ? r1 : b2[j]; p2[j] = t >= 2 ? r2 : (t == 1 ? b2[j] : b1[j]); p3[j] = t >= 3 ? r3 : (t == 2 ? b2[j] : (t == 1 ? b1[j] : b0[j])); } }
.LBB0_694:
	s_or_b64 exec, exec, s[0:1]
	v_mov_b32_dpp v237, v121 row_ror:1 row_mask:0xf bank_mask:0xf
	v_mov_b32_dpp v236, v121 row_ror:2 row_mask:0xf bank_mask:0xf
	v_mov_b32_dpp v161, v121 row_ror:3 row_mask:0xf bank_mask:0xf
	v_cmp_lt_i32_e32 vcc, 1, v205
	s_and_saveexec_b64 s[0:1], vcc
	s_xor_b64 s[0:1], exec, s[0:1]
	s_cbranch_execz .LBB0_698
	v_cmp_gt_i32_e32 vcc, 3, v205
	s_and_saveexec_b64 s[2:3], vcc
	s_cbranch_execz .LBB0_697
	s_waitcnt vmcnt(0)
	v_mov_b32_e32 v161, v169

; __device__ __forceinline__ unsigned cvt_pk_bf16(float lo, float hi) { unsigned r; asm("v_cvt_pk_bf16_f32 %0, %1, %2" : "=v"(r) : "v"(lo), "v"(hi)); return r; }
; __device__ __forceinline__ float siluf_(float x) { return x * sigmoidf_(x); }
; __device__ __forceinline__ float dpp_ror1(float v) { return __builtin_bit_cast(float, __builtin_amdgcn_update_dpp(0, __builtin_bit_cast(int, v), 0x121, 0xf, 0xf, false)); }
;     __device__ __forceinline__ void operator()(f32x4 (&acc)[2][2][4][2], const pg8::Unit& u, int wr, int wc, int fr, int fq) const {
;     ...
;                 for (int n = 0; n < 2; ++n) { const int ch = ch0 + bj * 128 + 4 * n;
;                     const f32x4 w0 = *(const f32x4*)(cw + ch), w1 = *(const f32x4*)(cw + CW + ch), w2 = *(const f32x4*)(cw + 2 * CW + ch), w3 = *(const f32x4*)(cw + 3 * CW + ch), bb = *(const f32x4*)(cb + ch);
; #pragma unroll
;                     for (int m = 0; m < 4; ++m) { const int row = row0 + ai * 128 + m * 16; const f32x4 g = acc[ai][bj][m][n]; f32x4 p1, p2, p3;
;                         if (prompt) { const f32x4 gp = (m == 0) ? hal[n] : acc[ai][bj][m > 0 ? m - 1 : 0][n];
; #pragma unroll
;                             for (int j = 0; j < 4; ++j) { p1[j] = dpp_ror1(fr == 15 ? gp[j] : g[j]); p2[j] = dpp_ror2(fr >= 14 ? gp[j] : g[j]); p3[j] = dpp_ror3(fr >= 13 ? gp[j] : g[j]); } }
;                         else { const int t = fr & 3; const float* sp = stp + (size_t)((row - MP) >> 2) * 3 * CW + ch;
;                             const f32x4 b0 = *(const f32x4*)sp, b1 = *(const f32x4*)(sp + CW), b2 = *(const f32x4*)(sp + 2 * CW);
; #pragma unroll
;                             for (int j = 0; j < 4; ++j) { const float r1 = dpp_ror1(g[j]), r2 = dpp_ror2(g[j]), r3 = dpp_ror3(g[j]);
;                                 p1[j] = t >= 1 ? r1 : b2[j]; p2[j] = t >= 2 ? r2 : (t == 1 ? b2[j] : b1[j]); p3[j] = t >= 3 ? r3 : (t == 2 ? b2[j] : (t == 1 ? b1[j] : b0[j])); } }
;                         float o[4];
; #pragma unroll
;                         for (int j = 0; j < 4; ++j) { const float y = bb[j] + w0[j] * p3[j] + w1[j] * p2[j] + w2[j] * p1[j] + w3[j] * g[j]; o[j] = is_rg ? y : siluf_(y); }
;                         u32x2 w; w.x = cvt_pk_bf16(o[0], o[1]); w.y = cvt_pk_bf16(o[2], o[3]);
;                         *(u32x2*)(dst + (size_t)row * ld + bj * 128 + 4 * n) = w; }
.LBB0_705:
	s_and_b64 vcc, exec, s[0:1]
	s_cbranch_vccz .LBB0_707
	s_waitcnt vmcnt(0) lgkmcnt(0)
	v_cndmask_b32_e64 v158, v118, v146, s[10:11]
	s_nop 1
	v_mov_b32_dpp v170, v158 row_ror:1 row_mask:0xf bank_mask:0xf
	v_cndmask_b32_e64 v158, v118, v146, s[8:9]
	v_cndmask_b32_e64 v146, v118, v146, s[6:7]
	s_nop 0
	v_mov_b32_dpp v162, v158 row_ror:2 row_mask:0xf bank_mask:0xf
	v_mov_b32_dpp v158, v146 row_ror:3 row_mask:0xf bank_mask:0xf
	v_cndmask_b32_e64 v146, v119, v147, s[10:11]
	s_nop 1
	v_mov_b32_dpp v171, v146 row_ror:1 row_mask:0xf bank_mask:0xf
	v_cndmask_b32_e64 v146, v119, v147, s[8:9]
	s_nop 1
	v_mov_b32_dpp v163, v146 row_ror:2 row_mask:0xf bank_mask:0xf
	v_cndmask_b32_e64 v146, v119, v147, s[6:7]
	s_nop 0
	s_nop 0
	v_mov_b32_dpp v159, v146 row_ror:3 row_mask:0xf bank_mask:0xf
	v_cndmask_b32_e64 v146, v120, v148, s[10:11]
	s_nop 1
	v_mov_b32_dpp v172, v146 row_ror:1 row_mask:0xf bank_mask:0xf
	v_cndmask_b32_e64 v146, v120, v148, s[8:9]
	s_nop 1
	v_mov_b32_dpp v164, v146 row_ror:2 row_mask:0xf bank_mask:0xf
	v_cndmask_b32_e64 v146, v120, v148, s[6:7]
	s_nop 1
	v_mov_b32_dpp v160, v146 row_ror:3 row_mask:0xf bank_mask:0xf
	v_cndmask_b32_e64 v146, v121, v149, s[10:11]
	s_nop 1
	v_mov_b32_dpp v173, v146 row_ror:1 row_mask:0xf bank_mask:0xf
	v_cndmask_b32_e64 v146, v121, v149, s[8:9]
	s_nop 1
	v_mov_b32_dpp v165, v146 row_ror:2 row_mask:0xf bank_mask:0xf
	v_cndmask_b32_e64 v146, v121, v149, s[6:7]
	s_nop 1
	v_mov_b32_dpp v161, v146 row_ror:3 row_mask:0xf bank_mask:0xf
.LBB0_707:
	s_waitcnt vmcnt(0)
	v_mov_b32_e32 v166, v154
	v_mov_b32_e32 v167, v138
	s_waitcnt lgkmcnt(0)
	v_mov_b32_e32 v146, v162
	v_mov_b32_e32 v147, v158
	v_pk_mul_f32 v[146:147], v[166:167], v[146:147]
	v_mov_b32_e32 v168, v150
	v_add_f32_e32 v138, v142, v147
	v_mov_b32_e32 v169, v134
	v_mov_b32_e32 v237, v170
	v_add_f32_e32 v138, v146, v138
	v_pk_mul_f32 v[146:147], v[168:169], v[236:237]
	v_mov_b32_e32 v158, v163
	v_add_f32_e32 v134, v147, v138
	v_add_f32_e32 v148, v146, v134
	v_mul_f32_e32 v134, 0xbfb8aa3b, v148
	v_exp_f32_e32 v134, v134
	v_mov_b32_e32 v138, v155
	v_pk_mul_f32 v[146:147], v[138:139], v[158:159]
	v_mov_b32_e32 v235, v171
	v_add_f32_e32 v134, 1.0, v134
	v_rcp_f32_e32 v149, v134
	v_add_f32_e32 v134, v143, v147
	v_add_f32_e32 v150, v146, v134
	v_mov_b32_e32 v134, v151
	v_pk_mul_f32 v[146:147], v[134:135], v[234:235]
	v_mov_b32_e32 v162, v156
	v_add_f32_e32 v147, v147, v150
	v_add_f32_e32 v150, v146, v147
	v_mul_f32_e32 v146, 0xbfb8aa3b, v150
	v_exp_f32_e32 v146, v146
	v_mul_f32_e32 v147, v148, v149
	v_cndmask_b32_e64 v148, v147, v148, s[4:5]
	v_mov_b32_e32 v163, v140
	v_add_f32_e32 v146, 1.0, v146
	v_rcp_f32_e32 v149, v146
	v_mov_b32_e32 v146, v164
	v_mov_b32_e32 v147, v160
	v_pk_mul_f32 v[146:147], v[162:163], v[146:147]
	v_mov_b32_e32 v170, v152
	v_add_f32_e32 v140, v144, v147
	v_mov_b32_e32 v171, v136
	v_mov_b32_e32 v233, v172
	v_add_f32_e32 v140, v146, v140
	v_pk_mul_f32 v[146:147], v[170:171], v[232:233]
	v_mov_b32_e32 v160, v165
	v_add_f32_e32 v136, v147, v140
	v_add_f32_e32 v151, v146, v136
	v_mov_b32_e32 v140, v157
	v_mul_f32_e32 v136, 0xbfb8aa3b, v151
	v_pk_mul_f32 v[146:147], v[140:141], v[160:161]
	v_exp_f32_e32 v152, v136
	v_add_f32_e32 v136, v145, v147
	v_add_f32_e32 v154, v146, v136
	v_mov_b32_e32 v136, v153
	v_mov_b32_e32 v231, v173
	v_pk_mul_f32 v[146:147], v[136:137], v[230:231]
	v_add_f32_e32 v152, 1.0, v152
	v_add_f32_e32 v147, v147, v154
	v_add_f32_e32 v146, v146, v147
	v_mul_f32_e32 v147, 0xbfb8aa3b, v146
	v_exp_f32_e32 v147, v147
	v_rcp_f32_e32 v152, v152
	v_mul_f32_e32 v149, v150, v149
	v_cndmask_b32_e64 v149, v149, v150, s[4:5]
	v_add_f32_e32 v147, 1.0, v147
	v_rcp_f32_e32 v147, v147
	v_mul_f32_e32 v150, v151, v152
	v_cndmask_b32_e64 v150, v150, v151, s[4:5]
	s_mov_b64 s[0:1], -1
	v_mul_f32_e32 v147, v146, v147
	v_cndmask_b32_e64 v147, v147, v146, s[4:5]
	v_cvt_pk_bf16_f32 v146, v148, v149
	v_cvt_pk_bf16_f32 v147, v150, v147
	s_and_b64 vcc, exec, s[18:19]
	v_mov_b32_e32 v172, v102
	v_mov_b32_e32 v164, v103
	v_mov_b32_e32 v156, v104
	v_mov_b32_e32 v154, v105
	v_mov_b32_e32 v78, v146
	v_mov_b32_e32 v79, v147
	s_cbranch_vccnz .LBB0_749
	v_add_u32_e32 v147, 0xffffe010, v202
	v_ashrrev_i32_e32 v147, 2, v147
	v_lshl_add_u32 v147, v147, 1, v147
	v_mad_i64_i32 v[148:149], s[0:1], v147, s47, 0
	v_lshl_add_u64 v[148:149], v[148:149], 2, v[208:209]
	v_lshl_add_u64 v[150:151], v[148:149], 0, s[24:25]
	s_lshl_b32 s0, s27, 2
	s_mov_b32 s1, s25
	global_load_dwordx4 v[158:161], v[148:149], off offset:512
	s_nop 0
	global_load_dwordx4 v[150:153], v[150:151], off offset:512
	v_lshl_add_u64 v[148:149], v[148:149], 0, s[0:1]
	global_load_dwordx4 v[154:157], v[148:149], off offset:512
	v_mov_b32_dpp v164, v102 row_ror:1 row_mask:0xf bank_mask:0xf
	v_mov_b32_dpp v165, v102 row_ror:2 row_mask:0xf bank_mask:0xf
	v_mov_b32_dpp v146, v102 row_ror:3 row_mask:0xf bank_mask:0xf
	v_cmp_lt_i32_e32 vcc, 1, v205
	s_and_saveexec_b64 s[0:1], vcc
	s_xor_b64 s[0:1], exec, s[0:1]
	s_cbranch_execz .LBB0_712
	v_cmp_gt_i32_e32 vcc, 3, v205
	s_and_saveexec_b64 s[2:3], vcc
	s_cbranch_execz .LBB0_711
	s_waitcnt vmcnt(0)
	v_mov_b32_e32 v146, v154

; __device__ __forceinline__ float dpp_ror1(float v) { return __builtin_bit_cast(float, __builtin_amdgcn_update_dpp(0, __builtin_bit_cast(int, v), 0x121, 0xf, 0xf, false)); }
; __device__ __forceinline__ float dpp_ror2(float v) { return __builtin_bit_cast(float, __builtin_amdgcn_update_dpp(0, __builtin_bit_cast(int, v), 0x122, 0xf, 0xf, false)); }
; __device__ __forceinline__ float dpp_ror3(float v) { return __builtin_bit_cast(float, __builtin_amdgcn_update_dpp(0, __builtin_bit_cast(int, v), 0x123, 0xf, 0xf, false)); }
;     __device__ __forceinline__ void operator()(f32x4 (&acc)[2][2][4][2], const pg8::Unit& u, int wr, int wc, int fr, int fq) const {
;     ...
;                         else { const int t = fr & 3; const float* sp = stp + (size_t)((row - MP) >> 2) * 3 * CW + ch;
;                             const f32x4 b0 = *(const f32x4*)sp, b1 = *(const f32x4*)(sp + CW), b2 = *(const f32x4*)(sp + 2 * CW);
; #pragma unroll
;                             for (int j = 0; j < 4; ++j) { const float r1 = dpp_ror1(g[j]), r2 = dpp_ror2(g[j]), r3 = dpp_ror3(g[j]);
;                                 p1[j] = t >= 1 ? r1 : b2[j]; p2[j] = t >= 2 ? r2 : (t == 1 ? b2[j] : b1[j]); p3[j] = t >= 3 ? r3 : (t == 2 ? b2[j] : (t == 1 ? b1[j] : b0[j])); } }
.LBB0_718:
	s_or_b64 exec, exec, s[0:1]
	v_mov_b32_dpp v172, v103 row_ror:1 row_mask:0xf bank_mask:0xf
	v_mov_b32_dpp v173, v103 row_ror:2 row_mask:0xf bank_mask:0xf
	v_mov_b32_dpp v147, v103 row_ror:3 row_mask:0xf bank_mask:0xf
	v_cmp_lt_i32_e32 vcc, 1, v205
	s_and_saveexec_b64 s[0:1], vcc
	s_xor_b64 s[0:1], exec, s[0:1]
	s_cbranch_execz .LBB0_722
	v_cmp_gt_i32_e32 vcc, 3, v205
	s_and_saveexec_b64 s[2:3], vcc
	s_cbranch_execz .LBB0_721
	s_waitcnt vmcnt(0)
	v_mov_b32_e32 v147, v155

; __device__ __forceinline__ float dpp_ror1(float v) { return __builtin_bit_cast(float, __builtin_amdgcn_update_dpp(0, __builtin_bit_cast(int, v), 0x121, 0xf, 0xf, false)); }
; __device__ __forceinline__ float dpp_ror2(float v) { return __builtin_bit_cast(float, __builtin_amdgcn_update_dpp(0, __builtin_bit_cast(int, v), 0x122, 0xf, 0xf, false)); }
; __device__ __forceinline__ float dpp_ror3(float v) { return __builtin_bit_cast(float, __builtin_amdgcn_update_dpp(0, __builtin_bit_cast(int, v), 0x123, 0xf, 0xf, false)); }
;     __device__ __forceinline__ void operator()(f32x4 (&acc)[2][2][4][2], const pg8::Unit& u, int wr, int wc, int fr, int fq) const {
;     ...
;                         else { const int t = fr & 3; const float* sp = stp + (size_t)((row - MP) >> 2) * 3 * CW + ch;
;                             const f32x4 b0 = *(const f32x4*)sp, b1 = *(const f32x4*)(sp + CW), b2 = *(const f32x4*)(sp + 2 * CW);
; #pragma unroll
;                             for (int j = 0; j < 4; ++j) { const float r1 = dpp_ror1(g[j]), r2 = dpp_ror2(g[j]), r3 = dpp_ror3(g[j]);
;                                 p1[j] = t >= 1 ? r1 : b2[j]; p2[j] = t >= 2 ? r2 : (t == 1 ? b2[j] : b1[j]); p3[j] = t >= 3 ? r3 : (t == 2 ? b2[j] : (t == 1 ? b1[j] : b0[j])); } }
.LBB0_728:
	s_or_b64 exec, exec, s[0:1]
	v_mov_b32_dpp v230, v104 row_ror:1 row_mask:0xf bank_mask:0xf
	v_mov_b32_dpp v231, v104 row_ror:2 row_mask:0xf bank_mask:0xf
	v_mov_b32_dpp v148, v104 row_ror:3 row_mask:0xf bank_mask:0xf
	v_cmp_lt_i32_e32 vcc, 1, v205
	s_and_saveexec_b64 s[0:1], vcc
	s_xor_b64 s[0:1], exec, s[0:1]
	s_cbranch_execz .LBB0_732
	v_cmp_gt_i32_e32 vcc, 3, v205
	s_and_saveexec_b64 s[2:3], vcc
	s_cbranch_execz .LBB0_731
	s_waitcnt vmcnt(0)
	v_mov_b32_e32 v148, v156

; __device__ __forceinline__ float dpp_ror1(float v) { return __builtin_bit_cast(float, __builtin_amdgcn_update_dpp(0, __builtin_bit_cast(int, v), 0x121, 0xf, 0xf, false)); }
; __device__ __forceinline__ float dpp_ror2(float v) { return __builtin_bit_cast(float, __builtin_amdgcn_update_dpp(0, __builtin_bit_cast(int, v), 0x122, 0xf, 0xf, false)); }
; __device__ __forceinline__ float dpp_ror3(float v) { return __builtin_bit_cast(float, __builtin_amdgcn_update_dpp(0, __builtin_bit_cast(int, v), 0x123, 0xf, 0xf, false)); }
;     __device__ __forceinline__ void operator()(f32x4 (&acc)[2][2][4][2], const pg8::Unit& u, int wr, int wc, int fr, int fq) const {
;     ...
;                         else { const int t = fr & 3; const float* sp = stp + (size_t)((row - MP) >> 2) * 3 * CW + ch;
;                             const f32x4 b0 = *(const f32x4*)sp, b1 = *(const f32x4*)(sp + CW), b2 = *(const f32x4*)(sp + 2 * CW);
; #pragma unroll
;                             for (int j = 0; j < 4; ++j) { const float r1 = dpp_ror1(g[j]), r2 = dpp_ror2(g[j]), r3 = dpp_ror3(g[j]);
;                                 p1[j] = t >= 1 ? r1 : b2[j]; p2[j] = t >= 2 ? r2 : (t == 1 ? b2[j] : b1[j]); p3[j] = t >= 3 ? r3 : (t == 2 ? b2[j] : (t == 1 ? b1[j] : b0[j])); } }
.LBB0_738:
	s_or_b64 exec, exec, s[0:1]
	v_mov_b32_dpp v233, v105 row_ror:1 row_mask:0xf bank_mask:0xf
	v_mov_b32_dpp v232, v105 row_ror:2 row_mask:0xf bank_mask:0xf
	v_mov_b32_dpp v149, v105 row_ror:3 row_mask:0xf bank_mask:0xf
	v_cmp_lt_i32_e32 vcc, 1, v205
	s_and_saveexec_b64 s[0:1], vcc
	s_xor_b64 s[0:1], exec, s[0:1]
	s_cbranch_execz .LBB0_742
	v_cmp_gt_i32_e32 vcc, 3, v205
	s_and_saveexec_b64 s[2:3], vcc
	s_cbranch_execz .LBB0_741
	s_waitcnt vmcnt(0)
	v_mov_b32_e32 v149, v157

; __device__ __forceinline__ unsigned cvt_pk_bf16(float lo, float hi) { unsigned r; asm("v_cvt_pk_bf16_f32 %0, %1, %2" : "=v"(r) : "v"(lo), "v"(hi)); return r; }
; __device__ __forceinline__ float siluf_(float x) { return x * sigmoidf_(x); }
; __device__ __forceinline__ float dpp_ror1(float v) { return __builtin_bit_cast(float, __builtin_amdgcn_update_dpp(0, __builtin_bit_cast(int, v), 0x121, 0xf, 0xf, false)); }
;     __device__ __forceinline__ void operator()(f32x4 (&acc)[2][2][4][2], const pg8::Unit& u, int wr, int wc, int fr, int fq) const {
;     ...
;                 for (int n = 0; n < 2; ++n) { const int ch = ch0 + bj * 128 + 4 * n;
;                     const f32x4 w0 = *(const f32x4*)(cw + ch), w1 = *(const f32x4*)(cw + CW + ch), w2 = *(const f32x4*)(cw + 2 * CW + ch), w3 = *(const f32x4*)(cw + 3 * CW + ch), bb = *(const f32x4*)(cb + ch);
; #pragma unroll
;                     for (int m = 0; m < 4; ++m) { const int row = row0 + ai * 128 + m * 16; const f32x4 g = acc[ai][bj][m][n]; f32x4 p1, p2, p3;
;                         if (prompt) { const f32x4 gp = (m == 0) ? hal[n] : acc[ai][bj][m > 0 ? m - 1 : 0][n];
; #pragma unroll
;                             for (int j = 0; j < 4; ++j) { p1[j] = dpp_ror1(fr == 15 ? gp[j] : g[j]); p2[j] = dpp_ror2(fr >= 14 ? gp[j] : g[j]); p3[j] = dpp_ror3(fr >= 13 ? gp[j] : g[j]); } }
;                         else { const int t = fr & 3; const float* sp = stp + (size_t)((row - MP) >> 2) * 3 * CW + ch;
;                             const f32x4 b0 = *(const f32x4*)sp, b1 = *(const f32x4*)(sp + CW), b2 = *(const f32x4*)(sp + 2 * CW);
; #pragma unroll
;                             for (int j = 0; j < 4; ++j) { const float r1 = dpp_ror1(g[j]), r2 = dpp_ror2(g[j]), r3 = dpp_ror3(g[j]);
;                                 p1[j] = t >= 1 ? r1 : b2[j]; p2[j] = t >= 2 ? r2 : (t == 1 ? b2[j] : b1[j]); p3[j] = t >= 3 ? r3 : (t == 2 ? b2[j] : (t == 1 ? b1[j] : b0[j])); } }
;                         float o[4];
; #pragma unroll
;                         for (int j = 0; j < 4; ++j) { const float y = bb[j] + w0[j] * p3[j] + w1[j] * p2[j] + w2[j] * p1[j] + w3[j] * g[j]; o[j] = is_rg ? y : siluf_(y); }
;                         u32x2 w; w.x = cvt_pk_bf16(o[0], o[1]); w.y = cvt_pk_bf16(o[2], o[3]);
;                         *(u32x2*)(dst + (size_t)row * ld + bj * 128 + 4 * n) = w; }
.LBB0_749:
	s_and_b64 vcc, exec, s[0:1]
	s_cbranch_vccz .LBB0_751
	v_cndmask_b32_e64 v146, v102, v118, s[10:11]
	v_cndmask_b32_e64 v147, v102, v118, s[6:7]
	s_nop 0
	v_mov_b32_dpp v158, v146 row_ror:1 row_mask:0xf bank_mask:0xf
	v_cndmask_b32_e64 v146, v102, v118, s[8:9]
	s_nop 1
	v_mov_b32_dpp v150, v146 row_ror:2 row_mask:0xf bank_mask:0xf
	v_cndmask_b32_e64 v148, v103, v119, s[6:7]
	v_mov_b32_dpp v146, v147 row_ror:3 row_mask:0xf bank_mask:0xf
	v_cndmask_b32_e64 v147, v103, v119, s[10:11]
	v_cndmask_b32_e64 v149, v104, v120, s[6:7]
	s_nop 0
	v_mov_b32_dpp v159, v147 row_ror:1 row_mask:0xf bank_mask:0xf
	v_cndmask_b32_e64 v147, v103, v119, s[8:9]
	s_nop 1
	v_mov_b32_dpp v151, v147 row_ror:2 row_mask:0xf bank_mask:0xf
	v_cndmask_b32_e64 v155, v105, v121, s[6:7]
	s_nop 0
	v_mov_b32_dpp v147, v148 row_ror:3 row_mask:0xf bank_mask:0xf
	v_cndmask_b32_e64 v148, v104, v120, s[10:11]
	s_nop 1
	v_mov_b32_dpp v160, v148 row_ror:1 row_mask:0xf bank_mask:0xf
	v_cndmask_b32_e64 v148, v104, v120, s[8:9]
	s_nop 1
	v_mov_b32_dpp v152, v148 row_ror:2 row_mask:0xf bank_mask:0xf
	s_nop 1
	v_mov_b32_dpp v148, v149 row_ror:3 row_mask:0xf bank_mask:0xf
	v_cndmask_b32_e64 v149, v105, v121, s[10:11]
	s_nop 1
	v_mov_b32_dpp v161, v149 row_ror:1 row_mask:0xf bank_mask:0xf
	v_cndmask_b32_e64 v149, v105, v121, s[8:9]
	s_nop 1
	v_mov_b32_dpp v153, v149 row_ror:2 row_mask:0xf bank_mask:0xf
	s_nop 1
	v_mov_b32_dpp v149, v155 row_ror:3 row_mask:0xf bank_mask:0xf
.LBB0_751:
	v_mov_b32_e32 v230, v150
	v_mov_b32_e32 v231, v146
	v_pk_mul_f32 v[230:231], v[166:167], v[230:231]
	v_mov_b32_e32 v173, v158
	v_add_f32_e32 v146, v142, v231
	v_add_f32_e32 v146, v230, v146
	v_pk_mul_f32 v[172:173], v[168:169], v[172:173]
	v_mov_b32_e32 v165, v159
	v_add_f32_e32 v146, v173, v146
	v_add_f32_e32 v150, v172, v146
	v_mul_f32_e32 v146, 0xbfb8aa3b, v150
	v_exp_f32_e32 v146, v146
	v_mov_b32_e32 v157, v160
	s_mov_b64 s[0:1], -1
	s_and_b64 vcc, exec, s[18:19]
	v_add_f32_e32 v146, 1.0, v146
	v_rcp_f32_e32 v155, v146
	v_mov_b32_e32 v146, v151
	v_pk_mul_f32 v[146:147], v[138:139], v[146:147]
	v_mov_b32_e32 v172, v86
	v_add_f32_e32 v147, v143, v147
	v_add_f32_e32 v151, v146, v147
	v_pk_mul_f32 v[146:147], v[134:135], v[164:165]
	v_mov_b32_e32 v164, v87
	v_add_f32_e32 v147, v147, v151
	v_add_f32_e32 v151, v146, v147
	v_mul_f32_e32 v146, 0xbfb8aa3b, v151
	v_exp_f32_e32 v146, v146
	v_mul_f32_e32 v147, v150, v155
	v_cndmask_b32_e64 v150, v147, v150, s[4:5]
	v_mov_b32_e32 v147, v148
	v_add_f32_e32 v146, 1.0, v146
	v_rcp_f32_e32 v158, v146
	v_mov_b32_e32 v146, v152
	v_pk_mul_f32 v[146:147], v[162:163], v[146:147]
	v_mov_b32_e32 v155, v161
	v_add_f32_e32 v147, v144, v147
	v_add_f32_e32 v148, v146, v147
	v_pk_mul_f32 v[146:147], v[170:171], v[156:157]
	s_nop 0
	v_add_f32_e32 v147, v147, v148
	v_add_f32_e32 v152, v146, v147
	v_mul_f32_e32 v146, 0xbfb8aa3b, v152
	v_mov_b32_e32 v148, v153
	v_exp_f32_e32 v156, v146
	v_pk_mul_f32 v[146:147], v[140:141], v[148:149]
	v_add_f32_e32 v149, 1.0, v156
	v_add_f32_e32 v147, v145, v147
	v_add_f32_e32 v148, v146, v147
	v_pk_mul_f32 v[146:147], v[136:137], v[154:155]
	v_rcp_f32_e32 v149, v149
	v_add_f32_e32 v147, v147, v148
	v_add_f32_e32 v146, v146, v147
	v_mul_f32_e32 v147, 0xbfb8aa3b, v146
	v_exp_f32_e32 v147, v147
	v_mul_f32_e32 v148, v151, v158
	v_mul_f32_e32 v149, v152, v149
	v_cndmask_b32_e64 v148, v148, v151, s[4:5]
	v_add_f32_e32 v147, 1.0, v147
	v_rcp_f32_e32 v147, v147
	v_cndmask_b32_e64 v149, v149, v152, s[4:5]
	v_mov_b32_e32 v156, v88
	v_mov_b32_e32 v154, v89
	v_mul_f32_e32 v147, v146, v147
	v_cndmask_b32_e64 v147, v147, v146, s[4:5]
	v_cvt_pk_bf16_f32 v146, v150, v148
	v_cvt_pk_bf16_f32 v147, v149, v147
	v_mov_b32_e32 v118, v146
	v_mov_b32_e32 v119, v147
	s_cbranch_vccnz .LBB0_793
	v_add_u32_e32 v147, 0xffffe020, v202
	v_ashrrev_i32_e32 v147, 2, v147
	v_lshl_add_u32 v147, v147, 1, v147
	v_mad_i64_i32 v[148:149], s[0:1], v147, s47, 0
	v_lshl_add_u64 v[148:149], v[148:149], 2, v[208:209]
	v_lshl_add_u64 v[150:151], v[148:149], 0, s[24:25]
	s_lshl_b32 s0, s27, 2
	s_mov_b32 s1, s25
	global_load_dwordx4 v[158:161], v[148:149], off offset:512
	s_nop 0
	global_load_dwordx4 v[150:153], v[150:151], off offset:512
	v_lshl_add_u64 v[148:149], v[148:149], 0, s[0:1]
	global_load_dwordx4 v[154:157], v[148:149], off offset:512
	v_mov_b32_dpp v164, v86 row_ror:1 row_mask:0xf bank_mask:0xf
	v_mov_b32_dpp v165, v86 row_ror:2 row_mask:0xf bank_mask:0xf
	v_mov_b32_dpp v146, v86 row_ror:3 row_mask:0xf bank_mask:0xf
	v_cmp_lt_i32_e32 vcc, 1, v205
	s_and_saveexec_b64 s[0:1], vcc
	s_xor_b64 s[0:1], exec, s[0:1]
	s_cbranch_execz .LBB0_756
	v_cmp_gt_i32_e32 vcc, 3, v205
	s_and_saveexec_b64 s[2:3], vcc
	s_cbranch_execz .LBB0_755
	s_waitcnt vmcnt(0)
	v_mov_b32_e32 v146, v154

; __device__ __forceinline__ float dpp_ror1(float v) { return __builtin_bit_cast(float, __builtin_amdgcn_update_dpp(0, __builtin_bit_cast(int, v), 0x121, 0xf, 0xf, false)); }
; __device__ __forceinline__ float dpp_ror2(float v) { return __builtin_bit_cast(float, __builtin_amdgcn_update_dpp(0, __builtin_bit_cast(int, v), 0x122, 0xf, 0xf, false)); }
; __device__ __forceinline__ float dpp_ror3(float v) { return __builtin_bit_cast(float, __builtin_amdgcn_update_dpp(0, __builtin_bit_cast(int, v), 0x123, 0xf, 0xf, false)); }
;     __device__ __forceinline__ void operator()(f32x4 (&acc)[2][2][4][2], const pg8::Unit& u, int wr, int wc, int fr, int fq) const {
;     ...
;                         else { const int t = fr & 3; const float* sp = stp + (size_t)((row - MP) >> 2) * 3 * CW + ch;
;                             const f32x4 b0 = *(const f32x4*)sp, b1 = *(const f32x4*)(sp + CW), b2 = *(const f32x4*)(sp + 2 * CW);
; #pragma unroll
;                             for (int j = 0; j < 4; ++j) { const float r1 = dpp_ror1(g[j]), r2 = dpp_ror2(g[j]), r3 = dpp_ror3(g[j]);
;                                 p1[j] = t >= 1 ? r1 : b2[j]; p2[j] = t >= 2 ? r2 : (t == 1 ? b2[j] : b1[j]); p3[j] = t >= 3 ? r3 : (t == 2 ? b2[j] : (t == 1 ? b1[j] : b0[j])); } }
.LBB0_762:
	s_or_b64 exec, exec, s[0:1]
	v_mov_b32_dpp v172, v87 row_ror:1 row_mask:0xf bank_mask:0xf
	v_mov_b32_dpp v173, v87 row_ror:2 row_mask:0xf bank_mask:0xf
	v_mov_b32_dpp v147, v87 row_ror:3 row_mask:0xf bank_mask:0xf
	v_cmp_lt_i32_e32 vcc, 1, v205
	s_and_saveexec_b64 s[0:1], vcc
	s_xor_b64 s[0:1], exec, s[0:1]
	s_cbranch_execz .LBB0_766
	v_cmp_gt_i32_e32 vcc, 3, v205
	s_and_saveexec_b64 s[2:3], vcc
	s_cbranch_execz .LBB0_765
	s_waitcnt vmcnt(0)
	v_mov_b32_e32 v147, v155

; __device__ __forceinline__ float dpp_ror1(float v) { return __builtin_bit_cast(float, __builtin_amdgcn_update_dpp(0, __builtin_bit_cast(int, v), 0x121, 0xf, 0xf, false)); }
; __device__ __forceinline__ float dpp_ror2(float v) { return __builtin_bit_cast(float, __builtin_amdgcn_update_dpp(0, __builtin_bit_cast(int, v), 0x122, 0xf, 0xf, false)); }
; __device__ __forceinline__ float dpp_ror3(float v) { return __builtin_bit_cast(float, __builtin_amdgcn_update_dpp(0, __builtin_bit_cast(int, v), 0x123, 0xf, 0xf, false)); }
;     __device__ __forceinline__ void operator()(f32x4 (&acc)[2][2][4][2], const pg8::Unit& u, int wr, int wc, int fr, int fq) const {
;     ...
;                         else { const int t = fr & 3; const float* sp = stp + (size_t)((row - MP) >> 2) * 3 * CW + ch;
;                             const f32x4 b0 = *(const f32x4*)sp, b1 = *(const f32x4*)(sp + CW), b2 = *(const f32x4*)(sp + 2 * CW);
; #pragma unroll
;                             for (int j = 0; j < 4; ++j) { const float r1 = dpp_ror1(g[j]), r2 = dpp_ror2(g[j]), r3 = dpp_ror3(g[j]);
;                                 p1[j] = t >= 1 ? r1 : b2[j]; p2[j] = t >= 2 ? r2 : (t == 1 ? b2[j] : b1[j]); p3[j] = t >= 3 ? r3 : (t == 2 ? b2[j] : (t == 1 ? b1[j] : b0[j])); } }
.LBB0_772:
	s_or_b64 exec, exec, s[0:1]
	v_mov_b32_dpp v230, v88 row_ror:1 row_mask:0xf bank_mask:0xf
	v_mov_b32_dpp v231, v88 row_ror:2 row_mask:0xf bank_mask:0xf
	v_mov_b32_dpp v148, v88 row_ror:3 row_mask:0xf bank_mask:0xf
	v_cmp_lt_i32_e32 vcc, 1, v205
	s_and_saveexec_b64 s[0:1], vcc
	s_xor_b64 s[0:1], exec, s[0:1]
	s_cbranch_execz .LBB0_776
	v_cmp_gt_i32_e32 vcc, 3, v205
	s_and_saveexec_b64 s[2:3], vcc
	s_cbranch_execz .LBB0_775
	s_waitcnt vmcnt(0)
	v_mov_b32_e32 v148, v156

; __device__ __forceinline__ float dpp_ror1(float v) { return __builtin_bit_cast(float, __builtin_amdgcn_update_dpp(0, __builtin_bit_cast(int, v), 0x121, 0xf, 0xf, false)); }
; __device__ __forceinline__ float dpp_ror2(float v) { return __builtin_bit_cast(float, __builtin_amdgcn_update_dpp(0, __builtin_bit_cast(int, v), 0x122, 0xf, 0xf, false)); }
; __device__ __forceinline__ float dpp_ror3(float v) { return __builtin_bit_cast(float, __builtin_amdgcn_update_dpp(0, __builtin_bit_cast(int, v), 0x123, 0xf, 0xf, false)); }
;     __device__ __forceinline__ void operator()(f32x4 (&acc)[2][2][4][2], const pg8::Unit& u, int wr, int wc, int fr, int fq) const {
;     ...
;                         else { const int t = fr & 3; const float* sp = stp + (size_t)((row - MP) >> 2) * 3 * CW + ch;
;                             const f32x4 b0 = *(const f32x4*)sp, b1 = *(const f32x4*)(sp + CW), b2 = *(const f32x4*)(sp + 2 * CW);
; #pragma unroll
;                             for (int j = 0; j < 4; ++j) { const float r1 = dpp_ror1(g[j]), r2 = dpp_ror2(g[j]), r3 = dpp_ror3(g[j]);
;                                 p1[j] = t >= 1 ? r1 : b2[j]; p2[j] = t >= 2 ? r2 : (t == 1 ? b2[j] : b1[j]); p3[j] = t >= 3 ? r3 : (t == 2 ? b2[j] : (t == 1 ? b1[j] : b0[j])); } }
.LBB0_782:
	s_or_b64 exec, exec, s[0:1]
	v_mov_b32_dpp v233, v89 row_ror:1 row_mask:0xf bank_mask:0xf
	v_mov_b32_dpp v232, v89 row_ror:2 row_mask:0xf bank_mask:0xf
	v_mov_b32_dpp v149, v89 row_ror:3 row_mask:0xf bank_mask:0xf
	v_cmp_lt_i32_e32 vcc, 1, v205
	s_and_saveexec_b64 s[0:1], vcc
	s_xor_b64 s[0:1], exec, s[0:1]
	s_cbranch_execz .LBB0_786
	v_cmp_gt_i32_e32 vcc, 3, v205
	s_and_saveexec_b64 s[2:3], vcc
	s_cbranch_execz .LBB0_785
	s_waitcnt vmcnt(0)
	v_mov_b32_e32 v149, v157

; __device__ __forceinline__ unsigned cvt_pk_bf16(float lo, float hi) { unsigned r; asm("v_cvt_pk_bf16_f32 %0, %1, %2" : "=v"(r) : "v"(lo), "v"(hi)); return r; }
; __device__ __forceinline__ float siluf_(float x) { return x * sigmoidf_(x); }
; __device__ __forceinline__ float dpp_ror1(float v) { return __builtin_bit_cast(float, __builtin_amdgcn_update_dpp(0, __builtin_bit_cast(int, v), 0x121, 0xf, 0xf, false)); }
;     __device__ __forceinline__ void operator()(f32x4 (&acc)[2][2][4][2], const pg8::Unit& u, int wr, int wc, int fr, int fq) const {
;     ...
;                 for (int n = 0; n < 2; ++n) { const int ch = ch0 + bj * 128 + 4 * n;
;                     const f32x4 w0 = *(const f32x4*)(cw + ch), w1 = *(const f32x4*)(cw + CW + ch), w2 = *(const f32x4*)(cw + 2 * CW + ch), w3 = *(const f32x4*)(cw + 3 * CW + ch), bb = *(const f32x4*)(cb + ch);
; #pragma unroll
;                     for (int m = 0; m < 4; ++m) { const int row = row0 + ai * 128 + m * 16; const f32x4 g = acc[ai][bj][m][n]; f32x4 p1, p2, p3;
;                         if (prompt) { const f32x4 gp = (m == 0) ? hal[n] : acc[ai][bj][m > 0 ? m - 1 : 0][n];
; #pragma unroll
;                             for (int j = 0; j < 4; ++j) { p1[j] = dpp_ror1(fr == 15 ? gp[j] : g[j]); p2[j] = dpp_ror2(fr >= 14 ? gp[j] : g[j]); p3[j] = dpp_ror3(fr >= 13 ? gp[j] : g[j]); } }
;                         else { const int t = fr & 3; const float* sp = stp + (size_t)((row - MP) >> 2) * 3 * CW + ch;
;                             const f32x4 b0 = *(const f32x4*)sp, b1 = *(const f32x4*)(sp + CW), b2 = *(const f32x4*)(sp + 2 * CW);
; #pragma unroll
;                             for (int j = 0; j < 4; ++j) { const float r1 = dpp_ror1(g[j]), r2 = dpp_ror2(g[j]), r3 = dpp_ror3(g[j]);
;                                 p1[j] = t >= 1 ? r1 : b2[j]; p2[j] = t >= 2 ? r2 : (t == 1 ? b2[j] : b1[j]); p3[j] = t >= 3 ? r3 : (t == 2 ? b2[j] : (t == 1 ? b1[j] : b0[j])); } }
;                         float o[4];
; #pragma unroll
;                         for (int j = 0; j < 4; ++j) { const float y = bb[j] + w0[j] * p3[j] + w1[j] * p2[j] + w2[j] * p1[j] + w3[j] * g[j]; o[j] = is_rg ? y : siluf_(y); }
;                         u32x2 w; w.x = cvt_pk_bf16(o[0], o[1]); w.y = cvt_pk_bf16(o[2], o[3]);
;                         *(u32x2*)(dst + (size_t)row * ld + bj * 128 + 4 * n) = w; }
.LBB0_793:
	s_and_b64 vcc, exec, s[0:1]
	s_cbranch_vccz .LBB0_795
	v_cndmask_b32_e64 v146, v86, v102, s[10:11]
	v_cndmask_b32_e64 v147, v86, v102, s[6:7]
	s_nop 0
	v_mov_b32_dpp v158, v146 row_ror:1 row_mask:0xf bank_mask:0xf
	v_cndmask_b32_e64 v146, v86, v102, s[8:9]
	s_nop 1
	v_mov_b32_dpp v150, v146 row_ror:2 row_mask:0xf bank_mask:0xf
	v_cndmask_b32_e64 v148, v87, v103, s[6:7]
	v_mov_b32_dpp v146, v147 row_ror:3 row_mask:0xf bank_mask:0xf
	v_cndmask_b32_e64 v147, v87, v103, s[10:11]
	v_cndmask_b32_e64 v149, v88, v104, s[6:7]
	s_nop 0
	v_mov_b32_dpp v159, v147 row_ror:1 row_mask:0xf bank_mask:0xf
	v_cndmask_b32_e64 v147, v87, v103, s[8:9]
	s_nop 1
	v_mov_b32_dpp v151, v147 row_ror:2 row_mask:0xf bank_mask:0xf
	v_cndmask_b32_e64 v155, v89, v105, s[6:7]
	s_nop 0
	v_mov_b32_dpp v147, v148 row_ror:3 row_mask:0xf bank_mask:0xf
	v_cndmask_b32_e64 v148, v88, v104, s[10:11]
	s_nop 1
	v_mov_b32_dpp v160, v148 row_ror:1 row_mask:0xf bank_mask:0xf
	v_cndmask_b32_e64 v148, v88, v104, s[8:9]
	s_nop 1
	v_mov_b32_dpp v152, v148 row_ror:2 row_mask:0xf bank_mask:0xf
	s_nop 1
	v_mov_b32_dpp v148, v149 row_ror:3 row_mask:0xf bank_mask:0xf
	v_cndmask_b32_e64 v149, v89, v105, s[10:11]
	s_nop 1
	v_mov_b32_dpp v161, v149 row_ror:1 row_mask:0xf bank_mask:0xf
	v_cndmask_b32_e64 v149, v89, v105, s[8:9]
	s_nop 1
	v_mov_b32_dpp v153, v149 row_ror:2 row_mask:0xf bank_mask:0xf
	s_nop 1
	v_mov_b32_dpp v149, v155 row_ror:3 row_mask:0xf bank_mask:0xf
.LBB0_795:
	v_mov_b32_e32 v230, v150
	v_mov_b32_e32 v231, v146
	v_pk_mul_f32 v[230:231], v[166:167], v[230:231]
	v_mov_b32_e32 v173, v158
	v_add_f32_e32 v146, v142, v231
	v_add_f32_e32 v146, v230, v146
	v_pk_mul_f32 v[172:173], v[168:169], v[172:173]
	v_mov_b32_e32 v165, v159
	v_add_f32_e32 v146, v173, v146
	v_add_f32_e32 v150, v172, v146
	v_mul_f32_e32 v146, 0xbfb8aa3b, v150
	v_exp_f32_e32 v146, v146
	v_mov_b32_e32 v157, v160
	s_mov_b64 s[0:1], -1
	s_and_b64 vcc, exec, s[18:19]
	v_add_f32_e32 v146, 1.0, v146
	v_rcp_f32_e32 v155, v146
	v_mov_b32_e32 v146, v151
	v_pk_mul_f32 v[146:147], v[138:139], v[146:147]
	v_mov_b32_e32 v172, v70
	v_add_f32_e32 v147, v143, v147
	v_add_f32_e32 v151, v146, v147
	v_pk_mul_f32 v[146:147], v[134:135], v[164:165]
	v_mov_b32_e32 v164, v71
	v_add_f32_e32 v147, v147, v151
	v_add_f32_e32 v151, v146, v147
	v_mul_f32_e32 v146, 0xbfb8aa3b, v151
	v_exp_f32_e32 v146, v146
	v_mul_f32_e32 v147, v150, v155
	v_cndmask_b32_e64 v150, v147, v150, s[4:5]
	v_mov_b32_e32 v147, v148
	v_add_f32_e32 v146, 1.0, v146
	v_rcp_f32_e32 v158, v146
	v_mov_b32_e32 v146, v152
	v_pk_mul_f32 v[146:147], v[162:163], v[146:147]
	v_mov_b32_e32 v155, v161
	v_add_f32_e32 v147, v144, v147
	v_add_f32_e32 v148, v146, v147
	v_pk_mul_f32 v[146:147], v[170:171], v[156:157]
	s_nop 0
	v_add_f32_e32 v147, v147, v148
	v_add_f32_e32 v152, v146, v147
	v_mul_f32_e32 v146, 0xbfb8aa3b, v152
	v_mov_b32_e32 v148, v153
	v_exp_f32_e32 v156, v146
	v_pk_mul_f32 v[146:147], v[140:141], v[148:149]
	v_add_f32_e32 v149, 1.0, v156
	v_add_f32_e32 v147, v145, v147
	v_add_f32_e32 v148, v146, v147
	v_pk_mul_f32 v[146:147], v[136:137], v[154:155]
	v_rcp_f32_e32 v149, v149
	v_add_f32_e32 v147, v147, v148
	v_add_f32_e32 v146, v146, v147
	v_mul_f32_e32 v147, 0xbfb8aa3b, v146
	v_exp_f32_e32 v147, v147
	v_mul_f32_e32 v148, v151, v158
	v_mul_f32_e32 v149, v152, v149
	v_cndmask_b32_e64 v148, v148, v151, s[4:5]
	v_add_f32_e32 v147, 1.0, v147
	v_rcp_f32_e32 v147, v147
	v_cndmask_b32_e64 v149, v149, v152, s[4:5]
	v_mov_b32_e32 v156, v72
	v_mov_b32_e32 v154, v73
	v_mul_f32_e32 v147, v146, v147
	v_cndmask_b32_e64 v147, v147, v146, s[4:5]
	v_cvt_pk_bf16_f32 v146, v150, v148
	v_cvt_pk_bf16_f32 v147, v149, v147
	v_mov_b32_e32 v102, v146
	v_mov_b32_e32 v103, v147
	s_cbranch_vccnz .LBB0_837
	v_add_u32_e32 v147, 0xffffe030, v202
	v_ashrrev_i32_e32 v147, 2, v147
	v_lshl_add_u32 v147, v147, 1, v147
	v_mad_i64_i32 v[148:149], s[0:1], v147, s47, 0
	v_lshl_add_u64 v[148:149], v[148:149], 2, v[208:209]
	v_lshl_add_u64 v[150:151], v[148:149], 0, s[24:25]
	s_lshl_b32 s0, s27, 2
	s_mov_b32 s1, s25
	global_load_dwordx4 v[158:161], v[148:149], off offset:512
	s_nop 0
	global_load_dwordx4 v[150:153], v[150:151], off offset:512
	v_lshl_add_u64 v[148:149], v[148:149], 0, s[0:1]
	global_load_dwordx4 v[154:157], v[148:149], off offset:512
	v_mov_b32_dpp v164, v70 row_ror:1 row_mask:0xf bank_mask:0xf
	v_mov_b32_dpp v165, v70 row_ror:2 row_mask:0xf bank_mask:0xf
	v_mov_b32_dpp v146, v70 row_ror:3 row_mask:0xf bank_mask:0xf
	v_cmp_lt_i32_e32 vcc, 1, v205
	s_and_saveexec_b64 s[0:1], vcc
	s_xor_b64 s[0:1], exec, s[0:1]
	s_cbranch_execz .LBB0_800
	v_cmp_gt_i32_e32 vcc, 3, v205
	s_and_saveexec_b64 s[2:3], vcc
	s_cbranch_execz .LBB0_799
	s_waitcnt vmcnt(0)
	v_mov_b32_e32 v146, v154

; __device__ __forceinline__ float dpp_ror1(float v) { return __builtin_bit_cast(float, __builtin_amdgcn_update_dpp(0, __builtin_bit_cast(int, v), 0x121, 0xf, 0xf, false)); }
; __device__ __forceinline__ float dpp_ror2(float v) { return __builtin_bit_cast(float, __builtin_amdgcn_update_dpp(0, __builtin_bit_cast(int, v), 0x122, 0xf, 0xf, false)); }
; __device__ __forceinline__ float dpp_ror3(float v) { return __builtin_bit_cast(float, __builtin_amdgcn_update_dpp(0, __builtin_bit_cast(int, v), 0x123, 0xf, 0xf, false)); }
;     __device__ __forceinline__ void operator()(f32x4 (&acc)[2][2][4][2], const pg8::Unit& u, int wr, int wc, int fr, int fq) const {
;     ...
;                         else { const int t = fr & 3; const float* sp = stp + (size_t)((row - MP) >> 2) * 3 * CW + ch;
;                             const f32x4 b0 = *(const f32x4*)sp, b1 = *(const f32x4*)(sp + CW), b2 = *(const f32x4*)(sp + 2 * CW);
; #pragma unroll
;                             for (int j = 0; j < 4; ++j) { const float r1 = dpp_ror1(g[j]), r2 = dpp_ror2(g[j]), r3 = dpp_ror3(g[j]);
;                                 p1[j] = t >= 1 ? r1 : b2[j]; p2[j] = t >= 2 ? r2 : (t == 1 ? b2[j] : b1[j]); p3[j] = t >= 3 ? r3 : (t == 2 ? b2[j] : (t == 1 ? b1[j] : b0[j])); } }
.LBB0_806:
	s_or_b64 exec, exec, s[0:1]
	v_mov_b32_dpp v172, v71 row_ror:1 row_mask:0xf bank_mask:0xf
	v_mov_b32_dpp v173, v71 row_ror:2 row_mask:0xf bank_mask:0xf
	v_mov_b32_dpp v147, v71 row_ror:3 row_mask:0xf bank_mask:0xf
	v_cmp_lt_i32_e32 vcc, 1, v205
	s_and_saveexec_b64 s[0:1], vcc
	s_xor_b64 s[0:1], exec, s[0:1]
	s_cbranch_execz .LBB0_810
	v_cmp_gt_i32_e32 vcc, 3, v205
	s_and_saveexec_b64 s[2:3], vcc
	s_cbranch_execz .LBB0_809
	s_waitcnt vmcnt(0)
	v_mov_b32_e32 v147, v155

; __device__ __forceinline__ float dpp_ror1(float v) { return __builtin_bit_cast(float, __builtin_amdgcn_update_dpp(0, __builtin_bit_cast(int, v), 0x121, 0xf, 0xf, false)); }
; __device__ __forceinline__ float dpp_ror2(float v) { return __builtin_bit_cast(float, __builtin_amdgcn_update_dpp(0, __builtin_bit_cast(int, v), 0x122, 0xf, 0xf, false)); }
; __device__ __forceinline__ float dpp_ror3(float v) { return __builtin_bit_cast(float, __builtin_amdgcn_update_dpp(0, __builtin_bit_cast(int, v), 0x123, 0xf, 0xf, false)); }
;     __device__ __forceinline__ void operator()(f32x4 (&acc)[2][2][4][2], const pg8::Unit& u, int wr, int wc, int fr, int fq) const {
;     ...
;                         else { const int t = fr & 3; const float* sp = stp + (size_t)((row - MP) >> 2) * 3 * CW + ch;
;                             const f32x4 b0 = *(const f32x4*)sp, b1 = *(const f32x4*)(sp + CW), b2 = *(const f32x4*)(sp + 2 * CW);
; #pragma unroll
;                             for (int j = 0; j < 4; ++j) { const float r1 = dpp_ror1(g[j]), r2 = dpp_ror2(g[j]), r3 = dpp_ror3(g[j]);
;                                 p1[j] = t >= 1 ? r1 : b2[j]; p2[j] = t >= 2 ? r2 : (t == 1 ? b2[j] : b1[j]); p3[j] = t >= 3 ? r3 : (t == 2 ? b2[j] : (t == 1 ? b1[j] : b0[j])); } }
.LBB0_816:
	s_or_b64 exec, exec, s[0:1]
	v_mov_b32_dpp v230, v72 row_ror:1 row_mask:0xf bank_mask:0xf
	v_mov_b32_dpp v231, v72 row_ror:2 row_mask:0xf bank_mask:0xf
	v_mov_b32_dpp v148, v72 row_ror:3 row_mask:0xf bank_mask:0xf
	v_cmp_lt_i32_e32 vcc, 1, v205
	s_and_saveexec_b64 s[0:1], vcc
	s_xor_b64 s[0:1], exec, s[0:1]
	s_cbranch_execz .LBB0_820
	v_cmp_gt_i32_e32 vcc, 3, v205
	s_and_saveexec_b64 s[2:3], vcc
	s_cbranch_execz .LBB0_819
	s_waitcnt vmcnt(0)
	v_mov_b32_e32 v148, v156

; __device__ __forceinline__ float dpp_ror1(float v) { return __builtin_bit_cast(float, __builtin_amdgcn_update_dpp(0, __builtin_bit_cast(int, v), 0x121, 0xf, 0xf, false)); }
; __device__ __forceinline__ float dpp_ror2(float v) { return __builtin_bit_cast(float, __builtin_amdgcn_update_dpp(0, __builtin_bit_cast(int, v), 0x122, 0xf, 0xf, false)); }
; __device__ __forceinline__ float dpp_ror3(float v) { return __builtin_bit_cast(float, __builtin_amdgcn_update_dpp(0, __builtin_bit_cast(int, v), 0x123, 0xf, 0xf, false)); }
;     __device__ __forceinline__ void operator()(f32x4 (&acc)[2][2][4][2], const pg8::Unit& u, int wr, int wc, int fr, int fq) const {
;     ...
;                         else { const int t = fr & 3; const float* sp = stp + (size_t)((row - MP) >> 2) * 3 * CW + ch;
;                             const f32x4 b0 = *(const f32x4*)sp, b1 = *(const f32x4*)(sp + CW), b2 = *(const f32x4*)(sp + 2 * CW);
; #pragma unroll
;                             for (int j = 0; j < 4; ++j) { const float r1 = dpp_ror1(g[j]), r2 = dpp_ror2(g[j]), r3 = dpp_ror3(g[j]);
;                                 p1[j] = t >= 1 ? r1 : b2[j]; p2[j] = t >= 2 ? r2 : (t == 1 ? b2[j] : b1[j]); p3[j] = t >= 3 ? r3 : (t == 2 ? b2[j] : (t == 1 ? b1[j] : b0[j])); } }
.LBB0_826:
	s_or_b64 exec, exec, s[0:1]
	v_mov_b32_dpp v233, v73 row_ror:1 row_mask:0xf bank_mask:0xf
	v_mov_b32_dpp v232, v73 row_ror:2 row_mask:0xf bank_mask:0xf
	v_mov_b32_dpp v149, v73 row_ror:3 row_mask:0xf bank_mask:0xf
	v_cmp_lt_i32_e32 vcc, 1, v205
	s_and_saveexec_b64 s[0:1], vcc
	s_xor_b64 s[0:1], exec, s[0:1]
	s_cbranch_execz .LBB0_830
	v_cmp_gt_i32_e32 vcc, 3, v205
	s_and_saveexec_b64 s[2:3], vcc
	s_cbranch_execz .LBB0_829
	s_waitcnt vmcnt(0)
	v_mov_b32_e32 v149, v157

; __device__ __forceinline__ unsigned cvt_pk_bf16(float lo, float hi) { unsigned r; asm("v_cvt_pk_bf16_f32 %0, %1, %2" : "=v"(r) : "v"(lo), "v"(hi)); return r; }
; __device__ __forceinline__ float siluf_(float x) { return x * sigmoidf_(x); }
; __device__ __forceinline__ float dpp_ror1(float v) { return __builtin_bit_cast(float, __builtin_amdgcn_update_dpp(0, __builtin_bit_cast(int, v), 0x121, 0xf, 0xf, false)); }
;     __device__ __forceinline__ void operator()(f32x4 (&acc)[2][2][4][2], const pg8::Unit& u, int wr, int wc, int fr, int fq) const {
;     ...
;                 for (int n = 0; n < 2; ++n) { const int ch = ch0 + bj * 128 + 4 * n;
;                     const f32x4 w0 = *(const f32x4*)(cw + ch), w1 = *(const f32x4*)(cw + CW + ch), w2 = *(const f32x4*)(cw + 2 * CW + ch), w3 = *(const f32x4*)(cw + 3 * CW + ch), bb = *(const f32x4*)(cb + ch);
; #pragma unroll
;                     for (int m = 0; m < 4; ++m) { const int row = row0 + ai * 128 + m * 16; const f32x4 g = acc[ai][bj][m][n]; f32x4 p1, p2, p3;
;                         if (prompt) { const f32x4 gp = (m == 0) ? hal[n] : acc[ai][bj][m > 0 ? m - 1 : 0][n];
; #pragma unroll
;                             for (int j = 0; j < 4; ++j) { p1[j] = dpp_ror1(fr == 15 ? gp[j] : g[j]); p2[j] = dpp_ror2(fr >= 14 ? gp[j] : g[j]); p3[j] = dpp_ror3(fr >= 13 ? gp[j] : g[j]); } }
;                         else { const int t = fr & 3; const float* sp = stp + (size_t)((row - MP) >> 2) * 3 * CW + ch;
;                             const f32x4 b0 = *(const f32x4*)sp, b1 = *(const f32x4*)(sp + CW), b2 = *(const f32x4*)(sp + 2 * CW);
; #pragma unroll
;                             for (int j = 0; j < 4; ++j) { const float r1 = dpp_ror1(g[j]), r2 = dpp_ror2(g[j]), r3 = dpp_ror3(g[j]);
;                                 p1[j] = t >= 1 ? r1 : b2[j]; p2[j] = t >= 2 ? r2 : (t == 1 ? b2[j] : b1[j]); p3[j] = t >= 3 ? r3 : (t == 2 ? b2[j] : (t == 1 ? b1[j] : b0[j])); } }
;                         float o[4];
; #pragma unroll
;                         for (int j = 0; j < 4; ++j) { const float y = bb[j] + w0[j] * p3[j] + w1[j] * p2[j] + w2[j] * p1[j] + w3[j] * g[j]; o[j] = is_rg ? y : siluf_(y); }
;                         u32x2 w; w.x = cvt_pk_bf16(o[0], o[1]); w.y = cvt_pk_bf16(o[2], o[3]);
;                         *(u32x2*)(dst + (size_t)row * ld + bj * 128 + 4 * n) = w; }
.LBB0_837:
	s_and_b64 vcc, exec, s[0:1]
	s_cbranch_vccz .LBB0_839
	v_cndmask_b32_e64 v146, v70, v86, s[10:11]
	v_cndmask_b32_e64 v147, v70, v86, s[6:7]
	s_nop 0
	v_mov_b32_dpp v158, v146 row_ror:1 row_mask:0xf bank_mask:0xf
	v_cndmask_b32_e64 v146, v70, v86, s[8:9]
	s_nop 1
	v_mov_b32_dpp v150, v146 row_ror:2 row_mask:0xf bank_mask:0xf
	v_cndmask_b32_e64 v148, v71, v87, s[6:7]
	v_mov_b32_dpp v146, v147 row_ror:3 row_mask:0xf bank_mask:0xf
	v_cndmask_b32_e64 v147, v71, v87, s[10:11]
	v_cndmask_b32_e64 v149, v72, v88, s[6:7]
	s_nop 0
	v_mov_b32_dpp v159, v147 row_ror:1 row_mask:0xf bank_mask:0xf
	v_cndmask_b32_e64 v147, v71, v87, s[8:9]
	s_nop 1
	v_mov_b32_dpp v151, v147 row_ror:2 row_mask:0xf bank_mask:0xf
	v_cndmask_b32_e64 v155, v73, v89, s[6:7]
	s_nop 0
	v_mov_b32_dpp v147, v148 row_ror:3 row_mask:0xf bank_mask:0xf
	v_cndmask_b32_e64 v148, v72, v88, s[10:11]
	s_nop 1
	v_mov_b32_dpp v160, v148 row_ror:1 row_mask:0xf bank_mask:0xf
	v_cndmask_b32_e64 v148, v72, v88, s[8:9]
	s_nop 1
	v_mov_b32_dpp v152, v148 row_ror:2 row_mask:0xf bank_mask:0xf
	s_nop 1
	v_mov_b32_dpp v148, v149 row_ror:3 row_mask:0xf bank_mask:0xf
	v_cndmask_b32_e64 v149, v73, v89, s[10:11]
	s_nop 1
	v_mov_b32_dpp v161, v149 row_ror:1 row_mask:0xf bank_mask:0xf
	v_cndmask_b32_e64 v149, v73, v89, s[8:9]
	s_nop 1
	v_mov_b32_dpp v153, v149 row_ror:2 row_mask:0xf bank_mask:0xf
	s_nop 1
	v_mov_b32_dpp v149, v155 row_ror:3 row_mask:0xf bank_mask:0xf
.LBB0_839:
	v_mov_b32_e32 v230, v150
	v_mov_b32_e32 v231, v146
	v_pk_mul_f32 v[166:167], v[166:167], v[230:231]
	v_mov_b32_e32 v173, v158
	v_add_f32_e32 v142, v142, v167
	v_add_f32_e32 v142, v166, v142
	v_pk_mul_f32 v[166:167], v[168:169], v[172:173]
	v_mov_b32_e32 v165, v159
	v_add_f32_e32 v142, v167, v142
	v_add_f32_e32 v142, v166, v142
	v_mul_f32_e32 v146, 0xbfb8aa3b, v142
	v_exp_f32_e32 v146, v146
	v_pk_mul_f32 v[134:135], v[134:135], v[164:165]
	v_mov_b32_e32 v157, v160
	v_mov_b32_e32 v155, v161
	v_add_f32_e32 v146, 1.0, v146
	v_rcp_f32_e32 v150, v146
	v_mov_b32_e32 v146, v151
	v_pk_mul_f32 v[138:139], v[138:139], v[146:147]
	s_mov_b64 s[0:1], -1
	v_add_f32_e32 v139, v143, v139
	v_add_f32_e32 v138, v138, v139
	v_add_f32_e32 v135, v135, v138
	v_add_f32_e32 v138, v134, v135
	v_mul_f32_e32 v134, 0xbfb8aa3b, v138
	v_exp_f32_e32 v134, v134
	v_mul_f32_e32 v135, v142, v150
	v_cndmask_b32_e64 v139, v135, v142, s[4:5]
	v_mov_b32_e32 v135, v148
	v_add_f32_e32 v134, 1.0, v134
	v_rcp_f32_e32 v142, v134
	v_mov_b32_e32 v134, v152
	v_pk_mul_f32 v[134:135], v[162:163], v[134:135]
	v_mov_b32_e32 v148, v153
	v_add_f32_e32 v135, v144, v135
	v_add_f32_e32 v143, v134, v135
	v_pk_mul_f32 v[134:135], v[170:171], v[156:157]
	s_and_b64 vcc, exec, s[18:19]
	v_add_f32_e32 v135, v135, v143
	v_add_f32_e32 v143, v134, v135
	v_mul_f32_e32 v134, 0xbfb8aa3b, v143
	v_exp_f32_e32 v144, v134
	v_pk_mul_f32 v[134:135], v[140:141], v[148:149]
	v_mov_b32_e32 v232, v114
	v_add_f32_e32 v135, v145, v135
	v_add_f32_e32 v140, v134, v135
	v_pk_mul_f32 v[134:135], v[136:137], v[154:155]
	v_add_f32_e32 v137, 1.0, v144
	v_add_f32_e32 v135, v135, v140
	v_add_f32_e32 v134, v134, v135
	v_mul_f32_e32 v135, 0xbfb8aa3b, v134
	v_exp_f32_e32 v135, v135
	v_rcp_f32_e32 v137, v137
	v_mul_f32_e32 v136, v138, v142
	v_cndmask_b32_e64 v136, v136, v138, s[4:5]
	v_add_f32_e32 v135, 1.0, v135
	v_rcp_f32_e32 v135, v135
	v_mul_f32_e32 v137, v143, v137
	v_cndmask_b32_e64 v137, v137, v143, s[4:5]
	v_mov_b32_e32 v230, v115
	v_mul_f32_e32 v135, v134, v135
	v_cndmask_b32_e64 v135, v135, v134, s[4:5]
	v_cvt_pk_bf16_f32 v134, v139, v136
	v_cvt_pk_bf16_f32 v135, v137, v135
	v_mov_b32_e32 v86, v134
	v_mov_b32_e32 v87, v135
	global_load_dwordx4 v[138:141], v[210:211], off offset:528
	global_load_dwordx4 v[150:153], v[212:213], off offset:528
	global_load_dwordx4 v[134:137], v[214:215], off offset:528
	global_load_dwordx4 v[146:149], v[216:217], off offset:528
	global_load_dwordx4 v[142:145], v[218:219], off offset:528
	v_mov_b32_e32 v172, v116
	v_mov_b32_e32 v170, v117
	s_cbranch_vccnz .LBB0_881
	v_add_u32_e32 v155, 0xffffe000, v202
	v_ashrrev_i32_e32 v155, 2, v155
	v_lshl_add_u32 v155, v155, 1, v155
	v_mad_i64_i32 v[156:157], s[0:1], v155, s47, 0
	v_lshl_add_u64 v[156:157], v[156:157], 2, v[208:209]
	v_lshl_add_u64 v[158:159], v[156:157], 0, s[24:25]
	s_lshl_b32 s0, s27, 2
	s_mov_b32 s1, s25
	global_load_dwordx4 v[166:169], v[156:157], off offset:528
	s_nop 0
	global_load_dwordx4 v[158:161], v[158:159], off offset:528
	v_lshl_add_u64 v[156:157], v[156:157], 0, s[0:1]
	global_load_dwordx4 v[162:165], v[156:157], off offset:528
	v_mov_b32_dpp v170, v114 row_ror:1 row_mask:0xf bank_mask:0xf
	v_mov_b32_dpp v171, v114 row_ror:2 row_mask:0xf bank_mask:0xf
	v_mov_b32_dpp v154, v114 row_ror:3 row_mask:0xf bank_mask:0xf
	v_cmp_lt_i32_e32 vcc, 1, v205
	s_and_saveexec_b64 s[0:1], vcc
	s_xor_b64 s[0:1], exec, s[0:1]
	s_cbranch_execz .LBB0_844
	v_cmp_gt_i32_e32 vcc, 3, v205
	s_and_saveexec_b64 s[2:3], vcc
	s_cbranch_execz .LBB0_843
	s_waitcnt vmcnt(0)
	v_mov_b32_e32 v154, v162

; __device__ __forceinline__ float dpp_ror1(float v) { return __builtin_bit_cast(float, __builtin_amdgcn_update_dpp(0, __builtin_bit_cast(int, v), 0x121, 0xf, 0xf, false)); }
; __device__ __forceinline__ float dpp_ror2(float v) { return __builtin_bit_cast(float, __builtin_amdgcn_update_dpp(0, __builtin_bit_cast(int, v), 0x122, 0xf, 0xf, false)); }
; __device__ __forceinline__ float dpp_ror3(float v) { return __builtin_bit_cast(float, __builtin_amdgcn_update_dpp(0, __builtin_bit_cast(int, v), 0x123, 0xf, 0xf, false)); }
;     __device__ __forceinline__ void operator()(f32x4 (&acc)[2][2][4][2], const pg8::Unit& u, int wr, int wc, int fr, int fq) const {
;     ...
;                         else { const int t = fr & 3; const float* sp = stp + (size_t)((row - MP) >> 2) * 3 * CW + ch;
;                             const f32x4 b0 = *(const f32x4*)sp, b1 = *(const f32x4*)(sp + CW), b2 = *(const f32x4*)(sp + 2 * CW);
; #pragma unroll
;                             for (int j = 0; j < 4; ++j) { const float r1 = dpp_ror1(g[j]), r2 = dpp_ror2(g[j]), r3 = dpp_ror3(g[j]);
;                                 p1[j] = t >= 1 ? r1 : b2[j]; p2[j] = t >= 2 ? r2 : (t == 1 ? b2[j] : b1[j]); p3[j] = t >= 3 ? r3 : (t == 2 ? b2[j] : (t == 1 ? b1[j] : b0[j])); } }
.LBB0_850:
	s_or_b64 exec, exec, s[0:1]
	v_mov_b32_dpp v172, v115 row_ror:1 row_mask:0xf bank_mask:0xf
	v_mov_b32_dpp v173, v115 row_ror:2 row_mask:0xf bank_mask:0xf
	v_mov_b32_dpp v155, v115 row_ror:3 row_mask:0xf bank_mask:0xf
	v_cmp_lt_i32_e32 vcc, 1, v205
	s_and_saveexec_b64 s[0:1], vcc
	s_xor_b64 s[0:1], exec, s[0:1]
	s_cbranch_execz .LBB0_854
	v_cmp_gt_i32_e32 vcc, 3, v205
	s_and_saveexec_b64 s[2:3], vcc
	s_cbranch_execz .LBB0_853
	s_waitcnt vmcnt(0)
	v_mov_b32_e32 v155, v163

; __device__ __forceinline__ float dpp_ror1(float v) { return __builtin_bit_cast(float, __builtin_amdgcn_update_dpp(0, __builtin_bit_cast(int, v), 0x121, 0xf, 0xf, false)); }
; __device__ __forceinline__ float dpp_ror2(float v) { return __builtin_bit_cast(float, __builtin_amdgcn_update_dpp(0, __builtin_bit_cast(int, v), 0x122, 0xf, 0xf, false)); }
; __device__ __forceinline__ float dpp_ror3(float v) { return __builtin_bit_cast(float, __builtin_amdgcn_update_dpp(0, __builtin_bit_cast(int, v), 0x123, 0xf, 0xf, false)); }
;     __device__ __forceinline__ void operator()(f32x4 (&acc)[2][2][4][2], const pg8::Unit& u, int wr, int wc, int fr, int fq) const {
;     ...
;                         else { const int t = fr & 3; const float* sp = stp + (size_t)((row - MP) >> 2) * 3 * CW + ch;
;                             const f32x4 b0 = *(const f32x4*)sp, b1 = *(const f32x4*)(sp + CW), b2 = *(const f32x4*)(sp + 2 * CW);
; #pragma unroll
;                             for (int j = 0; j < 4; ++j) { const float r1 = dpp_ror1(g[j]), r2 = dpp_ror2(g[j]), r3 = dpp_ror3(g[j]);
;                                 p1[j] = t >= 1 ? r1 : b2[j]; p2[j] = t >= 2 ? r2 : (t == 1 ? b2[j] : b1[j]); p3[j] = t >= 3 ? r3 : (t == 2 ? b2[j] : (t == 1 ? b1[j] : b0[j])); } }
.LBB0_860:
	s_or_b64 exec, exec, s[0:1]
	v_mov_b32_dpp v230, v116 row_ror:1 row_mask:0xf bank_mask:0xf
	v_mov_b32_dpp v231, v116 row_ror:2 row_mask:0xf bank_mask:0xf
	v_mov_b32_dpp v156, v116 row_ror:3 row_mask:0xf bank_mask:0xf
	v_cmp_lt_i32_e32 vcc, 1, v205
	s_and_saveexec_b64 s[0:1], vcc
	s_xor_b64 s[0:1], exec, s[0:1]
	s_cbranch_execz .LBB0_864
	v_cmp_gt_i32_e32 vcc, 3, v205
	s_and_saveexec_b64 s[2:3], vcc
	s_cbranch_execz .LBB0_863
	s_waitcnt vmcnt(0)
	v_mov_b32_e32 v156, v164

; __device__ __forceinline__ float dpp_ror1(float v) { return __builtin_bit_cast(float, __builtin_amdgcn_update_dpp(0, __builtin_bit_cast(int, v), 0x121, 0xf, 0xf, false)); }
; __device__ __forceinline__ float dpp_ror2(float v) { return __builtin_bit_cast(float, __builtin_amdgcn_update_dpp(0, __builtin_bit_cast(int, v), 0x122, 0xf, 0xf, false)); }
; __device__ __forceinline__ float dpp_ror3(float v) { return __builtin_bit_cast(float, __builtin_amdgcn_update_dpp(0, __builtin_bit_cast(int, v), 0x123, 0xf, 0xf, false)); }
;     __device__ __forceinline__ void operator()(f32x4 (&acc)[2][2][4][2], const pg8::Unit& u, int wr, int wc, int fr, int fq) const {
;     ...
;                         else { const int t = fr & 3; const float* sp = stp + (size_t)((row - MP) >> 2) * 3 * CW + ch;
;                             const f32x4 b0 = *(const f32x4*)sp, b1 = *(const f32x4*)(sp + CW), b2 = *(const f32x4*)(sp + 2 * CW);
; #pragma unroll
;                             for (int j = 0; j < 4; ++j) { const float r1 = dpp_ror1(g[j]), r2 = dpp_ror2(g[j]), r3 = dpp_ror3(g[j]);
;                                 p1[j] = t >= 1 ? r1 : b2[j]; p2[j] = t >= 2 ? r2 : (t == 1 ? b2[j] : b1[j]); p3[j] = t >= 3 ? r3 : (t == 2 ? b2[j] : (t == 1 ? b1[j] : b0[j])); } }
.LBB0_870:
	s_or_b64 exec, exec, s[0:1]
	v_mov_b32_dpp v233, v117 row_ror:1 row_mask:0xf bank_mask:0xf
	v_mov_b32_dpp v232, v117 row_ror:2 row_mask:0xf bank_mask:0xf
	v_mov_b32_dpp v157, v117 row_ror:3 row_mask:0xf bank_mask:0xf
	v_cmp_lt_i32_e32 vcc, 1, v205
	s_and_saveexec_b64 s[0:1], vcc
	s_xor_b64 s[0:1], exec, s[0:1]
	s_cbranch_execz .LBB0_874
	v_cmp_gt_i32_e32 vcc, 3, v205
	s_and_saveexec_b64 s[2:3], vcc
	s_cbranch_execz .LBB0_873
	s_waitcnt vmcnt(0)
	v_mov_b32_e32 v157, v165

; __device__ __forceinline__ unsigned cvt_pk_bf16(float lo, float hi) { unsigned r; asm("v_cvt_pk_bf16_f32 %0, %1, %2" : "=v"(r) : "v"(lo), "v"(hi)); return r; }
; __device__ __forceinline__ float siluf_(float x) { return x * sigmoidf_(x); }
; __device__ __forceinline__ float dpp_ror1(float v) { return __builtin_bit_cast(float, __builtin_amdgcn_update_dpp(0, __builtin_bit_cast(int, v), 0x121, 0xf, 0xf, false)); }
;     __device__ __forceinline__ void operator()(f32x4 (&acc)[2][2][4][2], const pg8::Unit& u, int wr, int wc, int fr, int fq) const {
;     ...
;                 for (int n = 0; n < 2; ++n) { const int ch = ch0 + bj * 128 + 4 * n;
;                     const f32x4 w0 = *(const f32x4*)(cw + ch), w1 = *(const f32x4*)(cw + CW + ch), w2 = *(const f32x4*)(cw + 2 * CW + ch), w3 = *(const f32x4*)(cw + 3 * CW + ch), bb = *(const f32x4*)(cb + ch);
; #pragma unroll
;                     for (int m = 0; m < 4; ++m) { const int row = row0 + ai * 128 + m * 16; const f32x4 g = acc[ai][bj][m][n]; f32x4 p1, p2, p3;
;                         if (prompt) { const f32x4 gp = (m == 0) ? hal[n] : acc[ai][bj][m > 0 ? m - 1 : 0][n];
; #pragma unroll
;                             for (int j = 0; j < 4; ++j) { p1[j] = dpp_ror1(fr == 15 ? gp[j] : g[j]); p2[j] = dpp_ror2(fr >= 14 ? gp[j] : g[j]); p3[j] = dpp_ror3(fr >= 13 ? gp[j] : g[j]); } }
;                         else { const int t = fr & 3; const float* sp = stp + (size_t)((row - MP) >> 2) * 3 * CW + ch;
;                             const f32x4 b0 = *(const f32x4*)sp, b1 = *(const f32x4*)(sp + CW), b2 = *(const f32x4*)(sp + 2 * CW);
; #pragma unroll
;                             for (int j = 0; j < 4; ++j) { const float r1 = dpp_ror1(g[j]), r2 = dpp_ror2(g[j]), r3 = dpp_ror3(g[j]);
;                                 p1[j] = t >= 1 ? r1 : b2[j]; p2[j] = t >= 2 ? r2 : (t == 1 ? b2[j] : b1[j]); p3[j] = t >= 3 ? r3 : (t == 2 ? b2[j] : (t == 1 ? b1[j] : b0[j])); } }
;                         float o[4];
; #pragma unroll
;                         for (int j = 0; j < 4; ++j) { const float y = bb[j] + w0[j] * p3[j] + w1[j] * p2[j] + w2[j] * p1[j] + w3[j] * g[j]; o[j] = is_rg ? y : siluf_(y); }
;                         u32x2 w; w.x = cvt_pk_bf16(o[0], o[1]); w.y = cvt_pk_bf16(o[2], o[3]);
;                         *(u32x2*)(dst + (size_t)row * ld + bj * 128 + 4 * n) = w; }
.LBB0_881:
	s_and_b64 vcc, exec, s[0:1]
	s_cbranch_vccz .LBB0_883
	v_cndmask_b32_e64 v154, v114, v130, s[10:11]
	s_nop 1
	v_mov_b32_dpp v166, v154 row_ror:1 row_mask:0xf bank_mask:0xf
	v_cndmask_b32_e64 v154, v114, v130, s[8:9]
	v_cndmask_b32_e64 v130, v114, v130, s[6:7]
	s_nop 0
	v_mov_b32_dpp v158, v154 row_ror:2 row_mask:0xf bank_mask:0xf
	v_mov_b32_dpp v154, v130 row_ror:3 row_mask:0xf bank_mask:0xf
	v_cndmask_b32_e64 v130, v115, v131, s[10:11]
	s_nop 1
	v_mov_b32_dpp v167, v130 row_ror:1 row_mask:0xf bank_mask:0xf
	v_cndmask_b32_e64 v130, v115, v131, s[8:9]
	s_nop 1
	v_mov_b32_dpp v159, v130 row_ror:2 row_mask:0xf bank_mask:0xf
	v_cndmask_b32_e64 v130, v115, v131, s[6:7]
	s_nop 0
	s_nop 0
	v_mov_b32_dpp v155, v130 row_ror:3 row_mask:0xf bank_mask:0xf
	v_cndmask_b32_e64 v130, v116, v132, s[10:11]
	s_nop 1
	v_mov_b32_dpp v168, v130 row_ror:1 row_mask:0xf bank_mask:0xf
	v_cndmask_b32_e64 v130, v116, v132, s[8:9]
	s_nop 1
	v_mov_b32_dpp v160, v130 row_ror:2 row_mask:0xf bank_mask:0xf
	v_cndmask_b32_e64 v130, v116, v132, s[6:7]
	s_nop 1
	v_mov_b32_dpp v156, v130 row_ror:3 row_mask:0xf bank_mask:0xf
	v_cndmask_b32_e64 v130, v117, v133, s[10:11]
	s_nop 1
	v_mov_b32_dpp v169, v130 row_ror:1 row_mask:0xf bank_mask:0xf
	v_cndmask_b32_e64 v130, v117, v133, s[8:9]
	s_nop 1
	v_mov_b32_dpp v161, v130 row_ror:2 row_mask:0xf bank_mask:0xf
	v_cndmask_b32_e64 v130, v117, v133, s[6:7]
	s_nop 1
	v_mov_b32_dpp v157, v130 row_ror:3 row_mask:0xf bank_mask:0xf
.LBB0_883:
	s_waitcnt vmcnt(0)
	v_mov_b32_e32 v162, v150
	v_mov_b32_e32 v163, v138
	v_mov_b32_e32 v130, v158
	v_mov_b32_e32 v131, v154
	v_pk_mul_f32 v[130:131], v[162:163], v[130:131]
	v_mov_b32_e32 v164, v146
	v_add_f32_e32 v131, v142, v131
	v_mov_b32_e32 v165, v134
	v_mov_b32_e32 v233, v166
	v_add_f32_e32 v132, v130, v131
	v_pk_mul_f32 v[130:131], v[164:165], v[232:233]
	v_mov_b32_e32 v138, v151
	v_add_f32_e32 v131, v131, v132
	v_add_f32_e32 v132, v130, v131
	v_mul_f32_e32 v130, 0xbfb8aa3b, v132
	v_exp_f32_e32 v130, v130
	v_mov_b32_e32 v154, v159
	v_mov_b32_e32 v134, v147
	v_mov_b32_e32 v231, v167
	v_add_f32_e32 v130, 1.0, v130
	v_rcp_f32_e32 v133, v130
	v_pk_mul_f32 v[130:131], v[138:139], v[154:155]
	v_mov_b32_e32 v158, v152
	v_add_f32_e32 v131, v143, v131
	v_add_f32_e32 v146, v130, v131
	v_pk_mul_f32 v[130:131], v[134:135], v[230:231]
	v_mov_b32_e32 v159, v140
	v_add_f32_e32 v131, v131, v146
	v_add_f32_e32 v146, v130, v131
	v_mul_f32_e32 v130, 0xbfb8aa3b, v146
	v_exp_f32_e32 v130, v130
	v_mul_f32_e32 v131, v132, v133
	v_cndmask_b32_e64 v132, v131, v132, s[4:5]
	v_mov_b32_e32 v131, v156
	v_add_f32_e32 v130, 1.0, v130
	v_rcp_f32_e32 v133, v130
	v_mov_b32_e32 v130, v160
	v_pk_mul_f32 v[130:131], v[158:159], v[130:131]
	v_mov_b32_e32 v166, v148
	v_add_f32_e32 v131, v144, v131
	v_mov_b32_e32 v167, v136
	v_mov_b32_e32 v173, v168
	v_add_f32_e32 v140, v130, v131
	v_pk_mul_f32 v[130:131], v[166:167], v[172:173]
	v_mov_b32_e32 v156, v161
	v_add_f32_e32 v131, v131, v140
	v_add_f32_e32 v147, v130, v131
	v_mul_f32_e32 v130, 0xbfb8aa3b, v147
	v_mov_b32_e32 v140, v153
	v_exp_f32_e32 v148, v130
	v_pk_mul_f32 v[130:131], v[140:141], v[156:157]
	v_mov_b32_e32 v136, v149
	v_add_f32_e32 v131, v145, v131
	v_mov_b32_e32 v171, v169
	v_add_f32_e32 v150, v130, v131
	v_pk_mul_f32 v[130:131], v[136:137], v[170:171]
	v_add_f32_e32 v148, 1.0, v148
	v_add_f32_e32 v131, v131, v150
	v_add_f32_e32 v130, v130, v131
	v_mul_f32_e32 v131, 0xbfb8aa3b, v130
	v_exp_f32_e32 v131, v131
	v_rcp_f32_e32 v148, v148
	v_mul_f32_e32 v133, v146, v133
	v_cndmask_b32_e64 v133, v133, v146, s[4:5]
	v_add_f32_e32 v131, 1.0, v131
	v_rcp_f32_e32 v131, v131
	v_mul_f32_e32 v146, v147, v148
	v_cndmask_b32_e64 v146, v146, v147, s[4:5]
	s_mov_b64 s[0:1], -1
	v_mul_f32_e32 v131, v130, v131
	v_cndmask_b32_e64 v131, v131, v130, s[4:5]
	v_cvt_pk_bf16_f32 v130, v132, v133
	v_cvt_pk_bf16_f32 v131, v146, v131
	s_and_b64 vcc, exec, s[18:19]
	v_mov_b32_e32 v168, v98
	v_mov_b32_e32 v160, v99
	v_mov_b32_e32 v152, v100
	v_mov_b32_e32 v150, v101
	v_mov_b32_e32 v80, v130
	v_mov_b32_e32 v81, v131
	flat_store_dwordx4 v[222:223], v[78:81] offset:256
	s_cbranch_vccnz .LBB0_925
	v_add_u32_e32 v131, 0xffffe010, v202
	v_ashrrev_i32_e32 v131, 2, v131
	v_lshl_add_u32 v131, v131, 1, v131
	v_mad_i64_i32 v[132:133], s[0:1], v131, s47, 0
	v_lshl_add_u64 v[132:133], v[132:133], 2, v[208:209]
	v_lshl_add_u64 v[146:147], v[132:133], 0, s[24:25]
	s_lshl_b32 s0, s27, 2
	s_mov_b32 s1, s25
	global_load_dwordx4 v[154:157], v[132:133], off offset:528
	s_nop 0
	global_load_dwordx4 v[146:149], v[146:147], off offset:528
	v_lshl_add_u64 v[132:133], v[132:133], 0, s[0:1]
	global_load_dwordx4 v[150:153], v[132:133], off offset:528
	v_mov_b32_dpp v160, v98 row_ror:1 row_mask:0xf bank_mask:0xf
	v_mov_b32_dpp v161, v98 row_ror:2 row_mask:0xf bank_mask:0xf
	v_mov_b32_dpp v130, v98 row_ror:3 row_mask:0xf bank_mask:0xf
	v_cmp_lt_i32_e32 vcc, 1, v205
	s_and_saveexec_b64 s[0:1], vcc
	s_xor_b64 s[0:1], exec, s[0:1]
	s_cbranch_execz .LBB0_888
	v_cmp_gt_i32_e32 vcc, 3, v205
	s_and_saveexec_b64 s[2:3], vcc
	s_cbranch_execz .LBB0_887
	s_waitcnt vmcnt(0)
	v_mov_b32_e32 v130, v150

; __device__ __forceinline__ float dpp_ror1(float v) { return __builtin_bit_cast(float, __builtin_amdgcn_update_dpp(0, __builtin_bit_cast(int, v), 0x121, 0xf, 0xf, false)); }
; __device__ __forceinline__ float dpp_ror2(float v) { return __builtin_bit_cast(float, __builtin_amdgcn_update_dpp(0, __builtin_bit_cast(int, v), 0x122, 0xf, 0xf, false)); }
; __device__ __forceinline__ float dpp_ror3(float v) { return __builtin_bit_cast(float, __builtin_amdgcn_update_dpp(0, __builtin_bit_cast(int, v), 0x123, 0xf, 0xf, false)); }
;     __device__ __forceinline__ void operator()(f32x4 (&acc)[2][2][4][2], const pg8::Unit& u, int wr, int wc, int fr, int fq) const {
;     ...
;                         else { const int t = fr & 3; const float* sp = stp + (size_t)((row - MP) >> 2) * 3 * CW + ch;
;                             const f32x4 b0 = *(const f32x4*)sp, b1 = *(const f32x4*)(sp + CW), b2 = *(const f32x4*)(sp + 2 * CW);
; #pragma unroll
;                             for (int j = 0; j < 4; ++j) { const float r1 = dpp_ror1(g[j]), r2 = dpp_ror2(g[j]), r3 = dpp_ror3(g[j]);
;                                 p1[j] = t >= 1 ? r1 : b2[j]; p2[j] = t >= 2 ? r2 : (t == 1 ? b2[j] : b1[j]); p3[j] = t >= 3 ? r3 : (t == 2 ? b2[j] : (t == 1 ? b1[j] : b0[j])); } }
.LBB0_894:
	s_or_b64 exec, exec, s[0:1]
	v_mov_b32_dpp v168, v99 row_ror:1 row_mask:0xf bank_mask:0xf
	v_mov_b32_dpp v169, v99 row_ror:2 row_mask:0xf bank_mask:0xf
	v_mov_b32_dpp v131, v99 row_ror:3 row_mask:0xf bank_mask:0xf
	v_cmp_lt_i32_e32 vcc, 1, v205
	s_and_saveexec_b64 s[0:1], vcc
	s_xor_b64 s[0:1], exec, s[0:1]
	s_cbranch_execz .LBB0_898
	v_cmp_gt_i32_e32 vcc, 3, v205
	s_and_saveexec_b64 s[2:3], vcc
	s_cbranch_execz .LBB0_897
	s_waitcnt vmcnt(0)
	v_mov_b32_e32 v131, v151

; __device__ __forceinline__ float dpp_ror1(float v) { return __builtin_bit_cast(float, __builtin_amdgcn_update_dpp(0, __builtin_bit_cast(int, v), 0x121, 0xf, 0xf, false)); }
; __device__ __forceinline__ float dpp_ror2(float v) { return __builtin_bit_cast(float, __builtin_amdgcn_update_dpp(0, __builtin_bit_cast(int, v), 0x122, 0xf, 0xf, false)); }
; __device__ __forceinline__ float dpp_ror3(float v) { return __builtin_bit_cast(float, __builtin_amdgcn_update_dpp(0, __builtin_bit_cast(int, v), 0x123, 0xf, 0xf, false)); }
;     __device__ __forceinline__ void operator()(f32x4 (&acc)[2][2][4][2], const pg8::Unit& u, int wr, int wc, int fr, int fq) const {
;     ...
;                         else { const int t = fr & 3; const float* sp = stp + (size_t)((row - MP) >> 2) * 3 * CW + ch;
;                             const f32x4 b0 = *(const f32x4*)sp, b1 = *(const f32x4*)(sp + CW), b2 = *(const f32x4*)(sp + 2 * CW);
; #pragma unroll
;                             for (int j = 0; j < 4; ++j) { const float r1 = dpp_ror1(g[j]), r2 = dpp_ror2(g[j]), r3 = dpp_ror3(g[j]);
;                                 p1[j] = t >= 1 ? r1 : b2[j]; p2[j] = t >= 2 ? r2 : (t == 1 ? b2[j] : b1[j]); p3[j] = t >= 3 ? r3 : (t == 2 ? b2[j] : (t == 1 ? b1[j] : b0[j])); } }
.LBB0_904:
	s_or_b64 exec, exec, s[0:1]
	v_mov_b32_dpp v170, v100 row_ror:1 row_mask:0xf bank_mask:0xf
	v_mov_b32_dpp v171, v100 row_ror:2 row_mask:0xf bank_mask:0xf
	v_mov_b32_dpp v132, v100 row_ror:3 row_mask:0xf bank_mask:0xf
	v_cmp_lt_i32_e32 vcc, 1, v205
	s_and_saveexec_b64 s[0:1], vcc
	s_xor_b64 s[0:1], exec, s[0:1]
	s_cbranch_execz .LBB0_908
	v_cmp_gt_i32_e32 vcc, 3, v205
	s_and_saveexec_b64 s[2:3], vcc
	s_cbranch_execz .LBB0_907
	s_waitcnt vmcnt(0)
	v_mov_b32_e32 v132, v152

; __device__ __forceinline__ float dpp_ror1(float v) { return __builtin_bit_cast(float, __builtin_amdgcn_update_dpp(0, __builtin_bit_cast(int, v), 0x121, 0xf, 0xf, false)); }
; __device__ __forceinline__ float dpp_ror2(float v) { return __builtin_bit_cast(float, __builtin_amdgcn_update_dpp(0, __builtin_bit_cast(int, v), 0x122, 0xf, 0xf, false)); }
; __device__ __forceinline__ float dpp_ror3(float v) { return __builtin_bit_cast(float, __builtin_amdgcn_update_dpp(0, __builtin_bit_cast(int, v), 0x123, 0xf, 0xf, false)); }
;     __device__ __forceinline__ void operator()(f32x4 (&acc)[2][2][4][2], const pg8::Unit& u, int wr, int wc, int fr, int fq) const {
;     ...
;                         else { const int t = fr & 3; const float* sp = stp + (size_t)((row - MP) >> 2) * 3 * CW + ch;
;                             const f32x4 b0 = *(const f32x4*)sp, b1 = *(const f32x4*)(sp + CW), b2 = *(const f32x4*)(sp + 2 * CW);
; #pragma unroll
;                             for (int j = 0; j < 4; ++j) { const float r1 = dpp_ror1(g[j]), r2 = dpp_ror2(g[j]), r3 = dpp_ror3(g[j]);
;                                 p1[j] = t >= 1 ? r1 : b2[j]; p2[j] = t >= 2 ? r2 : (t == 1 ? b2[j] : b1[j]); p3[j] = t >= 3 ? r3 : (t == 2 ? b2[j] : (t == 1 ? b1[j] : b0[j])); } }
.LBB0_914:
	s_or_b64 exec, exec, s[0:1]
	v_mov_b32_dpp v173, v101 row_ror:1 row_mask:0xf bank_mask:0xf
	v_mov_b32_dpp v172, v101 row_ror:2 row_mask:0xf bank_mask:0xf
	v_mov_b32_dpp v133, v101 row_ror:3 row_mask:0xf bank_mask:0xf
	v_cmp_lt_i32_e32 vcc, 1, v205
	s_and_saveexec_b64 s[0:1], vcc
	s_xor_b64 s[0:1], exec, s[0:1]
	s_cbranch_execz .LBB0_918
	v_cmp_gt_i32_e32 vcc, 3, v205
	s_and_saveexec_b64 s[2:3], vcc
	s_cbranch_execz .LBB0_917
	s_waitcnt vmcnt(0)
	v_mov_b32_e32 v133, v153

; __device__ __forceinline__ unsigned cvt_pk_bf16(float lo, float hi) { unsigned r; asm("v_cvt_pk_bf16_f32 %0, %1, %2" : "=v"(r) : "v"(lo), "v"(hi)); return r; }
; __device__ __forceinline__ float siluf_(float x) { return x * sigmoidf_(x); }
; __device__ __forceinline__ float dpp_ror1(float v) { return __builtin_bit_cast(float, __builtin_amdgcn_update_dpp(0, __builtin_bit_cast(int, v), 0x121, 0xf, 0xf, false)); }
;     __device__ __forceinline__ void operator()(f32x4 (&acc)[2][2][4][2], const pg8::Unit& u, int wr, int wc, int fr, int fq) const {
;     ...
;                 for (int n = 0; n < 2; ++n) { const int ch = ch0 + bj * 128 + 4 * n;
;                     const f32x4 w0 = *(const f32x4*)(cw + ch), w1 = *(const f32x4*)(cw + CW + ch), w2 = *(const f32x4*)(cw + 2 * CW + ch), w3 = *(const f32x4*)(cw + 3 * CW + ch), bb = *(const f32x4*)(cb + ch);
; #pragma unroll
;                     for (int m = 0; m < 4; ++m) { const int row = row0 + ai * 128 + m * 16; const f32x4 g = acc[ai][bj][m][n]; f32x4 p1, p2, p3;
;                         if (prompt) { const f32x4 gp = (m == 0) ? hal[n] : acc[ai][bj][m > 0 ? m - 1 : 0][n];
; #pragma unroll
;                             for (int j = 0; j < 4; ++j) { p1[j] = dpp_ror1(fr == 15 ? gp[j] : g[j]); p2[j] = dpp_ror2(fr >= 14 ? gp[j] : g[j]); p3[j] = dpp_ror3(fr >= 13 ? gp[j] : g[j]); } }
;                         else { const int t = fr & 3; const float* sp = stp + (size_t)((row - MP) >> 2) * 3 * CW + ch;
;                             const f32x4 b0 = *(const f32x4*)sp, b1 = *(const f32x4*)(sp + CW), b2 = *(const f32x4*)(sp + 2 * CW);
; #pragma unroll
;                             for (int j = 0; j < 4; ++j) { const float r1 = dpp_ror1(g[j]), r2 = dpp_ror2(g[j]), r3 = dpp_ror3(g[j]);
;                                 p1[j] = t >= 1 ? r1 : b2[j]; p2[j] = t >= 2 ? r2 : (t == 1 ? b2[j] : b1[j]); p3[j] = t >= 3 ? r3 : (t == 2 ? b2[j] : (t == 1 ? b1[j] : b0[j])); } }
;                         float o[4];
; #pragma unroll
;                         for (int j = 0; j < 4; ++j) { const float y = bb[j] + w0[j] * p3[j] + w1[j] * p2[j] + w2[j] * p1[j] + w3[j] * g[j]; o[j] = is_rg ? y : siluf_(y); }
;                         u32x2 w; w.x = cvt_pk_bf16(o[0], o[1]); w.y = cvt_pk_bf16(o[2], o[3]);
;                         *(u32x2*)(dst + (size_t)row * ld + bj * 128 + 4 * n) = w; }
.LBB0_925:
	s_and_b64 vcc, exec, s[0:1]
	s_cbranch_vccz .LBB0_927
	v_cndmask_b32_e64 v130, v98, v114, s[10:11]
	v_cndmask_b32_e64 v131, v98, v114, s[6:7]
	s_nop 0
	v_mov_b32_dpp v154, v130 row_ror:1 row_mask:0xf bank_mask:0xf
	v_cndmask_b32_e64 v130, v98, v114, s[8:9]
	s_nop 1
	v_mov_b32_dpp v146, v130 row_ror:2 row_mask:0xf bank_mask:0xf
	v_cndmask_b32_e64 v132, v99, v115, s[6:7]
	v_mov_b32_dpp v130, v131 row_ror:3 row_mask:0xf bank_mask:0xf
	v_cndmask_b32_e64 v131, v99, v115, s[10:11]
	v_cndmask_b32_e64 v133, v100, v116, s[6:7]
	s_nop 0
	v_mov_b32_dpp v155, v131 row_ror:1 row_mask:0xf bank_mask:0xf
	v_cndmask_b32_e64 v131, v99, v115, s[8:9]
	s_nop 1
	v_mov_b32_dpp v147, v131 row_ror:2 row_mask:0xf bank_mask:0xf
	v_cndmask_b32_e64 v151, v101, v117, s[6:7]
	s_nop 0
	v_mov_b32_dpp v131, v132 row_ror:3 row_mask:0xf bank_mask:0xf
	v_cndmask_b32_e64 v132, v100, v116, s[10:11]
	s_nop 1
	v_mov_b32_dpp v156, v132 row_ror:1 row_mask:0xf bank_mask:0xf
	v_cndmask_b32_e64 v132, v100, v116, s[8:9]
	s_nop 1
	v_mov_b32_dpp v148, v132 row_ror:2 row_mask:0xf bank_mask:0xf
	s_nop 1
	v_mov_b32_dpp v132, v133 row_ror:3 row_mask:0xf bank_mask:0xf
	v_cndmask_b32_e64 v133, v101, v117, s[10:11]
	s_nop 1
	v_mov_b32_dpp v157, v133 row_ror:1 row_mask:0xf bank_mask:0xf
	v_cndmask_b32_e64 v133, v101, v117, s[8:9]
	s_nop 1
	v_mov_b32_dpp v149, v133 row_ror:2 row_mask:0xf bank_mask:0xf
	s_nop 1
	v_mov_b32_dpp v133, v151 row_ror:3 row_mask:0xf bank_mask:0xf
.LBB0_927:
	v_mov_b32_e32 v170, v146
	v_mov_b32_e32 v171, v130
	v_pk_mul_f32 v[170:171], v[162:163], v[170:171]
	v_mov_b32_e32 v169, v154
	v_add_f32_e32 v130, v142, v171
	v_add_f32_e32 v130, v170, v130
	v_pk_mul_f32 v[168:169], v[164:165], v[168:169]
	v_mov_b32_e32 v161, v155
	v_add_f32_e32 v130, v169, v130
	v_add_f32_e32 v146, v168, v130
	v_mul_f32_e32 v130, 0xbfb8aa3b, v146
	v_exp_f32_e32 v130, v130
	v_mov_b32_e32 v153, v156
	s_mov_b64 s[0:1], -1
	s_and_b64 vcc, exec, s[18:19]
	v_add_f32_e32 v130, 1.0, v130
	v_rcp_f32_e32 v151, v130
	v_mov_b32_e32 v130, v147
	v_pk_mul_f32 v[130:131], v[138:139], v[130:131]
	v_mov_b32_e32 v168, v82
	v_add_f32_e32 v131, v143, v131
	v_add_f32_e32 v147, v130, v131
	v_pk_mul_f32 v[130:131], v[134:135], v[160:161]
	v_mov_b32_e32 v160, v83
	v_add_f32_e32 v131, v131, v147
	v_add_f32_e32 v147, v130, v131
	v_mul_f32_e32 v130, 0xbfb8aa3b, v147
	v_exp_f32_e32 v130, v130
	v_mul_f32_e32 v131, v146, v151
	v_cndmask_b32_e64 v146, v131, v146, s[4:5]
	v_mov_b32_e32 v131, v132
	v_add_f32_e32 v130, 1.0, v130
	v_rcp_f32_e32 v154, v130
	v_mov_b32_e32 v130, v148
	v_pk_mul_f32 v[130:131], v[158:159], v[130:131]
	v_mov_b32_e32 v151, v157
	v_add_f32_e32 v131, v144, v131
	v_add_f32_e32 v132, v130, v131
	v_pk_mul_f32 v[130:131], v[166:167], v[152:153]
	s_nop 0
	v_add_f32_e32 v131, v131, v132
	v_add_f32_e32 v148, v130, v131
	v_mul_f32_e32 v130, 0xbfb8aa3b, v148
	v_mov_b32_e32 v132, v149
	v_exp_f32_e32 v152, v130
	v_pk_mul_f32 v[130:131], v[140:141], v[132:133]
	v_add_f32_e32 v133, 1.0, v152
	v_add_f32_e32 v131, v145, v131
	v_add_f32_e32 v132, v130, v131
	v_pk_mul_f32 v[130:131], v[136:137], v[150:151]
	v_rcp_f32_e32 v133, v133
	v_add_f32_e32 v131, v131, v132
	v_add_f32_e32 v130, v130, v131
	v_mul_f32_e32 v131, 0xbfb8aa3b, v130
	v_exp_f32_e32 v131, v131
	v_mul_f32_e32 v132, v147, v154
	v_mul_f32_e32 v133, v148, v133
	v_cndmask_b32_e64 v132, v132, v147, s[4:5]
	v_add_f32_e32 v131, 1.0, v131
	v_rcp_f32_e32 v131, v131
	v_cndmask_b32_e64 v133, v133, v148, s[4:5]
	v_mov_b32_e32 v152, v84
	v_mov_b32_e32 v150, v85
	v_mul_f32_e32 v131, v130, v131
	v_cndmask_b32_e64 v131, v131, v130, s[4:5]
	v_cvt_pk_bf16_f32 v130, v146, v132
	v_cvt_pk_bf16_f32 v131, v133, v131
	v_mov_b32_e32 v120, v130
	v_mov_b32_e32 v121, v131
	flat_store_dwordx4 v[224:225], v[118:121] offset:256
	s_cbranch_vccnz .LBB0_969
	v_add_u32_e32 v131, 0xffffe020, v202
	v_ashrrev_i32_e32 v131, 2, v131
	v_lshl_add_u32 v131, v131, 1, v131
	v_mad_i64_i32 v[132:133], s[0:1], v131, s47, 0
	v_lshl_add_u64 v[132:133], v[132:133], 2, v[208:209]
	v_lshl_add_u64 v[146:147], v[132:133], 0, s[24:25]
	s_lshl_b32 s0, s27, 2
	s_mov_b32 s1, s25
	global_load_dwordx4 v[154:157], v[132:133], off offset:528
	s_nop 0
	global_load_dwordx4 v[146:149], v[146:147], off offset:528
	v_lshl_add_u64 v[132:133], v[132:133], 0, s[0:1]
	global_load_dwordx4 v[150:153], v[132:133], off offset:528
	v_mov_b32_dpp v160, v82 row_ror:1 row_mask:0xf bank_mask:0xf
	v_mov_b32_dpp v161, v82 row_ror:2 row_mask:0xf bank_mask:0xf
	v_mov_b32_dpp v130, v82 row_ror:3 row_mask:0xf bank_mask:0xf
	v_cmp_lt_i32_e32 vcc, 1, v205
	s_and_saveexec_b64 s[0:1], vcc
	s_xor_b64 s[0:1], exec, s[0:1]
	s_cbranch_execz .LBB0_932
	v_cmp_gt_i32_e32 vcc, 3, v205
	s_and_saveexec_b64 s[2:3], vcc
	s_cbranch_execz .LBB0_931
	s_waitcnt vmcnt(0)
	v_mov_b32_e32 v130, v150

; __device__ __forceinline__ float dpp_ror1(float v) { return __builtin_bit_cast(float, __builtin_amdgcn_update_dpp(0, __builtin_bit_cast(int, v), 0x121, 0xf, 0xf, false)); }
; __device__ __forceinline__ float dpp_ror2(float v) { return __builtin_bit_cast(float, __builtin_amdgcn_update_dpp(0, __builtin_bit_cast(int, v), 0x122, 0xf, 0xf, false)); }
; __device__ __forceinline__ float dpp_ror3(float v) { return __builtin_bit_cast(float, __builtin_amdgcn_update_dpp(0, __builtin_bit_cast(int, v), 0x123, 0xf, 0xf, false)); }
;     __device__ __forceinline__ void operator()(f32x4 (&acc)[2][2][4][2], const pg8::Unit& u, int wr, int wc, int fr, int fq) const {
;     ...
;                         else { const int t = fr & 3; const float* sp = stp + (size_t)((row - MP) >> 2) * 3 * CW + ch;
;                             const f32x4 b0 = *(const f32x4*)sp, b1 = *(const f32x4*)(sp + CW), b2 = *(const f32x4*)(sp + 2 * CW);
; #pragma unroll
;                             for (int j = 0; j < 4; ++j) { const float r1 = dpp_ror1(g[j]), r2 = dpp_ror2(g[j]), r3 = dpp_ror3(g[j]);
;                                 p1[j] = t >= 1 ? r1 : b2[j]; p2[j] = t >= 2 ? r2 : (t == 1 ? b2[j] : b1[j]); p3[j] = t >= 3 ? r3 : (t == 2 ? b2[j] : (t == 1 ? b1[j] : b0[j])); } }
.LBB0_938:
	s_or_b64 exec, exec, s[0:1]
	v_mov_b32_dpp v168, v83 row_ror:1 row_mask:0xf bank_mask:0xf
	v_mov_b32_dpp v169, v83 row_ror:2 row_mask:0xf bank_mask:0xf
	v_mov_b32_dpp v131, v83 row_ror:3 row_mask:0xf bank_mask:0xf
	v_cmp_lt_i32_e32 vcc, 1, v205
	s_and_saveexec_b64 s[0:1], vcc
	s_xor_b64 s[0:1], exec, s[0:1]
	s_cbranch_execz .LBB0_942
	v_cmp_gt_i32_e32 vcc, 3, v205
	s_and_saveexec_b64 s[2:3], vcc
	s_cbranch_execz .LBB0_941
	s_waitcnt vmcnt(0)
	v_mov_b32_e32 v131, v151

; __device__ __forceinline__ float dpp_ror1(float v) { return __builtin_bit_cast(float, __builtin_amdgcn_update_dpp(0, __builtin_bit_cast(int, v), 0x121, 0xf, 0xf, false)); }
; __device__ __forceinline__ float dpp_ror2(float v) { return __builtin_bit_cast(float, __builtin_amdgcn_update_dpp(0, __builtin_bit_cast(int, v), 0x122, 0xf, 0xf, false)); }
; __device__ __forceinline__ float dpp_ror3(float v) { return __builtin_bit_cast(float, __builtin_amdgcn_update_dpp(0, __builtin_bit_cast(int, v), 0x123, 0xf, 0xf, false)); }
;     __device__ __forceinline__ void operator()(f32x4 (&acc)[2][2][4][2], const pg8::Unit& u, int wr, int wc, int fr, int fq) const {
;     ...
;                         else { const int t = fr & 3; const float* sp = stp + (size_t)((row - MP) >> 2) * 3 * CW + ch;
;                             const f32x4 b0 = *(const f32x4*)sp, b1 = *(const f32x4*)(sp + CW), b2 = *(const f32x4*)(sp + 2 * CW);
; #pragma unroll
;                             for (int j = 0; j < 4; ++j) { const float r1 = dpp_ror1(g[j]), r2 = dpp_ror2(g[j]), r3 = dpp_ror3(g[j]);
;                                 p1[j] = t >= 1 ? r1 : b2[j]; p2[j] = t >= 2 ? r2 : (t == 1 ? b2[j] : b1[j]); p3[j] = t >= 3 ? r3 : (t == 2 ? b2[j] : (t == 1 ? b1[j] : b0[j])); } }
.LBB0_948:
	s_or_b64 exec, exec, s[0:1]
	v_mov_b32_dpp v170, v84 row_ror:1 row_mask:0xf bank_mask:0xf
	v_mov_b32_dpp v171, v84 row_ror:2 row_mask:0xf bank_mask:0xf
	v_mov_b32_dpp v132, v84 row_ror:3 row_mask:0xf bank_mask:0xf
	v_cmp_lt_i32_e32 vcc, 1, v205
	s_and_saveexec_b64 s[0:1], vcc
	s_xor_b64 s[0:1], exec, s[0:1]
	s_cbranch_execz .LBB0_952
	v_cmp_gt_i32_e32 vcc, 3, v205
	s_and_saveexec_b64 s[2:3], vcc
	s_cbranch_execz .LBB0_951
	s_waitcnt vmcnt(0)
	v_mov_b32_e32 v132, v152

; __device__ __forceinline__ float dpp_ror1(float v) { return __builtin_bit_cast(float, __builtin_amdgcn_update_dpp(0, __builtin_bit_cast(int, v), 0x121, 0xf, 0xf, false)); }
; __device__ __forceinline__ float dpp_ror2(float v) { return __builtin_bit_cast(float, __builtin_amdgcn_update_dpp(0, __builtin_bit_cast(int, v), 0x122, 0xf, 0xf, false)); }
; __device__ __forceinline__ float dpp_ror3(float v) { return __builtin_bit_cast(float, __builtin_amdgcn_update_dpp(0, __builtin_bit_cast(int, v), 0x123, 0xf, 0xf, false)); }
;     __device__ __forceinline__ void operator()(f32x4 (&acc)[2][2][4][2], const pg8::Unit& u, int wr, int wc, int fr, int fq) const {
;     ...
;                         else { const int t = fr & 3; const float* sp = stp + (size_t)((row - MP) >> 2) * 3 * CW + ch;
;                             const f32x4 b0 = *(const f32x4*)sp, b1 = *(const f32x4*)(sp + CW), b2 = *(const f32x4*)(sp + 2 * CW);
; #pragma unroll
;                             for (int j = 0; j < 4; ++j) { const float r1 = dpp_ror1(g[j]), r2 = dpp_ror2(g[j]), r3 = dpp_ror3(g[j]);
;                                 p1[j] = t >= 1 ? r1 : b2[j]; p2[j] = t >= 2 ? r2 : (t == 1 ? b2[j] : b1[j]); p3[j] = t >= 3 ? r3 : (t == 2 ? b2[j] : (t == 1 ? b1[j] : b0[j])); } }
.LBB0_958:
	s_or_b64 exec, exec, s[0:1]
	v_mov_b32_dpp v173, v85 row_ror:1 row_mask:0xf bank_mask:0xf
	v_mov_b32_dpp v172, v85 row_ror:2 row_mask:0xf bank_mask:0xf
	v_mov_b32_dpp v133, v85 row_ror:3 row_mask:0xf bank_mask:0xf
	v_cmp_lt_i32_e32 vcc, 1, v205
	s_and_saveexec_b64 s[0:1], vcc
	s_xor_b64 s[0:1], exec, s[0:1]
	s_cbranch_execz .LBB0_962
	v_cmp_gt_i32_e32 vcc, 3, v205
	s_and_saveexec_b64 s[2:3], vcc
	s_cbranch_execz .LBB0_961
	s_waitcnt vmcnt(0)
	v_mov_b32_e32 v133, v153

; __device__ __forceinline__ unsigned cvt_pk_bf16(float lo, float hi) { unsigned r; asm("v_cvt_pk_bf16_f32 %0, %1, %2" : "=v"(r) : "v"(lo), "v"(hi)); return r; }
; __device__ __forceinline__ float siluf_(float x) { return x * sigmoidf_(x); }
; __device__ __forceinline__ float dpp_ror1(float v) { return __builtin_bit_cast(float, __builtin_amdgcn_update_dpp(0, __builtin_bit_cast(int, v), 0x121, 0xf, 0xf, false)); }
;     __device__ __forceinline__ void operator()(f32x4 (&acc)[2][2][4][2], const pg8::Unit& u, int wr, int wc, int fr, int fq) const {
;     ...
;                 for (int n = 0; n < 2; ++n) { const int ch = ch0 + bj * 128 + 4 * n;
;                     const f32x4 w0 = *(const f32x4*)(cw + ch), w1 = *(const f32x4*)(cw + CW + ch), w2 = *(const f32x4*)(cw + 2 * CW + ch), w3 = *(const f32x4*)(cw + 3 * CW + ch), bb = *(const f32x4*)(cb + ch);
; #pragma unroll
;                     for (int m = 0; m < 4; ++m) { const int row = row0 + ai * 128 + m * 16; const f32x4 g = acc[ai][bj][m][n]; f32x4 p1, p2, p3;
;                         if (prompt) { const f32x4 gp = (m == 0) ? hal[n] : acc[ai][bj][m > 0 ? m - 1 : 0][n];
; #pragma unroll
;                             for (int j = 0; j < 4; ++j) { p1[j] = dpp_ror1(fr == 15 ? gp[j] : g[j]); p2[j] = dpp_ror2(fr >= 14 ? gp[j] : g[j]); p3[j] = dpp_ror3(fr >= 13 ? gp[j] : g[j]); } }
;                         else { const int t = fr & 3; const float* sp = stp + (size_t)((row - MP) >> 2) * 3 * CW + ch;
;                             const f32x4 b0 = *(const f32x4*)sp, b1 = *(const f32x4*)(sp + CW), b2 = *(const f32x4*)(sp + 2 * CW);
; #pragma unroll
;                             for (int j = 0; j < 4; ++j) { const float r1 = dpp_ror1(g[j]), r2 = dpp_ror2(g[j]), r3 = dpp_ror3(g[j]);
;                                 p1[j] = t >= 1 ? r1 : b2[j]; p2[j] = t >= 2 ? r2 : (t == 1 ? b2[j] : b1[j]); p3[j] = t >= 3 ? r3 : (t == 2 ? b2[j] : (t == 1 ? b1[j] : b0[j])); } }
;                         float o[4];
; #pragma unroll
;                         for (int j = 0; j < 4; ++j) { const float y = bb[j] + w0[j] * p3[j] + w1[j] * p2[j] + w2[j] * p1[j] + w3[j] * g[j]; o[j] = is_rg ? y : siluf_(y); }
;                         u32x2 w; w.x = cvt_pk_bf16(o[0], o[1]); w.y = cvt_pk_bf16(o[2], o[3]);
;                         *(u32x2*)(dst + (size_t)row * ld + bj * 128 + 4 * n) = w; }
.LBB0_969:
	s_and_b64 vcc, exec, s[0:1]
	s_cbranch_vccz .LBB0_971
	v_cndmask_b32_e64 v130, v82, v98, s[10:11]
	v_cndmask_b32_e64 v131, v82, v98, s[6:7]
	s_nop 0
	v_mov_b32_dpp v154, v130 row_ror:1 row_mask:0xf bank_mask:0xf
	v_cndmask_b32_e64 v130, v82, v98, s[8:9]
	s_nop 1
	v_mov_b32_dpp v146, v130 row_ror:2 row_mask:0xf bank_mask:0xf
	v_cndmask_b32_e64 v132, v83, v99, s[6:7]
	v_mov_b32_dpp v130, v131 row_ror:3 row_mask:0xf bank_mask:0xf
	v_cndmask_b32_e64 v131, v83, v99, s[10:11]
	v_cndmask_b32_e64 v133, v84, v100, s[6:7]
	s_nop 0
	v_mov_b32_dpp v155, v131 row_ror:1 row_mask:0xf bank_mask:0xf
	v_cndmask_b32_e64 v131, v83, v99, s[8:9]
	s_nop 1
	v_mov_b32_dpp v147, v131 row_ror:2 row_mask:0xf bank_mask:0xf
	v_cndmask_b32_e64 v151, v85, v101, s[6:7]
	s_nop 0
	v_mov_b32_dpp v131, v132 row_ror:3 row_mask:0xf bank_mask:0xf
	v_cndmask_b32_e64 v132, v84, v100, s[10:11]
	s_nop 1
	v_mov_b32_dpp v156, v132 row_ror:1 row_mask:0xf bank_mask:0xf
	v_cndmask_b32_e64 v132, v84, v100, s[8:9]
	s_nop 1
	v_mov_b32_dpp v148, v132 row_ror:2 row_mask:0xf bank_mask:0xf
	s_nop 1
	v_mov_b32_dpp v132, v133 row_ror:3 row_mask:0xf bank_mask:0xf
	v_cndmask_b32_e64 v133, v85, v101, s[10:11]
	s_nop 1
	v_mov_b32_dpp v157, v133 row_ror:1 row_mask:0xf bank_mask:0xf
	v_cndmask_b32_e64 v133, v85, v101, s[8:9]
	s_nop 1
	v_mov_b32_dpp v149, v133 row_ror:2 row_mask:0xf bank_mask:0xf
	s_nop 1
	v_mov_b32_dpp v133, v151 row_ror:3 row_mask:0xf bank_mask:0xf
.LBB0_971:
	v_mov_b32_e32 v170, v146
	v_mov_b32_e32 v171, v130
	v_pk_mul_f32 v[170:171], v[162:163], v[170:171]
	v_mov_b32_e32 v169, v154
	v_add_f32_e32 v130, v142, v171
	v_add_f32_e32 v130, v170, v130
	v_pk_mul_f32 v[168:169], v[164:165], v[168:169]
	v_mov_b32_e32 v161, v155
	v_add_f32_e32 v130, v169, v130
	v_add_f32_e32 v146, v168, v130
	v_mul_f32_e32 v130, 0xbfb8aa3b, v146
	v_exp_f32_e32 v130, v130
	v_mov_b32_e32 v153, v156
	s_mov_b64 s[0:1], -1
	s_and_b64 vcc, exec, s[18:19]
	v_add_f32_e32 v130, 1.0, v130
	v_rcp_f32_e32 v151, v130
	v_mov_b32_e32 v130, v147
	v_pk_mul_f32 v[130:131], v[138:139], v[130:131]
	v_mov_b32_e32 v168, v66
	v_add_f32_e32 v131, v143, v131
	v_add_f32_e32 v147, v130, v131
	v_pk_mul_f32 v[130:131], v[134:135], v[160:161]
	v_mov_b32_e32 v160, v67
	v_add_f32_e32 v131, v131, v147
	v_add_f32_e32 v147, v130, v131
	v_mul_f32_e32 v130, 0xbfb8aa3b, v147
	v_exp_f32_e32 v130, v130
	v_mul_f32_e32 v131, v146, v151
	v_cndmask_b32_e64 v146, v131, v146, s[4:5]
	v_mov_b32_e32 v131, v132
	v_add_f32_e32 v130, 1.0, v130
	v_rcp_f32_e32 v154, v130
	v_mov_b32_e32 v130, v148
	v_pk_mul_f32 v[130:131], v[158:159], v[130:131]
	v_mov_b32_e32 v151, v157
	v_add_f32_e32 v131, v144, v131
	v_add_f32_e32 v132, v130, v131
	v_pk_mul_f32 v[130:131], v[166:167], v[152:153]
	s_nop 0
	v_add_f32_e32 v131, v131, v132
	v_add_f32_e32 v148, v130, v131
	v_mul_f32_e32 v130, 0xbfb8aa3b, v148
	v_mov_b32_e32 v132, v149
	v_exp_f32_e32 v152, v130
	v_pk_mul_f32 v[130:131], v[140:141], v[132:133]
	v_add_f32_e32 v133, 1.0, v152
	v_add_f32_e32 v131, v145, v131
	v_add_f32_e32 v132, v130, v131
	v_pk_mul_f32 v[130:131], v[136:137], v[150:151]
	v_rcp_f32_e32 v133, v133
	v_add_f32_e32 v131, v131, v132
	v_add_f32_e32 v130, v130, v131
	v_mul_f32_e32 v131, 0xbfb8aa3b, v130
	v_exp_f32_e32 v131, v131
	v_mul_f32_e32 v132, v147, v154
	v_mul_f32_e32 v133, v148, v133
	v_cndmask_b32_e64 v132, v132, v147, s[4:5]
	v_add_f32_e32 v131, 1.0, v131
	v_rcp_f32_e32 v131, v131
	v_cndmask_b32_e64 v133, v133, v148, s[4:5]
	v_mov_b32_e32 v152, v68
	v_mov_b32_e32 v150, v69
	v_mul_f32_e32 v131, v130, v131
	v_cndmask_b32_e64 v131, v131, v130, s[4:5]
	v_cvt_pk_bf16_f32 v130, v146, v132
	v_cvt_pk_bf16_f32 v131, v133, v131
	v_mov_b32_e32 v104, v130
	v_mov_b32_e32 v105, v131
	flat_store_dwordx4 v[226:227], v[102:105] offset:256
	s_cbranch_vccnz .LBB0_1013
	v_add_u32_e32 v131, 0xffffe030, v202
	v_ashrrev_i32_e32 v131, 2, v131
	v_lshl_add_u32 v131, v131, 1, v131
	v_mad_i64_i32 v[132:133], s[0:1], v131, s47, 0
	v_lshl_add_u64 v[132:133], v[132:133], 2, v[208:209]
	v_lshl_add_u64 v[146:147], v[132:133], 0, s[24:25]
	s_lshl_b32 s0, s27, 2
	s_mov_b32 s1, s25
	global_load_dwordx4 v[154:157], v[132:133], off offset:528
	s_nop 0
	global_load_dwordx4 v[146:149], v[146:147], off offset:528
	v_lshl_add_u64 v[132:133], v[132:133], 0, s[0:1]
	global_load_dwordx4 v[150:153], v[132:133], off offset:528
	v_mov_b32_dpp v160, v66 row_ror:1 row_mask:0xf bank_mask:0xf
	v_mov_b32_dpp v161, v66 row_ror:2 row_mask:0xf bank_mask:0xf
	v_mov_b32_dpp v130, v66 row_ror:3 row_mask:0xf bank_mask:0xf
	v_cmp_lt_i32_e32 vcc, 1, v205
	s_and_saveexec_b64 s[0:1], vcc
	s_xor_b64 s[0:1], exec, s[0:1]
	s_cbranch_execz .LBB0_976
	v_cmp_gt_i32_e32 vcc, 3, v205
	s_and_saveexec_b64 s[2:3], vcc
	s_cbranch_execz .LBB0_975
	s_waitcnt vmcnt(0)
	v_mov_b32_e32 v130, v150

; __device__ __forceinline__ float dpp_ror1(float v) { return __builtin_bit_cast(float, __builtin_amdgcn_update_dpp(0, __builtin_bit_cast(int, v), 0x121, 0xf, 0xf, false)); }
; __device__ __forceinline__ float dpp_ror2(float v) { return __builtin_bit_cast(float, __builtin_amdgcn_update_dpp(0, __builtin_bit_cast(int, v), 0x122, 0xf, 0xf, false)); }
; __device__ __forceinline__ float dpp_ror3(float v) { return __builtin_bit_cast(float, __builtin_amdgcn_update_dpp(0, __builtin_bit_cast(int, v), 0x123, 0xf, 0xf, false)); }
;     __device__ __forceinline__ void operator()(f32x4 (&acc)[2][2][4][2], const pg8::Unit& u, int wr, int wc, int fr, int fq) const {
;     ...
;                         else { const int t = fr & 3; const float* sp = stp + (size_t)((row - MP) >> 2) * 3 * CW + ch;
;                             const f32x4 b0 = *(const f32x4*)sp, b1 = *(const f32x4*)(sp + CW), b2 = *(const f32x4*)(sp + 2 * CW);
; #pragma unroll
;                             for (int j = 0; j < 4; ++j) { const float r1 = dpp_ror1(g[j]), r2 = dpp_ror2(g[j]), r3 = dpp_ror3(g[j]);
;                                 p1[j] = t >= 1 ? r1 : b2[j]; p2[j] = t >= 2 ? r2 : (t == 1 ? b2[j] : b1[j]); p3[j] = t >= 3 ? r3 : (t == 2 ? b2[j] : (t == 1 ? b1[j] : b0[j])); } }
.LBB0_982:
	s_or_b64 exec, exec, s[0:1]
	v_mov_b32_dpp v168, v67 row_ror:1 row_mask:0xf bank_mask:0xf
	v_mov_b32_dpp v169, v67 row_ror:2 row_mask:0xf bank_mask:0xf
	v_mov_b32_dpp v131, v67 row_ror:3 row_mask:0xf bank_mask:0xf
	v_cmp_lt_i32_e32 vcc, 1, v205
	s_and_saveexec_b64 s[0:1], vcc
	s_xor_b64 s[0:1], exec, s[0:1]
	s_cbranch_execz .LBB0_986
	v_cmp_gt_i32_e32 vcc, 3, v205
	s_and_saveexec_b64 s[2:3], vcc
	s_cbranch_execz .LBB0_985
	s_waitcnt vmcnt(0)
	v_mov_b32_e32 v131, v151

; __device__ __forceinline__ float dpp_ror1(float v) { return __builtin_bit_cast(float, __builtin_amdgcn_update_dpp(0, __builtin_bit_cast(int, v), 0x121, 0xf, 0xf, false)); }
; __device__ __forceinline__ float dpp_ror2(float v) { return __builtin_bit_cast(float, __builtin_amdgcn_update_dpp(0, __builtin_bit_cast(int, v), 0x122, 0xf, 0xf, false)); }
; __device__ __forceinline__ float dpp_ror3(float v) { return __builtin_bit_cast(float, __builtin_amdgcn_update_dpp(0, __builtin_bit_cast(int, v), 0x123, 0xf, 0xf, false)); }
;     __device__ __forceinline__ void operator()(f32x4 (&acc)[2][2][4][2], const pg8::Unit& u, int wr, int wc, int fr, int fq) const {
;     ...
;                         else { const int t = fr & 3; const float* sp = stp + (size_t)((row - MP) >> 2) * 3 * CW + ch;
;                             const f32x4 b0 = *(const f32x4*)sp, b1 = *(const f32x4*)(sp + CW), b2 = *(const f32x4*)(sp + 2 * CW);
; #pragma unroll
;                             for (int j = 0; j < 4; ++j) { const float r1 = dpp_ror1(g[j]), r2 = dpp_ror2(g[j]), r3 = dpp_ror3(g[j]);
;                                 p1[j] = t >= 1 ? r1 : b2[j]; p2[j] = t >= 2 ? r2 : (t == 1 ? b2[j] : b1[j]); p3[j] = t >= 3 ? r3 : (t == 2 ? b2[j] : (t == 1 ? b1[j] : b0[j])); } }
.LBB0_992:
	s_or_b64 exec, exec, s[0:1]
	v_mov_b32_dpp v170, v68 row_ror:1 row_mask:0xf bank_mask:0xf
	v_mov_b32_dpp v171, v68 row_ror:2 row_mask:0xf bank_mask:0xf
	v_mov_b32_dpp v132, v68 row_ror:3 row_mask:0xf bank_mask:0xf
	v_cmp_lt_i32_e32 vcc, 1, v205
	s_and_saveexec_b64 s[0:1], vcc
	s_xor_b64 s[0:1], exec, s[0:1]
	s_cbranch_execz .LBB0_996
	v_cmp_gt_i32_e32 vcc, 3, v205
	s_and_saveexec_b64 s[2:3], vcc
	s_cbranch_execz .LBB0_995
	s_waitcnt vmcnt(0)
	v_mov_b32_e32 v132, v152

; __device__ __forceinline__ float dpp_ror1(float v) { return __builtin_bit_cast(float, __builtin_amdgcn_update_dpp(0, __builtin_bit_cast(int, v), 0x121, 0xf, 0xf, false)); }
; __device__ __forceinline__ float dpp_ror2(float v) { return __builtin_bit_cast(float, __builtin_amdgcn_update_dpp(0, __builtin_bit_cast(int, v), 0x122, 0xf, 0xf, false)); }
; __device__ __forceinline__ float dpp_ror3(float v) { return __builtin_bit_cast(float, __builtin_amdgcn_update_dpp(0, __builtin_bit_cast(int, v), 0x123, 0xf, 0xf, false)); }
;     __device__ __forceinline__ void operator()(f32x4 (&acc)[2][2][4][2], const pg8::Unit& u, int wr, int wc, int fr, int fq) const {
;     ...
;                         else { const int t = fr & 3; const float* sp = stp + (size_t)((row - MP) >> 2) * 3 * CW + ch;
;                             const f32x4 b0 = *(const f32x4*)sp, b1 = *(const f32x4*)(sp + CW), b2 = *(const f32x4*)(sp + 2 * CW);
; #pragma unroll
;                             for (int j = 0; j < 4; ++j) { const float r1 = dpp_ror1(g[j]), r2 = dpp_ror2(g[j]), r3 = dpp_ror3(g[j]);
;                                 p1[j] = t >= 1 ? r1 : b2[j]; p2[j] = t >= 2 ? r2 : (t == 1 ? b2[j] : b1[j]); p3[j] = t >= 3 ? r3 : (t == 2 ? b2[j] : (t == 1 ? b1[j] : b0[j])); } }
.LBB0_1002:
	s_or_b64 exec, exec, s[0:1]
	v_mov_b32_dpp v173, v69 row_ror:1 row_mask:0xf bank_mask:0xf
	v_mov_b32_dpp v172, v69 row_ror:2 row_mask:0xf bank_mask:0xf
	v_mov_b32_dpp v133, v69 row_ror:3 row_mask:0xf bank_mask:0xf
	v_cmp_lt_i32_e32 vcc, 1, v205
	s_and_saveexec_b64 s[0:1], vcc
	s_xor_b64 s[0:1], exec, s[0:1]
	s_cbranch_execz .LBB0_1006
	v_cmp_gt_i32_e32 vcc, 3, v205
	s_and_saveexec_b64 s[2:3], vcc
	s_cbranch_execz .LBB0_1005
	s_waitcnt vmcnt(0)
	v_mov_b32_e32 v133, v153

; __device__ __forceinline__ float dpp_ror1(float v) { return __builtin_bit_cast(float, __builtin_amdgcn_update_dpp(0, __builtin_bit_cast(int, v), 0x121, 0xf, 0xf, false)); }
; __device__ __forceinline__ float dpp_ror2(float v) { return __builtin_bit_cast(float, __builtin_amdgcn_update_dpp(0, __builtin_bit_cast(int, v), 0x122, 0xf, 0xf, false)); }
; __device__ __forceinline__ float dpp_ror3(float v) { return __builtin_bit_cast(float, __builtin_amdgcn_update_dpp(0, __builtin_bit_cast(int, v), 0x123, 0xf, 0xf, false)); }
;     __device__ __forceinline__ void operator()(f32x4 (&acc)[2][2][4][2], const pg8::Unit& u, int wr, int wc, int fr, int fq) const {
;     ...
;                         if (prompt) { const f32x4 gp = (m == 0) ? hal[n] : acc[ai][bj][m > 0 ? m - 1 : 0][n];
; #pragma unroll
;                             for (int j = 0; j < 4; ++j) { p1[j] = dpp_ror1(fr == 15 ? gp[j] : g[j]); p2[j] = dpp_ror2(fr >= 14 ? gp[j] : g[j]); p3[j] = dpp_ror3(fr >= 13 ? gp[j] : g[j]); } }
.LBB0_1013:
	s_and_b64 vcc, exec, s[0:1]
	s_cbranch_vccz .LBB0_1015
	v_cndmask_b32_e64 v130, v66, v82, s[10:11]
	v_cndmask_b32_e64 v131, v66, v82, s[6:7]
	s_nop 0
	v_mov_b32_dpp v154, v130 row_ror:1 row_mask:0xf bank_mask:0xf
	v_cndmask_b32_e64 v130, v66, v82, s[8:9]
	s_nop 1
	v_mov_b32_dpp v146, v130 row_ror:2 row_mask:0xf bank_mask:0xf
	v_cndmask_b32_e64 v132, v67, v83, s[6:7]
	v_mov_b32_dpp v130, v131 row_ror:3 row_mask:0xf bank_mask:0xf
	v_cndmask_b32_e64 v131, v67, v83, s[10:11]
	v_cndmask_b32_e64 v133, v68, v84, s[6:7]
	s_nop 0
	v_mov_b32_dpp v155, v131 row_ror:1 row_mask:0xf bank_mask:0xf
	v_cndmask_b32_e64 v131, v67, v83, s[8:9]
	s_nop 1
	v_mov_b32_dpp v147, v131 row_ror:2 row_mask:0xf bank_mask:0xf
	v_cndmask_b32_e64 v151, v69, v85, s[6:7]
	s_nop 0
	v_mov_b32_dpp v131, v132 row_ror:3 row_mask:0xf bank_mask:0xf
	v_cndmask_b32_e64 v132, v68, v84, s[10:11]
	s_nop 1
	v_mov_b32_dpp v156, v132 row_ror:1 row_mask:0xf bank_mask:0xf
	v_cndmask_b32_e64 v132, v68, v84, s[8:9]
	s_nop 1
	v_mov_b32_dpp v148, v132 row_ror:2 row_mask:0xf bank_mask:0xf
	s_nop 1
	v_mov_b32_dpp v132, v133 row_ror:3 row_mask:0xf bank_mask:0xf
	v_cndmask_b32_e64 v133, v69, v85, s[10:11]
	s_nop 1
	v_mov_b32_dpp v157, v133 row_ror:1 row_mask:0xf bank_mask:0xf
	v_cndmask_b32_e64 v133, v69, v85, s[8:9]
	s_nop 1
	v_mov_b32_dpp v149, v133 row_ror:2 row_mask:0xf bank_mask:0xf
	s_nop 1
	v_mov_b32_dpp v133, v151 row_ror:3 row_mask:0xf bank_mask:0xf

; __device__ __forceinline__ float dpp_ror1(float v) { return __builtin_bit_cast(float, __builtin_amdgcn_update_dpp(0, __builtin_bit_cast(int, v), 0x121, 0xf, 0xf, false)); }
; __device__ __forceinline__ float dpp_ror2(float v) { return __builtin_bit_cast(float, __builtin_amdgcn_update_dpp(0, __builtin_bit_cast(int, v), 0x122, 0xf, 0xf, false)); }
; __device__ __forceinline__ float dpp_ror3(float v) { return __builtin_bit_cast(float, __builtin_amdgcn_update_dpp(0, __builtin_bit_cast(int, v), 0x123, 0xf, 0xf, false)); }
;     __device__ __forceinline__ void operator()(f32x4 (&acc)[2][2][4][2], const pg8::Unit& u, int wr, int wc, int fr, int fq) const {
;     ...
;                 for (int n = 0; n < 2; ++n) { const int ch = ch0 + bj * 128 + 4 * n;
;                     const f32x4 w0 = *(const f32x4*)(cw + ch), w1 = *(const f32x4*)(cw + CW + ch), w2 = *(const f32x4*)(cw + 2 * CW + ch), w3 = *(const f32x4*)(cw + 3 * CW + ch), bb = *(const f32x4*)(cb + ch);
; #pragma unroll
;                     for (int m = 0; m < 4; ++m) { const int row = row0 + ai * 128 + m * 16; const f32x4 g = acc[ai][bj][m][n]; f32x4 p1, p2, p3;
;                         if (prompt) { const f32x4 gp = (m == 0) ? hal[n] : acc[ai][bj][m > 0 ? m - 1 : 0][n];
; #pragma unroll
;                             for (int j = 0; j < 4; ++j) { p1[j] = dpp_ror1(fr == 15 ? gp[j] : g[j]); p2[j] = dpp_ror2(fr >= 14 ? gp[j] : g[j]); p3[j] = dpp_ror3(fr >= 13 ? gp[j] : g[j]); } }
;                         else { const int t = fr & 3; const float* sp = stp + (size_t)((row - MP) >> 2) * 3 * CW + ch;
;                             const f32x4 b0 = *(const f32x4*)sp, b1 = *(const f32x4*)(sp + CW), b2 = *(const f32x4*)(sp + 2 * CW);
; #pragma unroll
;                             for (int j = 0; j < 4; ++j) { const float r1 = dpp_ror1(g[j]), r2 = dpp_ror2(g[j]), r3 = dpp_ror3(g[j]);
;                                 p1[j] = t >= 1 ? r1 : b2[j]; p2[j] = t >= 2 ? r2 : (t == 1 ? b2[j] : b1[j]); p3[j] = t >= 3 ? r3 : (t == 2 ? b2[j] : (t == 1 ? b1[j] : b0[j])); } }
.LBB0_1017:
	s_or_b64 exec, exec, s[2:3]
	global_load_dwordx4 v[138:141], v[210:211], off
	global_load_dwordx4 v[150:153], v[212:213], off
	global_load_dwordx4 v[134:137], v[214:215], off
	global_load_dwordx4 v[146:149], v[216:217], off
	global_load_dwordx4 v[142:145], v[218:219], off
	s_mov_b64 s[2:3], -1
	s_and_b64 vcc, exec, s[18:19]
	v_mov_b32_e32 v228, v62
	v_mov_b32_e32 v226, v63
	v_mov_b32_e32 v224, v64
	v_mov_b32_e32 v222, v65
	s_cbranch_vccnz .LBB0_1059
	v_add_u32_e32 v155, 0xffffe080, v202
	v_ashrrev_i32_e32 v155, 2, v155
	v_lshl_add_u32 v155, v155, 1, v155
	v_mad_i64_i32 v[156:157], s[2:3], v155, s47, 0
	v_lshl_add_u64 v[156:157], v[156:157], 2, v[208:209]
	v_lshl_add_u64 v[162:163], v[156:157], 0, s[24:25]
	s_lshl_b32 s2, s27, 2
	s_mov_b32 s3, s25
	global_load_dwordx4 v[170:173], v[156:157], off
	s_nop 0
	global_load_dwordx4 v[162:165], v[162:163], off
	v_lshl_add_u64 v[156:157], v[156:157], 0, s[2:3]
	global_load_dwordx4 v[166:169], v[156:157], off
	v_mov_b32_dpp v222, v62 row_ror:1 row_mask:0xf bank_mask:0xf
	v_mov_b32_dpp v223, v62 row_ror:2 row_mask:0xf bank_mask:0xf
	v_mov_b32_dpp v154, v62 row_ror:3 row_mask:0xf bank_mask:0xf
	v_cmp_lt_i32_e32 vcc, 1, v205
	s_and_saveexec_b64 s[2:3], vcc
	s_xor_b64 s[2:3], exec, s[2:3]
	s_cbranch_execz .LBB0_1022
	v_cmp_gt_i32_e32 vcc, 3, v205
	s_and_saveexec_b64 s[20:21], vcc
	s_cbranch_execz .LBB0_1021
	s_waitcnt vmcnt(0)
	v_mov_b32_e32 v154, v166

; __device__ __forceinline__ float dpp_ror1(float v) { return __builtin_bit_cast(float, __builtin_amdgcn_update_dpp(0, __builtin_bit_cast(int, v), 0x121, 0xf, 0xf, false)); }
; __device__ __forceinline__ float dpp_ror2(float v) { return __builtin_bit_cast(float, __builtin_amdgcn_update_dpp(0, __builtin_bit_cast(int, v), 0x122, 0xf, 0xf, false)); }
; __device__ __forceinline__ float dpp_ror3(float v) { return __builtin_bit_cast(float, __builtin_amdgcn_update_dpp(0, __builtin_bit_cast(int, v), 0x123, 0xf, 0xf, false)); }
;     __device__ __forceinline__ void operator()(f32x4 (&acc)[2][2][4][2], const pg8::Unit& u, int wr, int wc, int fr, int fq) const {
;     ...
;                         else { const int t = fr & 3; const float* sp = stp + (size_t)((row - MP) >> 2) * 3 * CW + ch;
;                             const f32x4 b0 = *(const f32x4*)sp, b1 = *(const f32x4*)(sp + CW), b2 = *(const f32x4*)(sp + 2 * CW);
; #pragma unroll
;                             for (int j = 0; j < 4; ++j) { const float r1 = dpp_ror1(g[j]), r2 = dpp_ror2(g[j]), r3 = dpp_ror3(g[j]);
;                                 p1[j] = t >= 1 ? r1 : b2[j]; p2[j] = t >= 2 ? r2 : (t == 1 ? b2[j] : b1[j]); p3[j] = t >= 3 ? r3 : (t == 2 ? b2[j] : (t == 1 ? b1[j] : b0[j])); } }
.LBB0_1028:
	s_or_b64 exec, exec, s[2:3]
	v_mov_b32_dpp v224, v63 row_ror:1 row_mask:0xf bank_mask:0xf
	v_mov_b32_dpp v225, v63 row_ror:2 row_mask:0xf bank_mask:0xf
	v_mov_b32_dpp v155, v63 row_ror:3 row_mask:0xf bank_mask:0xf
	v_cmp_lt_i32_e32 vcc, 1, v205
	s_and_saveexec_b64 s[2:3], vcc
	s_xor_b64 s[2:3], exec, s[2:3]
	s_cbranch_execz .LBB0_1032
	v_cmp_gt_i32_e32 vcc, 3, v205
	s_and_saveexec_b64 s[20:21], vcc
	s_cbranch_execz .LBB0_1031
	s_waitcnt vmcnt(0)
	v_mov_b32_e32 v155, v167

; __device__ __forceinline__ float dpp_ror1(float v) { return __builtin_bit_cast(float, __builtin_amdgcn_update_dpp(0, __builtin_bit_cast(int, v), 0x121, 0xf, 0xf, false)); }
; __device__ __forceinline__ float dpp_ror2(float v) { return __builtin_bit_cast(float, __builtin_amdgcn_update_dpp(0, __builtin_bit_cast(int, v), 0x122, 0xf, 0xf, false)); }
; __device__ __forceinline__ float dpp_ror3(float v) { return __builtin_bit_cast(float, __builtin_amdgcn_update_dpp(0, __builtin_bit_cast(int, v), 0x123, 0xf, 0xf, false)); }
;     __device__ __forceinline__ void operator()(f32x4 (&acc)[2][2][4][2], const pg8::Unit& u, int wr, int wc, int fr, int fq) const {
;     ...
;                         else { const int t = fr & 3; const float* sp = stp + (size_t)((row - MP) >> 2) * 3 * CW + ch;
;                             const f32x4 b0 = *(const f32x4*)sp, b1 = *(const f32x4*)(sp + CW), b2 = *(const f32x4*)(sp + 2 * CW);
; #pragma unroll
;                             for (int j = 0; j < 4; ++j) { const float r1 = dpp_ror1(g[j]), r2 = dpp_ror2(g[j]), r3 = dpp_ror3(g[j]);
;                                 p1[j] = t >= 1 ? r1 : b2[j]; p2[j] = t >= 2 ? r2 : (t == 1 ? b2[j] : b1[j]); p3[j] = t >= 3 ? r3 : (t == 2 ? b2[j] : (t == 1 ? b1[j] : b0[j])); } }
.LBB0_1038:
	s_or_b64 exec, exec, s[2:3]
	v_mov_b32_dpp v226, v64 row_ror:1 row_mask:0xf bank_mask:0xf
	v_mov_b32_dpp v227, v64 row_ror:2 row_mask:0xf bank_mask:0xf
	v_mov_b32_dpp v156, v64 row_ror:3 row_mask:0xf bank_mask:0xf
	v_cmp_lt_i32_e32 vcc, 1, v205
	s_and_saveexec_b64 s[2:3], vcc
	s_xor_b64 s[2:3], exec, s[2:3]
	s_cbranch_execz .LBB0_1042
	v_cmp_gt_i32_e32 vcc, 3, v205
	s_and_saveexec_b64 s[20:21], vcc
	s_cbranch_execz .LBB0_1041
	s_waitcnt vmcnt(0)
	v_mov_b32_e32 v156, v168

; __device__ __forceinline__ float dpp_ror1(float v) { return __builtin_bit_cast(float, __builtin_amdgcn_update_dpp(0, __builtin_bit_cast(int, v), 0x121, 0xf, 0xf, false)); }
; __device__ __forceinline__ float dpp_ror2(float v) { return __builtin_bit_cast(float, __builtin_amdgcn_update_dpp(0, __builtin_bit_cast(int, v), 0x122, 0xf, 0xf, false)); }
; __device__ __forceinline__ float dpp_ror3(float v) { return __builtin_bit_cast(float, __builtin_amdgcn_update_dpp(0, __builtin_bit_cast(int, v), 0x123, 0xf, 0xf, false)); }
;     __device__ __forceinline__ void operator()(f32x4 (&acc)[2][2][4][2], const pg8::Unit& u, int wr, int wc, int fr, int fq) const {
;     ...
;                         else { const int t = fr & 3; const float* sp = stp + (size_t)((row - MP) >> 2) * 3 * CW + ch;
;                             const f32x4 b0 = *(const f32x4*)sp, b1 = *(const f32x4*)(sp + CW), b2 = *(const f32x4*)(sp + 2 * CW);
; #pragma unroll
;                             for (int j = 0; j < 4; ++j) { const float r1 = dpp_ror1(g[j]), r2 = dpp_ror2(g[j]), r3 = dpp_ror3(g[j]);
;                                 p1[j] = t >= 1 ? r1 : b2[j]; p2[j] = t >= 2 ? r2 : (t == 1 ? b2[j] : b1[j]); p3[j] = t >= 3 ? r3 : (t == 2 ? b2[j] : (t == 1 ? b1[j] : b0[j])); } }
.LBB0_1048:
	s_or_b64 exec, exec, s[2:3]
	v_mov_b32_dpp v229, v65 row_ror:1 row_mask:0xf bank_mask:0xf
	v_mov_b32_dpp v228, v65 row_ror:2 row_mask:0xf bank_mask:0xf
	v_mov_b32_dpp v157, v65 row_ror:3 row_mask:0xf bank_mask:0xf
	v_cmp_lt_i32_e32 vcc, 1, v205
	s_and_saveexec_b64 s[2:3], vcc
	s_xor_b64 s[2:3], exec, s[2:3]
	s_cbranch_execz .LBB0_1052
	v_cmp_gt_i32_e32 vcc, 3, v205
	s_and_saveexec_b64 s[20:21], vcc
	s_cbranch_execz .LBB0_1051
	s_waitcnt vmcnt(0)
	v_mov_b32_e32 v157, v169

; __device__ __forceinline__ unsigned cvt_pk_bf16(float lo, float hi) { unsigned r; asm("v_cvt_pk_bf16_f32 %0, %1, %2" : "=v"(r) : "v"(lo), "v"(hi)); return r; }
; __device__ __forceinline__ float siluf_(float x) { return x * sigmoidf_(x); }
; __device__ __forceinline__ float dpp_ror1(float v) { return __builtin_bit_cast(float, __builtin_amdgcn_update_dpp(0, __builtin_bit_cast(int, v), 0x121, 0xf, 0xf, false)); }
;     __device__ __forceinline__ void operator()(f32x4 (&acc)[2][2][4][2], const pg8::Unit& u, int wr, int wc, int fr, int fq) const {
;     ...
;                 for (int n = 0; n < 2; ++n) { const int ch = ch0 + bj * 128 + 4 * n;
;                     const f32x4 w0 = *(const f32x4*)(cw + ch), w1 = *(const f32x4*)(cw + CW + ch), w2 = *(const f32x4*)(cw + 2 * CW + ch), w3 = *(const f32x4*)(cw + 3 * CW + ch), bb = *(const f32x4*)(cb + ch);
; #pragma unroll
;                     for (int m = 0; m < 4; ++m) { const int row = row0 + ai * 128 + m * 16; const f32x4 g = acc[ai][bj][m][n]; f32x4 p1, p2, p3;
;                         if (prompt) { const f32x4 gp = (m == 0) ? hal[n] : acc[ai][bj][m > 0 ? m - 1 : 0][n];
; #pragma unroll
;                             for (int j = 0; j < 4; ++j) { p1[j] = dpp_ror1(fr == 15 ? gp[j] : g[j]); p2[j] = dpp_ror2(fr >= 14 ? gp[j] : g[j]); p3[j] = dpp_ror3(fr >= 13 ? gp[j] : g[j]); } }
;                         else { const int t = fr & 3; const float* sp = stp + (size_t)((row - MP) >> 2) * 3 * CW + ch;
;                             const f32x4 b0 = *(const f32x4*)sp, b1 = *(const f32x4*)(sp + CW), b2 = *(const f32x4*)(sp + 2 * CW);
; #pragma unroll
;                             for (int j = 0; j < 4; ++j) { const float r1 = dpp_ror1(g[j]), r2 = dpp_ror2(g[j]), r3 = dpp_ror3(g[j]);
;                                 p1[j] = t >= 1 ? r1 : b2[j]; p2[j] = t >= 2 ? r2 : (t == 1 ? b2[j] : b1[j]); p3[j] = t >= 3 ? r3 : (t == 2 ? b2[j] : (t == 1 ? b1[j] : b0[j])); } }
;                         float o[4];
; #pragma unroll
;                         for (int j = 0; j < 4; ++j) { const float y = bb[j] + w0[j] * p3[j] + w1[j] * p2[j] + w2[j] * p1[j] + w3[j] * g[j]; o[j] = is_rg ? y : siluf_(y); }
;                         u32x2 w; w.x = cvt_pk_bf16(o[0], o[1]); w.y = cvt_pk_bf16(o[2], o[3]);
;                         *(u32x2*)(dst + (size_t)row * ld + bj * 128 + 4 * n) = w; }
.LBB0_1059:
	s_and_b64 vcc, exec, s[2:3]
	s_cbranch_vccz .LBB0_1061
	s_waitcnt lgkmcnt(0)
	v_cndmask_b32_e64 v154, v62, v158, s[10:11]
	v_cndmask_b32_e64 v155, v62, v158, s[6:7]
	s_nop 0
	v_mov_b32_dpp v170, v154 row_ror:1 row_mask:0xf bank_mask:0xf
	v_cndmask_b32_e64 v154, v62, v158, s[8:9]
	s_nop 1
	v_mov_b32_dpp v162, v154 row_ror:2 row_mask:0xf bank_mask:0xf
	v_cndmask_b32_e64 v156, v63, v159, s[6:7]
	v_mov_b32_dpp v154, v155 row_ror:3 row_mask:0xf bank_mask:0xf
	v_cndmask_b32_e64 v155, v63, v159, s[10:11]
	v_cndmask_b32_e64 v157, v64, v160, s[6:7]
	s_nop 0
	v_mov_b32_dpp v171, v155 row_ror:1 row_mask:0xf bank_mask:0xf
	v_cndmask_b32_e64 v155, v63, v159, s[8:9]
	s_nop 1
	v_mov_b32_dpp v163, v155 row_ror:2 row_mask:0xf bank_mask:0xf
	v_cndmask_b32_e64 v158, v65, v161, s[6:7]
	s_nop 0
	v_mov_b32_dpp v155, v156 row_ror:3 row_mask:0xf bank_mask:0xf
	v_cndmask_b32_e64 v156, v64, v160, s[10:11]
	s_nop 1
	v_mov_b32_dpp v172, v156 row_ror:1 row_mask:0xf bank_mask:0xf
	v_cndmask_b32_e64 v156, v64, v160, s[8:9]
	s_nop 1
	v_mov_b32_dpp v164, v156 row_ror:2 row_mask:0xf bank_mask:0xf
	s_nop 1
	v_mov_b32_dpp v156, v157 row_ror:3 row_mask:0xf bank_mask:0xf
	v_cndmask_b32_e64 v157, v65, v161, s[10:11]
	s_nop 1
	v_mov_b32_dpp v173, v157 row_ror:1 row_mask:0xf bank_mask:0xf
	v_cndmask_b32_e64 v157, v65, v161, s[8:9]
	s_nop 1
	v_mov_b32_dpp v165, v157 row_ror:2 row_mask:0xf bank_mask:0xf
	s_nop 1
	v_mov_b32_dpp v157, v158 row_ror:3 row_mask:0xf bank_mask:0xf
.LBB0_1061:
	s_waitcnt vmcnt(0)
	v_mov_b32_e32 v166, v150
	v_mov_b32_e32 v167, v138
	s_waitcnt lgkmcnt(0)
	v_mov_b32_e32 v158, v162
	v_mov_b32_e32 v159, v154
	v_pk_mul_f32 v[158:159], v[166:167], v[158:159]
	v_mov_b32_e32 v168, v146
	v_add_f32_e32 v138, v142, v159
	v_mov_b32_e32 v169, v134
	v_mov_b32_e32 v229, v170
	v_add_f32_e32 v138, v158, v138
	v_pk_mul_f32 v[158:159], v[168:169], v[228:229]
	v_mov_b32_e32 v154, v163
	v_add_f32_e32 v134, v159, v138
	v_add_f32_e32 v158, v158, v134
	v_mul_f32_e32 v134, 0xbfb8aa3b, v158
	v_exp_f32_e32 v134, v134
	v_mov_b32_e32 v138, v151
	v_pk_mul_f32 v[150:151], v[138:139], v[154:155]
	v_mov_b32_e32 v227, v171
	v_add_f32_e32 v134, 1.0, v134
	v_rcp_f32_e32 v159, v134
	v_add_f32_e32 v134, v143, v151
	v_add_f32_e32 v150, v150, v134
	v_mov_b32_e32 v134, v147
	v_pk_mul_f32 v[146:147], v[134:135], v[226:227]
	v_mov_b32_e32 v162, v152
	v_add_f32_e32 v147, v147, v150
	v_add_f32_e32 v150, v146, v147
	v_mul_f32_e32 v146, 0xbfb8aa3b, v150
	v_exp_f32_e32 v146, v146
	v_mul_f32_e32 v147, v158, v159
	v_cndmask_b32_e64 v151, v147, v158, s[4:5]
	v_mov_b32_e32 v163, v140
	v_add_f32_e32 v146, 1.0, v146
	v_rcp_f32_e32 v154, v146
	v_mov_b32_e32 v146, v164
	v_mov_b32_e32 v147, v156
	v_pk_mul_f32 v[146:147], v[162:163], v[146:147]
	v_mov_b32_e32 v170, v148
	v_add_f32_e32 v140, v144, v147
	v_mov_b32_e32 v171, v136
	v_mov_b32_e32 v225, v172
	v_add_f32_e32 v140, v146, v140
	v_pk_mul_f32 v[146:147], v[170:171], v[224:225]
	v_mov_b32_e32 v156, v165
	v_add_f32_e32 v136, v147, v140
	v_add_f32_e32 v148, v146, v136
	v_mov_b32_e32 v140, v153
	v_mul_f32_e32 v136, 0xbfb8aa3b, v148
	v_pk_mul_f32 v[146:147], v[140:141], v[156:157]
	v_exp_f32_e32 v152, v136
	v_add_f32_e32 v136, v145, v147
	v_add_f32_e32 v153, v146, v136
	v_mov_b32_e32 v136, v149
	v_mov_b32_e32 v223, v173
	v_pk_mul_f32 v[146:147], v[136:137], v[222:223]
	v_add_f32_e32 v152, 1.0, v152
	v_add_f32_e32 v147, v147, v153
	v_add_f32_e32 v146, v146, v147
	v_mul_f32_e32 v147, 0xbfb8aa3b, v146
	v_exp_f32_e32 v147, v147
	v_rcp_f32_e32 v152, v152
	v_mul_f32_e32 v149, v150, v154
	v_cndmask_b32_e64 v149, v149, v150, s[4:5]
	v_add_f32_e32 v147, 1.0, v147
	v_rcp_f32_e32 v147, v147
	v_mul_f32_e32 v150, v148, v152
	v_cndmask_b32_e64 v148, v150, v148, s[4:5]
	s_mov_b64 s[2:3], -1
	v_mul_f32_e32 v147, v146, v147
	v_cndmask_b32_e64 v147, v147, v146, s[4:5]
	v_cvt_pk_bf16_f32 v146, v151, v149
	v_cvt_pk_bf16_f32 v147, v148, v147
	v_lshlrev_b64 v[148:149], v182, v[194:195]
	v_lshl_add_u64 v[222:223], v[148:149], 1, v[220:221]
	s_and_b64 vcc, exec, s[18:19]
	v_mov_b32_e32 v172, v46
	v_mov_b32_e32 v164, v47
	v_mov_b32_e32 v156, v48
	v_mov_b32_e32 v154, v49
	v_mov_b32_e32 v70, v146
	v_mov_b32_e32 v71, v147
	s_cbranch_vccnz .LBB0_1103
	v_add_u32_e32 v147, 0xffffe090, v202
	v_ashrrev_i32_e32 v147, 2, v147
	v_lshl_add_u32 v147, v147, 1, v147
	v_mad_i64_i32 v[148:149], s[2:3], v147, s47, 0
	v_lshl_add_u64 v[148:149], v[148:149], 2, v[208:209]
	v_lshl_add_u64 v[150:151], v[148:149], 0, s[24:25]
	s_lshl_b32 s2, s27, 2
	s_mov_b32 s3, s25
	global_load_dwordx4 v[158:161], v[148:149], off
	s_nop 0
	global_load_dwordx4 v[150:153], v[150:151], off
	v_lshl_add_u64 v[148:149], v[148:149], 0, s[2:3]
	global_load_dwordx4 v[154:157], v[148:149], off
	v_mov_b32_dpp v164, v46 row_ror:1 row_mask:0xf bank_mask:0xf
	v_mov_b32_dpp v165, v46 row_ror:2 row_mask:0xf bank_mask:0xf
	v_mov_b32_dpp v146, v46 row_ror:3 row_mask:0xf bank_mask:0xf
	v_cmp_lt_i32_e32 vcc, 1, v205
	s_and_saveexec_b64 s[2:3], vcc
	s_xor_b64 s[2:3], exec, s[2:3]
	s_cbranch_execz .LBB0_1066
	v_cmp_gt_i32_e32 vcc, 3, v205
	s_and_saveexec_b64 s[20:21], vcc
	s_cbranch_execz .LBB0_1065
	s_waitcnt vmcnt(0)
	v_mov_b32_e32 v146, v154

; __device__ __forceinline__ float dpp_ror1(float v) { return __builtin_bit_cast(float, __builtin_amdgcn_update_dpp(0, __builtin_bit_cast(int, v), 0x121, 0xf, 0xf, false)); }
; __device__ __forceinline__ float dpp_ror2(float v) { return __builtin_bit_cast(float, __builtin_amdgcn_update_dpp(0, __builtin_bit_cast(int, v), 0x122, 0xf, 0xf, false)); }
; __device__ __forceinline__ float dpp_ror3(float v) { return __builtin_bit_cast(float, __builtin_amdgcn_update_dpp(0, __builtin_bit_cast(int, v), 0x123, 0xf, 0xf, false)); }
;     __device__ __forceinline__ void operator()(f32x4 (&acc)[2][2][4][2], const pg8::Unit& u, int wr, int wc, int fr, int fq) const {
;     ...
;                         else { const int t = fr & 3; const float* sp = stp + (size_t)((row - MP) >> 2) * 3 * CW + ch;
;                             const f32x4 b0 = *(const f32x4*)sp, b1 = *(const f32x4*)(sp + CW), b2 = *(const f32x4*)(sp + 2 * CW);
; #pragma unroll
;                             for (int j = 0; j < 4; ++j) { const float r1 = dpp_ror1(g[j]), r2 = dpp_ror2(g[j]), r3 = dpp_ror3(g[j]);
;                                 p1[j] = t >= 1 ? r1 : b2[j]; p2[j] = t >= 2 ? r2 : (t == 1 ? b2[j] : b1[j]); p3[j] = t >= 3 ? r3 : (t == 2 ? b2[j] : (t == 1 ? b1[j] : b0[j])); } }
.LBB0_1072:
	s_or_b64 exec, exec, s[2:3]
	v_mov_b32_dpp v172, v47 row_ror:1 row_mask:0xf bank_mask:0xf
	v_mov_b32_dpp v173, v47 row_ror:2 row_mask:0xf bank_mask:0xf
	v_mov_b32_dpp v147, v47 row_ror:3 row_mask:0xf bank_mask:0xf
	v_cmp_lt_i32_e32 vcc, 1, v205
	s_and_saveexec_b64 s[2:3], vcc
	s_xor_b64 s[2:3], exec, s[2:3]
	s_cbranch_execz .LBB0_1076
	v_cmp_gt_i32_e32 vcc, 3, v205
	s_and_saveexec_b64 s[20:21], vcc
	s_cbranch_execz .LBB0_1075
	s_waitcnt vmcnt(0)
	v_mov_b32_e32 v147, v155

; __device__ __forceinline__ float dpp_ror1(float v) { return __builtin_bit_cast(float, __builtin_amdgcn_update_dpp(0, __builtin_bit_cast(int, v), 0x121, 0xf, 0xf, false)); }
; __device__ __forceinline__ float dpp_ror2(float v) { return __builtin_bit_cast(float, __builtin_amdgcn_update_dpp(0, __builtin_bit_cast(int, v), 0x122, 0xf, 0xf, false)); }
; __device__ __forceinline__ float dpp_ror3(float v) { return __builtin_bit_cast(float, __builtin_amdgcn_update_dpp(0, __builtin_bit_cast(int, v), 0x123, 0xf, 0xf, false)); }
;     __device__ __forceinline__ void operator()(f32x4 (&acc)[2][2][4][2], const pg8::Unit& u, int wr, int wc, int fr, int fq) const {
;     ...
;                         else { const int t = fr & 3; const float* sp = stp + (size_t)((row - MP) >> 2) * 3 * CW + ch;
;                             const f32x4 b0 = *(const f32x4*)sp, b1 = *(const f32x4*)(sp + CW), b2 = *(const f32x4*)(sp + 2 * CW);
; #pragma unroll
;                             for (int j = 0; j < 4; ++j) { const float r1 = dpp_ror1(g[j]), r2 = dpp_ror2(g[j]), r3 = dpp_ror3(g[j]);
;                                 p1[j] = t >= 1 ? r1 : b2[j]; p2[j] = t >= 2 ? r2 : (t == 1 ? b2[j] : b1[j]); p3[j] = t >= 3 ? r3 : (t == 2 ? b2[j] : (t == 1 ? b1[j] : b0[j])); } }
.LBB0_1082:
	s_or_b64 exec, exec, s[2:3]
	v_mov_b32_dpp v224, v48 row_ror:1 row_mask:0xf bank_mask:0xf
	v_mov_b32_dpp v225, v48 row_ror:2 row_mask:0xf bank_mask:0xf
	v_mov_b32_dpp v148, v48 row_ror:3 row_mask:0xf bank_mask:0xf
	v_cmp_lt_i32_e32 vcc, 1, v205
	s_and_saveexec_b64 s[2:3], vcc
	s_xor_b64 s[2:3], exec, s[2:3]
	s_cbranch_execz .LBB0_1086
	v_cmp_gt_i32_e32 vcc, 3, v205
	s_and_saveexec_b64 s[20:21], vcc
	s_cbranch_execz .LBB0_1085
	s_waitcnt vmcnt(0)
	v_mov_b32_e32 v148, v156

; __device__ __forceinline__ float dpp_ror1(float v) { return __builtin_bit_cast(float, __builtin_amdgcn_update_dpp(0, __builtin_bit_cast(int, v), 0x121, 0xf, 0xf, false)); }
; __device__ __forceinline__ float dpp_ror2(float v) { return __builtin_bit_cast(float, __builtin_amdgcn_update_dpp(0, __builtin_bit_cast(int, v), 0x122, 0xf, 0xf, false)); }
; __device__ __forceinline__ float dpp_ror3(float v) { return __builtin_bit_cast(float, __builtin_amdgcn_update_dpp(0, __builtin_bit_cast(int, v), 0x123, 0xf, 0xf, false)); }
;     __device__ __forceinline__ void operator()(f32x4 (&acc)[2][2][4][2], const pg8::Unit& u, int wr, int wc, int fr, int fq) const {
;     ...
;                         else { const int t = fr & 3; const float* sp = stp + (size_t)((row - MP) >> 2) * 3 * CW + ch;
;                             const f32x4 b0 = *(const f32x4*)sp, b1 = *(const f32x4*)(sp + CW), b2 = *(const f32x4*)(sp + 2 * CW);
; #pragma unroll
;                             for (int j = 0; j < 4; ++j) { const float r1 = dpp_ror1(g[j]), r2 = dpp_ror2(g[j]), r3 = dpp_ror3(g[j]);
;                                 p1[j] = t >= 1 ? r1 : b2[j]; p2[j] = t >= 2 ? r2 : (t == 1 ? b2[j] : b1[j]); p3[j] = t >= 3 ? r3 : (t == 2 ? b2[j] : (t == 1 ? b1[j] : b0[j])); } }
.LBB0_1092:
	s_or_b64 exec, exec, s[2:3]
	v_mov_b32_dpp v227, v49 row_ror:1 row_mask:0xf bank_mask:0xf
	v_mov_b32_dpp v226, v49 row_ror:2 row_mask:0xf bank_mask:0xf
	v_mov_b32_dpp v149, v49 row_ror:3 row_mask:0xf bank_mask:0xf
	v_cmp_lt_i32_e32 vcc, 1, v205
	s_and_saveexec_b64 s[2:3], vcc
	s_xor_b64 s[2:3], exec, s[2:3]
	s_cbranch_execz .LBB0_1096
	v_cmp_gt_i32_e32 vcc, 3, v205
	s_and_saveexec_b64 s[20:21], vcc
	s_cbranch_execz .LBB0_1095
	s_waitcnt vmcnt(0)
	v_mov_b32_e32 v149, v157

; __device__ __forceinline__ unsigned cvt_pk_bf16(float lo, float hi) { unsigned r; asm("v_cvt_pk_bf16_f32 %0, %1, %2" : "=v"(r) : "v"(lo), "v"(hi)); return r; }
; __device__ __forceinline__ float siluf_(float x) { return x * sigmoidf_(x); }
; __device__ __forceinline__ float dpp_ror1(float v) { return __builtin_bit_cast(float, __builtin_amdgcn_update_dpp(0, __builtin_bit_cast(int, v), 0x121, 0xf, 0xf, false)); }
;     __device__ __forceinline__ void operator()(f32x4 (&acc)[2][2][4][2], const pg8::Unit& u, int wr, int wc, int fr, int fq) const {
;     ...
;                 for (int n = 0; n < 2; ++n) { const int ch = ch0 + bj * 128 + 4 * n;
;                     const f32x4 w0 = *(const f32x4*)(cw + ch), w1 = *(const f32x4*)(cw + CW + ch), w2 = *(const f32x4*)(cw + 2 * CW + ch), w3 = *(const f32x4*)(cw + 3 * CW + ch), bb = *(const f32x4*)(cb + ch);
; #pragma unroll
;                     for (int m = 0; m < 4; ++m) { const int row = row0 + ai * 128 + m * 16; const f32x4 g = acc[ai][bj][m][n]; f32x4 p1, p2, p3;
;                         if (prompt) { const f32x4 gp = (m == 0) ? hal[n] : acc[ai][bj][m > 0 ? m - 1 : 0][n];
; #pragma unroll
;                             for (int j = 0; j < 4; ++j) { p1[j] = dpp_ror1(fr == 15 ? gp[j] : g[j]); p2[j] = dpp_ror2(fr >= 14 ? gp[j] : g[j]); p3[j] = dpp_ror3(fr >= 13 ? gp[j] : g[j]); } }
;                         else { const int t = fr & 3; const float* sp = stp + (size_t)((row - MP) >> 2) * 3 * CW + ch;
;                             const f32x4 b0 = *(const f32x4*)sp, b1 = *(const f32x4*)(sp + CW), b2 = *(const f32x4*)(sp + 2 * CW);
; #pragma unroll
;                             for (int j = 0; j < 4; ++j) { const float r1 = dpp_ror1(g[j]), r2 = dpp_ror2(g[j]), r3 = dpp_ror3(g[j]);
;                                 p1[j] = t >= 1 ? r1 : b2[j]; p2[j] = t >= 2 ? r2 : (t == 1 ? b2[j] : b1[j]); p3[j] = t >= 3 ? r3 : (t == 2 ? b2[j] : (t == 1 ? b1[j] : b0[j])); } }
;                         float o[4];
; #pragma unroll
;                         for (int j = 0; j < 4; ++j) { const float y = bb[j] + w0[j] * p3[j] + w1[j] * p2[j] + w2[j] * p1[j] + w3[j] * g[j]; o[j] = is_rg ? y : siluf_(y); }
;                         u32x2 w; w.x = cvt_pk_bf16(o[0], o[1]); w.y = cvt_pk_bf16(o[2], o[3]);
;                         *(u32x2*)(dst + (size_t)row * ld + bj * 128 + 4 * n) = w; }
.LBB0_1103:
	s_and_b64 vcc, exec, s[2:3]
	s_cbranch_vccz .LBB0_1105
	v_cndmask_b32_e64 v146, v46, v62, s[10:11]
	v_cndmask_b32_e64 v147, v46, v62, s[6:7]
	s_nop 0
	v_mov_b32_dpp v158, v146 row_ror:1 row_mask:0xf bank_mask:0xf
	v_cndmask_b32_e64 v146, v46, v62, s[8:9]
	s_nop 1
	v_mov_b32_dpp v150, v146 row_ror:2 row_mask:0xf bank_mask:0xf
	v_cndmask_b32_e64 v148, v47, v63, s[6:7]
	v_mov_b32_dpp v146, v147 row_ror:3 row_mask:0xf bank_mask:0xf
	v_cndmask_b32_e64 v147, v47, v63, s[10:11]
	v_cndmask_b32_e64 v149, v48, v64, s[6:7]
	s_nop 0
	v_mov_b32_dpp v159, v147 row_ror:1 row_mask:0xf bank_mask:0xf
	v_cndmask_b32_e64 v147, v47, v63, s[8:9]
	s_nop 1
	v_mov_b32_dpp v151, v147 row_ror:2 row_mask:0xf bank_mask:0xf
	v_cndmask_b32_e64 v155, v49, v65, s[6:7]
	s_nop 0
	v_mov_b32_dpp v147, v148 row_ror:3 row_mask:0xf bank_mask:0xf
	v_cndmask_b32_e64 v148, v48, v64, s[10:11]
	s_nop 1
	v_mov_b32_dpp v160, v148 row_ror:1 row_mask:0xf bank_mask:0xf
	v_cndmask_b32_e64 v148, v48, v64, s[8:9]
	s_nop 1
	v_mov_b32_dpp v152, v148 row_ror:2 row_mask:0xf bank_mask:0xf
	s_nop 1
	v_mov_b32_dpp v148, v149 row_ror:3 row_mask:0xf bank_mask:0xf
	v_cndmask_b32_e64 v149, v49, v65, s[10:11]
	s_nop 1
	v_mov_b32_dpp v161, v149 row_ror:1 row_mask:0xf bank_mask:0xf
	v_cndmask_b32_e64 v149, v49, v65, s[8:9]
	s_nop 1
	v_mov_b32_dpp v153, v149 row_ror:2 row_mask:0xf bank_mask:0xf
	s_nop 1
	v_mov_b32_dpp v149, v155 row_ror:3 row_mask:0xf bank_mask:0xf
.LBB0_1105:
	v_mov_b32_e32 v224, v150
	v_mov_b32_e32 v225, v146
	v_pk_mul_f32 v[224:225], v[166:167], v[224:225]
	v_mov_b32_e32 v173, v158
	v_add_f32_e32 v146, v142, v225
	v_add_f32_e32 v146, v224, v146
	v_pk_mul_f32 v[172:173], v[168:169], v[172:173]
	v_mov_b32_e32 v165, v159
	v_add_f32_e32 v146, v173, v146
	v_add_f32_e32 v150, v172, v146
	v_mul_f32_e32 v146, 0xbfb8aa3b, v150
	v_exp_f32_e32 v146, v146
	v_mov_b32_e32 v157, v160
	s_mov_b64 s[2:3], -1
	s_and_b64 vcc, exec, s[18:19]
	v_add_f32_e32 v146, 1.0, v146
	v_rcp_f32_e32 v155, v146
	v_mov_b32_e32 v146, v151
	v_pk_mul_f32 v[146:147], v[138:139], v[146:147]
	v_mov_b32_e32 v172, v26
	v_add_f32_e32 v147, v143, v147
	v_add_f32_e32 v151, v146, v147
	v_pk_mul_f32 v[146:147], v[134:135], v[164:165]
	v_mov_b32_e32 v164, v27
	v_add_f32_e32 v147, v147, v151
	v_add_f32_e32 v151, v146, v147
	v_mul_f32_e32 v146, 0xbfb8aa3b, v151
	v_exp_f32_e32 v146, v146
	v_mul_f32_e32 v147, v150, v155
	v_cndmask_b32_e64 v150, v147, v150, s[4:5]
	v_mov_b32_e32 v147, v148
	v_add_f32_e32 v146, 1.0, v146
	v_rcp_f32_e32 v158, v146
	v_mov_b32_e32 v146, v152
	v_pk_mul_f32 v[146:147], v[162:163], v[146:147]
	v_mov_b32_e32 v155, v161
	v_add_f32_e32 v147, v144, v147
	v_add_f32_e32 v148, v146, v147
	v_pk_mul_f32 v[146:147], v[170:171], v[156:157]
	s_nop 0
	v_add_f32_e32 v147, v147, v148
	v_add_f32_e32 v152, v146, v147
	v_mul_f32_e32 v146, 0xbfb8aa3b, v152
	v_mov_b32_e32 v148, v153
	v_exp_f32_e32 v156, v146
	v_pk_mul_f32 v[146:147], v[140:141], v[148:149]
	v_add_f32_e32 v149, 1.0, v156
	v_add_f32_e32 v147, v145, v147
	v_add_f32_e32 v148, v146, v147
	v_pk_mul_f32 v[146:147], v[136:137], v[154:155]
	v_rcp_f32_e32 v149, v149
	v_add_f32_e32 v147, v147, v148
	v_add_f32_e32 v146, v146, v147
	v_mul_f32_e32 v147, 0xbfb8aa3b, v146
	v_exp_f32_e32 v147, v147
	v_mul_f32_e32 v148, v151, v158
	v_mul_f32_e32 v149, v152, v149
	v_cndmask_b32_e64 v148, v148, v151, s[4:5]
	v_add_f32_e32 v147, 1.0, v147
	v_rcp_f32_e32 v147, v147
	v_cndmask_b32_e64 v149, v149, v152, s[4:5]
	v_mov_b32_e32 v156, v28
	v_mov_b32_e32 v154, v29
	v_mul_f32_e32 v147, v146, v147
	v_cndmask_b32_e64 v147, v147, v146, s[4:5]
	v_cvt_pk_bf16_f32 v146, v150, v148
	v_cvt_pk_bf16_f32 v147, v149, v147
	v_lshlrev_b64 v[148:149], v182, v[192:193]
	v_lshl_add_u64 v[224:225], v[148:149], 1, v[220:221]
	v_mov_b32_e32 v62, v146
	v_mov_b32_e32 v63, v147
	s_cbranch_vccnz .LBB0_1147
	v_add_u32_e32 v147, 0xffffe0a0, v202
	v_ashrrev_i32_e32 v147, 2, v147
	v_lshl_add_u32 v147, v147, 1, v147
	v_mad_i64_i32 v[148:149], s[2:3], v147, s47, 0
	v_lshl_add_u64 v[148:149], v[148:149], 2, v[208:209]
	v_lshl_add_u64 v[150:151], v[148:149], 0, s[24:25]
	s_lshl_b32 s2, s27, 2
	s_mov_b32 s3, s25
	global_load_dwordx4 v[158:161], v[148:149], off
	s_nop 0
	global_load_dwordx4 v[150:153], v[150:151], off
	v_lshl_add_u64 v[148:149], v[148:149], 0, s[2:3]
	global_load_dwordx4 v[154:157], v[148:149], off
	v_mov_b32_dpp v164, v26 row_ror:1 row_mask:0xf bank_mask:0xf
	v_mov_b32_dpp v165, v26 row_ror:2 row_mask:0xf bank_mask:0xf
	v_mov_b32_dpp v146, v26 row_ror:3 row_mask:0xf bank_mask:0xf
	v_cmp_lt_i32_e32 vcc, 1, v205
	s_and_saveexec_b64 s[2:3], vcc
	s_xor_b64 s[2:3], exec, s[2:3]
	s_cbranch_execz .LBB0_1110
	v_cmp_gt_i32_e32 vcc, 3, v205
	s_and_saveexec_b64 s[20:21], vcc
	s_cbranch_execz .LBB0_1109
	s_waitcnt vmcnt(0)
	v_mov_b32_e32 v146, v154

; __device__ __forceinline__ float dpp_ror1(float v) { return __builtin_bit_cast(float, __builtin_amdgcn_update_dpp(0, __builtin_bit_cast(int, v), 0x121, 0xf, 0xf, false)); }
; __device__ __forceinline__ float dpp_ror2(float v) { return __builtin_bit_cast(float, __builtin_amdgcn_update_dpp(0, __builtin_bit_cast(int, v), 0x122, 0xf, 0xf, false)); }
; __device__ __forceinline__ float dpp_ror3(float v) { return __builtin_bit_cast(float, __builtin_amdgcn_update_dpp(0, __builtin_bit_cast(int, v), 0x123, 0xf, 0xf, false)); }
;     __device__ __forceinline__ void operator()(f32x4 (&acc)[2][2][4][2], const pg8::Unit& u, int wr, int wc, int fr, int fq) const {
;     ...
;                         else { const int t = fr & 3; const float* sp = stp + (size_t)((row - MP) >> 2) * 3 * CW + ch;
;                             const f32x4 b0 = *(const f32x4*)sp, b1 = *(const f32x4*)(sp + CW), b2 = *(const f32x4*)(sp + 2 * CW);
; #pragma unroll
;                             for (int j = 0; j < 4; ++j) { const float r1 = dpp_ror1(g[j]), r2 = dpp_ror2(g[j]), r3 = dpp_ror3(g[j]);
;                                 p1[j] = t >= 1 ? r1 : b2[j]; p2[j] = t >= 2 ? r2 : (t == 1 ? b2[j] : b1[j]); p3[j] = t >= 3 ? r3 : (t == 2 ? b2[j] : (t == 1 ? b1[j] : b0[j])); } }
.LBB0_1116:
	s_or_b64 exec, exec, s[2:3]
	v_mov_b32_dpp v172, v27 row_ror:1 row_mask:0xf bank_mask:0xf
	v_mov_b32_dpp v173, v27 row_ror:2 row_mask:0xf bank_mask:0xf
	v_mov_b32_dpp v147, v27 row_ror:3 row_mask:0xf bank_mask:0xf
	v_cmp_lt_i32_e32 vcc, 1, v205
	s_and_saveexec_b64 s[2:3], vcc
	s_xor_b64 s[2:3], exec, s[2:3]
	s_cbranch_execz .LBB0_1120
	v_cmp_gt_i32_e32 vcc, 3, v205
	s_and_saveexec_b64 s[20:21], vcc
	s_cbranch_execz .LBB0_1119
	s_waitcnt vmcnt(0)
	v_mov_b32_e32 v147, v155

; __device__ __forceinline__ float dpp_ror1(float v) { return __builtin_bit_cast(float, __builtin_amdgcn_update_dpp(0, __builtin_bit_cast(int, v), 0x121, 0xf, 0xf, false)); }
; __device__ __forceinline__ float dpp_ror2(float v) { return __builtin_bit_cast(float, __builtin_amdgcn_update_dpp(0, __builtin_bit_cast(int, v), 0x122, 0xf, 0xf, false)); }
; __device__ __forceinline__ float dpp_ror3(float v) { return __builtin_bit_cast(float, __builtin_amdgcn_update_dpp(0, __builtin_bit_cast(int, v), 0x123, 0xf, 0xf, false)); }
;     __device__ __forceinline__ void operator()(f32x4 (&acc)[2][2][4][2], const pg8::Unit& u, int wr, int wc, int fr, int fq) const {
;     ...
;                         else { const int t = fr & 3; const float* sp = stp + (size_t)((row - MP) >> 2) * 3 * CW + ch;
;                             const f32x4 b0 = *(const f32x4*)sp, b1 = *(const f32x4*)(sp + CW), b2 = *(const f32x4*)(sp + 2 * CW);
; #pragma unroll
;                             for (int j = 0; j < 4; ++j) { const float r1 = dpp_ror1(g[j]), r2 = dpp_ror2(g[j]), r3 = dpp_ror3(g[j]);
;                                 p1[j] = t >= 1 ? r1 : b2[j]; p2[j] = t >= 2 ? r2 : (t == 1 ? b2[j] : b1[j]); p3[j] = t >= 3 ? r3 : (t == 2 ? b2[j] : (t == 1 ? b1[j] : b0[j])); } }
.LBB0_1126:
	s_or_b64 exec, exec, s[2:3]
	v_mov_b32_dpp v226, v28 row_ror:1 row_mask:0xf bank_mask:0xf
	v_mov_b32_dpp v227, v28 row_ror:2 row_mask:0xf bank_mask:0xf
	v_mov_b32_dpp v148, v28 row_ror:3 row_mask:0xf bank_mask:0xf
	v_cmp_lt_i32_e32 vcc, 1, v205
	s_and_saveexec_b64 s[2:3], vcc
	s_xor_b64 s[2:3], exec, s[2:3]
	s_cbranch_execz .LBB0_1130
	v_cmp_gt_i32_e32 vcc, 3, v205
	s_and_saveexec_b64 s[20:21], vcc
	s_cbranch_execz .LBB0_1129
	s_waitcnt vmcnt(0)
	v_mov_b32_e32 v148, v156

; __device__ __forceinline__ float dpp_ror1(float v) { return __builtin_bit_cast(float, __builtin_amdgcn_update_dpp(0, __builtin_bit_cast(int, v), 0x121, 0xf, 0xf, false)); }
; __device__ __forceinline__ float dpp_ror2(float v) { return __builtin_bit_cast(float, __builtin_amdgcn_update_dpp(0, __builtin_bit_cast(int, v), 0x122, 0xf, 0xf, false)); }
; __device__ __forceinline__ float dpp_ror3(float v) { return __builtin_bit_cast(float, __builtin_amdgcn_update_dpp(0, __builtin_bit_cast(int, v), 0x123, 0xf, 0xf, false)); }
;     __device__ __forceinline__ void operator()(f32x4 (&acc)[2][2][4][2], const pg8::Unit& u, int wr, int wc, int fr, int fq) const {
;     ...
;                         else { const int t = fr & 3; const float* sp = stp + (size_t)((row - MP) >> 2) * 3 * CW + ch;
;                             const f32x4 b0 = *(const f32x4*)sp, b1 = *(const f32x4*)(sp + CW), b2 = *(const f32x4*)(sp + 2 * CW);
; #pragma unroll
;                             for (int j = 0; j < 4; ++j) { const float r1 = dpp_ror1(g[j]), r2 = dpp_ror2(g[j]), r3 = dpp_ror3(g[j]);
;                                 p1[j] = t >= 1 ? r1 : b2[j]; p2[j] = t >= 2 ? r2 : (t == 1 ? b2[j] : b1[j]); p3[j] = t >= 3 ? r3 : (t == 2 ? b2[j] : (t == 1 ? b1[j] : b0[j])); } }
.LBB0_1136:
	s_or_b64 exec, exec, s[2:3]
	v_mov_b32_dpp v229, v29 row_ror:1 row_mask:0xf bank_mask:0xf
	v_mov_b32_dpp v228, v29 row_ror:2 row_mask:0xf bank_mask:0xf
	v_mov_b32_dpp v149, v29 row_ror:3 row_mask:0xf bank_mask:0xf
	v_cmp_lt_i32_e32 vcc, 1, v205
	s_and_saveexec_b64 s[2:3], vcc
	s_xor_b64 s[2:3], exec, s[2:3]
	s_cbranch_execz .LBB0_1140
	v_cmp_gt_i32_e32 vcc, 3, v205
	s_and_saveexec_b64 s[20:21], vcc
	s_cbranch_execz .LBB0_1139
	s_waitcnt vmcnt(0)
	v_mov_b32_e32 v149, v157

; __device__ __forceinline__ unsigned cvt_pk_bf16(float lo, float hi) { unsigned r; asm("v_cvt_pk_bf16_f32 %0, %1, %2" : "=v"(r) : "v"(lo), "v"(hi)); return r; }
; __device__ __forceinline__ float siluf_(float x) { return x * sigmoidf_(x); }
; __device__ __forceinline__ float dpp_ror1(float v) { return __builtin_bit_cast(float, __builtin_amdgcn_update_dpp(0, __builtin_bit_cast(int, v), 0x121, 0xf, 0xf, false)); }
;     __device__ __forceinline__ void operator()(f32x4 (&acc)[2][2][4][2], const pg8::Unit& u, int wr, int wc, int fr, int fq) const {
;     ...
;                 for (int n = 0; n < 2; ++n) { const int ch = ch0 + bj * 128 + 4 * n;
;                     const f32x4 w0 = *(const f32x4*)(cw + ch), w1 = *(const f32x4*)(cw + CW + ch), w2 = *(const f32x4*)(cw + 2 * CW + ch), w3 = *(const f32x4*)(cw + 3 * CW + ch), bb = *(const f32x4*)(cb + ch);
; #pragma unroll
;                     for (int m = 0; m < 4; ++m) { const int row = row0 + ai * 128 + m * 16; const f32x4 g = acc[ai][bj][m][n]; f32x4 p1, p2, p3;
;                         if (prompt) { const f32x4 gp = (m == 0) ? hal[n] : acc[ai][bj][m > 0 ? m - 1 : 0][n];
; #pragma unroll
;                             for (int j = 0; j < 4; ++j) { p1[j] = dpp_ror1(fr == 15 ? gp[j] : g[j]); p2[j] = dpp_ror2(fr >= 14 ? gp[j] : g[j]); p3[j] = dpp_ror3(fr >= 13 ? gp[j] : g[j]); } }
;                         else { const int t = fr & 3; const float* sp = stp + (size_t)((row - MP) >> 2) * 3 * CW + ch;
;                             const f32x4 b0 = *(const f32x4*)sp, b1 = *(const f32x4*)(sp + CW), b2 = *(const f32x4*)(sp + 2 * CW);
; #pragma unroll
;                             for (int j = 0; j < 4; ++j) { const float r1 = dpp_ror1(g[j]), r2 = dpp_ror2(g[j]), r3 = dpp_ror3(g[j]);
;                                 p1[j] = t >= 1 ? r1 : b2[j]; p2[j] = t >= 2 ? r2 : (t == 1 ? b2[j] : b1[j]); p3[j] = t >= 3 ? r3 : (t == 2 ? b2[j] : (t == 1 ? b1[j] : b0[j])); } }
;                         float o[4];
; #pragma unroll
;                         for (int j = 0; j < 4; ++j) { const float y = bb[j] + w0[j] * p3[j] + w1[j] * p2[j] + w2[j] * p1[j] + w3[j] * g[j]; o[j] = is_rg ? y : siluf_(y); }
;                         u32x2 w; w.x = cvt_pk_bf16(o[0], o[1]); w.y = cvt_pk_bf16(o[2], o[3]);
;                         *(u32x2*)(dst + (size_t)row * ld + bj * 128 + 4 * n) = w; }
.LBB0_1147:
	s_and_b64 vcc, exec, s[2:3]
	s_cbranch_vccz .LBB0_1149
	v_cndmask_b32_e64 v146, v26, v46, s[10:11]
	v_cndmask_b32_e64 v147, v26, v46, s[6:7]
	s_nop 0
	v_mov_b32_dpp v158, v146 row_ror:1 row_mask:0xf bank_mask:0xf
	v_cndmask_b32_e64 v146, v26, v46, s[8:9]
	s_nop 1
	v_mov_b32_dpp v150, v146 row_ror:2 row_mask:0xf bank_mask:0xf
	v_cndmask_b32_e64 v148, v27, v47, s[6:7]
	v_mov_b32_dpp v146, v147 row_ror:3 row_mask:0xf bank_mask:0xf
	v_cndmask_b32_e64 v147, v27, v47, s[10:11]
	v_cndmask_b32_e64 v149, v28, v48, s[6:7]
	s_nop 0
	v_mov_b32_dpp v159, v147 row_ror:1 row_mask:0xf bank_mask:0xf
	v_cndmask_b32_e64 v147, v27, v47, s[8:9]
	s_nop 1
	v_mov_b32_dpp v151, v147 row_ror:2 row_mask:0xf bank_mask:0xf
	v_cndmask_b32_e64 v155, v29, v49, s[6:7]
	s_nop 0
	v_mov_b32_dpp v147, v148 row_ror:3 row_mask:0xf bank_mask:0xf
	v_cndmask_b32_e64 v148, v28, v48, s[10:11]
	s_nop 1
	v_mov_b32_dpp v160, v148 row_ror:1 row_mask:0xf bank_mask:0xf
	v_cndmask_b32_e64 v148, v28, v48, s[8:9]
	s_nop 1
	v_mov_b32_dpp v152, v148 row_ror:2 row_mask:0xf bank_mask:0xf
	s_nop 1
	v_mov_b32_dpp v148, v149 row_ror:3 row_mask:0xf bank_mask:0xf
	v_cndmask_b32_e64 v149, v29, v49, s[10:11]
	s_nop 1
	v_mov_b32_dpp v161, v149 row_ror:1 row_mask:0xf bank_mask:0xf
	v_cndmask_b32_e64 v149, v29, v49, s[8:9]
	s_nop 1
	v_mov_b32_dpp v153, v149 row_ror:2 row_mask:0xf bank_mask:0xf
	s_nop 1
	v_mov_b32_dpp v149, v155 row_ror:3 row_mask:0xf bank_mask:0xf
.LBB0_1149:
	v_mov_b32_e32 v226, v150
	v_mov_b32_e32 v227, v146
	v_pk_mul_f32 v[226:227], v[166:167], v[226:227]
	v_mov_b32_e32 v173, v158
	v_add_f32_e32 v146, v142, v227
	v_add_f32_e32 v146, v226, v146
	v_pk_mul_f32 v[172:173], v[168:169], v[172:173]
	v_mov_b32_e32 v165, v159
	v_add_f32_e32 v146, v173, v146
	v_add_f32_e32 v150, v172, v146
	v_mul_f32_e32 v146, 0xbfb8aa3b, v150
	v_exp_f32_e32 v146, v146
	v_mov_b32_e32 v157, v160
	s_mov_b64 s[2:3], -1
	s_and_b64 vcc, exec, s[18:19]
	v_add_f32_e32 v146, 1.0, v146
	v_rcp_f32_e32 v155, v146
	v_mov_b32_e32 v146, v151
	v_pk_mul_f32 v[146:147], v[138:139], v[146:147]
	v_mov_b32_e32 v172, v14
	v_add_f32_e32 v147, v143, v147
	v_add_f32_e32 v151, v146, v147
	v_pk_mul_f32 v[146:147], v[134:135], v[164:165]
	v_mov_b32_e32 v164, v15
	v_add_f32_e32 v147, v147, v151
	v_add_f32_e32 v151, v146, v147
	v_mul_f32_e32 v146, 0xbfb8aa3b, v151
	v_exp_f32_e32 v146, v146
	v_mul_f32_e32 v147, v150, v155
	v_cndmask_b32_e64 v150, v147, v150, s[4:5]
	v_mov_b32_e32 v147, v148
	v_add_f32_e32 v146, 1.0, v146
	v_rcp_f32_e32 v158, v146
	v_mov_b32_e32 v146, v152
	v_pk_mul_f32 v[146:147], v[162:163], v[146:147]
	v_mov_b32_e32 v155, v161
	v_add_f32_e32 v147, v144, v147
	v_add_f32_e32 v148, v146, v147
	v_pk_mul_f32 v[146:147], v[170:171], v[156:157]
	s_nop 0
	v_add_f32_e32 v147, v147, v148
	v_add_f32_e32 v152, v146, v147
	v_mul_f32_e32 v146, 0xbfb8aa3b, v152
	v_mov_b32_e32 v148, v153
	v_exp_f32_e32 v156, v146
	v_pk_mul_f32 v[146:147], v[140:141], v[148:149]
	v_add_f32_e32 v149, 1.0, v156
	v_add_f32_e32 v147, v145, v147
	v_add_f32_e32 v148, v146, v147
	v_pk_mul_f32 v[146:147], v[136:137], v[154:155]
	v_rcp_f32_e32 v149, v149
	v_add_f32_e32 v147, v147, v148
	v_add_f32_e32 v146, v146, v147
	v_mul_f32_e32 v147, 0xbfb8aa3b, v146
	v_exp_f32_e32 v147, v147
	v_mul_f32_e32 v148, v151, v158
	v_mul_f32_e32 v149, v152, v149
	v_cndmask_b32_e64 v148, v148, v151, s[4:5]
	v_add_f32_e32 v147, 1.0, v147
	v_rcp_f32_e32 v147, v147
	v_cndmask_b32_e64 v149, v149, v152, s[4:5]
	v_mov_b32_e32 v156, v16
	v_mov_b32_e32 v154, v17
	v_mul_f32_e32 v147, v146, v147
	v_cndmask_b32_e64 v147, v147, v146, s[4:5]
	v_cvt_pk_bf16_f32 v146, v150, v148
	v_cvt_pk_bf16_f32 v147, v149, v147
	v_lshlrev_b64 v[148:149], v182, v[190:191]
	v_lshl_add_u64 v[226:227], v[148:149], 1, v[220:221]
	v_mov_b32_e32 v46, v146
	v_mov_b32_e32 v47, v147
	s_cbranch_vccnz .LBB0_1191
	v_add_u32_e32 v147, 0xffffe0b0, v202
	v_ashrrev_i32_e32 v147, 2, v147
	v_lshl_add_u32 v147, v147, 1, v147
	v_mad_i64_i32 v[148:149], s[2:3], v147, s47, 0
	v_lshl_add_u64 v[148:149], v[148:149], 2, v[208:209]
	v_lshl_add_u64 v[150:151], v[148:149], 0, s[24:25]
	s_lshl_b32 s2, s27, 2
	s_mov_b32 s3, s25
	global_load_dwordx4 v[158:161], v[148:149], off
	s_nop 0
	global_load_dwordx4 v[150:153], v[150:151], off
	v_lshl_add_u64 v[148:149], v[148:149], 0, s[2:3]
	global_load_dwordx4 v[154:157], v[148:149], off
	v_mov_b32_dpp v164, v14 row_ror:1 row_mask:0xf bank_mask:0xf
	v_mov_b32_dpp v165, v14 row_ror:2 row_mask:0xf bank_mask:0xf
	v_mov_b32_dpp v146, v14 row_ror:3 row_mask:0xf bank_mask:0xf
	v_cmp_lt_i32_e32 vcc, 1, v205
	s_and_saveexec_b64 s[2:3], vcc
	s_xor_b64 s[2:3], exec, s[2:3]
	s_cbranch_execz .LBB0_1154
	v_cmp_gt_i32_e32 vcc, 3, v205
	s_and_saveexec_b64 s[20:21], vcc
	s_cbranch_execz .LBB0_1153
	s_waitcnt vmcnt(0)
	v_mov_b32_e32 v146, v154

; __device__ __forceinline__ float dpp_ror1(float v) { return __builtin_bit_cast(float, __builtin_amdgcn_update_dpp(0, __builtin_bit_cast(int, v), 0x121, 0xf, 0xf, false)); }
; __device__ __forceinline__ float dpp_ror2(float v) { return __builtin_bit_cast(float, __builtin_amdgcn_update_dpp(0, __builtin_bit_cast(int, v), 0x122, 0xf, 0xf, false)); }
; __device__ __forceinline__ float dpp_ror3(float v) { return __builtin_bit_cast(float, __builtin_amdgcn_update_dpp(0, __builtin_bit_cast(int, v), 0x123, 0xf, 0xf, false)); }
;     __device__ __forceinline__ void operator()(f32x4 (&acc)[2][2][4][2], const pg8::Unit& u, int wr, int wc, int fr, int fq) const {
;     ...
;                         else { const int t = fr & 3; const float* sp = stp + (size_t)((row - MP) >> 2) * 3 * CW + ch;
;                             const f32x4 b0 = *(const f32x4*)sp, b1 = *(const f32x4*)(sp + CW), b2 = *(const f32x4*)(sp + 2 * CW);
; #pragma unroll
;                             for (int j = 0; j < 4; ++j) { const float r1 = dpp_ror1(g[j]), r2 = dpp_ror2(g[j]), r3 = dpp_ror3(g[j]);
;                                 p1[j] = t >= 1 ? r1 : b2[j]; p2[j] = t >= 2 ? r2 : (t == 1 ? b2[j] : b1[j]); p3[j] = t >= 3 ? r3 : (t == 2 ? b2[j] : (t == 1 ? b1[j] : b0[j])); } }
.LBB0_1160:
	s_or_b64 exec, exec, s[2:3]
	v_mov_b32_dpp v172, v15 row_ror:1 row_mask:0xf bank_mask:0xf
	v_mov_b32_dpp v173, v15 row_ror:2 row_mask:0xf bank_mask:0xf
	v_mov_b32_dpp v147, v15 row_ror:3 row_mask:0xf bank_mask:0xf
	v_cmp_lt_i32_e32 vcc, 1, v205
	s_and_saveexec_b64 s[2:3], vcc
	s_xor_b64 s[2:3], exec, s[2:3]
	s_cbranch_execz .LBB0_1164
	v_cmp_gt_i32_e32 vcc, 3, v205
	s_and_saveexec_b64 s[20:21], vcc
	s_cbranch_execz .LBB0_1163
	s_waitcnt vmcnt(0)
	v_mov_b32_e32 v147, v155

; __device__ __forceinline__ float dpp_ror1(float v) { return __builtin_bit_cast(float, __builtin_amdgcn_update_dpp(0, __builtin_bit_cast(int, v), 0x121, 0xf, 0xf, false)); }
; __device__ __forceinline__ float dpp_ror2(float v) { return __builtin_bit_cast(float, __builtin_amdgcn_update_dpp(0, __builtin_bit_cast(int, v), 0x122, 0xf, 0xf, false)); }
; __device__ __forceinline__ float dpp_ror3(float v) { return __builtin_bit_cast(float, __builtin_amdgcn_update_dpp(0, __builtin_bit_cast(int, v), 0x123, 0xf, 0xf, false)); }
;     __device__ __forceinline__ void operator()(f32x4 (&acc)[2][2][4][2], const pg8::Unit& u, int wr, int wc, int fr, int fq) const {
;     ...
;                         else { const int t = fr & 3; const float* sp = stp + (size_t)((row - MP) >> 2) * 3 * CW + ch;
;                             const f32x4 b0 = *(const f32x4*)sp, b1 = *(const f32x4*)(sp + CW), b2 = *(const f32x4*)(sp + 2 * CW);
; #pragma unroll
;                             for (int j = 0; j < 4; ++j) { const float r1 = dpp_ror1(g[j]), r2 = dpp_ror2(g[j]), r3 = dpp_ror3(g[j]);
;                                 p1[j] = t >= 1 ? r1 : b2[j]; p2[j] = t >= 2 ? r2 : (t == 1 ? b2[j] : b1[j]); p3[j] = t >= 3 ? r3 : (t == 2 ? b2[j] : (t == 1 ? b1[j] : b0[j])); } }
.LBB0_1170:
	s_or_b64 exec, exec, s[2:3]
	v_mov_b32_dpp v228, v16 row_ror:1 row_mask:0xf bank_mask:0xf
	v_mov_b32_dpp v229, v16 row_ror:2 row_mask:0xf bank_mask:0xf
	v_mov_b32_dpp v148, v16 row_ror:3 row_mask:0xf bank_mask:0xf
	v_cmp_lt_i32_e32 vcc, 1, v205
	s_and_saveexec_b64 s[2:3], vcc
	s_xor_b64 s[2:3], exec, s[2:3]
	s_cbranch_execz .LBB0_1174
	v_cmp_gt_i32_e32 vcc, 3, v205
	s_and_saveexec_b64 s[20:21], vcc
	s_cbranch_execz .LBB0_1173
	s_waitcnt vmcnt(0)
	v_mov_b32_e32 v148, v156

; __device__ __forceinline__ float dpp_ror1(float v) { return __builtin_bit_cast(float, __builtin_amdgcn_update_dpp(0, __builtin_bit_cast(int, v), 0x121, 0xf, 0xf, false)); }
; __device__ __forceinline__ float dpp_ror2(float v) { return __builtin_bit_cast(float, __builtin_amdgcn_update_dpp(0, __builtin_bit_cast(int, v), 0x122, 0xf, 0xf, false)); }
; __device__ __forceinline__ float dpp_ror3(float v) { return __builtin_bit_cast(float, __builtin_amdgcn_update_dpp(0, __builtin_bit_cast(int, v), 0x123, 0xf, 0xf, false)); }
;     __device__ __forceinline__ void operator()(f32x4 (&acc)[2][2][4][2], const pg8::Unit& u, int wr, int wc, int fr, int fq) const {
;     ...
;                         else { const int t = fr & 3; const float* sp = stp + (size_t)((row - MP) >> 2) * 3 * CW + ch;
;                             const f32x4 b0 = *(const f32x4*)sp, b1 = *(const f32x4*)(sp + CW), b2 = *(const f32x4*)(sp + 2 * CW);
; #pragma unroll
;                             for (int j = 0; j < 4; ++j) { const float r1 = dpp_ror1(g[j]), r2 = dpp_ror2(g[j]), r3 = dpp_ror3(g[j]);
;                                 p1[j] = t >= 1 ? r1 : b2[j]; p2[j] = t >= 2 ? r2 : (t == 1 ? b2[j] : b1[j]); p3[j] = t >= 3 ? r3 : (t == 2 ? b2[j] : (t == 1 ? b1[j] : b0[j])); } }
.LBB0_1180:
	s_or_b64 exec, exec, s[2:3]
	v_mov_b32_dpp v231, v17 row_ror:1 row_mask:0xf bank_mask:0xf
	v_mov_b32_dpp v230, v17 row_ror:2 row_mask:0xf bank_mask:0xf
	v_mov_b32_dpp v149, v17 row_ror:3 row_mask:0xf bank_mask:0xf
	v_cmp_lt_i32_e32 vcc, 1, v205
	s_and_saveexec_b64 s[2:3], vcc
	s_xor_b64 s[2:3], exec, s[2:3]
	s_cbranch_execz .LBB0_1184
	v_cmp_gt_i32_e32 vcc, 3, v205
	s_and_saveexec_b64 s[20:21], vcc
	s_cbranch_execz .LBB0_1183
	s_waitcnt vmcnt(0)
	v_mov_b32_e32 v149, v157

; __device__ __forceinline__ unsigned cvt_pk_bf16(float lo, float hi) { unsigned r; asm("v_cvt_pk_bf16_f32 %0, %1, %2" : "=v"(r) : "v"(lo), "v"(hi)); return r; }
; __device__ __forceinline__ float siluf_(float x) { return x * sigmoidf_(x); }
; __device__ __forceinline__ float dpp_ror1(float v) { return __builtin_bit_cast(float, __builtin_amdgcn_update_dpp(0, __builtin_bit_cast(int, v), 0x121, 0xf, 0xf, false)); }
;     __device__ __forceinline__ void operator()(f32x4 (&acc)[2][2][4][2], const pg8::Unit& u, int wr, int wc, int fr, int fq) const {
;     ...
;                 for (int n = 0; n < 2; ++n) { const int ch = ch0 + bj * 128 + 4 * n;
;                     const f32x4 w0 = *(const f32x4*)(cw + ch), w1 = *(const f32x4*)(cw + CW + ch), w2 = *(const f32x4*)(cw + 2 * CW + ch), w3 = *(const f32x4*)(cw + 3 * CW + ch), bb = *(const f32x4*)(cb + ch);
; #pragma unroll
;                     for (int m = 0; m < 4; ++m) { const int row = row0 + ai * 128 + m * 16; const f32x4 g = acc[ai][bj][m][n]; f32x4 p1, p2, p3;
;                         if (prompt) { const f32x4 gp = (m == 0) ? hal[n] : acc[ai][bj][m > 0 ? m - 1 : 0][n];
; #pragma unroll
;                             for (int j = 0; j < 4; ++j) { p1[j] = dpp_ror1(fr == 15 ? gp[j] : g[j]); p2[j] = dpp_ror2(fr >= 14 ? gp[j] : g[j]); p3[j] = dpp_ror3(fr >= 13 ? gp[j] : g[j]); } }
;                         else { const int t = fr & 3; const float* sp = stp + (size_t)((row - MP) >> 2) * 3 * CW + ch;
;                             const f32x4 b0 = *(const f32x4*)sp, b1 = *(const f32x4*)(sp + CW), b2 = *(const f32x4*)(sp + 2 * CW);
; #pragma unroll
;                             for (int j = 0; j < 4; ++j) { const float r1 = dpp_ror1(g[j]), r2 = dpp_ror2(g[j]), r3 = dpp_ror3(g[j]);
;                                 p1[j] = t >= 1 ? r1 : b2[j]; p2[j] = t >= 2 ? r2 : (t == 1 ? b2[j] : b1[j]); p3[j] = t >= 3 ? r3 : (t == 2 ? b2[j] : (t == 1 ? b1[j] : b0[j])); } }
;                         float o[4];
; #pragma unroll
;                         for (int j = 0; j < 4; ++j) { const float y = bb[j] + w0[j] * p3[j] + w1[j] * p2[j] + w2[j] * p1[j] + w3[j] * g[j]; o[j] = is_rg ? y : siluf_(y); }
;                         u32x2 w; w.x = cvt_pk_bf16(o[0], o[1]); w.y = cvt_pk_bf16(o[2], o[3]);
;                         *(u32x2*)(dst + (size_t)row * ld + bj * 128 + 4 * n) = w; }
.LBB0_1191:
	s_and_b64 vcc, exec, s[2:3]
	s_cbranch_vccz .LBB0_1193
	v_cndmask_b32_e64 v146, v14, v26, s[10:11]
	v_cndmask_b32_e64 v147, v14, v26, s[6:7]
	s_nop 0
	v_mov_b32_dpp v158, v146 row_ror:1 row_mask:0xf bank_mask:0xf
	v_cndmask_b32_e64 v146, v14, v26, s[8:9]
	s_nop 1
	v_mov_b32_dpp v150, v146 row_ror:2 row_mask:0xf bank_mask:0xf
	v_cndmask_b32_e64 v148, v15, v27, s[6:7]
	v_mov_b32_dpp v146, v147 row_ror:3 row_mask:0xf bank_mask:0xf
	v_cndmask_b32_e64 v147, v15, v27, s[10:11]
	v_cndmask_b32_e64 v149, v16, v28, s[6:7]
	s_nop 0
	v_mov_b32_dpp v159, v147 row_ror:1 row_mask:0xf bank_mask:0xf
	v_cndmask_b32_e64 v147, v15, v27, s[8:9]
	s_nop 1
	v_mov_b32_dpp v151, v147 row_ror:2 row_mask:0xf bank_mask:0xf
	v_cndmask_b32_e64 v155, v17, v29, s[6:7]
	s_nop 0
	v_mov_b32_dpp v147, v148 row_ror:3 row_mask:0xf bank_mask:0xf
	v_cndmask_b32_e64 v148, v16, v28, s[10:11]
	s_nop 1
	v_mov_b32_dpp v160, v148 row_ror:1 row_mask:0xf bank_mask:0xf
	v_cndmask_b32_e64 v148, v16, v28, s[8:9]
	s_nop 1
	v_mov_b32_dpp v152, v148 row_ror:2 row_mask:0xf bank_mask:0xf
	s_nop 1
	v_mov_b32_dpp v148, v149 row_ror:3 row_mask:0xf bank_mask:0xf
	v_cndmask_b32_e64 v149, v17, v29, s[10:11]
	s_nop 1
	v_mov_b32_dpp v161, v149 row_ror:1 row_mask:0xf bank_mask:0xf
	v_cndmask_b32_e64 v149, v17, v29, s[8:9]
	s_nop 1
	v_mov_b32_dpp v153, v149 row_ror:2 row_mask:0xf bank_mask:0xf
	s_nop 1
	v_mov_b32_dpp v149, v155 row_ror:3 row_mask:0xf bank_mask:0xf
.LBB0_1193:
	v_mov_b32_e32 v228, v150
	v_mov_b32_e32 v229, v146
	v_pk_mul_f32 v[166:167], v[166:167], v[228:229]
	v_mov_b32_e32 v173, v158
	v_add_f32_e32 v142, v142, v167
	v_add_f32_e32 v142, v166, v142
	v_pk_mul_f32 v[166:167], v[168:169], v[172:173]
	v_mov_b32_e32 v165, v159
	v_add_f32_e32 v142, v167, v142
	v_add_f32_e32 v142, v166, v142
	v_mul_f32_e32 v146, 0xbfb8aa3b, v142
	v_exp_f32_e32 v146, v146
	v_pk_mul_f32 v[134:135], v[134:135], v[164:165]
	v_mov_b32_e32 v157, v160
	v_mov_b32_e32 v155, v161
	v_add_f32_e32 v146, 1.0, v146
	v_rcp_f32_e32 v150, v146
	v_mov_b32_e32 v146, v151
	v_pk_mul_f32 v[138:139], v[138:139], v[146:147]
	s_mov_b64 s[2:3], -1
	v_add_f32_e32 v139, v143, v139
	v_add_f32_e32 v138, v138, v139
	v_add_f32_e32 v135, v135, v138
	v_add_f32_e32 v138, v134, v135
	v_mul_f32_e32 v134, 0xbfb8aa3b, v138
	v_exp_f32_e32 v134, v134
	v_mul_f32_e32 v135, v142, v150
	v_cndmask_b32_e64 v139, v135, v142, s[4:5]
	v_mov_b32_e32 v135, v148
	v_add_f32_e32 v134, 1.0, v134
	v_rcp_f32_e32 v142, v134
	v_mov_b32_e32 v134, v152
	v_pk_mul_f32 v[134:135], v[162:163], v[134:135]
	v_mov_b32_e32 v148, v153
	v_add_f32_e32 v135, v144, v135
	v_add_f32_e32 v143, v134, v135
	v_pk_mul_f32 v[134:135], v[170:171], v[156:157]
	s_and_b64 vcc, exec, s[18:19]
	v_add_f32_e32 v135, v135, v143
	v_add_f32_e32 v143, v134, v135
	v_mul_f32_e32 v134, 0xbfb8aa3b, v143
	v_exp_f32_e32 v144, v134
	v_pk_mul_f32 v[134:135], v[140:141], v[148:149]
	v_mov_b32_e32 v230, v58
	v_add_f32_e32 v135, v145, v135
	v_add_f32_e32 v140, v134, v135
	v_pk_mul_f32 v[134:135], v[136:137], v[154:155]
	v_add_f32_e32 v137, 1.0, v144
	v_add_f32_e32 v135, v135, v140
	v_add_f32_e32 v134, v134, v135
	v_mul_f32_e32 v135, 0xbfb8aa3b, v134
	v_exp_f32_e32 v135, v135
	v_rcp_f32_e32 v137, v137
	v_mul_f32_e32 v136, v138, v142
	v_cndmask_b32_e64 v136, v136, v138, s[4:5]
	v_add_f32_e32 v135, 1.0, v135
	v_rcp_f32_e32 v135, v135
	v_mul_f32_e32 v137, v143, v137
	v_cndmask_b32_e64 v137, v137, v143, s[4:5]
	v_mov_b32_e32 v228, v59
	v_mul_f32_e32 v135, v134, v135
	v_cndmask_b32_e64 v135, v135, v134, s[4:5]
	v_cvt_pk_bf16_f32 v134, v139, v136
	v_cvt_pk_bf16_f32 v135, v137, v135
	v_lshlrev_b64 v[136:137], v182, v[188:189]
	v_lshl_add_u64 v[220:221], v[136:137], 1, v[220:221]
	v_mov_b32_e32 v26, v134
	v_mov_b32_e32 v27, v135
	global_load_dwordx4 v[138:141], v[210:211], off offset:16
	global_load_dwordx4 v[150:153], v[212:213], off offset:16
	global_load_dwordx4 v[134:137], v[214:215], off offset:16
	global_load_dwordx4 v[146:149], v[216:217], off offset:16
	global_load_dwordx4 v[142:145], v[218:219], off offset:16
	v_mov_b32_e32 v172, v60
	v_mov_b32_e32 v170, v61
	s_cbranch_vccnz .LBB0_1235
	v_add_u32_e32 v155, 0xffffe080, v202
	v_ashrrev_i32_e32 v155, 2, v155
	v_lshl_add_u32 v155, v155, 1, v155
	v_mad_i64_i32 v[156:157], s[2:3], v155, s47, 0
	v_lshl_add_u64 v[156:157], v[156:157], 2, v[208:209]
	v_lshl_add_u64 v[158:159], v[156:157], 0, s[24:25]
	s_lshl_b32 s2, s27, 2
	s_mov_b32 s3, s25
	global_load_dwordx4 v[166:169], v[156:157], off offset:16
	s_nop 0
	global_load_dwordx4 v[158:161], v[158:159], off offset:16
	v_lshl_add_u64 v[156:157], v[156:157], 0, s[2:3]
	global_load_dwordx4 v[162:165], v[156:157], off offset:16
	v_mov_b32_dpp v170, v58 row_ror:1 row_mask:0xf bank_mask:0xf
	v_mov_b32_dpp v171, v58 row_ror:2 row_mask:0xf bank_mask:0xf
	v_mov_b32_dpp v154, v58 row_ror:3 row_mask:0xf bank_mask:0xf
	v_cmp_lt_i32_e32 vcc, 1, v205
	s_and_saveexec_b64 s[2:3], vcc
	s_xor_b64 s[2:3], exec, s[2:3]
	s_cbranch_execz .LBB0_1198
	v_cmp_gt_i32_e32 vcc, 3, v205
	s_and_saveexec_b64 s[20:21], vcc
	s_cbranch_execz .LBB0_1197
	s_waitcnt vmcnt(0)
	v_mov_b32_e32 v154, v162

; __device__ __forceinline__ float dpp_ror1(float v) { return __builtin_bit_cast(float, __builtin_amdgcn_update_dpp(0, __builtin_bit_cast(int, v), 0x121, 0xf, 0xf, false)); }
; __device__ __forceinline__ float dpp_ror2(float v) { return __builtin_bit_cast(float, __builtin_amdgcn_update_dpp(0, __builtin_bit_cast(int, v), 0x122, 0xf, 0xf, false)); }
; __device__ __forceinline__ float dpp_ror3(float v) { return __builtin_bit_cast(float, __builtin_amdgcn_update_dpp(0, __builtin_bit_cast(int, v), 0x123, 0xf, 0xf, false)); }
;     __device__ __forceinline__ void operator()(f32x4 (&acc)[2][2][4][2], const pg8::Unit& u, int wr, int wc, int fr, int fq) const {
;     ...
;                         else { const int t = fr & 3; const float* sp = stp + (size_t)((row - MP) >> 2) * 3 * CW + ch;
;                             const f32x4 b0 = *(const f32x4*)sp, b1 = *(const f32x4*)(sp + CW), b2 = *(const f32x4*)(sp + 2 * CW);
; #pragma unroll
;                             for (int j = 0; j < 4; ++j) { const float r1 = dpp_ror1(g[j]), r2 = dpp_ror2(g[j]), r3 = dpp_ror3(g[j]);
;                                 p1[j] = t >= 1 ? r1 : b2[j]; p2[j] = t >= 2 ? r2 : (t == 1 ? b2[j] : b1[j]); p3[j] = t >= 3 ? r3 : (t == 2 ? b2[j] : (t == 1 ? b1[j] : b0[j])); } }
.LBB0_1204:
	s_or_b64 exec, exec, s[2:3]
	v_mov_b32_dpp v172, v59 row_ror:1 row_mask:0xf bank_mask:0xf
	v_mov_b32_dpp v173, v59 row_ror:2 row_mask:0xf bank_mask:0xf
	v_mov_b32_dpp v155, v59 row_ror:3 row_mask:0xf bank_mask:0xf
	v_cmp_lt_i32_e32 vcc, 1, v205
	s_and_saveexec_b64 s[2:3], vcc
	s_xor_b64 s[2:3], exec, s[2:3]
	s_cbranch_execz .LBB0_1208
	v_cmp_gt_i32_e32 vcc, 3, v205
	s_and_saveexec_b64 s[20:21], vcc
	s_cbranch_execz .LBB0_1207
	s_waitcnt vmcnt(0)
	v_mov_b32_e32 v155, v163

; __device__ __forceinline__ float dpp_ror1(float v) { return __builtin_bit_cast(float, __builtin_amdgcn_update_dpp(0, __builtin_bit_cast(int, v), 0x121, 0xf, 0xf, false)); }
; __device__ __forceinline__ float dpp_ror2(float v) { return __builtin_bit_cast(float, __builtin_amdgcn_update_dpp(0, __builtin_bit_cast(int, v), 0x122, 0xf, 0xf, false)); }
; __device__ __forceinline__ float dpp_ror3(float v) { return __builtin_bit_cast(float, __builtin_amdgcn_update_dpp(0, __builtin_bit_cast(int, v), 0x123, 0xf, 0xf, false)); }
;     __device__ __forceinline__ void operator()(f32x4 (&acc)[2][2][4][2], const pg8::Unit& u, int wr, int wc, int fr, int fq) const {
;     ...
;                         else { const int t = fr & 3; const float* sp = stp + (size_t)((row - MP) >> 2) * 3 * CW + ch;
;                             const f32x4 b0 = *(const f32x4*)sp, b1 = *(const f32x4*)(sp + CW), b2 = *(const f32x4*)(sp + 2 * CW);
; #pragma unroll
;                             for (int j = 0; j < 4; ++j) { const float r1 = dpp_ror1(g[j]), r2 = dpp_ror2(g[j]), r3 = dpp_ror3(g[j]);
;                                 p1[j] = t >= 1 ? r1 : b2[j]; p2[j] = t >= 2 ? r2 : (t == 1 ? b2[j] : b1[j]); p3[j] = t >= 3 ? r3 : (t == 2 ? b2[j] : (t == 1 ? b1[j] : b0[j])); } }
.LBB0_1214:
	s_or_b64 exec, exec, s[2:3]
	v_mov_b32_dpp v182, v60 row_ror:1 row_mask:0xf bank_mask:0xf
	v_mov_b32_dpp v228, v60 row_ror:2 row_mask:0xf bank_mask:0xf
	v_mov_b32_dpp v156, v60 row_ror:3 row_mask:0xf bank_mask:0xf
	v_cmp_lt_i32_e32 vcc, 1, v205
	s_and_saveexec_b64 s[2:3], vcc
	s_xor_b64 s[2:3], exec, s[2:3]
	s_cbranch_execz .LBB0_1218
	v_cmp_gt_i32_e32 vcc, 3, v205
	s_and_saveexec_b64 s[20:21], vcc
	s_cbranch_execz .LBB0_1217
	s_waitcnt vmcnt(0)
	v_mov_b32_e32 v156, v164

; __device__ __forceinline__ float dpp_ror1(float v) { return __builtin_bit_cast(float, __builtin_amdgcn_update_dpp(0, __builtin_bit_cast(int, v), 0x121, 0xf, 0xf, false)); }
; __device__ __forceinline__ float dpp_ror2(float v) { return __builtin_bit_cast(float, __builtin_amdgcn_update_dpp(0, __builtin_bit_cast(int, v), 0x122, 0xf, 0xf, false)); }
; __device__ __forceinline__ float dpp_ror3(float v) { return __builtin_bit_cast(float, __builtin_amdgcn_update_dpp(0, __builtin_bit_cast(int, v), 0x123, 0xf, 0xf, false)); }
;     __device__ __forceinline__ void operator()(f32x4 (&acc)[2][2][4][2], const pg8::Unit& u, int wr, int wc, int fr, int fq) const {
;     ...
;                         else { const int t = fr & 3; const float* sp = stp + (size_t)((row - MP) >> 2) * 3 * CW + ch;
;                             const f32x4 b0 = *(const f32x4*)sp, b1 = *(const f32x4*)(sp + CW), b2 = *(const f32x4*)(sp + 2 * CW);
; #pragma unroll
;                             for (int j = 0; j < 4; ++j) { const float r1 = dpp_ror1(g[j]), r2 = dpp_ror2(g[j]), r3 = dpp_ror3(g[j]);
;                                 p1[j] = t >= 1 ? r1 : b2[j]; p2[j] = t >= 2 ? r2 : (t == 1 ? b2[j] : b1[j]); p3[j] = t >= 3 ? r3 : (t == 2 ? b2[j] : (t == 1 ? b1[j] : b0[j])); } }
.LBB0_1224:
	s_or_b64 exec, exec, s[2:3]
	v_mov_b32_dpp v230, v61 row_ror:1 row_mask:0xf bank_mask:0xf
	v_mov_b32_dpp v229, v61 row_ror:2 row_mask:0xf bank_mask:0xf
	v_mov_b32_dpp v157, v61 row_ror:3 row_mask:0xf bank_mask:0xf
	v_cmp_lt_i32_e32 vcc, 1, v205
	s_and_saveexec_b64 s[2:3], vcc
	s_xor_b64 s[2:3], exec, s[2:3]
	s_cbranch_execz .LBB0_1228
	v_cmp_gt_i32_e32 vcc, 3, v205
	s_and_saveexec_b64 s[20:21], vcc
	s_cbranch_execz .LBB0_1227
	s_waitcnt vmcnt(0)
	v_mov_b32_e32 v157, v165

; __device__ __forceinline__ unsigned cvt_pk_bf16(float lo, float hi) { unsigned r; asm("v_cvt_pk_bf16_f32 %0, %1, %2" : "=v"(r) : "v"(lo), "v"(hi)); return r; }
; __device__ __forceinline__ float siluf_(float x) { return x * sigmoidf_(x); }
; __device__ __forceinline__ float dpp_ror1(float v) { return __builtin_bit_cast(float, __builtin_amdgcn_update_dpp(0, __builtin_bit_cast(int, v), 0x121, 0xf, 0xf, false)); }
;     __device__ __forceinline__ void operator()(f32x4 (&acc)[2][2][4][2], const pg8::Unit& u, int wr, int wc, int fr, int fq) const {
;     ...
;                 for (int n = 0; n < 2; ++n) { const int ch = ch0 + bj * 128 + 4 * n;
;                     const f32x4 w0 = *(const f32x4*)(cw + ch), w1 = *(const f32x4*)(cw + CW + ch), w2 = *(const f32x4*)(cw + 2 * CW + ch), w3 = *(const f32x4*)(cw + 3 * CW + ch), bb = *(const f32x4*)(cb + ch);
; #pragma unroll
;                     for (int m = 0; m < 4; ++m) { const int row = row0 + ai * 128 + m * 16; const f32x4 g = acc[ai][bj][m][n]; f32x4 p1, p2, p3;
;                         if (prompt) { const f32x4 gp = (m == 0) ? hal[n] : acc[ai][bj][m > 0 ? m - 1 : 0][n];
; #pragma unroll
;                             for (int j = 0; j < 4; ++j) { p1[j] = dpp_ror1(fr == 15 ? gp[j] : g[j]); p2[j] = dpp_ror2(fr >= 14 ? gp[j] : g[j]); p3[j] = dpp_ror3(fr >= 13 ? gp[j] : g[j]); } }
;                         else { const int t = fr & 3; const float* sp = stp + (size_t)((row - MP) >> 2) * 3 * CW + ch;
;                             const f32x4 b0 = *(const f32x4*)sp, b1 = *(const f32x4*)(sp + CW), b2 = *(const f32x4*)(sp + 2 * CW);
; #pragma unroll
;                             for (int j = 0; j < 4; ++j) { const float r1 = dpp_ror1(g[j]), r2 = dpp_ror2(g[j]), r3 = dpp_ror3(g[j]);
;                                 p1[j] = t >= 1 ? r1 : b2[j]; p2[j] = t >= 2 ? r2 : (t == 1 ? b2[j] : b1[j]); p3[j] = t >= 3 ? r3 : (t == 2 ? b2[j] : (t == 1 ? b1[j] : b0[j])); } }
;                         float o[4];
; #pragma unroll
;                         for (int j = 0; j < 4; ++j) { const float y = bb[j] + w0[j] * p3[j] + w1[j] * p2[j] + w2[j] * p1[j] + w3[j] * g[j]; o[j] = is_rg ? y : siluf_(y); }
;                         u32x2 w; w.x = cvt_pk_bf16(o[0], o[1]); w.y = cvt_pk_bf16(o[2], o[3]);
;                         *(u32x2*)(dst + (size_t)row * ld + bj * 128 + 4 * n) = w; }
.LBB0_1235:
	s_and_b64 vcc, exec, s[2:3]
	s_cbranch_vccz .LBB0_1237
	v_cndmask_b32_e64 v154, v58, v130, s[10:11]
	s_nop 1
	v_mov_b32_dpp v166, v154 row_ror:1 row_mask:0xf bank_mask:0xf
	v_cndmask_b32_e64 v154, v58, v130, s[8:9]
	v_cndmask_b32_e64 v130, v58, v130, s[6:7]
	s_nop 0
	v_mov_b32_dpp v158, v154 row_ror:2 row_mask:0xf bank_mask:0xf
	v_mov_b32_dpp v154, v130 row_ror:3 row_mask:0xf bank_mask:0xf
	v_cndmask_b32_e64 v130, v59, v131, s[10:11]
	s_nop 1
	v_mov_b32_dpp v167, v130 row_ror:1 row_mask:0xf bank_mask:0xf
	v_cndmask_b32_e64 v130, v59, v131, s[8:9]
	s_nop 1
	v_mov_b32_dpp v159, v130 row_ror:2 row_mask:0xf bank_mask:0xf
	v_cndmask_b32_e64 v130, v59, v131, s[6:7]
	s_nop 0
	s_nop 0
	v_mov_b32_dpp v155, v130 row_ror:3 row_mask:0xf bank_mask:0xf
	v_cndmask_b32_e64 v130, v60, v132, s[10:11]
	s_nop 1
	v_mov_b32_dpp v168, v130 row_ror:1 row_mask:0xf bank_mask:0xf
	v_cndmask_b32_e64 v130, v60, v132, s[8:9]
	s_nop 1
	v_mov_b32_dpp v160, v130 row_ror:2 row_mask:0xf bank_mask:0xf
	v_cndmask_b32_e64 v130, v60, v132, s[6:7]
	s_nop 1
	v_mov_b32_dpp v156, v130 row_ror:3 row_mask:0xf bank_mask:0xf
	v_cndmask_b32_e64 v130, v61, v133, s[10:11]
	s_nop 1
	v_mov_b32_dpp v169, v130 row_ror:1 row_mask:0xf bank_mask:0xf
	v_cndmask_b32_e64 v130, v61, v133, s[8:9]
	s_nop 1
	v_mov_b32_dpp v161, v130 row_ror:2 row_mask:0xf bank_mask:0xf
	v_cndmask_b32_e64 v130, v61, v133, s[6:7]
	s_nop 1
	v_mov_b32_dpp v157, v130 row_ror:3 row_mask:0xf bank_mask:0xf
.LBB0_1237:
	s_waitcnt vmcnt(0)
	v_mov_b32_e32 v162, v150
	v_mov_b32_e32 v163, v138
	v_mov_b32_e32 v130, v158
	v_mov_b32_e32 v131, v154
	v_pk_mul_f32 v[130:131], v[162:163], v[130:131]
	v_mov_b32_e32 v164, v146
	v_add_f32_e32 v131, v142, v131
	v_mov_b32_e32 v165, v134
	v_mov_b32_e32 v231, v166
	v_add_f32_e32 v132, v130, v131
	v_pk_mul_f32 v[130:131], v[164:165], v[230:231]
	v_mov_b32_e32 v138, v151
	v_add_f32_e32 v131, v131, v132
	v_add_f32_e32 v132, v130, v131
	v_mul_f32_e32 v130, 0xbfb8aa3b, v132
	v_exp_f32_e32 v130, v130
	v_mov_b32_e32 v154, v159
	v_mov_b32_e32 v134, v147
	v_mov_b32_e32 v229, v167
	v_add_f32_e32 v130, 1.0, v130
	v_rcp_f32_e32 v133, v130
	v_pk_mul_f32 v[130:131], v[138:139], v[154:155]
	v_mov_b32_e32 v158, v152
	v_add_f32_e32 v131, v143, v131
	v_add_f32_e32 v146, v130, v131
	v_pk_mul_f32 v[130:131], v[134:135], v[228:229]
	v_mov_b32_e32 v159, v140
	v_add_f32_e32 v131, v131, v146
	v_add_f32_e32 v146, v130, v131
	v_mul_f32_e32 v130, 0xbfb8aa3b, v146
	v_exp_f32_e32 v130, v130
	v_mul_f32_e32 v131, v132, v133
	v_cndmask_b32_e64 v132, v131, v132, s[4:5]
	v_mov_b32_e32 v131, v156
	v_add_f32_e32 v130, 1.0, v130
	v_rcp_f32_e32 v133, v130
	v_mov_b32_e32 v130, v160
	v_pk_mul_f32 v[130:131], v[158:159], v[130:131]
	v_mov_b32_e32 v166, v148
	v_add_f32_e32 v131, v144, v131
	v_mov_b32_e32 v167, v136
	v_mov_b32_e32 v173, v168
	v_add_f32_e32 v140, v130, v131
	v_pk_mul_f32 v[130:131], v[166:167], v[172:173]
	v_mov_b32_e32 v156, v161
	v_add_f32_e32 v131, v131, v140
	v_add_f32_e32 v147, v130, v131
	v_mul_f32_e32 v130, 0xbfb8aa3b, v147
	v_mov_b32_e32 v140, v153
	v_exp_f32_e32 v148, v130
	v_pk_mul_f32 v[130:131], v[140:141], v[156:157]
	v_mov_b32_e32 v136, v149
	v_add_f32_e32 v131, v145, v131
	v_mov_b32_e32 v171, v169
	v_add_f32_e32 v150, v130, v131
	v_pk_mul_f32 v[130:131], v[136:137], v[170:171]
	v_add_f32_e32 v148, 1.0, v148
	v_add_f32_e32 v131, v131, v150
	v_add_f32_e32 v130, v130, v131
	v_mul_f32_e32 v131, 0xbfb8aa3b, v130
	v_exp_f32_e32 v131, v131
	v_rcp_f32_e32 v148, v148
	v_mul_f32_e32 v133, v146, v133
	v_cndmask_b32_e64 v133, v133, v146, s[4:5]
	v_add_f32_e32 v131, 1.0, v131
	v_rcp_f32_e32 v131, v131
	v_mul_f32_e32 v146, v147, v148
	v_cndmask_b32_e64 v146, v146, v147, s[4:5]
	s_mov_b64 s[2:3], -1
	v_mul_f32_e32 v131, v130, v131
	v_cndmask_b32_e64 v131, v131, v130, s[4:5]
	v_cvt_pk_bf16_f32 v130, v132, v133
	v_cvt_pk_bf16_f32 v131, v146, v131
	s_and_b64 vcc, exec, s[18:19]
	v_mov_b32_e32 v168, v42
	v_mov_b32_e32 v160, v43
	v_mov_b32_e32 v152, v44
	v_mov_b32_e32 v150, v45
	v_mov_b32_e32 v72, v130
	v_mov_b32_e32 v73, v131
	flat_store_dwordx4 v[222:223], v[70:73]
	s_cbranch_vccnz .LBB0_1279
	v_add_u32_e32 v131, 0xffffe090, v202
	v_ashrrev_i32_e32 v131, 2, v131
	v_lshl_add_u32 v131, v131, 1, v131
	v_mad_i64_i32 v[132:133], s[2:3], v131, s47, 0
	v_lshl_add_u64 v[132:133], v[132:133], 2, v[208:209]
	v_lshl_add_u64 v[146:147], v[132:133], 0, s[24:25]
	s_lshl_b32 s2, s27, 2
	s_mov_b32 s3, s25
	global_load_dwordx4 v[154:157], v[132:133], off offset:16
	s_nop 0
	global_load_dwordx4 v[146:149], v[146:147], off offset:16
	v_lshl_add_u64 v[132:133], v[132:133], 0, s[2:3]
	global_load_dwordx4 v[150:153], v[132:133], off offset:16
	v_mov_b32_dpp v160, v42 row_ror:1 row_mask:0xf bank_mask:0xf
	v_mov_b32_dpp v161, v42 row_ror:2 row_mask:0xf bank_mask:0xf
	v_mov_b32_dpp v130, v42 row_ror:3 row_mask:0xf bank_mask:0xf
	v_cmp_lt_i32_e32 vcc, 1, v205
	s_and_saveexec_b64 s[2:3], vcc
	s_xor_b64 s[2:3], exec, s[2:3]
	s_cbranch_execz .LBB0_1242
	v_cmp_gt_i32_e32 vcc, 3, v205
	s_and_saveexec_b64 s[20:21], vcc
	s_cbranch_execz .LBB0_1241
	s_waitcnt vmcnt(0)
	v_mov_b32_e32 v130, v150

; __device__ __forceinline__ float dpp_ror1(float v) { return __builtin_bit_cast(float, __builtin_amdgcn_update_dpp(0, __builtin_bit_cast(int, v), 0x121, 0xf, 0xf, false)); }
; __device__ __forceinline__ float dpp_ror2(float v) { return __builtin_bit_cast(float, __builtin_amdgcn_update_dpp(0, __builtin_bit_cast(int, v), 0x122, 0xf, 0xf, false)); }
; __device__ __forceinline__ float dpp_ror3(float v) { return __builtin_bit_cast(float, __builtin_amdgcn_update_dpp(0, __builtin_bit_cast(int, v), 0x123, 0xf, 0xf, false)); }
;     __device__ __forceinline__ void operator()(f32x4 (&acc)[2][2][4][2], const pg8::Unit& u, int wr, int wc, int fr, int fq) const {
;     ...
;                         else { const int t = fr & 3; const float* sp = stp + (size_t)((row - MP) >> 2) * 3 * CW + ch;
;                             const f32x4 b0 = *(const f32x4*)sp, b1 = *(const f32x4*)(sp + CW), b2 = *(const f32x4*)(sp + 2 * CW);
; #pragma unroll
;                             for (int j = 0; j < 4; ++j) { const float r1 = dpp_ror1(g[j]), r2 = dpp_ror2(g[j]), r3 = dpp_ror3(g[j]);
;                                 p1[j] = t >= 1 ? r1 : b2[j]; p2[j] = t >= 2 ? r2 : (t == 1 ? b2[j] : b1[j]); p3[j] = t >= 3 ? r3 : (t == 2 ? b2[j] : (t == 1 ? b1[j] : b0[j])); } }
.LBB0_1248:
	s_or_b64 exec, exec, s[2:3]
	v_mov_b32_dpp v168, v43 row_ror:1 row_mask:0xf bank_mask:0xf
	v_mov_b32_dpp v169, v43 row_ror:2 row_mask:0xf bank_mask:0xf
	v_mov_b32_dpp v131, v43 row_ror:3 row_mask:0xf bank_mask:0xf
	v_cmp_lt_i32_e32 vcc, 1, v205
	s_and_saveexec_b64 s[2:3], vcc
	s_xor_b64 s[2:3], exec, s[2:3]
	s_cbranch_execz .LBB0_1252
	v_cmp_gt_i32_e32 vcc, 3, v205
	s_and_saveexec_b64 s[20:21], vcc
	s_cbranch_execz .LBB0_1251
	s_waitcnt vmcnt(0)
	v_mov_b32_e32 v131, v151

; __device__ __forceinline__ float dpp_ror1(float v) { return __builtin_bit_cast(float, __builtin_amdgcn_update_dpp(0, __builtin_bit_cast(int, v), 0x121, 0xf, 0xf, false)); }
; __device__ __forceinline__ float dpp_ror2(float v) { return __builtin_bit_cast(float, __builtin_amdgcn_update_dpp(0, __builtin_bit_cast(int, v), 0x122, 0xf, 0xf, false)); }
; __device__ __forceinline__ float dpp_ror3(float v) { return __builtin_bit_cast(float, __builtin_amdgcn_update_dpp(0, __builtin_bit_cast(int, v), 0x123, 0xf, 0xf, false)); }
;     __device__ __forceinline__ void operator()(f32x4 (&acc)[2][2][4][2], const pg8::Unit& u, int wr, int wc, int fr, int fq) const {
;     ...
;                         else { const int t = fr & 3; const float* sp = stp + (size_t)((row - MP) >> 2) * 3 * CW + ch;
;                             const f32x4 b0 = *(const f32x4*)sp, b1 = *(const f32x4*)(sp + CW), b2 = *(const f32x4*)(sp + 2 * CW);
; #pragma unroll
;                             for (int j = 0; j < 4; ++j) { const float r1 = dpp_ror1(g[j]), r2 = dpp_ror2(g[j]), r3 = dpp_ror3(g[j]);
;                                 p1[j] = t >= 1 ? r1 : b2[j]; p2[j] = t >= 2 ? r2 : (t == 1 ? b2[j] : b1[j]); p3[j] = t >= 3 ? r3 : (t == 2 ? b2[j] : (t == 1 ? b1[j] : b0[j])); } }
.LBB0_1258:
	s_or_b64 exec, exec, s[2:3]
	v_mov_b32_dpp v170, v44 row_ror:1 row_mask:0xf bank_mask:0xf
	v_mov_b32_dpp v171, v44 row_ror:2 row_mask:0xf bank_mask:0xf
	v_mov_b32_dpp v132, v44 row_ror:3 row_mask:0xf bank_mask:0xf
	v_cmp_lt_i32_e32 vcc, 1, v205
	s_and_saveexec_b64 s[2:3], vcc
	s_xor_b64 s[2:3], exec, s[2:3]
	s_cbranch_execz .LBB0_1262
	v_cmp_gt_i32_e32 vcc, 3, v205
	s_and_saveexec_b64 s[20:21], vcc
	s_cbranch_execz .LBB0_1261
	s_waitcnt vmcnt(0)
	v_mov_b32_e32 v132, v152

; __device__ __forceinline__ float dpp_ror1(float v) { return __builtin_bit_cast(float, __builtin_amdgcn_update_dpp(0, __builtin_bit_cast(int, v), 0x121, 0xf, 0xf, false)); }
; __device__ __forceinline__ float dpp_ror2(float v) { return __builtin_bit_cast(float, __builtin_amdgcn_update_dpp(0, __builtin_bit_cast(int, v), 0x122, 0xf, 0xf, false)); }
; __device__ __forceinline__ float dpp_ror3(float v) { return __builtin_bit_cast(float, __builtin_amdgcn_update_dpp(0, __builtin_bit_cast(int, v), 0x123, 0xf, 0xf, false)); }
;     __device__ __forceinline__ void operator()(f32x4 (&acc)[2][2][4][2], const pg8::Unit& u, int wr, int wc, int fr, int fq) const {
;     ...
;                         else { const int t = fr & 3; const float* sp = stp + (size_t)((row - MP) >> 2) * 3 * CW + ch;
;                             const f32x4 b0 = *(const f32x4*)sp, b1 = *(const f32x4*)(sp + CW), b2 = *(const f32x4*)(sp + 2 * CW);
; #pragma unroll
;                             for (int j = 0; j < 4; ++j) { const float r1 = dpp_ror1(g[j]), r2 = dpp_ror2(g[j]), r3 = dpp_ror3(g[j]);
;                                 p1[j] = t >= 1 ? r1 : b2[j]; p2[j] = t >= 2 ? r2 : (t == 1 ? b2[j] : b1[j]); p3[j] = t >= 3 ? r3 : (t == 2 ? b2[j] : (t == 1 ? b1[j] : b0[j])); } }
.LBB0_1268:
	s_or_b64 exec, exec, s[2:3]
	v_mov_b32_dpp v173, v45 row_ror:1 row_mask:0xf bank_mask:0xf
	v_mov_b32_dpp v172, v45 row_ror:2 row_mask:0xf bank_mask:0xf
	v_mov_b32_dpp v133, v45 row_ror:3 row_mask:0xf bank_mask:0xf
	v_cmp_lt_i32_e32 vcc, 1, v205
	s_and_saveexec_b64 s[2:3], vcc
	s_xor_b64 s[2:3], exec, s[2:3]
	s_cbranch_execz .LBB0_1272
	v_cmp_gt_i32_e32 vcc, 3, v205
	s_and_saveexec_b64 s[20:21], vcc
	s_cbranch_execz .LBB0_1271
	s_waitcnt vmcnt(0)
	v_mov_b32_e32 v133, v153

; __device__ __forceinline__ unsigned cvt_pk_bf16(float lo, float hi) { unsigned r; asm("v_cvt_pk_bf16_f32 %0, %1, %2" : "=v"(r) : "v"(lo), "v"(hi)); return r; }
; __device__ __forceinline__ float siluf_(float x) { return x * sigmoidf_(x); }
; __device__ __forceinline__ float dpp_ror1(float v) { return __builtin_bit_cast(float, __builtin_amdgcn_update_dpp(0, __builtin_bit_cast(int, v), 0x121, 0xf, 0xf, false)); }
;     __device__ __forceinline__ void operator()(f32x4 (&acc)[2][2][4][2], const pg8::Unit& u, int wr, int wc, int fr, int fq) const {
;     ...
;                 for (int n = 0; n < 2; ++n) { const int ch = ch0 + bj * 128 + 4 * n;
;                     const f32x4 w0 = *(const f32x4*)(cw + ch), w1 = *(const f32x4*)(cw + CW + ch), w2 = *(const f32x4*)(cw + 2 * CW + ch), w3 = *(const f32x4*)(cw + 3 * CW + ch), bb = *(const f32x4*)(cb + ch);
; #pragma unroll
;                     for (int m = 0; m < 4; ++m) { const int row = row0 + ai * 128 + m * 16; const f32x4 g = acc[ai][bj][m][n]; f32x4 p1, p2, p3;
;                         if (prompt) { const f32x4 gp = (m == 0) ? hal[n] : acc[ai][bj][m > 0 ? m - 1 : 0][n];
; #pragma unroll
;                             for (int j = 0; j < 4; ++j) { p1[j] = dpp_ror1(fr == 15 ? gp[j] : g[j]); p2[j] = dpp_ror2(fr >= 14 ? gp[j] : g[j]); p3[j] = dpp_ror3(fr >= 13 ? gp[j] : g[j]); } }
;                         else { const int t = fr & 3; const float* sp = stp + (size_t)((row - MP) >> 2) * 3 * CW + ch;
;                             const f32x4 b0 = *(const f32x4*)sp, b1 = *(const f32x4*)(sp + CW), b2 = *(const f32x4*)(sp + 2 * CW);
; #pragma unroll
;                             for (int j = 0; j < 4; ++j) { const float r1 = dpp_ror1(g[j]), r2 = dpp_ror2(g[j]), r3 = dpp_ror3(g[j]);
;                                 p1[j] = t >= 1 ? r1 : b2[j]; p2[j] = t >= 2 ? r2 : (t == 1 ? b2[j] : b1[j]); p3[j] = t >= 3 ? r3 : (t == 2 ? b2[j] : (t == 1 ? b1[j] : b0[j])); } }
;                         float o[4];
; #pragma unroll
;                         for (int j = 0; j < 4; ++j) { const float y = bb[j] + w0[j] * p3[j] + w1[j] * p2[j] + w2[j] * p1[j] + w3[j] * g[j]; o[j] = is_rg ? y : siluf_(y); }
;                         u32x2 w; w.x = cvt_pk_bf16(o[0], o[1]); w.y = cvt_pk_bf16(o[2], o[3]);
;                         *(u32x2*)(dst + (size_t)row * ld + bj * 128 + 4 * n) = w; }
.LBB0_1279:
	s_and_b64 vcc, exec, s[2:3]
	s_cbranch_vccz .LBB0_1281
	v_cndmask_b32_e64 v130, v42, v58, s[10:11]
	v_cndmask_b32_e64 v131, v42, v58, s[6:7]
	s_nop 0
	v_mov_b32_dpp v154, v130 row_ror:1 row_mask:0xf bank_mask:0xf
	v_cndmask_b32_e64 v130, v42, v58, s[8:9]
	s_nop 1
	v_mov_b32_dpp v146, v130 row_ror:2 row_mask:0xf bank_mask:0xf
	v_cndmask_b32_e64 v132, v43, v59, s[6:7]
	v_mov_b32_dpp v130, v131 row_ror:3 row_mask:0xf bank_mask:0xf
	v_cndmask_b32_e64 v131, v43, v59, s[10:11]
	v_cndmask_b32_e64 v133, v44, v60, s[6:7]
	s_nop 0
	v_mov_b32_dpp v155, v131 row_ror:1 row_mask:0xf bank_mask:0xf
	v_cndmask_b32_e64 v131, v43, v59, s[8:9]
	s_nop 1
	v_mov_b32_dpp v147, v131 row_ror:2 row_mask:0xf bank_mask:0xf
	v_cndmask_b32_e64 v151, v45, v61, s[6:7]
	s_nop 0
	v_mov_b32_dpp v131, v132 row_ror:3 row_mask:0xf bank_mask:0xf
	v_cndmask_b32_e64 v132, v44, v60, s[10:11]
	s_nop 1
	v_mov_b32_dpp v156, v132 row_ror:1 row_mask:0xf bank_mask:0xf
	v_cndmask_b32_e64 v132, v44, v60, s[8:9]
	s_nop 1
	v_mov_b32_dpp v148, v132 row_ror:2 row_mask:0xf bank_mask:0xf
	s_nop 1
	v_mov_b32_dpp v132, v133 row_ror:3 row_mask:0xf bank_mask:0xf
	v_cndmask_b32_e64 v133, v45, v61, s[10:11]
	s_nop 1
	v_mov_b32_dpp v157, v133 row_ror:1 row_mask:0xf bank_mask:0xf
	v_cndmask_b32_e64 v133, v45, v61, s[8:9]
	s_nop 1
	v_mov_b32_dpp v149, v133 row_ror:2 row_mask:0xf bank_mask:0xf
	s_nop 1
	v_mov_b32_dpp v133, v151 row_ror:3 row_mask:0xf bank_mask:0xf
.LBB0_1281:
	v_mov_b32_e32 v170, v146
	v_mov_b32_e32 v171, v130
	v_pk_mul_f32 v[170:171], v[162:163], v[170:171]
	v_mov_b32_e32 v169, v154
	v_add_f32_e32 v130, v142, v171
	v_add_f32_e32 v130, v170, v130
	v_pk_mul_f32 v[168:169], v[164:165], v[168:169]
	v_mov_b32_e32 v161, v155
	v_add_f32_e32 v130, v169, v130
	v_add_f32_e32 v146, v168, v130
	v_mul_f32_e32 v130, 0xbfb8aa3b, v146
	v_exp_f32_e32 v130, v130
	v_mov_b32_e32 v153, v156
	s_mov_b64 s[2:3], -1
	s_and_b64 vcc, exec, s[18:19]
	v_add_f32_e32 v130, 1.0, v130
	v_rcp_f32_e32 v151, v130
	v_mov_b32_e32 v130, v147
	v_pk_mul_f32 v[130:131], v[138:139], v[130:131]
	v_mov_b32_e32 v168, v30
	v_add_f32_e32 v131, v143, v131
	v_add_f32_e32 v147, v130, v131
	v_pk_mul_f32 v[130:131], v[134:135], v[160:161]
	v_mov_b32_e32 v160, v31
	v_add_f32_e32 v131, v131, v147
	v_add_f32_e32 v147, v130, v131
	v_mul_f32_e32 v130, 0xbfb8aa3b, v147
	v_exp_f32_e32 v130, v130
	v_mul_f32_e32 v131, v146, v151
	v_cndmask_b32_e64 v146, v131, v146, s[4:5]
	v_mov_b32_e32 v131, v132
	v_add_f32_e32 v130, 1.0, v130
	v_rcp_f32_e32 v154, v130
	v_mov_b32_e32 v130, v148
	v_pk_mul_f32 v[130:131], v[158:159], v[130:131]
	v_mov_b32_e32 v151, v157
	v_add_f32_e32 v131, v144, v131
	v_add_f32_e32 v132, v130, v131
	v_pk_mul_f32 v[130:131], v[166:167], v[152:153]
	s_nop 0
	v_add_f32_e32 v131, v131, v132
	v_add_f32_e32 v148, v130, v131
	v_mul_f32_e32 v130, 0xbfb8aa3b, v148
	v_mov_b32_e32 v132, v149
	v_exp_f32_e32 v152, v130
	v_pk_mul_f32 v[130:131], v[140:141], v[132:133]
	v_add_f32_e32 v133, 1.0, v152
	v_add_f32_e32 v131, v145, v131
	v_add_f32_e32 v132, v130, v131
	v_pk_mul_f32 v[130:131], v[136:137], v[150:151]
	v_rcp_f32_e32 v133, v133
	v_add_f32_e32 v131, v131, v132
	v_add_f32_e32 v130, v130, v131
	v_mul_f32_e32 v131, 0xbfb8aa3b, v130
	v_exp_f32_e32 v131, v131
	v_mul_f32_e32 v132, v147, v154
	v_mul_f32_e32 v133, v148, v133
	v_cndmask_b32_e64 v132, v132, v147, s[4:5]
	v_add_f32_e32 v131, 1.0, v131
	v_rcp_f32_e32 v131, v131
	v_cndmask_b32_e64 v133, v133, v148, s[4:5]
	v_mov_b32_e32 v152, v32
	v_mov_b32_e32 v150, v33
	v_mul_f32_e32 v131, v130, v131
	v_cndmask_b32_e64 v131, v131, v130, s[4:5]
	v_cvt_pk_bf16_f32 v130, v146, v132
	v_cvt_pk_bf16_f32 v131, v133, v131
	v_mov_b32_e32 v64, v130
	v_mov_b32_e32 v65, v131
	flat_store_dwordx4 v[224:225], v[62:65]
	s_cbranch_vccnz .LBB0_1323
	v_add_u32_e32 v131, 0xffffe0a0, v202
	v_ashrrev_i32_e32 v131, 2, v131
	v_lshl_add_u32 v131, v131, 1, v131
	v_mad_i64_i32 v[132:133], s[2:3], v131, s47, 0
	v_lshl_add_u64 v[132:133], v[132:133], 2, v[208:209]
	v_lshl_add_u64 v[146:147], v[132:133], 0, s[24:25]
	s_lshl_b32 s2, s27, 2
	s_mov_b32 s3, s25
	global_load_dwordx4 v[154:157], v[132:133], off offset:16
	s_nop 0
	global_load_dwordx4 v[146:149], v[146:147], off offset:16
	v_lshl_add_u64 v[132:133], v[132:133], 0, s[2:3]
	global_load_dwordx4 v[150:153], v[132:133], off offset:16
	v_mov_b32_dpp v160, v30 row_ror:1 row_mask:0xf bank_mask:0xf
	v_mov_b32_dpp v161, v30 row_ror:2 row_mask:0xf bank_mask:0xf
	v_mov_b32_dpp v130, v30 row_ror:3 row_mask:0xf bank_mask:0xf
	v_cmp_lt_i32_e32 vcc, 1, v205
	s_and_saveexec_b64 s[2:3], vcc
	s_xor_b64 s[2:3], exec, s[2:3]
	s_cbranch_execz .LBB0_1286
	v_cmp_gt_i32_e32 vcc, 3, v205
	s_and_saveexec_b64 s[20:21], vcc
	s_cbranch_execz .LBB0_1285
	s_waitcnt vmcnt(0)
	v_mov_b32_e32 v130, v150

; __device__ __forceinline__ float dpp_ror1(float v) { return __builtin_bit_cast(float, __builtin_amdgcn_update_dpp(0, __builtin_bit_cast(int, v), 0x121, 0xf, 0xf, false)); }
; __device__ __forceinline__ float dpp_ror2(float v) { return __builtin_bit_cast(float, __builtin_amdgcn_update_dpp(0, __builtin_bit_cast(int, v), 0x122, 0xf, 0xf, false)); }
; __device__ __forceinline__ float dpp_ror3(float v) { return __builtin_bit_cast(float, __builtin_amdgcn_update_dpp(0, __builtin_bit_cast(int, v), 0x123, 0xf, 0xf, false)); }
;     __device__ __forceinline__ void operator()(f32x4 (&acc)[2][2][4][2], const pg8::Unit& u, int wr, int wc, int fr, int fq) const {
;     ...
;                         else { const int t = fr & 3; const float* sp = stp + (size_t)((row - MP) >> 2) * 3 * CW + ch;
;                             const f32x4 b0 = *(const f32x4*)sp, b1 = *(const f32x4*)(sp + CW), b2 = *(const f32x4*)(sp + 2 * CW);
; #pragma unroll
;                             for (int j = 0; j < 4; ++j) { const float r1 = dpp_ror1(g[j]), r2 = dpp_ror2(g[j]), r3 = dpp_ror3(g[j]);
;                                 p1[j] = t >= 1 ? r1 : b2[j]; p2[j] = t >= 2 ? r2 : (t == 1 ? b2[j] : b1[j]); p3[j] = t >= 3 ? r3 : (t == 2 ? b2[j] : (t == 1 ? b1[j] : b0[j])); } }
.LBB0_1292:
	s_or_b64 exec, exec, s[2:3]
	v_mov_b32_dpp v168, v31 row_ror:1 row_mask:0xf bank_mask:0xf
	v_mov_b32_dpp v169, v31 row_ror:2 row_mask:0xf bank_mask:0xf
	v_mov_b32_dpp v131, v31 row_ror:3 row_mask:0xf bank_mask:0xf
	v_cmp_lt_i32_e32 vcc, 1, v205
	s_and_saveexec_b64 s[2:3], vcc
	s_xor_b64 s[2:3], exec, s[2:3]
	s_cbranch_execz .LBB0_1296
	v_cmp_gt_i32_e32 vcc, 3, v205
	s_and_saveexec_b64 s[20:21], vcc
	s_cbranch_execz .LBB0_1295
	s_waitcnt vmcnt(0)
	v_mov_b32_e32 v131, v151

; __device__ __forceinline__ float dpp_ror1(float v) { return __builtin_bit_cast(float, __builtin_amdgcn_update_dpp(0, __builtin_bit_cast(int, v), 0x121, 0xf, 0xf, false)); }
; __device__ __forceinline__ float dpp_ror2(float v) { return __builtin_bit_cast(float, __builtin_amdgcn_update_dpp(0, __builtin_bit_cast(int, v), 0x122, 0xf, 0xf, false)); }
; __device__ __forceinline__ float dpp_ror3(float v) { return __builtin_bit_cast(float, __builtin_amdgcn_update_dpp(0, __builtin_bit_cast(int, v), 0x123, 0xf, 0xf, false)); }
;     __device__ __forceinline__ void operator()(f32x4 (&acc)[2][2][4][2], const pg8::Unit& u, int wr, int wc, int fr, int fq) const {
;     ...
;                         else { const int t = fr & 3; const float* sp = stp + (size_t)((row - MP) >> 2) * 3 * CW + ch;
;                             const f32x4 b0 = *(const f32x4*)sp, b1 = *(const f32x4*)(sp + CW), b2 = *(const f32x4*)(sp + 2 * CW);
; #pragma unroll
;                             for (int j = 0; j < 4; ++j) { const float r1 = dpp_ror1(g[j]), r2 = dpp_ror2(g[j]), r3 = dpp_ror3(g[j]);
;                                 p1[j] = t >= 1 ? r1 : b2[j]; p2[j] = t >= 2 ? r2 : (t == 1 ? b2[j] : b1[j]); p3[j] = t >= 3 ? r3 : (t == 2 ? b2[j] : (t == 1 ? b1[j] : b0[j])); } }
.LBB0_1302:
	s_or_b64 exec, exec, s[2:3]
	v_mov_b32_dpp v170, v32 row_ror:1 row_mask:0xf bank_mask:0xf
	v_mov_b32_dpp v171, v32 row_ror:2 row_mask:0xf bank_mask:0xf
	v_mov_b32_dpp v132, v32 row_ror:3 row_mask:0xf bank_mask:0xf
	v_cmp_lt_i32_e32 vcc, 1, v205
	s_and_saveexec_b64 s[2:3], vcc
	s_xor_b64 s[2:3], exec, s[2:3]
	s_cbranch_execz .LBB0_1306
	v_cmp_gt_i32_e32 vcc, 3, v205
	s_and_saveexec_b64 s[20:21], vcc
	s_cbranch_execz .LBB0_1305
	s_waitcnt vmcnt(0)
	v_mov_b32_e32 v132, v152

; __device__ __forceinline__ float dpp_ror1(float v) { return __builtin_bit_cast(float, __builtin_amdgcn_update_dpp(0, __builtin_bit_cast(int, v), 0x121, 0xf, 0xf, false)); }
; __device__ __forceinline__ float dpp_ror2(float v) { return __builtin_bit_cast(float, __builtin_amdgcn_update_dpp(0, __builtin_bit_cast(int, v), 0x122, 0xf, 0xf, false)); }
; __device__ __forceinline__ float dpp_ror3(float v) { return __builtin_bit_cast(float, __builtin_amdgcn_update_dpp(0, __builtin_bit_cast(int, v), 0x123, 0xf, 0xf, false)); }
;     __device__ __forceinline__ void operator()(f32x4 (&acc)[2][2][4][2], const pg8::Unit& u, int wr, int wc, int fr, int fq) const {
;     ...
;                         else { const int t = fr & 3; const float* sp = stp + (size_t)((row - MP) >> 2) * 3 * CW + ch;
;                             const f32x4 b0 = *(const f32x4*)sp, b1 = *(const f32x4*)(sp + CW), b2 = *(const f32x4*)(sp + 2 * CW);
; #pragma unroll
;                             for (int j = 0; j < 4; ++j) { const float r1 = dpp_ror1(g[j]), r2 = dpp_ror2(g[j]), r3 = dpp_ror3(g[j]);
;                                 p1[j] = t >= 1 ? r1 : b2[j]; p2[j] = t >= 2 ? r2 : (t == 1 ? b2[j] : b1[j]); p3[j] = t >= 3 ? r3 : (t == 2 ? b2[j] : (t == 1 ? b1[j] : b0[j])); } }
.LBB0_1312:
	s_or_b64 exec, exec, s[2:3]
	v_mov_b32_dpp v173, v33 row_ror:1 row_mask:0xf bank_mask:0xf
	v_mov_b32_dpp v172, v33 row_ror:2 row_mask:0xf bank_mask:0xf
	v_mov_b32_dpp v133, v33 row_ror:3 row_mask:0xf bank_mask:0xf
	v_cmp_lt_i32_e32 vcc, 1, v205
	s_and_saveexec_b64 s[2:3], vcc
	s_xor_b64 s[2:3], exec, s[2:3]
	s_cbranch_execz .LBB0_1316
	v_cmp_gt_i32_e32 vcc, 3, v205
	s_and_saveexec_b64 s[20:21], vcc
	s_cbranch_execz .LBB0_1315
	s_waitcnt vmcnt(0)
	v_mov_b32_e32 v133, v153

; __device__ __forceinline__ unsigned cvt_pk_bf16(float lo, float hi) { unsigned r; asm("v_cvt_pk_bf16_f32 %0, %1, %2" : "=v"(r) : "v"(lo), "v"(hi)); return r; }
; __device__ __forceinline__ float siluf_(float x) { return x * sigmoidf_(x); }
; __device__ __forceinline__ float dpp_ror1(float v) { return __builtin_bit_cast(float, __builtin_amdgcn_update_dpp(0, __builtin_bit_cast(int, v), 0x121, 0xf, 0xf, false)); }
; __device__ __forceinline__ float dpp_ror2(float v) { return __builtin_bit_cast(float, __builtin_amdgcn_update_dpp(0, __builtin_bit_cast(int, v), 0x122, 0xf, 0xf, false)); }
; __device__ __forceinline__ float dpp_ror3(float v) { return __builtin_bit_cast(float, __builtin_amdgcn_update_dpp(0, __builtin_bit_cast(int, v), 0x123, 0xf, 0xf, false)); }
;     __device__ __forceinline__ void operator()(f32x4 (&acc)[2][2][4][2], const pg8::Unit& u, int wr, int wc, int fr, int fq) const {
;     ...
;                         if (prompt) { const f32x4 gp = (m == 0) ? hal[n] : acc[ai][bj][m > 0 ? m - 1 : 0][n];
; #pragma unroll
;                             for (int j = 0; j < 4; ++j) { p1[j] = dpp_ror1(fr == 15 ? gp[j] : g[j]); p2[j] = dpp_ror2(fr >= 14 ? gp[j] : g[j]); p3[j] = dpp_ror3(fr >= 13 ? gp[j] : g[j]); } }
;                         else { const int t = fr & 3; const float* sp = stp + (size_t)((row - MP) >> 2) * 3 * CW + ch;
;                             const f32x4 b0 = *(const f32x4*)sp, b1 = *(const f32x4*)(sp + CW), b2 = *(const f32x4*)(sp + 2 * CW);
; #pragma unroll
;                             for (int j = 0; j < 4; ++j) { const float r1 = dpp_ror1(g[j]), r2 = dpp_ror2(g[j]), r3 = dpp_ror3(g[j]);
;                                 p1[j] = t >= 1 ? r1 : b2[j]; p2[j] = t >= 2 ? r2 : (t == 1 ? b2[j] : b1[j]); p3[j] = t >= 3 ? r3 : (t == 2 ? b2[j] : (t == 1 ? b1[j] : b0[j])); } }
;                         float o[4];
; #pragma unroll
;                         for (int j = 0; j < 4; ++j) { const float y = bb[j] + w0[j] * p3[j] + w1[j] * p2[j] + w2[j] * p1[j] + w3[j] * g[j]; o[j] = is_rg ? y : siluf_(y); }
;                         u32x2 w; w.x = cvt_pk_bf16(o[0], o[1]); w.y = cvt_pk_bf16(o[2], o[3]);
;                         *(u32x2*)(dst + (size_t)row * ld + bj * 128 + 4 * n) = w; }
.LBB0_1323:
	s_and_b64 vcc, exec, s[2:3]
	s_cbranch_vccz .LBB0_1325
	v_cndmask_b32_e64 v130, v30, v42, s[10:11]
	v_cndmask_b32_e64 v131, v30, v42, s[6:7]
	s_nop 0
	v_mov_b32_dpp v154, v130 row_ror:1 row_mask:0xf bank_mask:0xf
	v_cndmask_b32_e64 v130, v30, v42, s[8:9]
	s_nop 1
	v_mov_b32_dpp v146, v130 row_ror:2 row_mask:0xf bank_mask:0xf
	v_cndmask_b32_e64 v132, v31, v43, s[6:7]
	v_mov_b32_dpp v130, v131 row_ror:3 row_mask:0xf bank_mask:0xf
	v_cndmask_b32_e64 v131, v31, v43, s[10:11]
	v_cndmask_b32_e64 v133, v32, v44, s[6:7]
	s_nop 0
	v_mov_b32_dpp v155, v131 row_ror:1 row_mask:0xf bank_mask:0xf
	v_cndmask_b32_e64 v131, v31, v43, s[8:9]
	s_nop 1
	v_mov_b32_dpp v147, v131 row_ror:2 row_mask:0xf bank_mask:0xf
	v_cndmask_b32_e64 v151, v33, v45, s[6:7]
	s_nop 0
	v_mov_b32_dpp v131, v132 row_ror:3 row_mask:0xf bank_mask:0xf
	v_cndmask_b32_e64 v132, v32, v44, s[10:11]
	s_nop 1
	v_mov_b32_dpp v156, v132 row_ror:1 row_mask:0xf bank_mask:0xf
	v_cndmask_b32_e64 v132, v32, v44, s[8:9]
	s_nop 1
	v_mov_b32_dpp v148, v132 row_ror:2 row_mask:0xf bank_mask:0xf
	s_nop 1
	v_mov_b32_dpp v132, v133 row_ror:3 row_mask:0xf bank_mask:0xf
	v_cndmask_b32_e64 v133, v33, v45, s[10:11]
	s_nop 1
	v_mov_b32_dpp v157, v133 row_ror:1 row_mask:0xf bank_mask:0xf
	v_cndmask_b32_e64 v133, v33, v45, s[8:9]
	s_nop 1
	v_mov_b32_dpp v149, v133 row_ror:2 row_mask:0xf bank_mask:0xf
	s_nop 1
	v_mov_b32_dpp v133, v151 row_ror:3 row_mask:0xf bank_mask:0xf
.LBB0_1325:
	v_mov_b32_e32 v170, v146
	v_mov_b32_e32 v171, v130
	v_pk_mul_f32 v[170:171], v[162:163], v[170:171]
	v_mov_b32_e32 v169, v154
	v_add_f32_e32 v130, v142, v171
	v_add_f32_e32 v130, v170, v130
	v_pk_mul_f32 v[168:169], v[164:165], v[168:169]
	v_mov_b32_e32 v161, v155
	v_add_f32_e32 v130, v169, v130
	v_add_f32_e32 v146, v168, v130
	v_mul_f32_e32 v130, 0xbfb8aa3b, v146
	v_exp_f32_e32 v130, v130
	v_mov_b32_e32 v153, v156
	s_mov_b64 s[2:3], -1
	s_and_b64 vcc, exec, s[18:19]
	v_add_f32_e32 v130, 1.0, v130
	v_rcp_f32_e32 v151, v130
	v_mov_b32_e32 v130, v147
	v_pk_mul_f32 v[130:131], v[138:139], v[130:131]
	v_mov_b32_e32 v168, v10
	v_add_f32_e32 v131, v143, v131
	v_add_f32_e32 v147, v130, v131
	v_pk_mul_f32 v[130:131], v[134:135], v[160:161]
	v_mov_b32_e32 v160, v11
	v_add_f32_e32 v131, v131, v147
	v_add_f32_e32 v147, v130, v131
	v_mul_f32_e32 v130, 0xbfb8aa3b, v147
	v_exp_f32_e32 v130, v130
	v_mul_f32_e32 v131, v146, v151
	v_cndmask_b32_e64 v146, v131, v146, s[4:5]
	v_mov_b32_e32 v131, v132
	v_add_f32_e32 v130, 1.0, v130
	v_rcp_f32_e32 v154, v130
	v_mov_b32_e32 v130, v148
	v_pk_mul_f32 v[130:131], v[158:159], v[130:131]
	v_mov_b32_e32 v151, v157
	v_add_f32_e32 v131, v144, v131
	v_add_f32_e32 v132, v130, v131
	v_pk_mul_f32 v[130:131], v[166:167], v[152:153]
	s_nop 0
	v_add_f32_e32 v131, v131, v132
	v_add_f32_e32 v148, v130, v131
	v_mul_f32_e32 v130, 0xbfb8aa3b, v148
	v_mov_b32_e32 v132, v149
	v_exp_f32_e32 v152, v130
	v_pk_mul_f32 v[130:131], v[140:141], v[132:133]
	v_add_f32_e32 v133, 1.0, v152
	v_add_f32_e32 v131, v145, v131
	v_add_f32_e32 v132, v130, v131
	v_pk_mul_f32 v[130:131], v[136:137], v[150:151]
	v_rcp_f32_e32 v133, v133
	v_add_f32_e32 v131, v131, v132
	v_add_f32_e32 v130, v130, v131
	v_mul_f32_e32 v131, 0xbfb8aa3b, v130
	v_exp_f32_e32 v131, v131
	v_mul_f32_e32 v132, v147, v154
	v_mul_f32_e32 v133, v148, v133
	v_cndmask_b32_e64 v132, v132, v147, s[4:5]
	v_add_f32_e32 v131, 1.0, v131
	v_rcp_f32_e32 v131, v131
	v_cndmask_b32_e64 v133, v133, v148, s[4:5]
	v_mov_b32_e32 v152, v12
	v_mov_b32_e32 v150, v13
	v_mul_f32_e32 v131, v130, v131
	v_cndmask_b32_e64 v131, v131, v130, s[4:5]
	v_cvt_pk_bf16_f32 v130, v146, v132
	v_cvt_pk_bf16_f32 v131, v133, v131
	v_mov_b32_e32 v48, v130
	v_mov_b32_e32 v49, v131
	flat_store_dwordx4 v[226:227], v[46:49]
	s_cbranch_vccnz .LBB0_1367
	v_add_u32_e32 v131, 0xffffe0b0, v202
	v_ashrrev_i32_e32 v131, 2, v131
	v_lshl_add_u32 v131, v131, 1, v131
	v_mad_i64_i32 v[132:133], s[2:3], v131, s47, 0
	v_lshl_add_u64 v[132:133], v[132:133], 2, v[208:209]
	v_lshl_add_u64 v[146:147], v[132:133], 0, s[24:25]
	s_lshl_b32 s2, s27, 2
	s_mov_b32 s3, s25
	global_load_dwordx4 v[154:157], v[132:133], off offset:16
	s_nop 0
	global_load_dwordx4 v[146:149], v[146:147], off offset:16
	v_lshl_add_u64 v[132:133], v[132:133], 0, s[2:3]
	global_load_dwordx4 v[150:153], v[132:133], off offset:16
	v_mov_b32_dpp v160, v10 row_ror:1 row_mask:0xf bank_mask:0xf
	v_mov_b32_dpp v161, v10 row_ror:2 row_mask:0xf bank_mask:0xf
	v_mov_b32_dpp v130, v10 row_ror:3 row_mask:0xf bank_mask:0xf
	v_cmp_lt_i32_e32 vcc, 1, v205
	s_and_saveexec_b64 s[2:3], vcc
	s_xor_b64 s[2:3], exec, s[2:3]
	s_cbranch_execz .LBB0_1330
	v_cmp_gt_i32_e32 vcc, 3, v205
	s_and_saveexec_b64 s[20:21], vcc
	s_cbranch_execz .LBB0_1329
	s_waitcnt vmcnt(0)
	v_mov_b32_e32 v130, v150

; __device__ __forceinline__ float dpp_ror1(float v) { return __builtin_bit_cast(float, __builtin_amdgcn_update_dpp(0, __builtin_bit_cast(int, v), 0x121, 0xf, 0xf, false)); }
; __device__ __forceinline__ float dpp_ror2(float v) { return __builtin_bit_cast(float, __builtin_amdgcn_update_dpp(0, __builtin_bit_cast(int, v), 0x122, 0xf, 0xf, false)); }
; __device__ __forceinline__ float dpp_ror3(float v) { return __builtin_bit_cast(float, __builtin_amdgcn_update_dpp(0, __builtin_bit_cast(int, v), 0x123, 0xf, 0xf, false)); }
;     __device__ __forceinline__ void operator()(f32x4 (&acc)[2][2][4][2], const pg8::Unit& u, int wr, int wc, int fr, int fq) const {
;     ...
;                         else { const int t = fr & 3; const float* sp = stp + (size_t)((row - MP) >> 2) * 3 * CW + ch;
;                             const f32x4 b0 = *(const f32x4*)sp, b1 = *(const f32x4*)(sp + CW), b2 = *(const f32x4*)(sp + 2 * CW);
; #pragma unroll
;                             for (int j = 0; j < 4; ++j) { const float r1 = dpp_ror1(g[j]), r2 = dpp_ror2(g[j]), r3 = dpp_ror3(g[j]);
;                                 p1[j] = t >= 1 ? r1 : b2[j]; p2[j] = t >= 2 ? r2 : (t == 1 ? b2[j] : b1[j]); p3[j] = t >= 3 ? r3 : (t == 2 ? b2[j] : (t == 1 ? b1[j] : b0[j])); } }
.LBB0_1336:
	s_or_b64 exec, exec, s[2:3]
	v_mov_b32_dpp v168, v11 row_ror:1 row_mask:0xf bank_mask:0xf
	v_mov_b32_dpp v169, v11 row_ror:2 row_mask:0xf bank_mask:0xf
	v_mov_b32_dpp v131, v11 row_ror:3 row_mask:0xf bank_mask:0xf
	v_cmp_lt_i32_e32 vcc, 1, v205
	s_and_saveexec_b64 s[2:3], vcc
	s_xor_b64 s[2:3], exec, s[2:3]
	s_cbranch_execz .LBB0_1340
	v_cmp_gt_i32_e32 vcc, 3, v205
	s_and_saveexec_b64 s[20:21], vcc
	s_cbranch_execz .LBB0_1339
	s_waitcnt vmcnt(0)
	v_mov_b32_e32 v131, v151

; __device__ __forceinline__ float dpp_ror1(float v) { return __builtin_bit_cast(float, __builtin_amdgcn_update_dpp(0, __builtin_bit_cast(int, v), 0x121, 0xf, 0xf, false)); }
; __device__ __forceinline__ float dpp_ror2(float v) { return __builtin_bit_cast(float, __builtin_amdgcn_update_dpp(0, __builtin_bit_cast(int, v), 0x122, 0xf, 0xf, false)); }
; __device__ __forceinline__ float dpp_ror3(float v) { return __builtin_bit_cast(float, __builtin_amdgcn_update_dpp(0, __builtin_bit_cast(int, v), 0x123, 0xf, 0xf, false)); }
;     __device__ __forceinline__ void operator()(f32x4 (&acc)[2][2][4][2], const pg8::Unit& u, int wr, int wc, int fr, int fq) const {
;     ...
;                         else { const int t = fr & 3; const float* sp = stp + (size_t)((row - MP) >> 2) * 3 * CW + ch;
;                             const f32x4 b0 = *(const f32x4*)sp, b1 = *(const f32x4*)(sp + CW), b2 = *(const f32x4*)(sp + 2 * CW);
; #pragma unroll
;                             for (int j = 0; j < 4; ++j) { const float r1 = dpp_ror1(g[j]), r2 = dpp_ror2(g[j]), r3 = dpp_ror3(g[j]);
;                                 p1[j] = t >= 1 ? r1 : b2[j]; p2[j] = t >= 2 ? r2 : (t == 1 ? b2[j] : b1[j]); p3[j] = t >= 3 ? r3 : (t == 2 ? b2[j] : (t == 1 ? b1[j] : b0[j])); } }
.LBB0_1346:
	s_or_b64 exec, exec, s[2:3]
	v_mov_b32_dpp v170, v12 row_ror:1 row_mask:0xf bank_mask:0xf
	v_mov_b32_dpp v171, v12 row_ror:2 row_mask:0xf bank_mask:0xf
	v_mov_b32_dpp v132, v12 row_ror:3 row_mask:0xf bank_mask:0xf
	v_cmp_lt_i32_e32 vcc, 1, v205
	s_and_saveexec_b64 s[2:3], vcc
	s_xor_b64 s[2:3], exec, s[2:3]
	s_cbranch_execz .LBB0_1350
	v_cmp_gt_i32_e32 vcc, 3, v205
	s_and_saveexec_b64 s[20:21], vcc
	s_cbranch_execz .LBB0_1349
	s_waitcnt vmcnt(0)
	v_mov_b32_e32 v132, v152

; __device__ __forceinline__ float dpp_ror1(float v) { return __builtin_bit_cast(float, __builtin_amdgcn_update_dpp(0, __builtin_bit_cast(int, v), 0x121, 0xf, 0xf, false)); }
; __device__ __forceinline__ float dpp_ror2(float v) { return __builtin_bit_cast(float, __builtin_amdgcn_update_dpp(0, __builtin_bit_cast(int, v), 0x122, 0xf, 0xf, false)); }
; __device__ __forceinline__ float dpp_ror3(float v) { return __builtin_bit_cast(float, __builtin_amdgcn_update_dpp(0, __builtin_bit_cast(int, v), 0x123, 0xf, 0xf, false)); }
;     __device__ __forceinline__ void operator()(f32x4 (&acc)[2][2][4][2], const pg8::Unit& u, int wr, int wc, int fr, int fq) const {
;     ...
;                         else { const int t = fr & 3; const float* sp = stp + (size_t)((row - MP) >> 2) * 3 * CW + ch;
;                             const f32x4 b0 = *(const f32x4*)sp, b1 = *(const f32x4*)(sp + CW), b2 = *(const f32x4*)(sp + 2 * CW);
; #pragma unroll
;                             for (int j = 0; j < 4; ++j) { const float r1 = dpp_ror1(g[j]), r2 = dpp_ror2(g[j]), r3 = dpp_ror3(g[j]);
;                                 p1[j] = t >= 1 ? r1 : b2[j]; p2[j] = t >= 2 ? r2 : (t == 1 ? b2[j] : b1[j]); p3[j] = t >= 3 ? r3 : (t == 2 ? b2[j] : (t == 1 ? b1[j] : b0[j])); } }
.LBB0_1356:
	s_or_b64 exec, exec, s[2:3]
	v_mov_b32_dpp v173, v13 row_ror:1 row_mask:0xf bank_mask:0xf
	v_mov_b32_dpp v172, v13 row_ror:2 row_mask:0xf bank_mask:0xf
	v_mov_b32_dpp v133, v13 row_ror:3 row_mask:0xf bank_mask:0xf
	v_cmp_lt_i32_e32 vcc, 1, v205
	s_and_saveexec_b64 s[2:3], vcc
	s_xor_b64 s[2:3], exec, s[2:3]
	s_cbranch_execz .LBB0_1360
	v_cmp_gt_i32_e32 vcc, 3, v205
	s_and_saveexec_b64 s[20:21], vcc
	s_cbranch_execz .LBB0_1359
	s_waitcnt vmcnt(0)
	v_mov_b32_e32 v133, v153

; __device__ __forceinline__ float dpp_ror1(float v) { return __builtin_bit_cast(float, __builtin_amdgcn_update_dpp(0, __builtin_bit_cast(int, v), 0x121, 0xf, 0xf, false)); }
; __device__ __forceinline__ float dpp_ror2(float v) { return __builtin_bit_cast(float, __builtin_amdgcn_update_dpp(0, __builtin_bit_cast(int, v), 0x122, 0xf, 0xf, false)); }
; __device__ __forceinline__ float dpp_ror3(float v) { return __builtin_bit_cast(float, __builtin_amdgcn_update_dpp(0, __builtin_bit_cast(int, v), 0x123, 0xf, 0xf, false)); }
;     __device__ __forceinline__ void operator()(f32x4 (&acc)[2][2][4][2], const pg8::Unit& u, int wr, int wc, int fr, int fq) const {
;     ...
;                         if (prompt) { const f32x4 gp = (m == 0) ? hal[n] : acc[ai][bj][m > 0 ? m - 1 : 0][n];
; #pragma unroll
;                             for (int j = 0; j < 4; ++j) { p1[j] = dpp_ror1(fr == 15 ? gp[j] : g[j]); p2[j] = dpp_ror2(fr >= 14 ? gp[j] : g[j]); p3[j] = dpp_ror3(fr >= 13 ? gp[j] : g[j]); } }
.LBB0_1367:
	s_and_b64 vcc, exec, s[2:3]
	s_cbranch_vccz .LBB0_1369
	v_cndmask_b32_e64 v130, v10, v30, s[10:11]
	v_cndmask_b32_e64 v131, v10, v30, s[6:7]
	s_nop 0
	v_mov_b32_dpp v154, v130 row_ror:1 row_mask:0xf bank_mask:0xf
	v_cndmask_b32_e64 v130, v10, v30, s[8:9]
	s_nop 1
	v_mov_b32_dpp v146, v130 row_ror:2 row_mask:0xf bank_mask:0xf
	v_cndmask_b32_e64 v132, v11, v31, s[6:7]
	v_mov_b32_dpp v130, v131 row_ror:3 row_mask:0xf bank_mask:0xf
	v_cndmask_b32_e64 v131, v11, v31, s[10:11]
	v_cndmask_b32_e64 v133, v12, v32, s[6:7]
	s_nop 0
	v_mov_b32_dpp v155, v131 row_ror:1 row_mask:0xf bank_mask:0xf
	v_cndmask_b32_e64 v131, v11, v31, s[8:9]
	s_nop 1
	v_mov_b32_dpp v147, v131 row_ror:2 row_mask:0xf bank_mask:0xf
	v_cndmask_b32_e64 v151, v13, v33, s[6:7]
	s_nop 0
	v_mov_b32_dpp v131, v132 row_ror:3 row_mask:0xf bank_mask:0xf
	v_cndmask_b32_e64 v132, v12, v32, s[10:11]
	s_nop 1
	v_mov_b32_dpp v156, v132 row_ror:1 row_mask:0xf bank_mask:0xf
	v_cndmask_b32_e64 v132, v12, v32, s[8:9]
	s_nop 1
	v_mov_b32_dpp v148, v132 row_ror:2 row_mask:0xf bank_mask:0xf
	s_nop 1
	v_mov_b32_dpp v132, v133 row_ror:3 row_mask:0xf bank_mask:0xf
	v_cndmask_b32_e64 v133, v13, v33, s[10:11]
	s_nop 1
	v_mov_b32_dpp v157, v133 row_ror:1 row_mask:0xf bank_mask:0xf
	v_cndmask_b32_e64 v133, v13, v33, s[8:9]
	s_nop 1
	v_mov_b32_dpp v149, v133 row_ror:2 row_mask:0xf bank_mask:0xf
	s_nop 1
	v_mov_b32_dpp v133, v151 row_ror:3 row_mask:0xf bank_mask:0xf

; __device__ __forceinline__ float dpp_ror1(float v) { return __builtin_bit_cast(float, __builtin_amdgcn_update_dpp(0, __builtin_bit_cast(int, v), 0x121, 0xf, 0xf, false)); }
; __device__ __forceinline__ float dpp_ror2(float v) { return __builtin_bit_cast(float, __builtin_amdgcn_update_dpp(0, __builtin_bit_cast(int, v), 0x122, 0xf, 0xf, false)); }
; __device__ __forceinline__ float dpp_ror3(float v) { return __builtin_bit_cast(float, __builtin_amdgcn_update_dpp(0, __builtin_bit_cast(int, v), 0x123, 0xf, 0xf, false)); }
;     __device__ __forceinline__ void operator()(f32x4 (&acc)[2][2][4][2], const pg8::Unit& u, int wr, int wc, int fr, int fq) const {
;     ...
;                 for (int n = 0; n < 2; ++n) { const int ch = ch0 + bj * 128 + 4 * n;
;                     const f32x4 w0 = *(const f32x4*)(cw + ch), w1 = *(const f32x4*)(cw + CW + ch), w2 = *(const f32x4*)(cw + 2 * CW + ch), w3 = *(const f32x4*)(cw + 3 * CW + ch), bb = *(const f32x4*)(cb + ch);
; #pragma unroll
;                     for (int m = 0; m < 4; ++m) { const int row = row0 + ai * 128 + m * 16; const f32x4 g = acc[ai][bj][m][n]; f32x4 p1, p2, p3;
;                         if (prompt) { const f32x4 gp = (m == 0) ? hal[n] : acc[ai][bj][m > 0 ? m - 1 : 0][n];
; #pragma unroll
;                             for (int j = 0; j < 4; ++j) { p1[j] = dpp_ror1(fr == 15 ? gp[j] : g[j]); p2[j] = dpp_ror2(fr >= 14 ? gp[j] : g[j]); p3[j] = dpp_ror3(fr >= 13 ? gp[j] : g[j]); } }
;                         else { const int t = fr & 3; const float* sp = stp + (size_t)((row - MP) >> 2) * 3 * CW + ch;
;                             const f32x4 b0 = *(const f32x4*)sp, b1 = *(const f32x4*)(sp + CW), b2 = *(const f32x4*)(sp + 2 * CW);
; #pragma unroll
;                             for (int j = 0; j < 4; ++j) { const float r1 = dpp_ror1(g[j]), r2 = dpp_ror2(g[j]), r3 = dpp_ror3(g[j]);
;                                 p1[j] = t >= 1 ? r1 : b2[j]; p2[j] = t >= 2 ? r2 : (t == 1 ? b2[j] : b1[j]); p3[j] = t >= 3 ? r3 : (t == 2 ? b2[j] : (t == 1 ? b1[j] : b0[j])); } }
.LBB0_1371:
	s_or_b64 exec, exec, s[2:3]
	global_load_dwordx4 v[138:141], v[210:211], off offset:512
	global_load_dwordx4 v[150:153], v[212:213], off offset:512
	global_load_dwordx4 v[134:137], v[214:215], off offset:512
	global_load_dwordx4 v[146:149], v[216:217], off offset:512
	global_load_dwordx4 v[142:145], v[218:219], off offset:512
	s_mov_b64 s[0:1], -1
	s_and_b64 vcc, exec, s[18:19]
	v_mov_b32_e32 v234, v54
	v_mov_b32_e32 v232, v55
	v_mov_b32_e32 v230, v56
	v_mov_b32_e32 v228, v57
	s_cbranch_vccnz .LBB0_1413
	v_add_u32_e32 v155, 0xffffe080, v202
	v_ashrrev_i32_e32 v155, 2, v155
	v_lshl_add_u32 v155, v155, 1, v155
	v_mad_i64_i32 v[156:157], s[0:1], v155, s47, 0
	v_lshl_add_u64 v[156:157], v[156:157], 2, v[208:209]
	v_lshl_add_u64 v[162:163], v[156:157], 0, s[24:25]
	s_lshl_b32 s0, s27, 2
	s_mov_b32 s1, s25
	global_load_dwordx4 v[170:173], v[156:157], off offset:512
	s_nop 0
	global_load_dwordx4 v[162:165], v[162:163], off offset:512
	v_lshl_add_u64 v[156:157], v[156:157], 0, s[0:1]
	global_load_dwordx4 v[166:169], v[156:157], off offset:512
	v_mov_b32_dpp v182, v54 row_ror:1 row_mask:0xf bank_mask:0xf
	v_mov_b32_dpp v207, v54 row_ror:2 row_mask:0xf bank_mask:0xf
	v_mov_b32_dpp v154, v54 row_ror:3 row_mask:0xf bank_mask:0xf
	v_cmp_lt_i32_e32 vcc, 1, v205
	s_and_saveexec_b64 s[0:1], vcc
	s_xor_b64 s[0:1], exec, s[0:1]
	s_cbranch_execz .LBB0_1376
	v_cmp_gt_i32_e32 vcc, 3, v205
	s_and_saveexec_b64 s[2:3], vcc
	s_cbranch_execz .LBB0_1375
	s_waitcnt vmcnt(0)
	v_mov_b32_e32 v154, v166

; __device__ __forceinline__ float dpp_ror1(float v) { return __builtin_bit_cast(float, __builtin_amdgcn_update_dpp(0, __builtin_bit_cast(int, v), 0x121, 0xf, 0xf, false)); }
; __device__ __forceinline__ float dpp_ror2(float v) { return __builtin_bit_cast(float, __builtin_amdgcn_update_dpp(0, __builtin_bit_cast(int, v), 0x122, 0xf, 0xf, false)); }
; __device__ __forceinline__ float dpp_ror3(float v) { return __builtin_bit_cast(float, __builtin_amdgcn_update_dpp(0, __builtin_bit_cast(int, v), 0x123, 0xf, 0xf, false)); }
;     __device__ __forceinline__ void operator()(f32x4 (&acc)[2][2][4][2], const pg8::Unit& u, int wr, int wc, int fr, int fq) const {
;     ...
;                         else { const int t = fr & 3; const float* sp = stp + (size_t)((row - MP) >> 2) * 3 * CW + ch;
;                             const f32x4 b0 = *(const f32x4*)sp, b1 = *(const f32x4*)(sp + CW), b2 = *(const f32x4*)(sp + 2 * CW);
; #pragma unroll
;                             for (int j = 0; j < 4; ++j) { const float r1 = dpp_ror1(g[j]), r2 = dpp_ror2(g[j]), r3 = dpp_ror3(g[j]);
;                                 p1[j] = t >= 1 ? r1 : b2[j]; p2[j] = t >= 2 ? r2 : (t == 1 ? b2[j] : b1[j]); p3[j] = t >= 3 ? r3 : (t == 2 ? b2[j] : (t == 1 ? b1[j] : b0[j])); } }
.LBB0_1382:
	s_or_b64 exec, exec, s[0:1]
	v_mov_b32_dpp v228, v55 row_ror:1 row_mask:0xf bank_mask:0xf
	v_mov_b32_dpp v229, v55 row_ror:2 row_mask:0xf bank_mask:0xf
	v_mov_b32_dpp v155, v55 row_ror:3 row_mask:0xf bank_mask:0xf
	v_cmp_lt_i32_e32 vcc, 1, v205
	s_and_saveexec_b64 s[0:1], vcc
	s_xor_b64 s[0:1], exec, s[0:1]
	s_cbranch_execz .LBB0_1386
	v_cmp_gt_i32_e32 vcc, 3, v205
	s_and_saveexec_b64 s[2:3], vcc
	s_cbranch_execz .LBB0_1385
	s_waitcnt vmcnt(0)
	v_mov_b32_e32 v155, v167

; __device__ __forceinline__ float dpp_ror1(float v) { return __builtin_bit_cast(float, __builtin_amdgcn_update_dpp(0, __builtin_bit_cast(int, v), 0x121, 0xf, 0xf, false)); }
; __device__ __forceinline__ float dpp_ror2(float v) { return __builtin_bit_cast(float, __builtin_amdgcn_update_dpp(0, __builtin_bit_cast(int, v), 0x122, 0xf, 0xf, false)); }
; __device__ __forceinline__ float dpp_ror3(float v) { return __builtin_bit_cast(float, __builtin_amdgcn_update_dpp(0, __builtin_bit_cast(int, v), 0x123, 0xf, 0xf, false)); }
;     __device__ __forceinline__ void operator()(f32x4 (&acc)[2][2][4][2], const pg8::Unit& u, int wr, int wc, int fr, int fq) const {
;     ...
;                         else { const int t = fr & 3; const float* sp = stp + (size_t)((row - MP) >> 2) * 3 * CW + ch;
;                             const f32x4 b0 = *(const f32x4*)sp, b1 = *(const f32x4*)(sp + CW), b2 = *(const f32x4*)(sp + 2 * CW);
; #pragma unroll
;                             for (int j = 0; j < 4; ++j) { const float r1 = dpp_ror1(g[j]), r2 = dpp_ror2(g[j]), r3 = dpp_ror3(g[j]);
;                                 p1[j] = t >= 1 ? r1 : b2[j]; p2[j] = t >= 2 ? r2 : (t == 1 ? b2[j] : b1[j]); p3[j] = t >= 3 ? r3 : (t == 2 ? b2[j] : (t == 1 ? b1[j] : b0[j])); } }
.LBB0_1392:
	s_or_b64 exec, exec, s[0:1]
	v_mov_b32_dpp v230, v56 row_ror:1 row_mask:0xf bank_mask:0xf
	v_mov_b32_dpp v231, v56 row_ror:2 row_mask:0xf bank_mask:0xf
	v_mov_b32_dpp v156, v56 row_ror:3 row_mask:0xf bank_mask:0xf
	v_cmp_lt_i32_e32 vcc, 1, v205
	s_and_saveexec_b64 s[0:1], vcc
	s_xor_b64 s[0:1], exec, s[0:1]
	s_cbranch_execz .LBB0_1396
	v_cmp_gt_i32_e32 vcc, 3, v205
	s_and_saveexec_b64 s[2:3], vcc
	s_cbranch_execz .LBB0_1395
	s_waitcnt vmcnt(0)
	v_mov_b32_e32 v156, v168

; __device__ __forceinline__ float dpp_ror1(float v) { return __builtin_bit_cast(float, __builtin_amdgcn_update_dpp(0, __builtin_bit_cast(int, v), 0x121, 0xf, 0xf, false)); }
; __device__ __forceinline__ float dpp_ror2(float v) { return __builtin_bit_cast(float, __builtin_amdgcn_update_dpp(0, __builtin_bit_cast(int, v), 0x122, 0xf, 0xf, false)); }
; __device__ __forceinline__ float dpp_ror3(float v) { return __builtin_bit_cast(float, __builtin_amdgcn_update_dpp(0, __builtin_bit_cast(int, v), 0x123, 0xf, 0xf, false)); }
;     __device__ __forceinline__ void operator()(f32x4 (&acc)[2][2][4][2], const pg8::Unit& u, int wr, int wc, int fr, int fq) const {
;     ...
;                         else { const int t = fr & 3; const float* sp = stp + (size_t)((row - MP) >> 2) * 3 * CW + ch;
;                             const f32x4 b0 = *(const f32x4*)sp, b1 = *(const f32x4*)(sp + CW), b2 = *(const f32x4*)(sp + 2 * CW);
; #pragma unroll
;                             for (int j = 0; j < 4; ++j) { const float r1 = dpp_ror1(g[j]), r2 = dpp_ror2(g[j]), r3 = dpp_ror3(g[j]);
;                                 p1[j] = t >= 1 ? r1 : b2[j]; p2[j] = t >= 2 ? r2 : (t == 1 ? b2[j] : b1[j]); p3[j] = t >= 3 ? r3 : (t == 2 ? b2[j] : (t == 1 ? b1[j] : b0[j])); } }
.LBB0_1402:
	s_or_b64 exec, exec, s[0:1]
	v_mov_b32_dpp v233, v57 row_ror:1 row_mask:0xf bank_mask:0xf
	v_mov_b32_dpp v232, v57 row_ror:2 row_mask:0xf bank_mask:0xf
	v_mov_b32_dpp v157, v57 row_ror:3 row_mask:0xf bank_mask:0xf
	v_cmp_lt_i32_e32 vcc, 1, v205
	s_and_saveexec_b64 s[0:1], vcc
	s_xor_b64 s[0:1], exec, s[0:1]
	s_cbranch_execz .LBB0_1406
	v_cmp_gt_i32_e32 vcc, 3, v205
	s_and_saveexec_b64 s[2:3], vcc
	s_cbranch_execz .LBB0_1405
	s_waitcnt vmcnt(0)
	v_mov_b32_e32 v157, v169

; __device__ __forceinline__ unsigned cvt_pk_bf16(float lo, float hi) { unsigned r; asm("v_cvt_pk_bf16_f32 %0, %1, %2" : "=v"(r) : "v"(lo), "v"(hi)); return r; }
; __device__ __forceinline__ float siluf_(float x) { return x * sigmoidf_(x); }
; __device__ __forceinline__ float dpp_ror1(float v) { return __builtin_bit_cast(float, __builtin_amdgcn_update_dpp(0, __builtin_bit_cast(int, v), 0x121, 0xf, 0xf, false)); }
; __device__ __forceinline__ float dpp_ror2(float v) { return __builtin_bit_cast(float, __builtin_amdgcn_update_dpp(0, __builtin_bit_cast(int, v), 0x122, 0xf, 0xf, false)); }
; __device__ __forceinline__ float dpp_ror3(float v) { return __builtin_bit_cast(float, __builtin_amdgcn_update_dpp(0, __builtin_bit_cast(int, v), 0x123, 0xf, 0xf, false)); }
;     __device__ __forceinline__ void operator()(f32x4 (&acc)[2][2][4][2], const pg8::Unit& u, int wr, int wc, int fr, int fq) const {
;     ...
;                         if (prompt) { const f32x4 gp = (m == 0) ? hal[n] : acc[ai][bj][m > 0 ? m - 1 : 0][n];
; #pragma unroll
;                             for (int j = 0; j < 4; ++j) { p1[j] = dpp_ror1(fr == 15 ? gp[j] : g[j]); p2[j] = dpp_ror2(fr >= 14 ? gp[j] : g[j]); p3[j] = dpp_ror3(fr >= 13 ? gp[j] : g[j]); } }
;                         else { const int t = fr & 3; const float* sp = stp + (size_t)((row - MP) >> 2) * 3 * CW + ch;
;                             const f32x4 b0 = *(const f32x4*)sp, b1 = *(const f32x4*)(sp + CW), b2 = *(const f32x4*)(sp + 2 * CW);
; #pragma unroll
;                             for (int j = 0; j < 4; ++j) { const float r1 = dpp_ror1(g[j]), r2 = dpp_ror2(g[j]), r3 = dpp_ror3(g[j]);
;                                 p1[j] = t >= 1 ? r1 : b2[j]; p2[j] = t >= 2 ? r2 : (t == 1 ? b2[j] : b1[j]); p3[j] = t >= 3 ? r3 : (t == 2 ? b2[j] : (t == 1 ? b1[j] : b0[j])); } }
;                         float o[4];
; #pragma unroll
;                         for (int j = 0; j < 4; ++j) { const float y = bb[j] + w0[j] * p3[j] + w1[j] * p2[j] + w2[j] * p1[j] + w3[j] * g[j]; o[j] = is_rg ? y : siluf_(y); }
;                         u32x2 w; w.x = cvt_pk_bf16(o[0], o[1]); w.y = cvt_pk_bf16(o[2], o[3]);
;                         *(u32x2*)(dst + (size_t)row * ld + bj * 128 + 4 * n) = w; }
.LBB0_1413:
	s_and_b64 vcc, exec, s[0:1]
	s_cbranch_vccz .LBB0_1415
	s_waitcnt lgkmcnt(0)
	v_cndmask_b32_e64 v154, v54, v158, s[10:11]
	v_cndmask_b32_e64 v155, v54, v158, s[6:7]
	s_nop 0
	v_mov_b32_dpp v170, v154 row_ror:1 row_mask:0xf bank_mask:0xf
	v_cndmask_b32_e64 v154, v54, v158, s[8:9]
	s_nop 1
	v_mov_b32_dpp v162, v154 row_ror:2 row_mask:0xf bank_mask:0xf
	v_cndmask_b32_e64 v156, v55, v159, s[6:7]
	v_mov_b32_dpp v154, v155 row_ror:3 row_mask:0xf bank_mask:0xf
	v_cndmask_b32_e64 v155, v55, v159, s[10:11]
	v_cndmask_b32_e64 v157, v56, v160, s[6:7]
	s_nop 0
	v_mov_b32_dpp v171, v155 row_ror:1 row_mask:0xf bank_mask:0xf
	v_cndmask_b32_e64 v155, v55, v159, s[8:9]
	s_nop 1
	v_mov_b32_dpp v163, v155 row_ror:2 row_mask:0xf bank_mask:0xf
	v_cndmask_b32_e64 v158, v57, v161, s[6:7]
	s_nop 0
	v_mov_b32_dpp v155, v156 row_ror:3 row_mask:0xf bank_mask:0xf
	v_cndmask_b32_e64 v156, v56, v160, s[10:11]
	s_nop 1
	v_mov_b32_dpp v172, v156 row_ror:1 row_mask:0xf bank_mask:0xf
	v_cndmask_b32_e64 v156, v56, v160, s[8:9]
	s_nop 1
	v_mov_b32_dpp v164, v156 row_ror:2 row_mask:0xf bank_mask:0xf
	s_nop 1
	v_mov_b32_dpp v156, v157 row_ror:3 row_mask:0xf bank_mask:0xf
	v_cndmask_b32_e64 v157, v57, v161, s[10:11]
	s_nop 1
	v_mov_b32_dpp v173, v157 row_ror:1 row_mask:0xf bank_mask:0xf
	v_cndmask_b32_e64 v157, v57, v161, s[8:9]
	s_nop 1
	v_mov_b32_dpp v165, v157 row_ror:2 row_mask:0xf bank_mask:0xf
	s_nop 1
	v_mov_b32_dpp v157, v158 row_ror:3 row_mask:0xf bank_mask:0xf
.LBB0_1415:
	s_waitcnt vmcnt(0)
	v_mov_b32_e32 v166, v150
	v_mov_b32_e32 v167, v138
	s_waitcnt lgkmcnt(0)
	v_mov_b32_e32 v158, v162
	v_mov_b32_e32 v159, v154
	v_pk_mul_f32 v[158:159], v[166:167], v[158:159]
	v_mov_b32_e32 v168, v146
	v_add_f32_e32 v138, v142, v159
	v_mov_b32_e32 v169, v134
	v_mov_b32_e32 v235, v170
	v_add_f32_e32 v138, v158, v138
	v_pk_mul_f32 v[158:159], v[168:169], v[234:235]
	v_mov_b32_e32 v154, v163
	v_add_f32_e32 v134, v159, v138
	v_add_f32_e32 v158, v158, v134
	v_mul_f32_e32 v134, 0xbfb8aa3b, v158
	v_exp_f32_e32 v134, v134
	v_mov_b32_e32 v138, v151
	v_pk_mul_f32 v[150:151], v[138:139], v[154:155]
	v_mov_b32_e32 v233, v171
	v_add_f32_e32 v134, 1.0, v134
	v_rcp_f32_e32 v159, v134
	v_add_f32_e32 v134, v143, v151
	v_add_f32_e32 v150, v150, v134
	v_mov_b32_e32 v134, v147
	v_pk_mul_f32 v[146:147], v[134:135], v[232:233]
	v_mov_b32_e32 v162, v152
	v_add_f32_e32 v147, v147, v150
	v_add_f32_e32 v150, v146, v147
	v_mul_f32_e32 v146, 0xbfb8aa3b, v150
	v_exp_f32_e32 v146, v146
	v_mul_f32_e32 v147, v158, v159
	v_cndmask_b32_e64 v151, v147, v158, s[4:5]
	v_mov_b32_e32 v163, v140
	v_add_f32_e32 v146, 1.0, v146
	v_rcp_f32_e32 v154, v146
	v_mov_b32_e32 v146, v164
	v_mov_b32_e32 v147, v156
	v_pk_mul_f32 v[146:147], v[162:163], v[146:147]
	v_mov_b32_e32 v170, v148
	v_add_f32_e32 v140, v144, v147
	v_mov_b32_e32 v171, v136
	v_mov_b32_e32 v231, v172
	v_add_f32_e32 v140, v146, v140
	v_pk_mul_f32 v[146:147], v[170:171], v[230:231]
	v_mov_b32_e32 v156, v165
	v_add_f32_e32 v136, v147, v140
	v_add_f32_e32 v148, v146, v136
	v_mov_b32_e32 v140, v153
	v_mul_f32_e32 v136, 0xbfb8aa3b, v148
	v_pk_mul_f32 v[146:147], v[140:141], v[156:157]
	v_exp_f32_e32 v152, v136
	v_add_f32_e32 v136, v145, v147
	v_add_f32_e32 v153, v146, v136
	v_mov_b32_e32 v136, v149
	v_mov_b32_e32 v229, v173
	v_pk_mul_f32 v[146:147], v[136:137], v[228:229]
	v_add_f32_e32 v152, 1.0, v152
	v_add_f32_e32 v147, v147, v153
	v_add_f32_e32 v146, v146, v147
	v_mul_f32_e32 v147, 0xbfb8aa3b, v146
	v_exp_f32_e32 v147, v147
	v_rcp_f32_e32 v152, v152
	v_mul_f32_e32 v149, v150, v154
	v_cndmask_b32_e64 v149, v149, v150, s[4:5]
	v_add_f32_e32 v147, 1.0, v147
	v_rcp_f32_e32 v147, v147
	v_mul_f32_e32 v150, v148, v152
	v_cndmask_b32_e64 v148, v150, v148, s[4:5]
	s_mov_b64 s[0:1], -1
	v_mul_f32_e32 v147, v146, v147
	v_cndmask_b32_e64 v147, v147, v146, s[4:5]
	v_cvt_pk_bf16_f32 v146, v151, v149
	v_cvt_pk_bf16_f32 v147, v148, v147
	s_and_b64 vcc, exec, s[18:19]
	v_mov_b32_e32 v172, v38
	v_mov_b32_e32 v164, v39
	v_mov_b32_e32 v156, v40
	v_mov_b32_e32 v154, v41
	v_mov_b32_e32 v14, v146
	v_mov_b32_e32 v15, v147
	s_cbranch_vccnz .LBB0_1457
	v_add_u32_e32 v147, 0xffffe090, v202
	v_ashrrev_i32_e32 v147, 2, v147
	v_lshl_add_u32 v147, v147, 1, v147
	v_mad_i64_i32 v[148:149], s[0:1], v147, s47, 0
	v_lshl_add_u64 v[148:149], v[148:149], 2, v[208:209]
	v_lshl_add_u64 v[150:151], v[148:149], 0, s[24:25]
	s_lshl_b32 s0, s27, 2
	s_mov_b32 s1, s25
	global_load_dwordx4 v[158:161], v[148:149], off offset:512
	s_nop 0
	global_load_dwordx4 v[150:153], v[150:151], off offset:512
	v_lshl_add_u64 v[148:149], v[148:149], 0, s[0:1]
	global_load_dwordx4 v[154:157], v[148:149], off offset:512
	v_mov_b32_dpp v164, v38 row_ror:1 row_mask:0xf bank_mask:0xf
	v_mov_b32_dpp v165, v38 row_ror:2 row_mask:0xf bank_mask:0xf
	v_mov_b32_dpp v146, v38 row_ror:3 row_mask:0xf bank_mask:0xf
	v_cmp_lt_i32_e32 vcc, 1, v205
	s_and_saveexec_b64 s[0:1], vcc
	s_xor_b64 s[0:1], exec, s[0:1]
	s_cbranch_execz .LBB0_1420
	v_cmp_gt_i32_e32 vcc, 3, v205
	s_and_saveexec_b64 s[2:3], vcc
	s_cbranch_execz .LBB0_1419
	s_waitcnt vmcnt(0)
	v_mov_b32_e32 v146, v154

; __device__ __forceinline__ float dpp_ror1(float v) { return __builtin_bit_cast(float, __builtin_amdgcn_update_dpp(0, __builtin_bit_cast(int, v), 0x121, 0xf, 0xf, false)); }
; __device__ __forceinline__ float dpp_ror2(float v) { return __builtin_bit_cast(float, __builtin_amdgcn_update_dpp(0, __builtin_bit_cast(int, v), 0x122, 0xf, 0xf, false)); }
; __device__ __forceinline__ float dpp_ror3(float v) { return __builtin_bit_cast(float, __builtin_amdgcn_update_dpp(0, __builtin_bit_cast(int, v), 0x123, 0xf, 0xf, false)); }
;     __device__ __forceinline__ void operator()(f32x4 (&acc)[2][2][4][2], const pg8::Unit& u, int wr, int wc, int fr, int fq) const {
;     ...
;                         else { const int t = fr & 3; const float* sp = stp + (size_t)((row - MP) >> 2) * 3 * CW + ch;
;                             const f32x4 b0 = *(const f32x4*)sp, b1 = *(const f32x4*)(sp + CW), b2 = *(const f32x4*)(sp + 2 * CW);
; #pragma unroll
;                             for (int j = 0; j < 4; ++j) { const float r1 = dpp_ror1(g[j]), r2 = dpp_ror2(g[j]), r3 = dpp_ror3(g[j]);
;                                 p1[j] = t >= 1 ? r1 : b2[j]; p2[j] = t >= 2 ? r2 : (t == 1 ? b2[j] : b1[j]); p3[j] = t >= 3 ? r3 : (t == 2 ? b2[j] : (t == 1 ? b1[j] : b0[j])); } }
.LBB0_1426:
	s_or_b64 exec, exec, s[0:1]
	v_mov_b32_dpp v172, v39 row_ror:1 row_mask:0xf bank_mask:0xf
	v_mov_b32_dpp v173, v39 row_ror:2 row_mask:0xf bank_mask:0xf
	v_mov_b32_dpp v147, v39 row_ror:3 row_mask:0xf bank_mask:0xf
	v_cmp_lt_i32_e32 vcc, 1, v205
	s_and_saveexec_b64 s[0:1], vcc
	s_xor_b64 s[0:1], exec, s[0:1]
	s_cbranch_execz .LBB0_1430
	v_cmp_gt_i32_e32 vcc, 3, v205
	s_and_saveexec_b64 s[2:3], vcc
	s_cbranch_execz .LBB0_1429
	s_waitcnt vmcnt(0)
	v_mov_b32_e32 v147, v155

; __device__ __forceinline__ float dpp_ror1(float v) { return __builtin_bit_cast(float, __builtin_amdgcn_update_dpp(0, __builtin_bit_cast(int, v), 0x121, 0xf, 0xf, false)); }
; __device__ __forceinline__ float dpp_ror2(float v) { return __builtin_bit_cast(float, __builtin_amdgcn_update_dpp(0, __builtin_bit_cast(int, v), 0x122, 0xf, 0xf, false)); }
; __device__ __forceinline__ float dpp_ror3(float v) { return __builtin_bit_cast(float, __builtin_amdgcn_update_dpp(0, __builtin_bit_cast(int, v), 0x123, 0xf, 0xf, false)); }
;     __device__ __forceinline__ void operator()(f32x4 (&acc)[2][2][4][2], const pg8::Unit& u, int wr, int wc, int fr, int fq) const {
;     ...
;                         else { const int t = fr & 3; const float* sp = stp + (size_t)((row - MP) >> 2) * 3 * CW + ch;
;                             const f32x4 b0 = *(const f32x4*)sp, b1 = *(const f32x4*)(sp + CW), b2 = *(const f32x4*)(sp + 2 * CW);
; #pragma unroll
;                             for (int j = 0; j < 4; ++j) { const float r1 = dpp_ror1(g[j]), r2 = dpp_ror2(g[j]), r3 = dpp_ror3(g[j]);
;                                 p1[j] = t >= 1 ? r1 : b2[j]; p2[j] = t >= 2 ? r2 : (t == 1 ? b2[j] : b1[j]); p3[j] = t >= 3 ? r3 : (t == 2 ? b2[j] : (t == 1 ? b1[j] : b0[j])); } }
.LBB0_1436:
	s_or_b64 exec, exec, s[0:1]
	v_mov_b32_dpp v182, v40 row_ror:1 row_mask:0xf bank_mask:0xf
	v_mov_b32_dpp v207, v40 row_ror:2 row_mask:0xf bank_mask:0xf
	v_mov_b32_dpp v148, v40 row_ror:3 row_mask:0xf bank_mask:0xf
	v_cmp_lt_i32_e32 vcc, 1, v205
	s_and_saveexec_b64 s[0:1], vcc
	s_xor_b64 s[0:1], exec, s[0:1]
	s_cbranch_execz .LBB0_1440
	v_cmp_gt_i32_e32 vcc, 3, v205
	s_and_saveexec_b64 s[2:3], vcc
	s_cbranch_execz .LBB0_1439
	s_waitcnt vmcnt(0)
	v_mov_b32_e32 v148, v156

; __device__ __forceinline__ float dpp_ror1(float v) { return __builtin_bit_cast(float, __builtin_amdgcn_update_dpp(0, __builtin_bit_cast(int, v), 0x121, 0xf, 0xf, false)); }
; __device__ __forceinline__ float dpp_ror2(float v) { return __builtin_bit_cast(float, __builtin_amdgcn_update_dpp(0, __builtin_bit_cast(int, v), 0x122, 0xf, 0xf, false)); }
; __device__ __forceinline__ float dpp_ror3(float v) { return __builtin_bit_cast(float, __builtin_amdgcn_update_dpp(0, __builtin_bit_cast(int, v), 0x123, 0xf, 0xf, false)); }
;     __device__ __forceinline__ void operator()(f32x4 (&acc)[2][2][4][2], const pg8::Unit& u, int wr, int wc, int fr, int fq) const {
;     ...
;                         else { const int t = fr & 3; const float* sp = stp + (size_t)((row - MP) >> 2) * 3 * CW + ch;
;                             const f32x4 b0 = *(const f32x4*)sp, b1 = *(const f32x4*)(sp + CW), b2 = *(const f32x4*)(sp + 2 * CW);
; #pragma unroll
;                             for (int j = 0; j < 4; ++j) { const float r1 = dpp_ror1(g[j]), r2 = dpp_ror2(g[j]), r3 = dpp_ror3(g[j]);
;                                 p1[j] = t >= 1 ? r1 : b2[j]; p2[j] = t >= 2 ? r2 : (t == 1 ? b2[j] : b1[j]); p3[j] = t >= 3 ? r3 : (t == 2 ? b2[j] : (t == 1 ? b1[j] : b0[j])); } }
.LBB0_1446:
	s_or_b64 exec, exec, s[0:1]
	v_mov_b32_dpp v229, v41 row_ror:1 row_mask:0xf bank_mask:0xf
	v_mov_b32_dpp v228, v41 row_ror:2 row_mask:0xf bank_mask:0xf
	v_mov_b32_dpp v149, v41 row_ror:3 row_mask:0xf bank_mask:0xf
	v_cmp_lt_i32_e32 vcc, 1, v205
	s_and_saveexec_b64 s[0:1], vcc
	s_xor_b64 s[0:1], exec, s[0:1]
	s_cbranch_execz .LBB0_1450
	v_cmp_gt_i32_e32 vcc, 3, v205
	s_and_saveexec_b64 s[2:3], vcc
	s_cbranch_execz .LBB0_1449
	s_waitcnt vmcnt(0)
	v_mov_b32_e32 v149, v157

; __device__ __forceinline__ unsigned cvt_pk_bf16(float lo, float hi) { unsigned r; asm("v_cvt_pk_bf16_f32 %0, %1, %2" : "=v"(r) : "v"(lo), "v"(hi)); return r; }
; __device__ __forceinline__ float siluf_(float x) { return x * sigmoidf_(x); }
; __device__ __forceinline__ float dpp_ror1(float v) { return __builtin_bit_cast(float, __builtin_amdgcn_update_dpp(0, __builtin_bit_cast(int, v), 0x121, 0xf, 0xf, false)); }
; __device__ __forceinline__ float dpp_ror2(float v) { return __builtin_bit_cast(float, __builtin_amdgcn_update_dpp(0, __builtin_bit_cast(int, v), 0x122, 0xf, 0xf, false)); }
; __device__ __forceinline__ float dpp_ror3(float v) { return __builtin_bit_cast(float, __builtin_amdgcn_update_dpp(0, __builtin_bit_cast(int, v), 0x123, 0xf, 0xf, false)); }
;     __device__ __forceinline__ void operator()(f32x4 (&acc)[2][2][4][2], const pg8::Unit& u, int wr, int wc, int fr, int fq) const {
;     ...
;                         if (prompt) { const f32x4 gp = (m == 0) ? hal[n] : acc[ai][bj][m > 0 ? m - 1 : 0][n];
; #pragma unroll
;                             for (int j = 0; j < 4; ++j) { p1[j] = dpp_ror1(fr == 15 ? gp[j] : g[j]); p2[j] = dpp_ror2(fr >= 14 ? gp[j] : g[j]); p3[j] = dpp_ror3(fr >= 13 ? gp[j] : g[j]); } }
;                         else { const int t = fr & 3; const float* sp = stp + (size_t)((row - MP) >> 2) * 3 * CW + ch;
;                             const f32x4 b0 = *(const f32x4*)sp, b1 = *(const f32x4*)(sp + CW), b2 = *(const f32x4*)(sp + 2 * CW);
; #pragma unroll
;                             for (int j = 0; j < 4; ++j) { const float r1 = dpp_ror1(g[j]), r2 = dpp_ror2(g[j]), r3 = dpp_ror3(g[j]);
;                                 p1[j] = t >= 1 ? r1 : b2[j]; p2[j] = t >= 2 ? r2 : (t == 1 ? b2[j] : b1[j]); p3[j] = t >= 3 ? r3 : (t == 2 ? b2[j] : (t == 1 ? b1[j] : b0[j])); } }
;                         float o[4];
; #pragma unroll
;                         for (int j = 0; j < 4; ++j) { const float y = bb[j] + w0[j] * p3[j] + w1[j] * p2[j] + w2[j] * p1[j] + w3[j] * g[j]; o[j] = is_rg ? y : siluf_(y); }
;                         u32x2 w; w.x = cvt_pk_bf16(o[0], o[1]); w.y = cvt_pk_bf16(o[2], o[3]);
;                         *(u32x2*)(dst + (size_t)row * ld + bj * 128 + 4 * n) = w; }
.LBB0_1457:
	s_and_b64 vcc, exec, s[0:1]
	s_cbranch_vccz .LBB0_1459
	v_cndmask_b32_e64 v146, v38, v54, s[10:11]
	v_cndmask_b32_e64 v147, v38, v54, s[6:7]
	s_nop 0
	v_mov_b32_dpp v158, v146 row_ror:1 row_mask:0xf bank_mask:0xf
	v_cndmask_b32_e64 v146, v38, v54, s[8:9]
	s_nop 1
	v_mov_b32_dpp v150, v146 row_ror:2 row_mask:0xf bank_mask:0xf
	v_cndmask_b32_e64 v148, v39, v55, s[6:7]
	v_mov_b32_dpp v146, v147 row_ror:3 row_mask:0xf bank_mask:0xf
	v_cndmask_b32_e64 v147, v39, v55, s[10:11]
	v_cndmask_b32_e64 v149, v40, v56, s[6:7]
	s_nop 0
	v_mov_b32_dpp v159, v147 row_ror:1 row_mask:0xf bank_mask:0xf
	v_cndmask_b32_e64 v147, v39, v55, s[8:9]
	s_nop 1
	v_mov_b32_dpp v151, v147 row_ror:2 row_mask:0xf bank_mask:0xf
	v_cndmask_b32_e64 v155, v41, v57, s[6:7]
	s_nop 0
	v_mov_b32_dpp v147, v148 row_ror:3 row_mask:0xf bank_mask:0xf
	v_cndmask_b32_e64 v148, v40, v56, s[10:11]
	s_nop 1
	v_mov_b32_dpp v160, v148 row_ror:1 row_mask:0xf bank_mask:0xf
	v_cndmask_b32_e64 v148, v40, v56, s[8:9]
	s_nop 1
	v_mov_b32_dpp v152, v148 row_ror:2 row_mask:0xf bank_mask:0xf
	s_nop 1
	v_mov_b32_dpp v148, v149 row_ror:3 row_mask:0xf bank_mask:0xf
	v_cndmask_b32_e64 v149, v41, v57, s[10:11]
	s_nop 1
	v_mov_b32_dpp v161, v149 row_ror:1 row_mask:0xf bank_mask:0xf
	v_cndmask_b32_e64 v149, v41, v57, s[8:9]
	s_nop 1
	v_mov_b32_dpp v153, v149 row_ror:2 row_mask:0xf bank_mask:0xf
	s_nop 1
	v_mov_b32_dpp v149, v155 row_ror:3 row_mask:0xf bank_mask:0xf
.LBB0_1459:
	v_mov_b32_e32 v228, v150
	v_mov_b32_e32 v229, v146
	v_pk_mul_f32 v[228:229], v[166:167], v[228:229]
	v_mov_b32_e32 v173, v158
	v_add_f32_e32 v146, v142, v229
	v_add_f32_e32 v146, v228, v146
	v_pk_mul_f32 v[172:173], v[168:169], v[172:173]
	v_mov_b32_e32 v165, v159
	v_add_f32_e32 v146, v173, v146
	v_add_f32_e32 v150, v172, v146
	v_mul_f32_e32 v146, 0xbfb8aa3b, v150
	v_exp_f32_e32 v146, v146
	v_mov_b32_e32 v157, v160
	s_mov_b64 s[0:1], -1
	s_and_b64 vcc, exec, s[18:19]
	v_add_f32_e32 v146, 1.0, v146
	v_rcp_f32_e32 v155, v146
	v_mov_b32_e32 v146, v151
	v_pk_mul_f32 v[146:147], v[138:139], v[146:147]
	v_mov_b32_e32 v172, v22
	v_add_f32_e32 v147, v143, v147
	v_add_f32_e32 v151, v146, v147
	v_pk_mul_f32 v[146:147], v[134:135], v[164:165]
	v_mov_b32_e32 v164, v23
	v_add_f32_e32 v147, v147, v151
	v_add_f32_e32 v151, v146, v147
	v_mul_f32_e32 v146, 0xbfb8aa3b, v151
	v_exp_f32_e32 v146, v146
	v_mul_f32_e32 v147, v150, v155
	v_cndmask_b32_e64 v150, v147, v150, s[4:5]
	v_mov_b32_e32 v147, v148
	v_add_f32_e32 v146, 1.0, v146
	v_rcp_f32_e32 v158, v146
	v_mov_b32_e32 v146, v152
	v_pk_mul_f32 v[146:147], v[162:163], v[146:147]
	v_mov_b32_e32 v155, v161
	v_add_f32_e32 v147, v144, v147
	v_add_f32_e32 v148, v146, v147
	v_pk_mul_f32 v[146:147], v[170:171], v[156:157]
	s_nop 0
	v_add_f32_e32 v147, v147, v148
	v_add_f32_e32 v152, v146, v147
	v_mul_f32_e32 v146, 0xbfb8aa3b, v152
	v_mov_b32_e32 v148, v153
	v_exp_f32_e32 v156, v146
	v_pk_mul_f32 v[146:147], v[140:141], v[148:149]
	v_add_f32_e32 v149, 1.0, v156
	v_add_f32_e32 v147, v145, v147
	v_add_f32_e32 v148, v146, v147
	v_pk_mul_f32 v[146:147], v[136:137], v[154:155]
	v_rcp_f32_e32 v149, v149
	v_add_f32_e32 v147, v147, v148
	v_add_f32_e32 v146, v146, v147
	v_mul_f32_e32 v147, 0xbfb8aa3b, v146
	v_exp_f32_e32 v147, v147
	v_mul_f32_e32 v148, v151, v158
	v_mul_f32_e32 v149, v152, v149
	v_cndmask_b32_e64 v148, v148, v151, s[4:5]
	v_add_f32_e32 v147, 1.0, v147
	v_rcp_f32_e32 v147, v147
	v_cndmask_b32_e64 v149, v149, v152, s[4:5]
	v_mov_b32_e32 v156, v24
	v_mov_b32_e32 v154, v25
	v_mul_f32_e32 v147, v146, v147
	v_cndmask_b32_e64 v147, v147, v146, s[4:5]
	v_cvt_pk_bf16_f32 v146, v150, v148
	v_cvt_pk_bf16_f32 v147, v149, v147
	v_mov_b32_e32 v54, v146
	v_mov_b32_e32 v55, v147
	s_cbranch_vccnz .LBB0_1501
	v_add_u32_e32 v147, 0xffffe0a0, v202
	v_ashrrev_i32_e32 v147, 2, v147
	v_lshl_add_u32 v147, v147, 1, v147
	v_mad_i64_i32 v[148:149], s[0:1], v147, s47, 0
	v_lshl_add_u64 v[148:149], v[148:149], 2, v[208:209]
	v_lshl_add_u64 v[150:151], v[148:149], 0, s[24:25]
	s_lshl_b32 s0, s27, 2
	s_mov_b32 s1, s25
	global_load_dwordx4 v[158:161], v[148:149], off offset:512
	s_nop 0
	global_load_dwordx4 v[150:153], v[150:151], off offset:512
	v_lshl_add_u64 v[148:149], v[148:149], 0, s[0:1]
	global_load_dwordx4 v[154:157], v[148:149], off offset:512
	v_mov_b32_dpp v164, v22 row_ror:1 row_mask:0xf bank_mask:0xf
	v_mov_b32_dpp v165, v22 row_ror:2 row_mask:0xf bank_mask:0xf
	v_mov_b32_dpp v146, v22 row_ror:3 row_mask:0xf bank_mask:0xf
	v_cmp_lt_i32_e32 vcc, 1, v205
	s_and_saveexec_b64 s[0:1], vcc
	s_xor_b64 s[0:1], exec, s[0:1]
	s_cbranch_execz .LBB0_1464
	v_cmp_gt_i32_e32 vcc, 3, v205
	s_and_saveexec_b64 s[2:3], vcc
	s_cbranch_execz .LBB0_1463
	s_waitcnt vmcnt(0)
	v_mov_b32_e32 v146, v154

; __device__ __forceinline__ float dpp_ror1(float v) { return __builtin_bit_cast(float, __builtin_amdgcn_update_dpp(0, __builtin_bit_cast(int, v), 0x121, 0xf, 0xf, false)); }
; __device__ __forceinline__ float dpp_ror2(float v) { return __builtin_bit_cast(float, __builtin_amdgcn_update_dpp(0, __builtin_bit_cast(int, v), 0x122, 0xf, 0xf, false)); }
; __device__ __forceinline__ float dpp_ror3(float v) { return __builtin_bit_cast(float, __builtin_amdgcn_update_dpp(0, __builtin_bit_cast(int, v), 0x123, 0xf, 0xf, false)); }
;     __device__ __forceinline__ void operator()(f32x4 (&acc)[2][2][4][2], const pg8::Unit& u, int wr, int wc, int fr, int fq) const {
;     ...
;                         else { const int t = fr & 3; const float* sp = stp + (size_t)((row - MP) >> 2) * 3 * CW + ch;
;                             const f32x4 b0 = *(const f32x4*)sp, b1 = *(const f32x4*)(sp + CW), b2 = *(const f32x4*)(sp + 2 * CW);
; #pragma unroll
;                             for (int j = 0; j < 4; ++j) { const float r1 = dpp_ror1(g[j]), r2 = dpp_ror2(g[j]), r3 = dpp_ror3(g[j]);
;                                 p1[j] = t >= 1 ? r1 : b2[j]; p2[j] = t >= 2 ? r2 : (t == 1 ? b2[j] : b1[j]); p3[j] = t >= 3 ? r3 : (t == 2 ? b2[j] : (t == 1 ? b1[j] : b0[j])); } }
.LBB0_1470:
	s_or_b64 exec, exec, s[0:1]
	v_mov_b32_dpp v172, v23 row_ror:1 row_mask:0xf bank_mask:0xf
	v_mov_b32_dpp v173, v23 row_ror:2 row_mask:0xf bank_mask:0xf
	v_mov_b32_dpp v147, v23 row_ror:3 row_mask:0xf bank_mask:0xf
	v_cmp_lt_i32_e32 vcc, 1, v205
	s_and_saveexec_b64 s[0:1], vcc
	s_xor_b64 s[0:1], exec, s[0:1]
	s_cbranch_execz .LBB0_1474
	v_cmp_gt_i32_e32 vcc, 3, v205
	s_and_saveexec_b64 s[2:3], vcc
	s_cbranch_execz .LBB0_1473
	s_waitcnt vmcnt(0)
	v_mov_b32_e32 v147, v155

; __device__ __forceinline__ float dpp_ror1(float v) { return __builtin_bit_cast(float, __builtin_amdgcn_update_dpp(0, __builtin_bit_cast(int, v), 0x121, 0xf, 0xf, false)); }
; __device__ __forceinline__ float dpp_ror2(float v) { return __builtin_bit_cast(float, __builtin_amdgcn_update_dpp(0, __builtin_bit_cast(int, v), 0x122, 0xf, 0xf, false)); }
; __device__ __forceinline__ float dpp_ror3(float v) { return __builtin_bit_cast(float, __builtin_amdgcn_update_dpp(0, __builtin_bit_cast(int, v), 0x123, 0xf, 0xf, false)); }
;     __device__ __forceinline__ void operator()(f32x4 (&acc)[2][2][4][2], const pg8::Unit& u, int wr, int wc, int fr, int fq) const {
;     ...
;                         else { const int t = fr & 3; const float* sp = stp + (size_t)((row - MP) >> 2) * 3 * CW + ch;
;                             const f32x4 b0 = *(const f32x4*)sp, b1 = *(const f32x4*)(sp + CW), b2 = *(const f32x4*)(sp + 2 * CW);
; #pragma unroll
;                             for (int j = 0; j < 4; ++j) { const float r1 = dpp_ror1(g[j]), r2 = dpp_ror2(g[j]), r3 = dpp_ror3(g[j]);
;                                 p1[j] = t >= 1 ? r1 : b2[j]; p2[j] = t >= 2 ? r2 : (t == 1 ? b2[j] : b1[j]); p3[j] = t >= 3 ? r3 : (t == 2 ? b2[j] : (t == 1 ? b1[j] : b0[j])); } }
.LBB0_1480:
	s_or_b64 exec, exec, s[0:1]
	v_mov_b32_dpp v182, v24 row_ror:1 row_mask:0xf bank_mask:0xf
	v_mov_b32_dpp v207, v24 row_ror:2 row_mask:0xf bank_mask:0xf
	v_mov_b32_dpp v148, v24 row_ror:3 row_mask:0xf bank_mask:0xf
	v_cmp_lt_i32_e32 vcc, 1, v205
	s_and_saveexec_b64 s[0:1], vcc
	s_xor_b64 s[0:1], exec, s[0:1]
	s_cbranch_execz .LBB0_1484
	v_cmp_gt_i32_e32 vcc, 3, v205
	s_and_saveexec_b64 s[2:3], vcc
	s_cbranch_execz .LBB0_1483
	s_waitcnt vmcnt(0)
	v_mov_b32_e32 v148, v156

; __device__ __forceinline__ float dpp_ror1(float v) { return __builtin_bit_cast(float, __builtin_amdgcn_update_dpp(0, __builtin_bit_cast(int, v), 0x121, 0xf, 0xf, false)); }
; __device__ __forceinline__ float dpp_ror2(float v) { return __builtin_bit_cast(float, __builtin_amdgcn_update_dpp(0, __builtin_bit_cast(int, v), 0x122, 0xf, 0xf, false)); }
; __device__ __forceinline__ float dpp_ror3(float v) { return __builtin_bit_cast(float, __builtin_amdgcn_update_dpp(0, __builtin_bit_cast(int, v), 0x123, 0xf, 0xf, false)); }
;     __device__ __forceinline__ void operator()(f32x4 (&acc)[2][2][4][2], const pg8::Unit& u, int wr, int wc, int fr, int fq) const {
;     ...
;                         else { const int t = fr & 3; const float* sp = stp + (size_t)((row - MP) >> 2) * 3 * CW + ch;
;                             const f32x4 b0 = *(const f32x4*)sp, b1 = *(const f32x4*)(sp + CW), b2 = *(const f32x4*)(sp + 2 * CW);
; #pragma unroll
;                             for (int j = 0; j < 4; ++j) { const float r1 = dpp_ror1(g[j]), r2 = dpp_ror2(g[j]), r3 = dpp_ror3(g[j]);
;                                 p1[j] = t >= 1 ? r1 : b2[j]; p2[j] = t >= 2 ? r2 : (t == 1 ? b2[j] : b1[j]); p3[j] = t >= 3 ? r3 : (t == 2 ? b2[j] : (t == 1 ? b1[j] : b0[j])); } }
.LBB0_1490:
	s_or_b64 exec, exec, s[0:1]
	v_mov_b32_dpp v229, v25 row_ror:1 row_mask:0xf bank_mask:0xf
	v_mov_b32_dpp v228, v25 row_ror:2 row_mask:0xf bank_mask:0xf
	v_mov_b32_dpp v149, v25 row_ror:3 row_mask:0xf bank_mask:0xf
	v_cmp_lt_i32_e32 vcc, 1, v205
	s_and_saveexec_b64 s[0:1], vcc
	s_xor_b64 s[0:1], exec, s[0:1]
	s_cbranch_execz .LBB0_1494
	v_cmp_gt_i32_e32 vcc, 3, v205
	s_and_saveexec_b64 s[2:3], vcc
	s_cbranch_execz .LBB0_1493
	s_waitcnt vmcnt(0)
	v_mov_b32_e32 v149, v157

; __device__ __forceinline__ unsigned cvt_pk_bf16(float lo, float hi) { unsigned r; asm("v_cvt_pk_bf16_f32 %0, %1, %2" : "=v"(r) : "v"(lo), "v"(hi)); return r; }
; __device__ __forceinline__ float siluf_(float x) { return x * sigmoidf_(x); }
; __device__ __forceinline__ float dpp_ror1(float v) { return __builtin_bit_cast(float, __builtin_amdgcn_update_dpp(0, __builtin_bit_cast(int, v), 0x121, 0xf, 0xf, false)); }
; __device__ __forceinline__ float dpp_ror2(float v) { return __builtin_bit_cast(float, __builtin_amdgcn_update_dpp(0, __builtin_bit_cast(int, v), 0x122, 0xf, 0xf, false)); }
; __device__ __forceinline__ float dpp_ror3(float v) { return __builtin_bit_cast(float, __builtin_amdgcn_update_dpp(0, __builtin_bit_cast(int, v), 0x123, 0xf, 0xf, false)); }
;     __device__ __forceinline__ void operator()(f32x4 (&acc)[2][2][4][2], const pg8::Unit& u, int wr, int wc, int fr, int fq) const {
;     ...
;                         if (prompt) { const f32x4 gp = (m == 0) ? hal[n] : acc[ai][bj][m > 0 ? m - 1 : 0][n];
; #pragma unroll
;                             for (int j = 0; j < 4; ++j) { p1[j] = dpp_ror1(fr == 15 ? gp[j] : g[j]); p2[j] = dpp_ror2(fr >= 14 ? gp[j] : g[j]); p3[j] = dpp_ror3(fr >= 13 ? gp[j] : g[j]); } }
;                         else { const int t = fr & 3; const float* sp = stp + (size_t)((row - MP) >> 2) * 3 * CW + ch;
;                             const f32x4 b0 = *(const f32x4*)sp, b1 = *(const f32x4*)(sp + CW), b2 = *(const f32x4*)(sp + 2 * CW);
; #pragma unroll
;                             for (int j = 0; j < 4; ++j) { const float r1 = dpp_ror1(g[j]), r2 = dpp_ror2(g[j]), r3 = dpp_ror3(g[j]);
;                                 p1[j] = t >= 1 ? r1 : b2[j]; p2[j] = t >= 2 ? r2 : (t == 1 ? b2[j] : b1[j]); p3[j] = t >= 3 ? r3 : (t == 2 ? b2[j] : (t == 1 ? b1[j] : b0[j])); } }
;                         float o[4];
; #pragma unroll
;                         for (int j = 0; j < 4; ++j) { const float y = bb[j] + w0[j] * p3[j] + w1[j] * p2[j] + w2[j] * p1[j] + w3[j] * g[j]; o[j] = is_rg ? y : siluf_(y); }
;                         u32x2 w; w.x = cvt_pk_bf16(o[0], o[1]); w.y = cvt_pk_bf16(o[2], o[3]);
;                         *(u32x2*)(dst + (size_t)row * ld + bj * 128 + 4 * n) = w; }
.LBB0_1501:
	s_and_b64 vcc, exec, s[0:1]
	s_cbranch_vccz .LBB0_1503
	v_cndmask_b32_e64 v146, v22, v38, s[10:11]
	v_cndmask_b32_e64 v147, v22, v38, s[6:7]
	s_nop 0
	v_mov_b32_dpp v158, v146 row_ror:1 row_mask:0xf bank_mask:0xf
	v_cndmask_b32_e64 v146, v22, v38, s[8:9]
	s_nop 1
	v_mov_b32_dpp v150, v146 row_ror:2 row_mask:0xf bank_mask:0xf
	v_cndmask_b32_e64 v148, v23, v39, s[6:7]
	v_mov_b32_dpp v146, v147 row_ror:3 row_mask:0xf bank_mask:0xf
	v_cndmask_b32_e64 v147, v23, v39, s[10:11]
	v_cndmask_b32_e64 v149, v24, v40, s[6:7]
	s_nop 0
	v_mov_b32_dpp v159, v147 row_ror:1 row_mask:0xf bank_mask:0xf
	v_cndmask_b32_e64 v147, v23, v39, s[8:9]
	s_nop 1
	v_mov_b32_dpp v151, v147 row_ror:2 row_mask:0xf bank_mask:0xf
	v_cndmask_b32_e64 v155, v25, v41, s[6:7]
	s_nop 0
	v_mov_b32_dpp v147, v148 row_ror:3 row_mask:0xf bank_mask:0xf
	v_cndmask_b32_e64 v148, v24, v40, s[10:11]
	s_nop 1
	v_mov_b32_dpp v160, v148 row_ror:1 row_mask:0xf bank_mask:0xf
	v_cndmask_b32_e64 v148, v24, v40, s[8:9]
	s_nop 1
	v_mov_b32_dpp v152, v148 row_ror:2 row_mask:0xf bank_mask:0xf
	s_nop 1
	v_mov_b32_dpp v148, v149 row_ror:3 row_mask:0xf bank_mask:0xf
	v_cndmask_b32_e64 v149, v25, v41, s[10:11]
	s_nop 1
	v_mov_b32_dpp v161, v149 row_ror:1 row_mask:0xf bank_mask:0xf
	v_cndmask_b32_e64 v149, v25, v41, s[8:9]
	s_nop 1
	v_mov_b32_dpp v153, v149 row_ror:2 row_mask:0xf bank_mask:0xf
	s_nop 1
	v_mov_b32_dpp v149, v155 row_ror:3 row_mask:0xf bank_mask:0xf
.LBB0_1503:
	v_mov_b32_e32 v228, v150
	v_mov_b32_e32 v229, v146
	v_pk_mul_f32 v[228:229], v[166:167], v[228:229]
	v_mov_b32_e32 v173, v158
	v_add_f32_e32 v146, v142, v229
	v_add_f32_e32 v146, v228, v146
	v_pk_mul_f32 v[172:173], v[168:169], v[172:173]
	v_mov_b32_e32 v165, v159
	v_add_f32_e32 v146, v173, v146
	v_add_f32_e32 v150, v172, v146
	v_mul_f32_e32 v146, 0xbfb8aa3b, v150
	v_exp_f32_e32 v146, v146
	v_mov_b32_e32 v157, v160
	s_mov_b64 s[0:1], -1
	s_and_b64 vcc, exec, s[18:19]
	v_add_f32_e32 v146, 1.0, v146
	v_rcp_f32_e32 v155, v146
	v_mov_b32_e32 v146, v151
	v_pk_mul_f32 v[146:147], v[138:139], v[146:147]
	v_mov_b32_e32 v172, v6
	v_add_f32_e32 v147, v143, v147
	v_add_f32_e32 v151, v146, v147
	v_pk_mul_f32 v[146:147], v[134:135], v[164:165]
	v_mov_b32_e32 v164, v7
	v_add_f32_e32 v147, v147, v151
	v_add_f32_e32 v151, v146, v147
	v_mul_f32_e32 v146, 0xbfb8aa3b, v151
	v_exp_f32_e32 v146, v146
	v_mul_f32_e32 v147, v150, v155
	v_cndmask_b32_e64 v150, v147, v150, s[4:5]
	v_mov_b32_e32 v147, v148
	v_add_f32_e32 v146, 1.0, v146
	v_rcp_f32_e32 v158, v146
	v_mov_b32_e32 v146, v152
	v_pk_mul_f32 v[146:147], v[162:163], v[146:147]
	v_mov_b32_e32 v155, v161
	v_add_f32_e32 v147, v144, v147
	v_add_f32_e32 v148, v146, v147
	v_pk_mul_f32 v[146:147], v[170:171], v[156:157]
	s_nop 0
	v_add_f32_e32 v147, v147, v148
	v_add_f32_e32 v152, v146, v147
	v_mul_f32_e32 v146, 0xbfb8aa3b, v152
	v_mov_b32_e32 v148, v153
	v_exp_f32_e32 v156, v146
	v_pk_mul_f32 v[146:147], v[140:141], v[148:149]
	v_add_f32_e32 v149, 1.0, v156
	v_add_f32_e32 v147, v145, v147
	v_add_f32_e32 v148, v146, v147
	v_pk_mul_f32 v[146:147], v[136:137], v[154:155]
	v_rcp_f32_e32 v149, v149
	v_add_f32_e32 v147, v147, v148
	v_add_f32_e32 v146, v146, v147
	v_mul_f32_e32 v147, 0xbfb8aa3b, v146
	v_exp_f32_e32 v147, v147
	v_mul_f32_e32 v148, v151, v158
	v_mul_f32_e32 v149, v152, v149
	v_cndmask_b32_e64 v148, v148, v151, s[4:5]
	v_add_f32_e32 v147, 1.0, v147
	v_rcp_f32_e32 v147, v147
	v_cndmask_b32_e64 v149, v149, v152, s[4:5]
	v_mov_b32_e32 v156, v8
	v_mov_b32_e32 v154, v9
	v_mul_f32_e32 v147, v146, v147
	v_cndmask_b32_e64 v147, v147, v146, s[4:5]
	v_cvt_pk_bf16_f32 v146, v150, v148
	v_cvt_pk_bf16_f32 v147, v149, v147
	v_mov_b32_e32 v38, v146
	v_mov_b32_e32 v39, v147
	s_cbranch_vccnz .LBB0_1545
	v_add_u32_e32 v147, 0xffffe0b0, v202
	v_ashrrev_i32_e32 v147, 2, v147
	v_lshl_add_u32 v147, v147, 1, v147
	v_mad_i64_i32 v[148:149], s[0:1], v147, s47, 0
	v_lshl_add_u64 v[148:149], v[148:149], 2, v[208:209]
	v_lshl_add_u64 v[150:151], v[148:149], 0, s[24:25]
	s_lshl_b32 s0, s27, 2
	s_mov_b32 s1, s25
	global_load_dwordx4 v[158:161], v[148:149], off offset:512
	s_nop 0
	global_load_dwordx4 v[150:153], v[150:151], off offset:512
	v_lshl_add_u64 v[148:149], v[148:149], 0, s[0:1]
	global_load_dwordx4 v[154:157], v[148:149], off offset:512
	v_mov_b32_dpp v164, v6 row_ror:1 row_mask:0xf bank_mask:0xf
	v_mov_b32_dpp v165, v6 row_ror:2 row_mask:0xf bank_mask:0xf
	v_mov_b32_dpp v146, v6 row_ror:3 row_mask:0xf bank_mask:0xf
	v_cmp_lt_i32_e32 vcc, 1, v205
	s_and_saveexec_b64 s[0:1], vcc
	s_xor_b64 s[0:1], exec, s[0:1]
	s_cbranch_execz .LBB0_1508
	v_cmp_gt_i32_e32 vcc, 3, v205
	s_and_saveexec_b64 s[2:3], vcc
	s_cbranch_execz .LBB0_1507
	s_waitcnt vmcnt(0)
	v_mov_b32_e32 v146, v154

; __device__ __forceinline__ float dpp_ror1(float v) { return __builtin_bit_cast(float, __builtin_amdgcn_update_dpp(0, __builtin_bit_cast(int, v), 0x121, 0xf, 0xf, false)); }
; __device__ __forceinline__ float dpp_ror2(float v) { return __builtin_bit_cast(float, __builtin_amdgcn_update_dpp(0, __builtin_bit_cast(int, v), 0x122, 0xf, 0xf, false)); }
; __device__ __forceinline__ float dpp_ror3(float v) { return __builtin_bit_cast(float, __builtin_amdgcn_update_dpp(0, __builtin_bit_cast(int, v), 0x123, 0xf, 0xf, false)); }
;     __device__ __forceinline__ void operator()(f32x4 (&acc)[2][2][4][2], const pg8::Unit& u, int wr, int wc, int fr, int fq) const {
;     ...
;                         else { const int t = fr & 3; const float* sp = stp + (size_t)((row - MP) >> 2) * 3 * CW + ch;
;                             const f32x4 b0 = *(const f32x4*)sp, b1 = *(const f32x4*)(sp + CW), b2 = *(const f32x4*)(sp + 2 * CW);
; #pragma unroll
;                             for (int j = 0; j < 4; ++j) { const float r1 = dpp_ror1(g[j]), r2 = dpp_ror2(g[j]), r3 = dpp_ror3(g[j]);
;                                 p1[j] = t >= 1 ? r1 : b2[j]; p2[j] = t >= 2 ? r2 : (t == 1 ? b2[j] : b1[j]); p3[j] = t >= 3 ? r3 : (t == 2 ? b2[j] : (t == 1 ? b1[j] : b0[j])); } }
.LBB0_1514:
	s_or_b64 exec, exec, s[0:1]
	v_mov_b32_dpp v172, v7 row_ror:1 row_mask:0xf bank_mask:0xf
	v_mov_b32_dpp v173, v7 row_ror:2 row_mask:0xf bank_mask:0xf
	v_mov_b32_dpp v147, v7 row_ror:3 row_mask:0xf bank_mask:0xf
	v_cmp_lt_i32_e32 vcc, 1, v205
	s_and_saveexec_b64 s[0:1], vcc
	s_xor_b64 s[0:1], exec, s[0:1]
	s_cbranch_execz .LBB0_1518
	v_cmp_gt_i32_e32 vcc, 3, v205
	s_and_saveexec_b64 s[2:3], vcc
	s_cbranch_execz .LBB0_1517
	s_waitcnt vmcnt(0)
	v_mov_b32_e32 v147, v155

; __device__ __forceinline__ float dpp_ror1(float v) { return __builtin_bit_cast(float, __builtin_amdgcn_update_dpp(0, __builtin_bit_cast(int, v), 0x121, 0xf, 0xf, false)); }
; __device__ __forceinline__ float dpp_ror2(float v) { return __builtin_bit_cast(float, __builtin_amdgcn_update_dpp(0, __builtin_bit_cast(int, v), 0x122, 0xf, 0xf, false)); }
; __device__ __forceinline__ float dpp_ror3(float v) { return __builtin_bit_cast(float, __builtin_amdgcn_update_dpp(0, __builtin_bit_cast(int, v), 0x123, 0xf, 0xf, false)); }
;     __device__ __forceinline__ void operator()(f32x4 (&acc)[2][2][4][2], const pg8::Unit& u, int wr, int wc, int fr, int fq) const {
;     ...
;                         else { const int t = fr & 3; const float* sp = stp + (size_t)((row - MP) >> 2) * 3 * CW + ch;
;                             const f32x4 b0 = *(const f32x4*)sp, b1 = *(const f32x4*)(sp + CW), b2 = *(const f32x4*)(sp + 2 * CW);
; #pragma unroll
;                             for (int j = 0; j < 4; ++j) { const float r1 = dpp_ror1(g[j]), r2 = dpp_ror2(g[j]), r3 = dpp_ror3(g[j]);
;                                 p1[j] = t >= 1 ? r1 : b2[j]; p2[j] = t >= 2 ? r2 : (t == 1 ? b2[j] : b1[j]); p3[j] = t >= 3 ? r3 : (t == 2 ? b2[j] : (t == 1 ? b1[j] : b0[j])); } }
.LBB0_1524:
	s_or_b64 exec, exec, s[0:1]
	v_mov_b32_dpp v182, v8 row_ror:1 row_mask:0xf bank_mask:0xf
	v_mov_b32_dpp v207, v8 row_ror:2 row_mask:0xf bank_mask:0xf
	v_mov_b32_dpp v148, v8 row_ror:3 row_mask:0xf bank_mask:0xf
	v_cmp_lt_i32_e32 vcc, 1, v205
	s_and_saveexec_b64 s[0:1], vcc
	s_xor_b64 s[0:1], exec, s[0:1]
	s_cbranch_execz .LBB0_1528
	v_cmp_gt_i32_e32 vcc, 3, v205
	s_and_saveexec_b64 s[2:3], vcc
	s_cbranch_execz .LBB0_1527
	s_waitcnt vmcnt(0)
	v_mov_b32_e32 v148, v156

; __device__ __forceinline__ float dpp_ror1(float v) { return __builtin_bit_cast(float, __builtin_amdgcn_update_dpp(0, __builtin_bit_cast(int, v), 0x121, 0xf, 0xf, false)); }
; __device__ __forceinline__ float dpp_ror2(float v) { return __builtin_bit_cast(float, __builtin_amdgcn_update_dpp(0, __builtin_bit_cast(int, v), 0x122, 0xf, 0xf, false)); }
; __device__ __forceinline__ float dpp_ror3(float v) { return __builtin_bit_cast(float, __builtin_amdgcn_update_dpp(0, __builtin_bit_cast(int, v), 0x123, 0xf, 0xf, false)); }
;     __device__ __forceinline__ void operator()(f32x4 (&acc)[2][2][4][2], const pg8::Unit& u, int wr, int wc, int fr, int fq) const {
;     ...
;                         else { const int t = fr & 3; const float* sp = stp + (size_t)((row - MP) >> 2) * 3 * CW + ch;
;                             const f32x4 b0 = *(const f32x4*)sp, b1 = *(const f32x4*)(sp + CW), b2 = *(const f32x4*)(sp + 2 * CW);
; #pragma unroll
;                             for (int j = 0; j < 4; ++j) { const float r1 = dpp_ror1(g[j]), r2 = dpp_ror2(g[j]), r3 = dpp_ror3(g[j]);
;                                 p1[j] = t >= 1 ? r1 : b2[j]; p2[j] = t >= 2 ? r2 : (t == 1 ? b2[j] : b1[j]); p3[j] = t >= 3 ? r3 : (t == 2 ? b2[j] : (t == 1 ? b1[j] : b0[j])); } }
.LBB0_1534:
	s_or_b64 exec, exec, s[0:1]
	v_mov_b32_dpp v229, v9 row_ror:1 row_mask:0xf bank_mask:0xf
	v_mov_b32_dpp v228, v9 row_ror:2 row_mask:0xf bank_mask:0xf
	v_mov_b32_dpp v149, v9 row_ror:3 row_mask:0xf bank_mask:0xf
	v_cmp_lt_i32_e32 vcc, 1, v205
	s_and_saveexec_b64 s[0:1], vcc
	s_xor_b64 s[0:1], exec, s[0:1]
	s_cbranch_execz .LBB0_1538
	v_cmp_gt_i32_e32 vcc, 3, v205
	s_and_saveexec_b64 s[2:3], vcc
	s_cbranch_execz .LBB0_1537
	s_waitcnt vmcnt(0)
	v_mov_b32_e32 v149, v157

; __device__ __forceinline__ unsigned cvt_pk_bf16(float lo, float hi) { unsigned r; asm("v_cvt_pk_bf16_f32 %0, %1, %2" : "=v"(r) : "v"(lo), "v"(hi)); return r; }
; __device__ __forceinline__ float siluf_(float x) { return x * sigmoidf_(x); }
; __device__ __forceinline__ float dpp_ror1(float v) { return __builtin_bit_cast(float, __builtin_amdgcn_update_dpp(0, __builtin_bit_cast(int, v), 0x121, 0xf, 0xf, false)); }
;     __device__ __forceinline__ void operator()(f32x4 (&acc)[2][2][4][2], const pg8::Unit& u, int wr, int wc, int fr, int fq) const {
;     ...
;                 for (int n = 0; n < 2; ++n) { const int ch = ch0 + bj * 128 + 4 * n;
;                     const f32x4 w0 = *(const f32x4*)(cw + ch), w1 = *(const f32x4*)(cw + CW + ch), w2 = *(const f32x4*)(cw + 2 * CW + ch), w3 = *(const f32x4*)(cw + 3 * CW + ch), bb = *(const f32x4*)(cb + ch);
; #pragma unroll
;                     for (int m = 0; m < 4; ++m) { const int row = row0 + ai * 128 + m * 16; const f32x4 g = acc[ai][bj][m][n]; f32x4 p1, p2, p3;
;                         if (prompt) { const f32x4 gp = (m == 0) ? hal[n] : acc[ai][bj][m > 0 ? m - 1 : 0][n];
; #pragma unroll
;                             for (int j = 0; j < 4; ++j) { p1[j] = dpp_ror1(fr == 15 ? gp[j] : g[j]); p2[j] = dpp_ror2(fr >= 14 ? gp[j] : g[j]); p3[j] = dpp_ror3(fr >= 13 ? gp[j] : g[j]); } }
;                         else { const int t = fr & 3; const float* sp = stp + (size_t)((row - MP) >> 2) * 3 * CW + ch;
;                             const f32x4 b0 = *(const f32x4*)sp, b1 = *(const f32x4*)(sp + CW), b2 = *(const f32x4*)(sp + 2 * CW);
; #pragma unroll
;                             for (int j = 0; j < 4; ++j) { const float r1 = dpp_ror1(g[j]), r2 = dpp_ror2(g[j]), r3 = dpp_ror3(g[j]);
;                                 p1[j] = t >= 1 ? r1 : b2[j]; p2[j] = t >= 2 ? r2 : (t == 1 ? b2[j] : b1[j]); p3[j] = t >= 3 ? r3 : (t == 2 ? b2[j] : (t == 1 ? b1[j] : b0[j])); } }
;                         float o[4];
; #pragma unroll
;                         for (int j = 0; j < 4; ++j) { const float y = bb[j] + w0[j] * p3[j] + w1[j] * p2[j] + w2[j] * p1[j] + w3[j] * g[j]; o[j] = is_rg ? y : siluf_(y); }
;                         u32x2 w; w.x = cvt_pk_bf16(o[0], o[1]); w.y = cvt_pk_bf16(o[2], o[3]);
;                         *(u32x2*)(dst + (size_t)row * ld + bj * 128 + 4 * n) = w; }
.LBB0_1545:
	s_and_b64 vcc, exec, s[0:1]
	s_cbranch_vccz .LBB0_1547
	v_cndmask_b32_e64 v146, v6, v22, s[10:11]
	v_cndmask_b32_e64 v147, v6, v22, s[6:7]
	s_nop 0
	v_mov_b32_dpp v158, v146 row_ror:1 row_mask:0xf bank_mask:0xf
	v_cndmask_b32_e64 v146, v6, v22, s[8:9]
	s_nop 1
	v_mov_b32_dpp v150, v146 row_ror:2 row_mask:0xf bank_mask:0xf
	v_cndmask_b32_e64 v148, v7, v23, s[6:7]
	v_mov_b32_dpp v146, v147 row_ror:3 row_mask:0xf bank_mask:0xf
	v_cndmask_b32_e64 v147, v7, v23, s[10:11]
	v_cndmask_b32_e64 v149, v8, v24, s[6:7]
	s_nop 0
	v_mov_b32_dpp v159, v147 row_ror:1 row_mask:0xf bank_mask:0xf
	v_cndmask_b32_e64 v147, v7, v23, s[8:9]
	s_nop 1
	v_mov_b32_dpp v151, v147 row_ror:2 row_mask:0xf bank_mask:0xf
	v_cndmask_b32_e64 v155, v9, v25, s[6:7]
	s_nop 0
	v_mov_b32_dpp v147, v148 row_ror:3 row_mask:0xf bank_mask:0xf
	v_cndmask_b32_e64 v148, v8, v24, s[10:11]
	s_nop 1
	v_mov_b32_dpp v160, v148 row_ror:1 row_mask:0xf bank_mask:0xf
	v_cndmask_b32_e64 v148, v8, v24, s[8:9]
	s_nop 1
	v_mov_b32_dpp v152, v148 row_ror:2 row_mask:0xf bank_mask:0xf
	s_nop 1
	v_mov_b32_dpp v148, v149 row_ror:3 row_mask:0xf bank_mask:0xf
	v_cndmask_b32_e64 v149, v9, v25, s[10:11]
	s_nop 1
	v_mov_b32_dpp v161, v149 row_ror:1 row_mask:0xf bank_mask:0xf
	v_cndmask_b32_e64 v149, v9, v25, s[8:9]
	s_nop 1
	v_mov_b32_dpp v153, v149 row_ror:2 row_mask:0xf bank_mask:0xf
	s_nop 1
	v_mov_b32_dpp v149, v155 row_ror:3 row_mask:0xf bank_mask:0xf
.LBB0_1547:
	v_mov_b32_e32 v228, v150
	v_mov_b32_e32 v229, v146
	v_pk_mul_f32 v[166:167], v[166:167], v[228:229]
	v_mov_b32_e32 v173, v158
	v_add_f32_e32 v142, v142, v167
	v_add_f32_e32 v142, v166, v142
	v_pk_mul_f32 v[166:167], v[168:169], v[172:173]
	v_mov_b32_e32 v165, v159
	v_add_f32_e32 v142, v167, v142
	v_add_f32_e32 v142, v166, v142
	v_mul_f32_e32 v146, 0xbfb8aa3b, v142
	v_exp_f32_e32 v146, v146
	v_pk_mul_f32 v[134:135], v[134:135], v[164:165]
	v_mov_b32_e32 v157, v160
	v_mov_b32_e32 v155, v161
	v_add_f32_e32 v146, 1.0, v146
	v_rcp_f32_e32 v150, v146
	v_mov_b32_e32 v146, v151
	v_pk_mul_f32 v[138:139], v[138:139], v[146:147]
	s_mov_b64 s[0:1], -1
	v_add_f32_e32 v139, v143, v139
	v_add_f32_e32 v138, v138, v139
	v_add_f32_e32 v135, v135, v138
	v_add_f32_e32 v138, v134, v135
	v_mul_f32_e32 v134, 0xbfb8aa3b, v138
	v_exp_f32_e32 v134, v134
	v_mul_f32_e32 v135, v142, v150
	v_cndmask_b32_e64 v139, v135, v142, s[4:5]
	v_mov_b32_e32 v135, v148
	v_add_f32_e32 v134, 1.0, v134
	v_rcp_f32_e32 v142, v134
	v_mov_b32_e32 v134, v152
	v_pk_mul_f32 v[134:135], v[162:163], v[134:135]
	v_mov_b32_e32 v148, v153
	v_add_f32_e32 v135, v144, v135
	v_add_f32_e32 v143, v134, v135
	v_pk_mul_f32 v[134:135], v[170:171], v[156:157]
	s_and_b64 vcc, exec, s[18:19]
	v_add_f32_e32 v135, v135, v143
	v_add_f32_e32 v143, v134, v135
	v_mul_f32_e32 v134, 0xbfb8aa3b, v143
	v_exp_f32_e32 v144, v134
	v_pk_mul_f32 v[134:135], v[140:141], v[148:149]
	v_mov_b32_e32 v172, v52
	v_add_f32_e32 v135, v145, v135
	v_add_f32_e32 v140, v134, v135
	v_pk_mul_f32 v[134:135], v[136:137], v[154:155]
	v_add_f32_e32 v137, 1.0, v144
	v_add_f32_e32 v135, v135, v140
	v_add_f32_e32 v134, v134, v135
	v_mul_f32_e32 v135, 0xbfb8aa3b, v134
	v_exp_f32_e32 v135, v135
	v_rcp_f32_e32 v137, v137
	v_mul_f32_e32 v136, v138, v142
	v_cndmask_b32_e64 v136, v136, v138, s[4:5]
	v_add_f32_e32 v135, 1.0, v135
	v_rcp_f32_e32 v135, v135
	v_mul_f32_e32 v137, v143, v137
	v_cndmask_b32_e64 v137, v137, v143, s[4:5]
	v_mov_b32_e32 v170, v53
	v_mul_f32_e32 v135, v134, v135
	v_cndmask_b32_e64 v135, v135, v134, s[4:5]
	v_cvt_pk_bf16_f32 v134, v139, v136
	v_cvt_pk_bf16_f32 v135, v137, v135
	v_mov_b32_e32 v22, v134
	v_mov_b32_e32 v23, v135
	global_load_dwordx4 v[138:141], v[210:211], off offset:528
	global_load_dwordx4 v[150:153], v[212:213], off offset:528
	global_load_dwordx4 v[134:137], v[214:215], off offset:528
	global_load_dwordx4 v[146:149], v[216:217], off offset:528
	global_load_dwordx4 v[142:145], v[218:219], off offset:528
	v_mov_b32_e32 v212, v50
	v_mov_b32_e32 v210, v51
	s_cbranch_vccnz .LBB0_1589
	v_add_u32_e32 v155, 0xffffe080, v202
	v_ashrrev_i32_e32 v155, 2, v155
	v_lshl_add_u32 v155, v155, 1, v155
	v_mad_i64_i32 v[156:157], s[0:1], v155, s47, 0
	v_lshl_add_u64 v[156:157], v[156:157], 2, v[208:209]
	v_lshl_add_u64 v[158:159], v[156:157], 0, s[24:25]
	s_lshl_b32 s0, s27, 2
	s_mov_b32 s1, s25
	global_load_dwordx4 v[166:169], v[156:157], off offset:528
	s_nop 0
	global_load_dwordx4 v[158:161], v[158:159], off offset:528
	v_lshl_add_u64 v[156:157], v[156:157], 0, s[0:1]
	global_load_dwordx4 v[162:165], v[156:157], off offset:528
	v_mov_b32_dpp v170, v50 row_ror:1 row_mask:0xf bank_mask:0xf
	v_mov_b32_dpp v171, v50 row_ror:2 row_mask:0xf bank_mask:0xf
	v_mov_b32_dpp v154, v50 row_ror:3 row_mask:0xf bank_mask:0xf
	v_cmp_lt_i32_e32 vcc, 1, v205
	s_and_saveexec_b64 s[0:1], vcc
	s_xor_b64 s[0:1], exec, s[0:1]
	s_cbranch_execz .LBB0_1552
	v_cmp_gt_i32_e32 vcc, 3, v205
	s_and_saveexec_b64 s[2:3], vcc
	s_cbranch_execz .LBB0_1551
	s_waitcnt vmcnt(0)
	v_mov_b32_e32 v154, v162

; __device__ __forceinline__ float dpp_ror1(float v) { return __builtin_bit_cast(float, __builtin_amdgcn_update_dpp(0, __builtin_bit_cast(int, v), 0x121, 0xf, 0xf, false)); }
; __device__ __forceinline__ float dpp_ror2(float v) { return __builtin_bit_cast(float, __builtin_amdgcn_update_dpp(0, __builtin_bit_cast(int, v), 0x122, 0xf, 0xf, false)); }
; __device__ __forceinline__ float dpp_ror3(float v) { return __builtin_bit_cast(float, __builtin_amdgcn_update_dpp(0, __builtin_bit_cast(int, v), 0x123, 0xf, 0xf, false)); }
;     __device__ __forceinline__ void operator()(f32x4 (&acc)[2][2][4][2], const pg8::Unit& u, int wr, int wc, int fr, int fq) const {
;     ...
;                         else { const int t = fr & 3; const float* sp = stp + (size_t)((row - MP) >> 2) * 3 * CW + ch;
;                             const f32x4 b0 = *(const f32x4*)sp, b1 = *(const f32x4*)(sp + CW), b2 = *(const f32x4*)(sp + 2 * CW);
; #pragma unroll
;                             for (int j = 0; j < 4; ++j) { const float r1 = dpp_ror1(g[j]), r2 = dpp_ror2(g[j]), r3 = dpp_ror3(g[j]);
;                                 p1[j] = t >= 1 ? r1 : b2[j]; p2[j] = t >= 2 ? r2 : (t == 1 ? b2[j] : b1[j]); p3[j] = t >= 3 ? r3 : (t == 2 ? b2[j] : (t == 1 ? b1[j] : b0[j])); } }
.LBB0_1558:
	s_or_b64 exec, exec, s[0:1]
	v_mov_b32_dpp v172, v51 row_ror:1 row_mask:0xf bank_mask:0xf
	v_mov_b32_dpp v173, v51 row_ror:2 row_mask:0xf bank_mask:0xf
	v_mov_b32_dpp v155, v51 row_ror:3 row_mask:0xf bank_mask:0xf
	v_cmp_lt_i32_e32 vcc, 1, v205
	s_and_saveexec_b64 s[0:1], vcc
	s_xor_b64 s[0:1], exec, s[0:1]
	s_cbranch_execz .LBB0_1562
	v_cmp_gt_i32_e32 vcc, 3, v205
	s_and_saveexec_b64 s[2:3], vcc
	s_cbranch_execz .LBB0_1561
	s_waitcnt vmcnt(0)
	v_mov_b32_e32 v155, v163

; __device__ __forceinline__ float dpp_ror1(float v) { return __builtin_bit_cast(float, __builtin_amdgcn_update_dpp(0, __builtin_bit_cast(int, v), 0x121, 0xf, 0xf, false)); }
; __device__ __forceinline__ float dpp_ror2(float v) { return __builtin_bit_cast(float, __builtin_amdgcn_update_dpp(0, __builtin_bit_cast(int, v), 0x122, 0xf, 0xf, false)); }
; __device__ __forceinline__ float dpp_ror3(float v) { return __builtin_bit_cast(float, __builtin_amdgcn_update_dpp(0, __builtin_bit_cast(int, v), 0x123, 0xf, 0xf, false)); }
;     __device__ __forceinline__ void operator()(f32x4 (&acc)[2][2][4][2], const pg8::Unit& u, int wr, int wc, int fr, int fq) const {
;     ...
;                         else { const int t = fr & 3; const float* sp = stp + (size_t)((row - MP) >> 2) * 3 * CW + ch;
;                             const f32x4 b0 = *(const f32x4*)sp, b1 = *(const f32x4*)(sp + CW), b2 = *(const f32x4*)(sp + 2 * CW);
; #pragma unroll
;                             for (int j = 0; j < 4; ++j) { const float r1 = dpp_ror1(g[j]), r2 = dpp_ror2(g[j]), r3 = dpp_ror3(g[j]);
;                                 p1[j] = t >= 1 ? r1 : b2[j]; p2[j] = t >= 2 ? r2 : (t == 1 ? b2[j] : b1[j]); p3[j] = t >= 3 ? r3 : (t == 2 ? b2[j] : (t == 1 ? b1[j] : b0[j])); } }
.LBB0_1568:
	s_or_b64 exec, exec, s[0:1]
	v_mov_b32_dpp v182, v52 row_ror:1 row_mask:0xf bank_mask:0xf
	v_mov_b32_dpp v207, v52 row_ror:2 row_mask:0xf bank_mask:0xf
	v_mov_b32_dpp v156, v52 row_ror:3 row_mask:0xf bank_mask:0xf
	v_cmp_lt_i32_e32 vcc, 1, v205
	s_and_saveexec_b64 s[0:1], vcc
	s_xor_b64 s[0:1], exec, s[0:1]
	s_cbranch_execz .LBB0_1572
	v_cmp_gt_i32_e32 vcc, 3, v205
	s_and_saveexec_b64 s[2:3], vcc
	s_cbranch_execz .LBB0_1571
	s_waitcnt vmcnt(0)
	v_mov_b32_e32 v156, v164

; __device__ __forceinline__ float dpp_ror1(float v) { return __builtin_bit_cast(float, __builtin_amdgcn_update_dpp(0, __builtin_bit_cast(int, v), 0x121, 0xf, 0xf, false)); }
; __device__ __forceinline__ float dpp_ror2(float v) { return __builtin_bit_cast(float, __builtin_amdgcn_update_dpp(0, __builtin_bit_cast(int, v), 0x122, 0xf, 0xf, false)); }
; __device__ __forceinline__ float dpp_ror3(float v) { return __builtin_bit_cast(float, __builtin_amdgcn_update_dpp(0, __builtin_bit_cast(int, v), 0x123, 0xf, 0xf, false)); }
;     __device__ __forceinline__ void operator()(f32x4 (&acc)[2][2][4][2], const pg8::Unit& u, int wr, int wc, int fr, int fq) const {
;     ...
;                         else { const int t = fr & 3; const float* sp = stp + (size_t)((row - MP) >> 2) * 3 * CW + ch;
;                             const f32x4 b0 = *(const f32x4*)sp, b1 = *(const f32x4*)(sp + CW), b2 = *(const f32x4*)(sp + 2 * CW);
; #pragma unroll
;                             for (int j = 0; j < 4; ++j) { const float r1 = dpp_ror1(g[j]), r2 = dpp_ror2(g[j]), r3 = dpp_ror3(g[j]);
;                                 p1[j] = t >= 1 ? r1 : b2[j]; p2[j] = t >= 2 ? r2 : (t == 1 ? b2[j] : b1[j]); p3[j] = t >= 3 ? r3 : (t == 2 ? b2[j] : (t == 1 ? b1[j] : b0[j])); } }
.LBB0_1578:
	s_or_b64 exec, exec, s[0:1]
	v_mov_b32_dpp v211, v53 row_ror:1 row_mask:0xf bank_mask:0xf
	v_mov_b32_dpp v210, v53 row_ror:2 row_mask:0xf bank_mask:0xf
	v_mov_b32_dpp v157, v53 row_ror:3 row_mask:0xf bank_mask:0xf
	v_cmp_lt_i32_e32 vcc, 1, v205
	s_and_saveexec_b64 s[0:1], vcc
	s_xor_b64 s[0:1], exec, s[0:1]
	s_cbranch_execz .LBB0_1582
	v_cmp_gt_i32_e32 vcc, 3, v205
	s_and_saveexec_b64 s[2:3], vcc
	s_cbranch_execz .LBB0_1581
	s_waitcnt vmcnt(0)
	v_mov_b32_e32 v157, v165

; __device__ __forceinline__ unsigned cvt_pk_bf16(float lo, float hi) { unsigned r; asm("v_cvt_pk_bf16_f32 %0, %1, %2" : "=v"(r) : "v"(lo), "v"(hi)); return r; }
; __device__ __forceinline__ float siluf_(float x) { return x * sigmoidf_(x); }
; __device__ __forceinline__ float dpp_ror1(float v) { return __builtin_bit_cast(float, __builtin_amdgcn_update_dpp(0, __builtin_bit_cast(int, v), 0x121, 0xf, 0xf, false)); }
; __device__ __forceinline__ float dpp_ror2(float v) { return __builtin_bit_cast(float, __builtin_amdgcn_update_dpp(0, __builtin_bit_cast(int, v), 0x122, 0xf, 0xf, false)); }
; __device__ __forceinline__ float dpp_ror3(float v) { return __builtin_bit_cast(float, __builtin_amdgcn_update_dpp(0, __builtin_bit_cast(int, v), 0x123, 0xf, 0xf, false)); }
;     __device__ __forceinline__ void operator()(f32x4 (&acc)[2][2][4][2], const pg8::Unit& u, int wr, int wc, int fr, int fq) const {
;     ...
;                         if (prompt) { const f32x4 gp = (m == 0) ? hal[n] : acc[ai][bj][m > 0 ? m - 1 : 0][n];
; #pragma unroll
;                             for (int j = 0; j < 4; ++j) { p1[j] = dpp_ror1(fr == 15 ? gp[j] : g[j]); p2[j] = dpp_ror2(fr >= 14 ? gp[j] : g[j]); p3[j] = dpp_ror3(fr >= 13 ? gp[j] : g[j]); } }
;                         else { const int t = fr & 3; const float* sp = stp + (size_t)((row - MP) >> 2) * 3 * CW + ch;
;                             const f32x4 b0 = *(const f32x4*)sp, b1 = *(const f32x4*)(sp + CW), b2 = *(const f32x4*)(sp + 2 * CW);
; #pragma unroll
;                             for (int j = 0; j < 4; ++j) { const float r1 = dpp_ror1(g[j]), r2 = dpp_ror2(g[j]), r3 = dpp_ror3(g[j]);
;                                 p1[j] = t >= 1 ? r1 : b2[j]; p2[j] = t >= 2 ? r2 : (t == 1 ? b2[j] : b1[j]); p3[j] = t >= 3 ? r3 : (t == 2 ? b2[j] : (t == 1 ? b1[j] : b0[j])); } }
;                         float o[4];
; #pragma unroll
;                         for (int j = 0; j < 4; ++j) { const float y = bb[j] + w0[j] * p3[j] + w1[j] * p2[j] + w2[j] * p1[j] + w3[j] * g[j]; o[j] = is_rg ? y : siluf_(y); }
;                         u32x2 w; w.x = cvt_pk_bf16(o[0], o[1]); w.y = cvt_pk_bf16(o[2], o[3]);
;                         *(u32x2*)(dst + (size_t)row * ld + bj * 128 + 4 * n) = w; }
.LBB0_1589:
	s_and_b64 vcc, exec, s[0:1]
	s_cbranch_vccz .LBB0_1591
	v_cndmask_b32_e64 v154, v50, v130, s[10:11]
	s_nop 1
	v_mov_b32_dpp v166, v154 row_ror:1 row_mask:0xf bank_mask:0xf
	v_cndmask_b32_e64 v154, v50, v130, s[8:9]
	v_cndmask_b32_e64 v130, v50, v130, s[6:7]
	s_nop 0
	v_mov_b32_dpp v158, v154 row_ror:2 row_mask:0xf bank_mask:0xf
	v_mov_b32_dpp v154, v130 row_ror:3 row_mask:0xf bank_mask:0xf
	v_cndmask_b32_e64 v130, v51, v131, s[10:11]
	s_nop 1
	v_mov_b32_dpp v167, v130 row_ror:1 row_mask:0xf bank_mask:0xf
	v_cndmask_b32_e64 v130, v51, v131, s[8:9]
	s_nop 1
	v_mov_b32_dpp v159, v130 row_ror:2 row_mask:0xf bank_mask:0xf
	v_cndmask_b32_e64 v130, v51, v131, s[6:7]
	s_nop 0
	s_nop 0
	v_mov_b32_dpp v155, v130 row_ror:3 row_mask:0xf bank_mask:0xf
	v_cndmask_b32_e64 v130, v52, v132, s[10:11]
	s_nop 1
	v_mov_b32_dpp v168, v130 row_ror:1 row_mask:0xf bank_mask:0xf
	v_cndmask_b32_e64 v130, v52, v132, s[8:9]
	s_nop 1
	v_mov_b32_dpp v160, v130 row_ror:2 row_mask:0xf bank_mask:0xf
	v_cndmask_b32_e64 v130, v52, v132, s[6:7]
	s_nop 1
	v_mov_b32_dpp v156, v130 row_ror:3 row_mask:0xf bank_mask:0xf
	v_cndmask_b32_e64 v130, v53, v133, s[10:11]
	s_nop 1
	v_mov_b32_dpp v169, v130 row_ror:1 row_mask:0xf bank_mask:0xf
	v_cndmask_b32_e64 v130, v53, v133, s[8:9]
	s_nop 1
	v_mov_b32_dpp v161, v130 row_ror:2 row_mask:0xf bank_mask:0xf
	v_cndmask_b32_e64 v130, v53, v133, s[6:7]
	s_nop 1
	v_mov_b32_dpp v157, v130 row_ror:3 row_mask:0xf bank_mask:0xf
.LBB0_1591:
	s_waitcnt vmcnt(0)
	v_mov_b32_e32 v162, v150
	v_mov_b32_e32 v163, v138
	v_mov_b32_e32 v130, v158
	v_mov_b32_e32 v131, v154
	v_pk_mul_f32 v[130:131], v[162:163], v[130:131]
	v_mov_b32_e32 v164, v146
	v_add_f32_e32 v131, v142, v131
	v_mov_b32_e32 v165, v134
	v_mov_b32_e32 v213, v166
	v_add_f32_e32 v132, v130, v131
	v_pk_mul_f32 v[130:131], v[164:165], v[212:213]
	v_mov_b32_e32 v138, v151
	v_add_f32_e32 v131, v131, v132
	v_add_f32_e32 v132, v130, v131
	v_mul_f32_e32 v130, 0xbfb8aa3b, v132
	v_exp_f32_e32 v130, v130
	v_mov_b32_e32 v154, v159
	v_mov_b32_e32 v134, v147
	v_mov_b32_e32 v211, v167
	v_add_f32_e32 v130, 1.0, v130
	v_rcp_f32_e32 v133, v130
	v_pk_mul_f32 v[130:131], v[138:139], v[154:155]
	v_mov_b32_e32 v158, v152
	v_add_f32_e32 v131, v143, v131
	v_add_f32_e32 v146, v130, v131
	v_pk_mul_f32 v[130:131], v[134:135], v[210:211]
	v_mov_b32_e32 v159, v140
	v_add_f32_e32 v131, v131, v146
	v_add_f32_e32 v146, v130, v131
	v_mul_f32_e32 v130, 0xbfb8aa3b, v146
	v_exp_f32_e32 v130, v130
	v_mul_f32_e32 v131, v132, v133
	v_cndmask_b32_e64 v132, v131, v132, s[4:5]
	v_mov_b32_e32 v131, v156
	v_add_f32_e32 v130, 1.0, v130
	v_rcp_f32_e32 v133, v130
	v_mov_b32_e32 v130, v160
	v_pk_mul_f32 v[130:131], v[158:159], v[130:131]
	v_mov_b32_e32 v166, v148
	v_add_f32_e32 v131, v144, v131
	v_mov_b32_e32 v167, v136
	v_mov_b32_e32 v173, v168
	v_add_f32_e32 v140, v130, v131
	v_pk_mul_f32 v[130:131], v[166:167], v[172:173]
	v_mov_b32_e32 v156, v161
	v_add_f32_e32 v131, v131, v140
	v_add_f32_e32 v147, v130, v131
	v_mul_f32_e32 v130, 0xbfb8aa3b, v147
	v_mov_b32_e32 v140, v153
	v_exp_f32_e32 v148, v130
	v_pk_mul_f32 v[130:131], v[140:141], v[156:157]
	v_mov_b32_e32 v136, v149
	v_add_f32_e32 v131, v145, v131
	v_mov_b32_e32 v171, v169
	v_add_f32_e32 v150, v130, v131
	v_pk_mul_f32 v[130:131], v[136:137], v[170:171]
	v_add_f32_e32 v148, 1.0, v148
	v_add_f32_e32 v131, v131, v150
	v_add_f32_e32 v130, v130, v131
	v_mul_f32_e32 v131, 0xbfb8aa3b, v130
	v_exp_f32_e32 v131, v131
	v_rcp_f32_e32 v148, v148
	v_mul_f32_e32 v133, v146, v133
	v_cndmask_b32_e64 v133, v133, v146, s[4:5]
	v_add_f32_e32 v131, 1.0, v131
	v_rcp_f32_e32 v131, v131
	v_mul_f32_e32 v146, v147, v148
	v_cndmask_b32_e64 v146, v146, v147, s[4:5]
	s_mov_b64 s[0:1], -1
	v_mul_f32_e32 v131, v130, v131
	v_cndmask_b32_e64 v131, v131, v130, s[4:5]
	v_cvt_pk_bf16_f32 v130, v132, v133
	v_cvt_pk_bf16_f32 v131, v146, v131
	s_and_b64 vcc, exec, s[18:19]
	v_mov_b32_e32 v168, v34
	v_mov_b32_e32 v160, v35
	v_mov_b32_e32 v152, v36
	v_mov_b32_e32 v150, v37
	v_mov_b32_e32 v16, v130
	v_mov_b32_e32 v17, v131
	flat_store_dwordx4 v[222:223], v[14:17] offset:256
	s_cbranch_vccnz .LBB0_1633
	v_add_u32_e32 v131, 0xffffe090, v202
	v_ashrrev_i32_e32 v131, 2, v131
	v_lshl_add_u32 v131, v131, 1, v131
	v_mad_i64_i32 v[132:133], s[0:1], v131, s47, 0
	v_lshl_add_u64 v[132:133], v[132:133], 2, v[208:209]
	v_lshl_add_u64 v[146:147], v[132:133], 0, s[24:25]
	s_lshl_b32 s0, s27, 2
	s_mov_b32 s1, s25
	global_load_dwordx4 v[154:157], v[132:133], off offset:528
	s_nop 0
	global_load_dwordx4 v[146:149], v[146:147], off offset:528
	v_lshl_add_u64 v[132:133], v[132:133], 0, s[0:1]
	global_load_dwordx4 v[150:153], v[132:133], off offset:528
	v_mov_b32_dpp v160, v34 row_ror:1 row_mask:0xf bank_mask:0xf
	v_mov_b32_dpp v161, v34 row_ror:2 row_mask:0xf bank_mask:0xf
	v_mov_b32_dpp v130, v34 row_ror:3 row_mask:0xf bank_mask:0xf
	v_cmp_lt_i32_e32 vcc, 1, v205
	s_and_saveexec_b64 s[0:1], vcc
	s_xor_b64 s[0:1], exec, s[0:1]
	s_cbranch_execz .LBB0_1596
	v_cmp_gt_i32_e32 vcc, 3, v205
	s_and_saveexec_b64 s[2:3], vcc
	s_cbranch_execz .LBB0_1595
	s_waitcnt vmcnt(0)
	v_mov_b32_e32 v130, v150

; __device__ __forceinline__ float dpp_ror1(float v) { return __builtin_bit_cast(float, __builtin_amdgcn_update_dpp(0, __builtin_bit_cast(int, v), 0x121, 0xf, 0xf, false)); }
; __device__ __forceinline__ float dpp_ror2(float v) { return __builtin_bit_cast(float, __builtin_amdgcn_update_dpp(0, __builtin_bit_cast(int, v), 0x122, 0xf, 0xf, false)); }
; __device__ __forceinline__ float dpp_ror3(float v) { return __builtin_bit_cast(float, __builtin_amdgcn_update_dpp(0, __builtin_bit_cast(int, v), 0x123, 0xf, 0xf, false)); }
;     __device__ __forceinline__ void operator()(f32x4 (&acc)[2][2][4][2], const pg8::Unit& u, int wr, int wc, int fr, int fq) const {
;     ...
;                         else { const int t = fr & 3; const float* sp = stp + (size_t)((row - MP) >> 2) * 3 * CW + ch;
;                             const f32x4 b0 = *(const f32x4*)sp, b1 = *(const f32x4*)(sp + CW), b2 = *(const f32x4*)(sp + 2 * CW);
; #pragma unroll
;                             for (int j = 0; j < 4; ++j) { const float r1 = dpp_ror1(g[j]), r2 = dpp_ror2(g[j]), r3 = dpp_ror3(g[j]);
;                                 p1[j] = t >= 1 ? r1 : b2[j]; p2[j] = t >= 2 ? r2 : (t == 1 ? b2[j] : b1[j]); p3[j] = t >= 3 ? r3 : (t == 2 ? b2[j] : (t == 1 ? b1[j] : b0[j])); } }
.LBB0_1602:
	s_or_b64 exec, exec, s[0:1]
	v_mov_b32_dpp v168, v35 row_ror:1 row_mask:0xf bank_mask:0xf
	v_mov_b32_dpp v169, v35 row_ror:2 row_mask:0xf bank_mask:0xf
	v_mov_b32_dpp v131, v35 row_ror:3 row_mask:0xf bank_mask:0xf
	v_cmp_lt_i32_e32 vcc, 1, v205
	s_and_saveexec_b64 s[0:1], vcc
	s_xor_b64 s[0:1], exec, s[0:1]
	s_cbranch_execz .LBB0_1606
	v_cmp_gt_i32_e32 vcc, 3, v205
	s_and_saveexec_b64 s[2:3], vcc
	s_cbranch_execz .LBB0_1605
	s_waitcnt vmcnt(0)
	v_mov_b32_e32 v131, v151

; __device__ __forceinline__ float dpp_ror1(float v) { return __builtin_bit_cast(float, __builtin_amdgcn_update_dpp(0, __builtin_bit_cast(int, v), 0x121, 0xf, 0xf, false)); }
; __device__ __forceinline__ float dpp_ror2(float v) { return __builtin_bit_cast(float, __builtin_amdgcn_update_dpp(0, __builtin_bit_cast(int, v), 0x122, 0xf, 0xf, false)); }
; __device__ __forceinline__ float dpp_ror3(float v) { return __builtin_bit_cast(float, __builtin_amdgcn_update_dpp(0, __builtin_bit_cast(int, v), 0x123, 0xf, 0xf, false)); }
;     __device__ __forceinline__ void operator()(f32x4 (&acc)[2][2][4][2], const pg8::Unit& u, int wr, int wc, int fr, int fq) const {
;     ...
;                         else { const int t = fr & 3; const float* sp = stp + (size_t)((row - MP) >> 2) * 3 * CW + ch;
;                             const f32x4 b0 = *(const f32x4*)sp, b1 = *(const f32x4*)(sp + CW), b2 = *(const f32x4*)(sp + 2 * CW);
; #pragma unroll
;                             for (int j = 0; j < 4; ++j) { const float r1 = dpp_ror1(g[j]), r2 = dpp_ror2(g[j]), r3 = dpp_ror3(g[j]);
;                                 p1[j] = t >= 1 ? r1 : b2[j]; p2[j] = t >= 2 ? r2 : (t == 1 ? b2[j] : b1[j]); p3[j] = t >= 3 ? r3 : (t == 2 ? b2[j] : (t == 1 ? b1[j] : b0[j])); } }
.LBB0_1612:
	s_or_b64 exec, exec, s[0:1]
	v_mov_b32_dpp v170, v36 row_ror:1 row_mask:0xf bank_mask:0xf
	v_mov_b32_dpp v171, v36 row_ror:2 row_mask:0xf bank_mask:0xf
	v_mov_b32_dpp v132, v36 row_ror:3 row_mask:0xf bank_mask:0xf
	v_cmp_lt_i32_e32 vcc, 1, v205
	s_and_saveexec_b64 s[0:1], vcc
	s_xor_b64 s[0:1], exec, s[0:1]
	s_cbranch_execz .LBB0_1616
	v_cmp_gt_i32_e32 vcc, 3, v205
	s_and_saveexec_b64 s[2:3], vcc
	s_cbranch_execz .LBB0_1615
	s_waitcnt vmcnt(0)
	v_mov_b32_e32 v132, v152

; __device__ __forceinline__ float dpp_ror1(float v) { return __builtin_bit_cast(float, __builtin_amdgcn_update_dpp(0, __builtin_bit_cast(int, v), 0x121, 0xf, 0xf, false)); }
; __device__ __forceinline__ float dpp_ror2(float v) { return __builtin_bit_cast(float, __builtin_amdgcn_update_dpp(0, __builtin_bit_cast(int, v), 0x122, 0xf, 0xf, false)); }
; __device__ __forceinline__ float dpp_ror3(float v) { return __builtin_bit_cast(float, __builtin_amdgcn_update_dpp(0, __builtin_bit_cast(int, v), 0x123, 0xf, 0xf, false)); }
;     __device__ __forceinline__ void operator()(f32x4 (&acc)[2][2][4][2], const pg8::Unit& u, int wr, int wc, int fr, int fq) const {
;     ...
;                         else { const int t = fr & 3; const float* sp = stp + (size_t)((row - MP) >> 2) * 3 * CW + ch;
;                             const f32x4 b0 = *(const f32x4*)sp, b1 = *(const f32x4*)(sp + CW), b2 = *(const f32x4*)(sp + 2 * CW);
; #pragma unroll
;                             for (int j = 0; j < 4; ++j) { const float r1 = dpp_ror1(g[j]), r2 = dpp_ror2(g[j]), r3 = dpp_ror3(g[j]);
;                                 p1[j] = t >= 1 ? r1 : b2[j]; p2[j] = t >= 2 ? r2 : (t == 1 ? b2[j] : b1[j]); p3[j] = t >= 3 ? r3 : (t == 2 ? b2[j] : (t == 1 ? b1[j] : b0[j])); } }
.LBB0_1622:
	s_or_b64 exec, exec, s[0:1]
	v_mov_b32_dpp v173, v37 row_ror:1 row_mask:0xf bank_mask:0xf
	v_mov_b32_dpp v172, v37 row_ror:2 row_mask:0xf bank_mask:0xf
	v_mov_b32_dpp v133, v37 row_ror:3 row_mask:0xf bank_mask:0xf
	v_cmp_lt_i32_e32 vcc, 1, v205
	s_and_saveexec_b64 s[0:1], vcc
	s_xor_b64 s[0:1], exec, s[0:1]
	s_cbranch_execz .LBB0_1626
	v_cmp_gt_i32_e32 vcc, 3, v205
	s_and_saveexec_b64 s[2:3], vcc
	s_cbranch_execz .LBB0_1625
	s_waitcnt vmcnt(0)
	v_mov_b32_e32 v133, v153

; __device__ __forceinline__ unsigned cvt_pk_bf16(float lo, float hi) { unsigned r; asm("v_cvt_pk_bf16_f32 %0, %1, %2" : "=v"(r) : "v"(lo), "v"(hi)); return r; }
; __device__ __forceinline__ float siluf_(float x) { return x * sigmoidf_(x); }
; __device__ __forceinline__ float dpp_ror1(float v) { return __builtin_bit_cast(float, __builtin_amdgcn_update_dpp(0, __builtin_bit_cast(int, v), 0x121, 0xf, 0xf, false)); }
; __device__ __forceinline__ float dpp_ror2(float v) { return __builtin_bit_cast(float, __builtin_amdgcn_update_dpp(0, __builtin_bit_cast(int, v), 0x122, 0xf, 0xf, false)); }
; __device__ __forceinline__ float dpp_ror3(float v) { return __builtin_bit_cast(float, __builtin_amdgcn_update_dpp(0, __builtin_bit_cast(int, v), 0x123, 0xf, 0xf, false)); }
;     __device__ __forceinline__ void operator()(f32x4 (&acc)[2][2][4][2], const pg8::Unit& u, int wr, int wc, int fr, int fq) const {
;     ...
;                         if (prompt) { const f32x4 gp = (m == 0) ? hal[n] : acc[ai][bj][m > 0 ? m - 1 : 0][n];
; #pragma unroll
;                             for (int j = 0; j < 4; ++j) { p1[j] = dpp_ror1(fr == 15 ? gp[j] : g[j]); p2[j] = dpp_ror2(fr >= 14 ? gp[j] : g[j]); p3[j] = dpp_ror3(fr >= 13 ? gp[j] : g[j]); } }
;                         else { const int t = fr & 3; const float* sp = stp + (size_t)((row - MP) >> 2) * 3 * CW + ch;
;                             const f32x4 b0 = *(const f32x4*)sp, b1 = *(const f32x4*)(sp + CW), b2 = *(const f32x4*)(sp + 2 * CW);
; #pragma unroll
;                             for (int j = 0; j < 4; ++j) { const float r1 = dpp_ror1(g[j]), r2 = dpp_ror2(g[j]), r3 = dpp_ror3(g[j]);
;                                 p1[j] = t >= 1 ? r1 : b2[j]; p2[j] = t >= 2 ? r2 : (t == 1 ? b2[j] : b1[j]); p3[j] = t >= 3 ? r3 : (t == 2 ? b2[j] : (t == 1 ? b1[j] : b0[j])); } }
;                         float o[4];
; #pragma unroll
;                         for (int j = 0; j < 4; ++j) { const float y = bb[j] + w0[j] * p3[j] + w1[j] * p2[j] + w2[j] * p1[j] + w3[j] * g[j]; o[j] = is_rg ? y : siluf_(y); }
;                         u32x2 w; w.x = cvt_pk_bf16(o[0], o[1]); w.y = cvt_pk_bf16(o[2], o[3]);
;                         *(u32x2*)(dst + (size_t)row * ld + bj * 128 + 4 * n) = w; }
.LBB0_1633:
	s_and_b64 vcc, exec, s[0:1]
	s_cbranch_vccz .LBB0_1635
	v_cndmask_b32_e64 v130, v34, v50, s[10:11]
	v_cndmask_b32_e64 v131, v34, v50, s[6:7]
	s_nop 0
	v_mov_b32_dpp v154, v130 row_ror:1 row_mask:0xf bank_mask:0xf
	v_cndmask_b32_e64 v130, v34, v50, s[8:9]
	s_nop 1
	v_mov_b32_dpp v146, v130 row_ror:2 row_mask:0xf bank_mask:0xf
	v_cndmask_b32_e64 v132, v35, v51, s[6:7]
	v_mov_b32_dpp v130, v131 row_ror:3 row_mask:0xf bank_mask:0xf
	v_cndmask_b32_e64 v131, v35, v51, s[10:11]
	v_cndmask_b32_e64 v133, v36, v52, s[6:7]
	s_nop 0
	v_mov_b32_dpp v155, v131 row_ror:1 row_mask:0xf bank_mask:0xf
	v_cndmask_b32_e64 v131, v35, v51, s[8:9]
	s_nop 1
	v_mov_b32_dpp v147, v131 row_ror:2 row_mask:0xf bank_mask:0xf
	v_cndmask_b32_e64 v151, v37, v53, s[6:7]
	s_nop 0
	v_mov_b32_dpp v131, v132 row_ror:3 row_mask:0xf bank_mask:0xf
	v_cndmask_b32_e64 v132, v36, v52, s[10:11]
	s_nop 1
	v_mov_b32_dpp v156, v132 row_ror:1 row_mask:0xf bank_mask:0xf
	v_cndmask_b32_e64 v132, v36, v52, s[8:9]
	s_nop 1
	v_mov_b32_dpp v148, v132 row_ror:2 row_mask:0xf bank_mask:0xf
	s_nop 1
	v_mov_b32_dpp v132, v133 row_ror:3 row_mask:0xf bank_mask:0xf
	v_cndmask_b32_e64 v133, v37, v53, s[10:11]
	s_nop 1
	v_mov_b32_dpp v157, v133 row_ror:1 row_mask:0xf bank_mask:0xf
	v_cndmask_b32_e64 v133, v37, v53, s[8:9]
	s_nop 1
	v_mov_b32_dpp v149, v133 row_ror:2 row_mask:0xf bank_mask:0xf
	s_nop 1
	v_mov_b32_dpp v133, v151 row_ror:3 row_mask:0xf bank_mask:0xf
.LBB0_1635:
	v_mov_b32_e32 v170, v146
	v_mov_b32_e32 v171, v130
	v_pk_mul_f32 v[170:171], v[162:163], v[170:171]
	v_mov_b32_e32 v169, v154
	v_add_f32_e32 v130, v142, v171
	v_add_f32_e32 v130, v170, v130
	v_pk_mul_f32 v[168:169], v[164:165], v[168:169]
	v_mov_b32_e32 v161, v155
	v_add_f32_e32 v130, v169, v130
	v_add_f32_e32 v146, v168, v130
	v_mul_f32_e32 v130, 0xbfb8aa3b, v146
	v_exp_f32_e32 v130, v130
	v_mov_b32_e32 v153, v156
	s_mov_b64 s[0:1], -1
	s_and_b64 vcc, exec, s[18:19]
	v_add_f32_e32 v130, 1.0, v130
	v_rcp_f32_e32 v151, v130
	v_mov_b32_e32 v130, v147
	v_pk_mul_f32 v[130:131], v[138:139], v[130:131]
	v_mov_b32_e32 v168, v18
	v_add_f32_e32 v131, v143, v131
	v_add_f32_e32 v147, v130, v131
	v_pk_mul_f32 v[130:131], v[134:135], v[160:161]
	v_mov_b32_e32 v160, v19
	v_add_f32_e32 v131, v131, v147
	v_add_f32_e32 v147, v130, v131
	v_mul_f32_e32 v130, 0xbfb8aa3b, v147
	v_exp_f32_e32 v130, v130
	v_mul_f32_e32 v131, v146, v151
	v_cndmask_b32_e64 v146, v131, v146, s[4:5]
	v_mov_b32_e32 v131, v132
	v_add_f32_e32 v130, 1.0, v130
	v_rcp_f32_e32 v154, v130
	v_mov_b32_e32 v130, v148
	v_pk_mul_f32 v[130:131], v[158:159], v[130:131]
	v_mov_b32_e32 v151, v157
	v_add_f32_e32 v131, v144, v131
	v_add_f32_e32 v132, v130, v131
	v_pk_mul_f32 v[130:131], v[166:167], v[152:153]
	s_nop 0
	v_add_f32_e32 v131, v131, v132
	v_add_f32_e32 v148, v130, v131
	v_mul_f32_e32 v130, 0xbfb8aa3b, v148
	v_mov_b32_e32 v132, v149
	v_exp_f32_e32 v152, v130
	v_pk_mul_f32 v[130:131], v[140:141], v[132:133]
	v_add_f32_e32 v133, 1.0, v152
	v_add_f32_e32 v131, v145, v131
	v_add_f32_e32 v132, v130, v131
	v_pk_mul_f32 v[130:131], v[136:137], v[150:151]
	v_rcp_f32_e32 v133, v133
	v_add_f32_e32 v131, v131, v132
	v_add_f32_e32 v130, v130, v131
	v_mul_f32_e32 v131, 0xbfb8aa3b, v130
	v_exp_f32_e32 v131, v131
	v_mul_f32_e32 v132, v147, v154
	v_mul_f32_e32 v133, v148, v133
	v_cndmask_b32_e64 v132, v132, v147, s[4:5]
	v_add_f32_e32 v131, 1.0, v131
	v_rcp_f32_e32 v131, v131
	v_cndmask_b32_e64 v133, v133, v148, s[4:5]
	v_mov_b32_e32 v152, v20
	v_mov_b32_e32 v150, v21
	v_mul_f32_e32 v131, v130, v131
	v_cndmask_b32_e64 v131, v131, v130, s[4:5]
	v_cvt_pk_bf16_f32 v130, v146, v132
	v_cvt_pk_bf16_f32 v131, v133, v131
	v_mov_b32_e32 v56, v130
	v_mov_b32_e32 v57, v131
	flat_store_dwordx4 v[224:225], v[54:57] offset:256
	s_cbranch_vccnz .LBB0_1677
	v_add_u32_e32 v131, 0xffffe0a0, v202
	v_ashrrev_i32_e32 v131, 2, v131
	v_lshl_add_u32 v131, v131, 1, v131
	v_mad_i64_i32 v[132:133], s[0:1], v131, s47, 0
	v_lshl_add_u64 v[132:133], v[132:133], 2, v[208:209]
	v_lshl_add_u64 v[146:147], v[132:133], 0, s[24:25]
	s_lshl_b32 s0, s27, 2
	s_mov_b32 s1, s25
	global_load_dwordx4 v[154:157], v[132:133], off offset:528
	s_nop 0
	global_load_dwordx4 v[146:149], v[146:147], off offset:528
	v_lshl_add_u64 v[132:133], v[132:133], 0, s[0:1]
	global_load_dwordx4 v[150:153], v[132:133], off offset:528
	v_mov_b32_dpp v160, v18 row_ror:1 row_mask:0xf bank_mask:0xf
	v_mov_b32_dpp v161, v18 row_ror:2 row_mask:0xf bank_mask:0xf
	v_mov_b32_dpp v130, v18 row_ror:3 row_mask:0xf bank_mask:0xf
	v_cmp_lt_i32_e32 vcc, 1, v205
	s_and_saveexec_b64 s[0:1], vcc
	s_xor_b64 s[0:1], exec, s[0:1]
	s_cbranch_execz .LBB0_1640
	v_cmp_gt_i32_e32 vcc, 3, v205
	s_and_saveexec_b64 s[2:3], vcc
	s_cbranch_execz .LBB0_1639
	s_waitcnt vmcnt(0)
	v_mov_b32_e32 v130, v150

; __device__ __forceinline__ float dpp_ror1(float v) { return __builtin_bit_cast(float, __builtin_amdgcn_update_dpp(0, __builtin_bit_cast(int, v), 0x121, 0xf, 0xf, false)); }
; __device__ __forceinline__ float dpp_ror2(float v) { return __builtin_bit_cast(float, __builtin_amdgcn_update_dpp(0, __builtin_bit_cast(int, v), 0x122, 0xf, 0xf, false)); }
; __device__ __forceinline__ float dpp_ror3(float v) { return __builtin_bit_cast(float, __builtin_amdgcn_update_dpp(0, __builtin_bit_cast(int, v), 0x123, 0xf, 0xf, false)); }
;     __device__ __forceinline__ void operator()(f32x4 (&acc)[2][2][4][2], const pg8::Unit& u, int wr, int wc, int fr, int fq) const {
;     ...
;                         else { const int t = fr & 3; const float* sp = stp + (size_t)((row - MP) >> 2) * 3 * CW + ch;
;                             const f32x4 b0 = *(const f32x4*)sp, b1 = *(const f32x4*)(sp + CW), b2 = *(const f32x4*)(sp + 2 * CW);
; #pragma unroll
;                             for (int j = 0; j < 4; ++j) { const float r1 = dpp_ror1(g[j]), r2 = dpp_ror2(g[j]), r3 = dpp_ror3(g[j]);
;                                 p1[j] = t >= 1 ? r1 : b2[j]; p2[j] = t >= 2 ? r2 : (t == 1 ? b2[j] : b1[j]); p3[j] = t >= 3 ? r3 : (t == 2 ? b2[j] : (t == 1 ? b1[j] : b0[j])); } }
.LBB0_1646:
	s_or_b64 exec, exec, s[0:1]
	v_mov_b32_dpp v168, v19 row_ror:1 row_mask:0xf bank_mask:0xf
	v_mov_b32_dpp v169, v19 row_ror:2 row_mask:0xf bank_mask:0xf
	v_mov_b32_dpp v131, v19 row_ror:3 row_mask:0xf bank_mask:0xf
	v_cmp_lt_i32_e32 vcc, 1, v205
	s_and_saveexec_b64 s[0:1], vcc
	s_xor_b64 s[0:1], exec, s[0:1]
	s_cbranch_execz .LBB0_1650
	v_cmp_gt_i32_e32 vcc, 3, v205
	s_and_saveexec_b64 s[2:3], vcc
	s_cbranch_execz .LBB0_1649
	s_waitcnt vmcnt(0)
	v_mov_b32_e32 v131, v151

; __device__ __forceinline__ float dpp_ror1(float v) { return __builtin_bit_cast(float, __builtin_amdgcn_update_dpp(0, __builtin_bit_cast(int, v), 0x121, 0xf, 0xf, false)); }
; __device__ __forceinline__ float dpp_ror2(float v) { return __builtin_bit_cast(float, __builtin_amdgcn_update_dpp(0, __builtin_bit_cast(int, v), 0x122, 0xf, 0xf, false)); }
; __device__ __forceinline__ float dpp_ror3(float v) { return __builtin_bit_cast(float, __builtin_amdgcn_update_dpp(0, __builtin_bit_cast(int, v), 0x123, 0xf, 0xf, false)); }
;     __device__ __forceinline__ void operator()(f32x4 (&acc)[2][2][4][2], const pg8::Unit& u, int wr, int wc, int fr, int fq) const {
;     ...
;                         else { const int t = fr & 3; const float* sp = stp + (size_t)((row - MP) >> 2) * 3 * CW + ch;
;                             const f32x4 b0 = *(const f32x4*)sp, b1 = *(const f32x4*)(sp + CW), b2 = *(const f32x4*)(sp + 2 * CW);
; #pragma unroll
;                             for (int j = 0; j < 4; ++j) { const float r1 = dpp_ror1(g[j]), r2 = dpp_ror2(g[j]), r3 = dpp_ror3(g[j]);
;                                 p1[j] = t >= 1 ? r1 : b2[j]; p2[j] = t >= 2 ? r2 : (t == 1 ? b2[j] : b1[j]); p3[j] = t >= 3 ? r3 : (t == 2 ? b2[j] : (t == 1 ? b1[j] : b0[j])); } }
.LBB0_1656:
	s_or_b64 exec, exec, s[0:1]
	v_mov_b32_dpp v170, v20 row_ror:1 row_mask:0xf bank_mask:0xf
	v_mov_b32_dpp v171, v20 row_ror:2 row_mask:0xf bank_mask:0xf
	v_mov_b32_dpp v132, v20 row_ror:3 row_mask:0xf bank_mask:0xf
	v_cmp_lt_i32_e32 vcc, 1, v205
	s_and_saveexec_b64 s[0:1], vcc
	s_xor_b64 s[0:1], exec, s[0:1]
	s_cbranch_execz .LBB0_1660
	v_cmp_gt_i32_e32 vcc, 3, v205
	s_and_saveexec_b64 s[2:3], vcc
	s_cbranch_execz .LBB0_1659
	s_waitcnt vmcnt(0)
	v_mov_b32_e32 v132, v152

; __device__ __forceinline__ float dpp_ror1(float v) { return __builtin_bit_cast(float, __builtin_amdgcn_update_dpp(0, __builtin_bit_cast(int, v), 0x121, 0xf, 0xf, false)); }
; __device__ __forceinline__ float dpp_ror2(float v) { return __builtin_bit_cast(float, __builtin_amdgcn_update_dpp(0, __builtin_bit_cast(int, v), 0x122, 0xf, 0xf, false)); }
; __device__ __forceinline__ float dpp_ror3(float v) { return __builtin_bit_cast(float, __builtin_amdgcn_update_dpp(0, __builtin_bit_cast(int, v), 0x123, 0xf, 0xf, false)); }
;     __device__ __forceinline__ void operator()(f32x4 (&acc)[2][2][4][2], const pg8::Unit& u, int wr, int wc, int fr, int fq) const {
;     ...
;                         else { const int t = fr & 3; const float* sp = stp + (size_t)((row - MP) >> 2) * 3 * CW + ch;
;                             const f32x4 b0 = *(const f32x4*)sp, b1 = *(const f32x4*)(sp + CW), b2 = *(const f32x4*)(sp + 2 * CW);
; #pragma unroll
;                             for (int j = 0; j < 4; ++j) { const float r1 = dpp_ror1(g[j]), r2 = dpp_ror2(g[j]), r3 = dpp_ror3(g[j]);
;                                 p1[j] = t >= 1 ? r1 : b2[j]; p2[j] = t >= 2 ? r2 : (t == 1 ? b2[j] : b1[j]); p3[j] = t >= 3 ? r3 : (t == 2 ? b2[j] : (t == 1 ? b1[j] : b0[j])); } }
.LBB0_1666:
	s_or_b64 exec, exec, s[0:1]
	v_mov_b32_dpp v173, v21 row_ror:1 row_mask:0xf bank_mask:0xf
	v_mov_b32_dpp v172, v21 row_ror:2 row_mask:0xf bank_mask:0xf
	v_mov_b32_dpp v133, v21 row_ror:3 row_mask:0xf bank_mask:0xf
	v_cmp_lt_i32_e32 vcc, 1, v205
	s_and_saveexec_b64 s[0:1], vcc
	s_xor_b64 s[0:1], exec, s[0:1]
	s_cbranch_execz .LBB0_1670
	v_cmp_gt_i32_e32 vcc, 3, v205
	s_and_saveexec_b64 s[2:3], vcc
	s_cbranch_execz .LBB0_1669
	s_waitcnt vmcnt(0)
	v_mov_b32_e32 v133, v153

; __device__ __forceinline__ unsigned cvt_pk_bf16(float lo, float hi) { unsigned r; asm("v_cvt_pk_bf16_f32 %0, %1, %2" : "=v"(r) : "v"(lo), "v"(hi)); return r; }
; __device__ __forceinline__ float siluf_(float x) { return x * sigmoidf_(x); }
; __device__ __forceinline__ float dpp_ror1(float v) { return __builtin_bit_cast(float, __builtin_amdgcn_update_dpp(0, __builtin_bit_cast(int, v), 0x121, 0xf, 0xf, false)); }
; __device__ __forceinline__ float dpp_ror2(float v) { return __builtin_bit_cast(float, __builtin_amdgcn_update_dpp(0, __builtin_bit_cast(int, v), 0x122, 0xf, 0xf, false)); }
; __device__ __forceinline__ float dpp_ror3(float v) { return __builtin_bit_cast(float, __builtin_amdgcn_update_dpp(0, __builtin_bit_cast(int, v), 0x123, 0xf, 0xf, false)); }
;     __device__ __forceinline__ void operator()(f32x4 (&acc)[2][2][4][2], const pg8::Unit& u, int wr, int wc, int fr, int fq) const {
;     ...
;                         if (prompt) { const f32x4 gp = (m == 0) ? hal[n] : acc[ai][bj][m > 0 ? m - 1 : 0][n];
; #pragma unroll
;                             for (int j = 0; j < 4; ++j) { p1[j] = dpp_ror1(fr == 15 ? gp[j] : g[j]); p2[j] = dpp_ror2(fr >= 14 ? gp[j] : g[j]); p3[j] = dpp_ror3(fr >= 13 ? gp[j] : g[j]); } }
;                         else { const int t = fr & 3; const float* sp = stp + (size_t)((row - MP) >> 2) * 3 * CW + ch;
;                             const f32x4 b0 = *(const f32x4*)sp, b1 = *(const f32x4*)(sp + CW), b2 = *(const f32x4*)(sp + 2 * CW);
; #pragma unroll
;                             for (int j = 0; j < 4; ++j) { const float r1 = dpp_ror1(g[j]), r2 = dpp_ror2(g[j]), r3 = dpp_ror3(g[j]);
;                                 p1[j] = t >= 1 ? r1 : b2[j]; p2[j] = t >= 2 ? r2 : (t == 1 ? b2[j] : b1[j]); p3[j] = t >= 3 ? r3 : (t == 2 ? b2[j] : (t == 1 ? b1[j] : b0[j])); } }
;                         float o[4];
; #pragma unroll
;                         for (int j = 0; j < 4; ++j) { const float y = bb[j] + w0[j] * p3[j] + w1[j] * p2[j] + w2[j] * p1[j] + w3[j] * g[j]; o[j] = is_rg ? y : siluf_(y); }
;                         u32x2 w; w.x = cvt_pk_bf16(o[0], o[1]); w.y = cvt_pk_bf16(o[2], o[3]);
;                         *(u32x2*)(dst + (size_t)row * ld + bj * 128 + 4 * n) = w; }
.LBB0_1677:
	s_and_b64 vcc, exec, s[0:1]
	s_cbranch_vccz .LBB0_1679
	v_cndmask_b32_e64 v130, v18, v34, s[10:11]
	v_cndmask_b32_e64 v131, v18, v34, s[6:7]
	s_nop 0
	v_mov_b32_dpp v154, v130 row_ror:1 row_mask:0xf bank_mask:0xf
	v_cndmask_b32_e64 v130, v18, v34, s[8:9]
	s_nop 1
	v_mov_b32_dpp v146, v130 row_ror:2 row_mask:0xf bank_mask:0xf
	v_cndmask_b32_e64 v132, v19, v35, s[6:7]
	v_mov_b32_dpp v130, v131 row_ror:3 row_mask:0xf bank_mask:0xf
	v_cndmask_b32_e64 v131, v19, v35, s[10:11]
	v_cndmask_b32_e64 v133, v20, v36, s[6:7]
	s_nop 0
	v_mov_b32_dpp v155, v131 row_ror:1 row_mask:0xf bank_mask:0xf
	v_cndmask_b32_e64 v131, v19, v35, s[8:9]
	s_nop 1
	v_mov_b32_dpp v147, v131 row_ror:2 row_mask:0xf bank_mask:0xf
	v_cndmask_b32_e64 v151, v21, v37, s[6:7]
	s_nop 0
	v_mov_b32_dpp v131, v132 row_ror:3 row_mask:0xf bank_mask:0xf
	v_cndmask_b32_e64 v132, v20, v36, s[10:11]
	s_nop 1
	v_mov_b32_dpp v156, v132 row_ror:1 row_mask:0xf bank_mask:0xf
	v_cndmask_b32_e64 v132, v20, v36, s[8:9]
	s_nop 1
	v_mov_b32_dpp v148, v132 row_ror:2 row_mask:0xf bank_mask:0xf
	s_nop 1
	v_mov_b32_dpp v132, v133 row_ror:3 row_mask:0xf bank_mask:0xf
	v_cndmask_b32_e64 v133, v21, v37, s[10:11]
	s_nop 1
	v_mov_b32_dpp v157, v133 row_ror:1 row_mask:0xf bank_mask:0xf
	v_cndmask_b32_e64 v133, v21, v37, s[8:9]
	s_nop 1
	v_mov_b32_dpp v149, v133 row_ror:2 row_mask:0xf bank_mask:0xf
	s_nop 1
	v_mov_b32_dpp v133, v151 row_ror:3 row_mask:0xf bank_mask:0xf
.LBB0_1679:
	v_mov_b32_e32 v170, v146
	v_mov_b32_e32 v171, v130
	v_pk_mul_f32 v[170:171], v[162:163], v[170:171]
	v_mov_b32_e32 v169, v154
	v_add_f32_e32 v130, v142, v171
	v_add_f32_e32 v130, v170, v130
	v_pk_mul_f32 v[168:169], v[164:165], v[168:169]
	v_mov_b32_e32 v161, v155
	v_add_f32_e32 v130, v169, v130
	v_add_f32_e32 v146, v168, v130
	v_mul_f32_e32 v130, 0xbfb8aa3b, v146
	v_exp_f32_e32 v130, v130
	v_mov_b32_e32 v153, v156
	s_and_b64 vcc, exec, s[18:19]
	s_mov_b64 s[0:1], -1
	v_add_f32_e32 v130, 1.0, v130
	v_rcp_f32_e32 v151, v130
	v_mov_b32_e32 v130, v147
	v_pk_mul_f32 v[130:131], v[138:139], v[130:131]
	s_nop 0
	v_add_f32_e32 v131, v143, v131
	v_add_f32_e32 v147, v130, v131
	v_pk_mul_f32 v[130:131], v[134:135], v[160:161]
	s_nop 0
	v_add_f32_e32 v131, v131, v147
	v_add_f32_e32 v147, v130, v131
	v_mul_f32_e32 v130, 0xbfb8aa3b, v147
	v_exp_f32_e32 v130, v130
	v_mul_f32_e32 v131, v146, v151
	v_cndmask_b32_e64 v146, v131, v146, s[4:5]
	v_mov_b32_e32 v131, v132
	v_add_f32_e32 v130, 1.0, v130
	v_rcp_f32_e32 v154, v130
	v_mov_b32_e32 v130, v148
	v_pk_mul_f32 v[130:131], v[158:159], v[130:131]
	v_mov_b32_e32 v151, v157
	v_add_f32_e32 v131, v144, v131
	v_add_f32_e32 v132, v130, v131
	v_pk_mul_f32 v[130:131], v[166:167], v[152:153]
	s_nop 0
	v_add_f32_e32 v131, v131, v132
	v_add_f32_e32 v148, v130, v131
	v_mul_f32_e32 v130, 0xbfb8aa3b, v148
	v_mov_b32_e32 v132, v149
	v_exp_f32_e32 v152, v130
	v_pk_mul_f32 v[130:131], v[140:141], v[132:133]
	v_add_f32_e32 v133, 1.0, v152
	v_add_f32_e32 v131, v145, v131
	v_add_f32_e32 v132, v130, v131
	v_pk_mul_f32 v[130:131], v[136:137], v[150:151]
	v_rcp_f32_e32 v133, v133
	v_add_f32_e32 v131, v131, v132
	v_add_f32_e32 v130, v130, v131
	v_mul_f32_e32 v131, 0xbfb8aa3b, v130
	v_exp_f32_e32 v131, v131
	v_mul_f32_e32 v132, v147, v154
	v_mul_f32_e32 v133, v148, v133
	v_cndmask_b32_e64 v132, v132, v147, s[4:5]
	v_add_f32_e32 v131, 1.0, v131
	v_rcp_f32_e32 v131, v131
	v_cndmask_b32_e64 v133, v133, v148, s[4:5]
	v_mul_f32_e32 v131, v130, v131
	v_cndmask_b32_e64 v131, v131, v130, s[4:5]
	v_cvt_pk_bf16_f32 v130, v146, v132
	v_cvt_pk_bf16_f32 v131, v133, v131
	v_mov_b32_e32 v40, v130
	v_mov_b32_e32 v41, v131
	flat_store_dwordx4 v[226:227], v[38:41] offset:256
	s_cbranch_vccnz .LBB0_1721
	v_add_u32_e32 v131, 0xffffe0b0, v202
	v_ashrrev_i32_e32 v131, 2, v131
	v_lshl_add_u32 v131, v131, 1, v131
	v_mad_i64_i32 v[132:133], s[0:1], v131, s47, 0
	v_lshl_add_u64 v[132:133], v[132:133], 2, v[208:209]
	v_lshl_add_u64 v[146:147], v[132:133], 0, s[24:25]
	s_lshl_b32 s24, s27, 2
	global_load_dwordx4 v[154:157], v[132:133], off offset:528
	s_nop 0
	global_load_dwordx4 v[146:149], v[146:147], off offset:528
	v_lshl_add_u64 v[132:133], v[132:133], 0, s[24:25]
	global_load_dwordx4 v[150:153], v[132:133], off offset:528
	v_mov_b32_dpp v160, v2 row_ror:1 row_mask:0xf bank_mask:0xf
	v_mov_b32_dpp v161, v2 row_ror:2 row_mask:0xf bank_mask:0xf
	v_mov_b32_dpp v130, v2 row_ror:3 row_mask:0xf bank_mask:0xf
	v_cmp_lt_i32_e32 vcc, 1, v205
	s_and_saveexec_b64 s[0:1], vcc
	s_xor_b64 s[0:1], exec, s[0:1]
	s_cbranch_execz .LBB0_1684
	v_cmp_gt_i32_e32 vcc, 3, v205
	s_and_saveexec_b64 s[2:3], vcc
	s_cbranch_execz .LBB0_1683
	s_waitcnt vmcnt(0)
	v_mov_b32_e32 v130, v150

; __device__ __forceinline__ float dpp_ror1(float v) { return __builtin_bit_cast(float, __builtin_amdgcn_update_dpp(0, __builtin_bit_cast(int, v), 0x121, 0xf, 0xf, false)); }
; __device__ __forceinline__ float dpp_ror2(float v) { return __builtin_bit_cast(float, __builtin_amdgcn_update_dpp(0, __builtin_bit_cast(int, v), 0x122, 0xf, 0xf, false)); }
; __device__ __forceinline__ float dpp_ror3(float v) { return __builtin_bit_cast(float, __builtin_amdgcn_update_dpp(0, __builtin_bit_cast(int, v), 0x123, 0xf, 0xf, false)); }
;     __device__ __forceinline__ void operator()(f32x4 (&acc)[2][2][4][2], const pg8::Unit& u, int wr, int wc, int fr, int fq) const {
;     ...
;                         else { const int t = fr & 3; const float* sp = stp + (size_t)((row - MP) >> 2) * 3 * CW + ch;
;                             const f32x4 b0 = *(const f32x4*)sp, b1 = *(const f32x4*)(sp + CW), b2 = *(const f32x4*)(sp + 2 * CW);
; #pragma unroll
;                             for (int j = 0; j < 4; ++j) { const float r1 = dpp_ror1(g[j]), r2 = dpp_ror2(g[j]), r3 = dpp_ror3(g[j]);
;                                 p1[j] = t >= 1 ? r1 : b2[j]; p2[j] = t >= 2 ? r2 : (t == 1 ? b2[j] : b1[j]); p3[j] = t >= 3 ? r3 : (t == 2 ? b2[j] : (t == 1 ? b1[j] : b0[j])); } }
.LBB0_1690:
	s_or_b64 exec, exec, s[0:1]
	v_mov_b32_dpp v168, v3 row_ror:1 row_mask:0xf bank_mask:0xf
	v_mov_b32_dpp v169, v3 row_ror:2 row_mask:0xf bank_mask:0xf
	v_mov_b32_dpp v131, v3 row_ror:3 row_mask:0xf bank_mask:0xf
	v_cmp_lt_i32_e32 vcc, 1, v205
	s_and_saveexec_b64 s[0:1], vcc
	s_xor_b64 s[0:1], exec, s[0:1]
	s_cbranch_execz .LBB0_1694
	v_cmp_gt_i32_e32 vcc, 3, v205
	s_and_saveexec_b64 s[2:3], vcc
	s_cbranch_execz .LBB0_1693
	s_waitcnt vmcnt(0)
	v_mov_b32_e32 v131, v151

; __device__ __forceinline__ float dpp_ror1(float v) { return __builtin_bit_cast(float, __builtin_amdgcn_update_dpp(0, __builtin_bit_cast(int, v), 0x121, 0xf, 0xf, false)); }
; __device__ __forceinline__ float dpp_ror2(float v) { return __builtin_bit_cast(float, __builtin_amdgcn_update_dpp(0, __builtin_bit_cast(int, v), 0x122, 0xf, 0xf, false)); }
; __device__ __forceinline__ float dpp_ror3(float v) { return __builtin_bit_cast(float, __builtin_amdgcn_update_dpp(0, __builtin_bit_cast(int, v), 0x123, 0xf, 0xf, false)); }
;     __device__ __forceinline__ void operator()(f32x4 (&acc)[2][2][4][2], const pg8::Unit& u, int wr, int wc, int fr, int fq) const {
;     ...
;                         else { const int t = fr & 3; const float* sp = stp + (size_t)((row - MP) >> 2) * 3 * CW + ch;
;                             const f32x4 b0 = *(const f32x4*)sp, b1 = *(const f32x4*)(sp + CW), b2 = *(const f32x4*)(sp + 2 * CW);
; #pragma unroll
;                             for (int j = 0; j < 4; ++j) { const float r1 = dpp_ror1(g[j]), r2 = dpp_ror2(g[j]), r3 = dpp_ror3(g[j]);
;                                 p1[j] = t >= 1 ? r1 : b2[j]; p2[j] = t >= 2 ? r2 : (t == 1 ? b2[j] : b1[j]); p3[j] = t >= 3 ? r3 : (t == 2 ? b2[j] : (t == 1 ? b1[j] : b0[j])); } }
.LBB0_1700:
	s_or_b64 exec, exec, s[0:1]
	v_mov_b32_dpp v170, v4 row_ror:1 row_mask:0xf bank_mask:0xf
	v_mov_b32_dpp v171, v4 row_ror:2 row_mask:0xf bank_mask:0xf
	v_mov_b32_dpp v132, v4 row_ror:3 row_mask:0xf bank_mask:0xf
	v_cmp_lt_i32_e32 vcc, 1, v205
	s_and_saveexec_b64 s[0:1], vcc
	s_xor_b64 s[0:1], exec, s[0:1]
	s_cbranch_execz .LBB0_1704
	v_cmp_gt_i32_e32 vcc, 3, v205
	s_and_saveexec_b64 s[2:3], vcc
	s_cbranch_execz .LBB0_1703
	s_waitcnt vmcnt(0)
	v_mov_b32_e32 v132, v152

; __device__ __forceinline__ float dpp_ror1(float v) { return __builtin_bit_cast(float, __builtin_amdgcn_update_dpp(0, __builtin_bit_cast(int, v), 0x121, 0xf, 0xf, false)); }
; __device__ __forceinline__ float dpp_ror2(float v) { return __builtin_bit_cast(float, __builtin_amdgcn_update_dpp(0, __builtin_bit_cast(int, v), 0x122, 0xf, 0xf, false)); }
; __device__ __forceinline__ float dpp_ror3(float v) { return __builtin_bit_cast(float, __builtin_amdgcn_update_dpp(0, __builtin_bit_cast(int, v), 0x123, 0xf, 0xf, false)); }
;     __device__ __forceinline__ void operator()(f32x4 (&acc)[2][2][4][2], const pg8::Unit& u, int wr, int wc, int fr, int fq) const {
;     ...
;                         else { const int t = fr & 3; const float* sp = stp + (size_t)((row - MP) >> 2) * 3 * CW + ch;
;                             const f32x4 b0 = *(const f32x4*)sp, b1 = *(const f32x4*)(sp + CW), b2 = *(const f32x4*)(sp + 2 * CW);
; #pragma unroll
;                             for (int j = 0; j < 4; ++j) { const float r1 = dpp_ror1(g[j]), r2 = dpp_ror2(g[j]), r3 = dpp_ror3(g[j]);
;                                 p1[j] = t >= 1 ? r1 : b2[j]; p2[j] = t >= 2 ? r2 : (t == 1 ? b2[j] : b1[j]); p3[j] = t >= 3 ? r3 : (t == 2 ? b2[j] : (t == 1 ? b1[j] : b0[j])); } }
.LBB0_1710:
	s_or_b64 exec, exec, s[0:1]
	v_mov_b32_dpp v173, v5 row_ror:1 row_mask:0xf bank_mask:0xf
	v_mov_b32_dpp v172, v5 row_ror:2 row_mask:0xf bank_mask:0xf
	v_mov_b32_dpp v133, v5 row_ror:3 row_mask:0xf bank_mask:0xf
	v_cmp_lt_i32_e32 vcc, 1, v205
	s_and_saveexec_b64 s[0:1], vcc
	s_xor_b64 s[0:1], exec, s[0:1]
	s_cbranch_execz .LBB0_1714
	v_cmp_gt_i32_e32 vcc, 3, v205
	s_and_saveexec_b64 s[2:3], vcc
	s_cbranch_execz .LBB0_1713
	s_waitcnt vmcnt(0)
	v_mov_b32_e32 v133, v153

; __device__ __forceinline__ float dpp_ror1(float v) { return __builtin_bit_cast(float, __builtin_amdgcn_update_dpp(0, __builtin_bit_cast(int, v), 0x121, 0xf, 0xf, false)); }
; __device__ __forceinline__ float dpp_ror2(float v) { return __builtin_bit_cast(float, __builtin_amdgcn_update_dpp(0, __builtin_bit_cast(int, v), 0x122, 0xf, 0xf, false)); }
; __device__ __forceinline__ float dpp_ror3(float v) { return __builtin_bit_cast(float, __builtin_amdgcn_update_dpp(0, __builtin_bit_cast(int, v), 0x123, 0xf, 0xf, false)); }
;     __device__ __forceinline__ void operator()(f32x4 (&acc)[2][2][4][2], const pg8::Unit& u, int wr, int wc, int fr, int fq) const {
;     ...
;                         if (prompt) { const f32x4 gp = (m == 0) ? hal[n] : acc[ai][bj][m > 0 ? m - 1 : 0][n];
; #pragma unroll
;                             for (int j = 0; j < 4; ++j) { p1[j] = dpp_ror1(fr == 15 ? gp[j] : g[j]); p2[j] = dpp_ror2(fr >= 14 ? gp[j] : g[j]); p3[j] = dpp_ror3(fr >= 13 ? gp[j] : g[j]); } }
.LBB0_1721:
	s_and_b64 vcc, exec, s[0:1]
	s_cbranch_vccz .LBB0_1723
	v_cndmask_b32_e64 v130, v2, v18, s[10:11]
	v_cndmask_b32_e64 v131, v2, v18, s[6:7]
	s_nop 0
	v_mov_b32_dpp v154, v130 row_ror:1 row_mask:0xf bank_mask:0xf
	v_cndmask_b32_e64 v130, v2, v18, s[8:9]
	s_nop 1
	v_mov_b32_dpp v146, v130 row_ror:2 row_mask:0xf bank_mask:0xf
	v_cndmask_b32_e64 v132, v3, v19, s[6:7]
	v_mov_b32_dpp v130, v131 row_ror:3 row_mask:0xf bank_mask:0xf
	v_cndmask_b32_e64 v131, v3, v19, s[10:11]
	v_cndmask_b32_e64 v133, v4, v20, s[6:7]
	s_nop 0
	v_mov_b32_dpp v155, v131 row_ror:1 row_mask:0xf bank_mask:0xf
	v_cndmask_b32_e64 v131, v3, v19, s[8:9]
	s_nop 1
	v_mov_b32_dpp v147, v131 row_ror:2 row_mask:0xf bank_mask:0xf
	v_cndmask_b32_e64 v150, v5, v21, s[6:7]
	s_nop 0
	v_mov_b32_dpp v131, v132 row_ror:3 row_mask:0xf bank_mask:0xf
	v_cndmask_b32_e64 v132, v4, v20, s[10:11]
	s_nop 1
	v_mov_b32_dpp v156, v132 row_ror:1 row_mask:0xf bank_mask:0xf
	v_cndmask_b32_e64 v132, v4, v20, s[8:9]
	s_nop 1
	v_mov_b32_dpp v148, v132 row_ror:2 row_mask:0xf bank_mask:0xf
	s_nop 1
	v_mov_b32_dpp v132, v133 row_ror:3 row_mask:0xf bank_mask:0xf
	v_cndmask_b32_e64 v133, v5, v21, s[10:11]
	s_nop 1
	v_mov_b32_dpp v157, v133 row_ror:1 row_mask:0xf bank_mask:0xf
	v_cndmask_b32_e64 v133, v5, v21, s[8:9]
	s_nop 1
	v_mov_b32_dpp v149, v133 row_ror:2 row_mask:0xf bank_mask:0xf
	s_nop 1
	v_mov_b32_dpp v133, v150 row_ror:3 row_mask:0xf bank_mask:0xf
